# hand-scheduled PEER gather loops (ring of 4 half-token buffers, prefetch distance 3, counted vmcnt)
# speedup vs baseline: 1.0109x; 1.0109x over previous
.LBB0_594:
	s_cmp_lt_i32 s56, 8
	s_cselect_b64 s[0:1], -1, 0
	s_and_b64 s[0:1], s[0:1], s[4:5]
	s_andn2_b64 vcc, exec, s[0:1]
	s_cbranch_vccnz .LBB0_619
	s_cmpk_gt_i32 s33, 0x7ff
	v_mbcnt_lo_u32_b32 v0, -1, 0
	v_mbcnt_hi_u32_b32 v0, -1, v0
	s_cbranch_scc1 .LBB0_619
	s_mov_b32 s63, s33
.LpgL0_group:
	v_mbcnt_lo_u32_b32 v249, -1, 0
	v_mbcnt_hi_u32_b32 v249, -1, v249
	v_and_b32_e32 v250, 15, v249
	v_lshrrev_b32_e32 v251, 4, v249
	v_and_b32_e32 v252, 3, v250
	v_cmp_eq_u32_e64 s[4:5], 1, v252
	v_cmp_eq_u32_e64 s[6:7], 2, v252
	v_cmp_eq_u32_e64 s[8:9], 3, v252
	v_cmp_eq_u32_e64 s[10:11], 0, v249
	s_add_u32 s12, s54, 0x29800000
	s_addc_u32 s13, s55, 0
	s_and_b32 s13, s13, 0xffff
	s_mov_b32 s14, 0x2000000
	s_mov_b32 s15, 0x20000
	s_add_u32 s16, s54, 0x8000000
	s_addc_u32 s17, s55, 0
	s_and_b32 s17, s17, 0xffff
	s_mov_b32 s18, 0x1000000
	s_mov_b32 s19, 0x20000
	s_add_u32 s20, s54, 0xc000000
	s_addc_u32 s21, s55, 0
	s_and_b32 s21, s21, 0xffff
	s_mov_b32 s22, 0x1000000
	s_mov_b32 s23, 0x20000
	s_add_u32 s30, s54, 0x80000
	s_addc_u32 s31, s55, 0
	s_add_u32 s34, s54, 0xc0000
	s_addc_u32 s35, s55, 0
	s_mov_b32 s94, 0xc3e00000
	s_mov_b32 s96, 0x800000
	s_mov_b32 s81, 0x1010101
	v_lshrrev_b32_e32 v253, 2, v250
	v_lshrrev_b32_e32 v254, 1, v251
	v_lshl_add_u32 v255, v253, 1, v254
	v_lshl_add_u32 v237, v255, 2, s91
	v_and_b32_e32 v255, 1, v251
	v_lshl_add_u32 v236, v255, 2, v252
	v_lshlrev_b32_e32 v236, 4, v236
	v_lshlrev_b32_e32 v254, 7, v254
	v_lshl_add_u32 v254, v252, 5, v254
	v_lshl_add_u32 v254, v255, 4, v254
	v_and_b32_e32 v253, 1, v253
	v_mov_b32_e32 v255, 0x7fff0000
	v_cmp_eq_u32_e32 vcc, 0, v253
	s_nop 1
	v_cndmask_b32_e32 v238, v255, v254, vcc
	v_cndmask_b32_e32 v239, v254, v255, vcc
	v_mov_b32_e32 v240, 0x7f7f7f7f
	v_mov_b32_e32 v255, 0x20202020
	v_cmp_gt_u32_e32 vcc, 8, v250
	s_nop 1
	v_cndmask_b32_e32 v241, v255, v240, vcc
	v_cndmask_b32_e32 v242, v240, v255, vcc
	v_lshrrev_b32_e32 v254, 3, v250
	v_lshl_add_u32 v254, v252, 1, v254
	v_lshl_add_u32 v255, v251, 1, v253
	v_lshl_add_u32 v244, v254, 3, v255
	v_lshlrev_b32_e32 v244, 2, v244
	v_add_u32_e32 v243, s91, v244
	v_and_b32_e32 v253, 3, v255
	v_lshrrev_b32_e32 v255, 2, v255
	v_lshl_add_u32 v253, v253, 1, v255
	v_lshl_add_u32 v253, v254, 3, v253
	v_lshlrev_b32_e32 v253, 2, v253
	v_add_u32_e32 v245, s91, v253
	v_add_u32_e32 v245, 0x1000, v245
	v_mov_b32_e32 v246, 0
	s_lshl_b32 s64, s63, 12
	s_add_u32 s24, s54, 0x28000000
	s_addc_u32 s25, s55, 0
	s_add_u32 s24, s24, s64
	s_addc_u32 s25, s25, 0
	s_lshl_b32 s64, s63, 12
	s_add_u32 s26, s54, 0x28800000
	s_addc_u32 s27, s55, 0
	s_add_u32 s26, s26, s64
	s_addc_u32 s27, s27, 0
	s_lshl_b32 s64, s63, 15
	s_add_u32 s28, s54, 0x18000000
	s_addc_u32 s29, s55, 0
	s_add_u32 s28, s28, s64
	s_addc_u32 s29, s29, 0
	s_lshl_b32 s64, s63, 5
	s_add_u32 s40, s54, 0x40000
	s_addc_u32 s41, s55, 0
	s_add_u32 s40, s40, s64
	s_addc_u32 s41, s41, 0
	s_lshl_b32 s64, s63, 5
	s_add_u32 s44, s54, 0x50000
	s_addc_u32 s45, s55, 0
	s_add_u32 s44, s44, s64
	s_addc_u32 s45, s45, 0
	s_lshl_b32 s61, s63, 14
	s_add_u32 s62, s61, 0x100
	v_mbcnt_lo_u32_b32 v253, -1, 0
	v_mbcnt_hi_u32_b32 v253, -1, v253
	v_lshlrev_b32_e32 v253, 2, v253
	global_load_dword v0, v253, s[24:25] offset:0
	global_load_dword v1, v253, s[24:25] offset:256
	global_load_dword v2, v253, s[24:25] offset:512
	global_load_dword v3, v253, s[24:25] offset:768
	global_load_dword v4, v253, s[24:25] offset:1024
	global_load_dword v5, v253, s[24:25] offset:1280
	global_load_dword v6, v253, s[24:25] offset:1536
	global_load_dword v7, v253, s[24:25] offset:1792
	global_load_dword v8, v253, s[24:25] offset:2048
	global_load_dword v9, v253, s[24:25] offset:2304
	global_load_dword v10, v253, s[24:25] offset:2560
	global_load_dword v11, v253, s[24:25] offset:2816
	global_load_dword v12, v253, s[24:25] offset:3072
	global_load_dword v13, v253, s[24:25] offset:3328
	global_load_dword v14, v253, s[24:25] offset:3584
	global_load_dword v15, v253, s[24:25] offset:3840
	v_add_u32_e32 v254, s91, v253
	s_waitcnt vmcnt(0)
	ds_write_b32 v254, v0 offset:0
	ds_write_b32 v254, v1 offset:256
	ds_write_b32 v254, v2 offset:512
	ds_write_b32 v254, v3 offset:768
	ds_write_b32 v254, v4 offset:1024
	ds_write_b32 v254, v5 offset:1280
	ds_write_b32 v254, v6 offset:1536
	ds_write_b32 v254, v7 offset:1792
	ds_write_b32 v254, v8 offset:2048
	ds_write_b32 v254, v9 offset:2304
	ds_write_b32 v254, v10 offset:2560
	ds_write_b32 v254, v11 offset:2816
	ds_write_b32 v254, v12 offset:3072
	ds_write_b32 v254, v13 offset:3328
	ds_write_b32 v254, v14 offset:3584
	ds_write_b32 v254, v15 offset:3840
	s_waitcnt lgkmcnt(0)
	v_mov_b32_e32 v204, 0
	v_mov_b32_e32 v205, 0
	v_mov_b32_e32 v206, 0
	v_mov_b32_e32 v207, 0
	v_mov_b32_e32 v208, 0
	v_mov_b32_e32 v209, 0
	v_mov_b32_e32 v210, 0
	v_mov_b32_e32 v211, 0
	v_mov_b32_e32 v212, 0
	v_mov_b32_e32 v213, 0
	v_mov_b32_e32 v214, 0
	v_mov_b32_e32 v215, 0
	v_mov_b32_e32 v216, 0
	v_mov_b32_e32 v217, 0
	v_mov_b32_e32 v218, 0
	v_mov_b32_e32 v219, 0
	v_mov_b32_e32 v176, 0
	v_mov_b32_e32 v177, 0
	v_mov_b32_e32 v178, 0
	v_mov_b32_e32 v179, 0
	v_mov_b32_e32 v180, 0
	v_mov_b32_e32 v181, 0
	v_mov_b32_e32 v182, 0
	v_mov_b32_e32 v183, 0
	v_mov_b32_e32 v184, 0
	v_mov_b32_e32 v185, 0
	v_mov_b32_e32 v186, 0
	v_mov_b32_e32 v187, 0
	v_mov_b32_e32 v188, 0
	v_mov_b32_e32 v189, 0
	v_mov_b32_e32 v190, 0
	v_mov_b32_e32 v191, 0
	s_mov_b32 s0, 0
	s_mov_b32 s1, 0
	s_mov_b32 s60, 0x200000
	ds_read_b32 v144, v237 offset:0
	ds_read_b32 v145, v237 offset:32
	ds_read_b32 v146, v237 offset:64
	ds_read_b32 v147, v237 offset:96
	ds_read_b32 v148, v237 offset:128
	ds_read_b32 v149, v237 offset:160
	ds_read_b32 v150, v237 offset:192
	ds_read_b32 v151, v237 offset:224
	s_waitcnt lgkmcnt(0)
	v_lshl_or_b32 v144, v144, 7, v236
	v_lshl_or_b32 v145, v145, 7, v236
	v_lshl_or_b32 v146, v146, 7, v236
	v_lshl_or_b32 v147, v147, 7, v236
	v_lshl_or_b32 v148, v148, 7, v236
	v_lshl_or_b32 v149, v149, 7, v236
	v_lshl_or_b32 v150, v150, 7, v236
	v_lshl_or_b32 v151, v151, 7, v236
	buffer_load_dwordx4 v[0:3], v144, s[16:19], s1 offen
	buffer_load_dwordx4 v[4:7], v145, s[16:19], s1 offen
	buffer_load_dwordx4 v[8:11], v146, s[16:19], s1 offen
	buffer_load_dwordx4 v[12:15], v147, s[16:19], s1 offen
	buffer_load_dwordx4 v[16:19], v148, s[16:19], s1 offen
	buffer_load_dwordx4 v[20:23], v149, s[16:19], s1 offen
	buffer_load_dwordx4 v[24:27], v150, s[16:19], s1 offen
	buffer_load_dwordx4 v[28:31], v151, s[16:19], s1 offen
	ds_read_b32 v144, v237 offset:256
	ds_read_b32 v145, v237 offset:288
	ds_read_b32 v146, v237 offset:320
	ds_read_b32 v147, v237 offset:352
	ds_read_b32 v148, v237 offset:384
	ds_read_b32 v149, v237 offset:416
	ds_read_b32 v150, v237 offset:448
	ds_read_b32 v151, v237 offset:480
	s_add_u32 s80, s61, 0x0
	buffer_load_dwordx4 v[128:131], v238, s[12:15], s80 offen
	buffer_load_dwordx4 v[132:135], v239, s[12:15], s80 offen
	s_waitcnt lgkmcnt(0)
	v_lshl_or_b32 v144, v144, 7, v236
	v_lshl_or_b32 v145, v145, 7, v236
	v_lshl_or_b32 v146, v146, 7, v236
	v_lshl_or_b32 v147, v147, 7, v236
	v_lshl_or_b32 v148, v148, 7, v236
	v_lshl_or_b32 v149, v149, 7, v236
	v_lshl_or_b32 v150, v150, 7, v236
	v_lshl_or_b32 v151, v151, 7, v236
	buffer_load_dwordx4 v[32:35], v144, s[16:19], s1 offen
	buffer_load_dwordx4 v[36:39], v145, s[16:19], s1 offen
	buffer_load_dwordx4 v[40:43], v146, s[16:19], s1 offen
	buffer_load_dwordx4 v[44:47], v147, s[16:19], s1 offen
	buffer_load_dwordx4 v[48:51], v148, s[16:19], s1 offen
	buffer_load_dwordx4 v[52:55], v149, s[16:19], s1 offen
	buffer_load_dwordx4 v[56:59], v150, s[16:19], s1 offen
	buffer_load_dwordx4 v[60:63], v151, s[16:19], s1 offen
	ds_read_b32 v144, v237 offset:512
	ds_read_b32 v145, v237 offset:544
	ds_read_b32 v146, v237 offset:576
	ds_read_b32 v147, v237 offset:608
	ds_read_b32 v148, v237 offset:640
	ds_read_b32 v149, v237 offset:672
	ds_read_b32 v150, v237 offset:704
	ds_read_b32 v151, v237 offset:736
	s_waitcnt lgkmcnt(0)
	v_lshl_or_b32 v144, v144, 7, v236
	v_lshl_or_b32 v145, v145, 7, v236
	v_lshl_or_b32 v146, v146, 7, v236
	v_lshl_or_b32 v147, v147, 7, v236
	v_lshl_or_b32 v148, v148, 7, v236
	v_lshl_or_b32 v149, v149, 7, v236
	v_lshl_or_b32 v150, v150, 7, v236
	v_lshl_or_b32 v151, v151, 7, v236
	buffer_load_dwordx4 v[64:67], v144, s[16:19], s1 offen
	buffer_load_dwordx4 v[68:71], v145, s[16:19], s1 offen
	buffer_load_dwordx4 v[72:75], v146, s[16:19], s1 offen
	buffer_load_dwordx4 v[76:79], v147, s[16:19], s1 offen
	buffer_load_dwordx4 v[80:83], v148, s[16:19], s1 offen
	buffer_load_dwordx4 v[84:87], v149, s[16:19], s1 offen
	buffer_load_dwordx4 v[88:91], v150, s[16:19], s1 offen
	buffer_load_dwordx4 v[92:95], v151, s[16:19], s1 offen
	ds_read_b32 v144, v237 offset:768
	ds_read_b32 v145, v237 offset:800
	ds_read_b32 v146, v237 offset:832
	ds_read_b32 v147, v237 offset:864
	ds_read_b32 v148, v237 offset:896
	ds_read_b32 v149, v237 offset:928
	ds_read_b32 v150, v237 offset:960
	ds_read_b32 v151, v237 offset:992
.LpgL0_uloop:
	s_add_u32 s80, s61, 0x800
	buffer_load_dwordx4 v[136:139], v238, s[12:15], s80 offen
	buffer_load_dwordx4 v[140:143], v239, s[12:15], s80 offen
	s_waitcnt lgkmcnt(0)
	v_lshl_or_b32 v144, v144, 7, v236
	v_lshl_or_b32 v145, v145, 7, v236
	v_lshl_or_b32 v146, v146, 7, v236
	v_lshl_or_b32 v147, v147, 7, v236
	v_lshl_or_b32 v148, v148, 7, v236
	v_lshl_or_b32 v149, v149, 7, v236
	v_lshl_or_b32 v150, v150, 7, v236
	v_lshl_or_b32 v151, v151, 7, v236
	buffer_load_dwordx4 v[96:99], v144, s[16:19], s1 offen
	buffer_load_dwordx4 v[100:103], v145, s[16:19], s1 offen
	buffer_load_dwordx4 v[104:107], v146, s[16:19], s1 offen
	buffer_load_dwordx4 v[108:111], v147, s[16:19], s1 offen
	buffer_load_dwordx4 v[112:115], v148, s[16:19], s1 offen
	buffer_load_dwordx4 v[116:119], v149, s[16:19], s1 offen
	buffer_load_dwordx4 v[120:123], v150, s[16:19], s1 offen
	buffer_load_dwordx4 v[124:127], v151, s[16:19], s1 offen
	ds_read_b32 v144, v237 offset:1024
	ds_read_b32 v145, v237 offset:1056
	ds_read_b32 v146, v237 offset:1088
	ds_read_b32 v147, v237 offset:1120
	ds_read_b32 v148, v237 offset:1152
	ds_read_b32 v149, v237 offset:1184
	ds_read_b32 v150, v237 offset:1216
	ds_read_b32 v151, v237 offset:1248
	s_waitcnt vmcnt(26)
	v_mfma_scale_f32_16x16x128_f8f6f4 v[160:163], v[0:3], v[128:135], 0, v240, v241 op_sel_hi:[0,0,0] cbsz:4
	v_cndmask_b32_e64 v176, v176, v177, s[4:5]
	v_cndmask_b32_e64 v180, v180, v181, s[4:5]
	v_cndmask_b32_e64 v184, v184, v185, s[4:5]
	v_mfma_scale_f32_16x16x128_f8f6f4 v[164:167], v[8:11], v[128:135], 0, v240, v241 op_sel_hi:[0,0,0] cbsz:4
	v_cndmask_b32_e64 v188, v188, v189, s[4:5]
	v_cndmask_b32_e64 v176, v176, v178, s[6:7]
	v_cndmask_b32_e64 v180, v180, v182, s[6:7]
	v_mfma_scale_f32_16x16x128_f8f6f4 v[168:171], v[16:19], v[128:135], 0, v240, v241 op_sel_hi:[0,0,0] cbsz:4
	v_cndmask_b32_e64 v184, v184, v186, s[6:7]
	v_cndmask_b32_e64 v188, v188, v190, s[6:7]
	v_cndmask_b32_e64 v176, v176, v179, s[8:9]
	v_mfma_scale_f32_16x16x128_f8f6f4 v[172:175], v[24:27], v[128:135], 0, v240, v241 op_sel_hi:[0,0,0] cbsz:4
	v_cndmask_b32_e64 v180, v180, v183, s[8:9]
	v_cndmask_b32_e64 v184, v184, v187, s[8:9]
	v_cndmask_b32_e64 v188, v188, v191, s[8:9]
	v_mfma_scale_f32_16x16x128_f8f6f4 v[160:163], v[4:7], v[128:135], v[160:163], v240, v242 op_sel_hi:[0,0,0] cbsz:4
	v_add_f32_dpp v176, v176, v176 quad_perm:[1,0,3,2] row_mask:0xf bank_mask:0xf bound_ctrl:1
	v_add_f32_dpp v180, v180, v180 quad_perm:[1,0,3,2] row_mask:0xf bank_mask:0xf bound_ctrl:1
	v_add_f32_dpp v184, v184, v184 quad_perm:[1,0,3,2] row_mask:0xf bank_mask:0xf bound_ctrl:1
	v_mfma_scale_f32_16x16x128_f8f6f4 v[164:167], v[12:15], v[128:135], v[164:167], v240, v242 op_sel_hi:[0,0,0] cbsz:4
	v_add_f32_dpp v188, v188, v188 quad_perm:[1,0,3,2] row_mask:0xf bank_mask:0xf bound_ctrl:1
	v_add_f32_dpp v176, v176, v176 quad_perm:[2,3,0,1] row_mask:0xf bank_mask:0xf bound_ctrl:1
	v_add_f32_dpp v180, v180, v180 quad_perm:[2,3,0,1] row_mask:0xf bank_mask:0xf bound_ctrl:1
	v_mfma_scale_f32_16x16x128_f8f6f4 v[168:171], v[20:23], v[128:135], v[168:171], v240, v242 op_sel_hi:[0,0,0] cbsz:4
	v_add_f32_dpp v184, v184, v184 quad_perm:[2,3,0,1] row_mask:0xf bank_mask:0xf bound_ctrl:1
	v_add_f32_dpp v188, v188, v188 quad_perm:[2,3,0,1] row_mask:0xf bank_mask:0xf bound_ctrl:1
	v_cndmask_b32_e64 v176, v176, v180, s[4:5]
	v_mfma_scale_f32_16x16x128_f8f6f4 v[172:175], v[28:31], v[128:135], v[172:175], v240, v242 op_sel_hi:[0,0,0] cbsz:4
	v_cndmask_b32_e64 v176, v176, v184, s[6:7]
	v_cndmask_b32_e64 v176, v176, v188, s[8:9]
	v_add_f32_e32 v219, v219, v176
	s_waitcnt lgkmcnt(0)
	v_lshl_or_b32 v144, v144, 7, v236
	v_lshl_or_b32 v145, v145, 7, v236
	v_lshl_or_b32 v146, v146, 7, v236
	v_lshl_or_b32 v147, v147, 7, v236
	v_lshl_or_b32 v148, v148, 7, v236
	v_lshl_or_b32 v149, v149, 7, v236
	v_lshl_or_b32 v150, v150, 7, v236
	v_lshl_or_b32 v151, v151, 7, v236
	buffer_load_dwordx4 v[0:3], v144, s[16:19], s1 offen
	buffer_load_dwordx4 v[4:7], v145, s[16:19], s1 offen
	buffer_load_dwordx4 v[8:11], v146, s[16:19], s1 offen
	buffer_load_dwordx4 v[12:15], v147, s[16:19], s1 offen
	buffer_load_dwordx4 v[16:19], v148, s[16:19], s1 offen
	buffer_load_dwordx4 v[20:23], v149, s[16:19], s1 offen
	buffer_load_dwordx4 v[24:27], v150, s[16:19], s1 offen
	buffer_load_dwordx4 v[28:31], v151, s[16:19], s1 offen
	ds_read_b32 v144, v237 offset:1280
	ds_read_b32 v145, v237 offset:1312
	ds_read_b32 v146, v237 offset:1344
	ds_read_b32 v147, v237 offset:1376
	ds_read_b32 v148, v237 offset:1408
	ds_read_b32 v149, v237 offset:1440
	ds_read_b32 v150, v237 offset:1472
	ds_read_b32 v151, v237 offset:1504
	s_waitcnt vmcnt(26)
	v_mfma_scale_f32_16x16x128_f8f6f4 v[176:179], v[32:35], v[128:135], 0, v240, v241 op_sel_hi:[0,0,0] cbsz:4
	v_cndmask_b32_e64 v160, v160, v161, s[4:5]
	v_cndmask_b32_e64 v164, v164, v165, s[4:5]
	v_cndmask_b32_e64 v168, v168, v169, s[4:5]
	v_mfma_scale_f32_16x16x128_f8f6f4 v[180:183], v[40:43], v[128:135], 0, v240, v241 op_sel_hi:[0,0,0] cbsz:4
	v_cndmask_b32_e64 v172, v172, v173, s[4:5]
	v_cndmask_b32_e64 v160, v160, v162, s[6:7]
	v_cndmask_b32_e64 v164, v164, v166, s[6:7]
	v_mfma_scale_f32_16x16x128_f8f6f4 v[184:187], v[48:51], v[128:135], 0, v240, v241 op_sel_hi:[0,0,0] cbsz:4
	v_cndmask_b32_e64 v168, v168, v170, s[6:7]
	v_cndmask_b32_e64 v172, v172, v174, s[6:7]
	v_cndmask_b32_e64 v160, v160, v163, s[8:9]
	v_mfma_scale_f32_16x16x128_f8f6f4 v[188:191], v[56:59], v[128:135], 0, v240, v241 op_sel_hi:[0,0,0] cbsz:4
	v_cndmask_b32_e64 v164, v164, v167, s[8:9]
	v_cndmask_b32_e64 v168, v168, v171, s[8:9]
	v_cndmask_b32_e64 v172, v172, v175, s[8:9]
	v_mfma_scale_f32_16x16x128_f8f6f4 v[176:179], v[36:39], v[128:135], v[176:179], v240, v242 op_sel_hi:[0,0,0] cbsz:4
	v_add_f32_dpp v160, v160, v160 quad_perm:[1,0,3,2] row_mask:0xf bank_mask:0xf bound_ctrl:1
	v_add_f32_dpp v164, v164, v164 quad_perm:[1,0,3,2] row_mask:0xf bank_mask:0xf bound_ctrl:1
	v_add_f32_dpp v168, v168, v168 quad_perm:[1,0,3,2] row_mask:0xf bank_mask:0xf bound_ctrl:1
	v_mfma_scale_f32_16x16x128_f8f6f4 v[180:183], v[44:47], v[128:135], v[180:183], v240, v242 op_sel_hi:[0,0,0] cbsz:4
	v_add_f32_dpp v172, v172, v172 quad_perm:[1,0,3,2] row_mask:0xf bank_mask:0xf bound_ctrl:1
	v_add_f32_dpp v160, v160, v160 quad_perm:[2,3,0,1] row_mask:0xf bank_mask:0xf bound_ctrl:1
	v_add_f32_dpp v164, v164, v164 quad_perm:[2,3,0,1] row_mask:0xf bank_mask:0xf bound_ctrl:1
	v_mfma_scale_f32_16x16x128_f8f6f4 v[184:187], v[52:55], v[128:135], v[184:187], v240, v242 op_sel_hi:[0,0,0] cbsz:4
	v_add_f32_dpp v168, v168, v168 quad_perm:[2,3,0,1] row_mask:0xf bank_mask:0xf bound_ctrl:1
	v_add_f32_dpp v172, v172, v172 quad_perm:[2,3,0,1] row_mask:0xf bank_mask:0xf bound_ctrl:1
	v_cndmask_b32_e64 v160, v160, v164, s[4:5]
	v_mfma_scale_f32_16x16x128_f8f6f4 v[188:191], v[60:63], v[128:135], v[188:191], v240, v242 op_sel_hi:[0,0,0] cbsz:4
	v_cndmask_b32_e64 v160, v160, v168, s[6:7]
	v_cndmask_b32_e64 v160, v160, v172, s[8:9]
	v_add_f32_e32 v204, v204, v160
	s_add_u32 s80, s61, 0x1000
	buffer_load_dwordx4 v[128:131], v238, s[12:15], s80 offen
	buffer_load_dwordx4 v[132:135], v239, s[12:15], s80 offen
	s_waitcnt lgkmcnt(0)
	v_lshl_or_b32 v144, v144, 7, v236
	v_lshl_or_b32 v145, v145, 7, v236
	v_lshl_or_b32 v146, v146, 7, v236
	v_lshl_or_b32 v147, v147, 7, v236
	v_lshl_or_b32 v148, v148, 7, v236
	v_lshl_or_b32 v149, v149, 7, v236
	v_lshl_or_b32 v150, v150, 7, v236
	v_lshl_or_b32 v151, v151, 7, v236
	buffer_load_dwordx4 v[32:35], v144, s[16:19], s1 offen
	buffer_load_dwordx4 v[36:39], v145, s[16:19], s1 offen
	buffer_load_dwordx4 v[40:43], v146, s[16:19], s1 offen
	buffer_load_dwordx4 v[44:47], v147, s[16:19], s1 offen
	buffer_load_dwordx4 v[48:51], v148, s[16:19], s1 offen
	buffer_load_dwordx4 v[52:55], v149, s[16:19], s1 offen
	buffer_load_dwordx4 v[56:59], v150, s[16:19], s1 offen
	buffer_load_dwordx4 v[60:63], v151, s[16:19], s1 offen
	ds_read_b32 v144, v237 offset:1536
	ds_read_b32 v145, v237 offset:1568
	ds_read_b32 v146, v237 offset:1600
	ds_read_b32 v147, v237 offset:1632
	ds_read_b32 v148, v237 offset:1664
	ds_read_b32 v149, v237 offset:1696
	ds_read_b32 v150, v237 offset:1728
	ds_read_b32 v151, v237 offset:1760
	s_waitcnt vmcnt(26)
	v_mfma_scale_f32_16x16x128_f8f6f4 v[160:163], v[64:67], v[136:143], 0, v240, v241 op_sel_hi:[0,0,0] cbsz:4
	v_cndmask_b32_e64 v176, v176, v177, s[4:5]
	v_cndmask_b32_e64 v180, v180, v181, s[4:5]
	v_cndmask_b32_e64 v184, v184, v185, s[4:5]
	v_mfma_scale_f32_16x16x128_f8f6f4 v[164:167], v[72:75], v[136:143], 0, v240, v241 op_sel_hi:[0,0,0] cbsz:4
	v_cndmask_b32_e64 v188, v188, v189, s[4:5]
	v_cndmask_b32_e64 v176, v176, v178, s[6:7]
	v_cndmask_b32_e64 v180, v180, v182, s[6:7]
	v_mfma_scale_f32_16x16x128_f8f6f4 v[168:171], v[80:83], v[136:143], 0, v240, v241 op_sel_hi:[0,0,0] cbsz:4
	v_cndmask_b32_e64 v184, v184, v186, s[6:7]
	v_cndmask_b32_e64 v188, v188, v190, s[6:7]
	v_cndmask_b32_e64 v176, v176, v179, s[8:9]
	v_mfma_scale_f32_16x16x128_f8f6f4 v[172:175], v[88:91], v[136:143], 0, v240, v241 op_sel_hi:[0,0,0] cbsz:4
	v_cndmask_b32_e64 v180, v180, v183, s[8:9]
	v_cndmask_b32_e64 v184, v184, v187, s[8:9]
	v_cndmask_b32_e64 v188, v188, v191, s[8:9]
	v_mfma_scale_f32_16x16x128_f8f6f4 v[160:163], v[68:71], v[136:143], v[160:163], v240, v242 op_sel_hi:[0,0,0] cbsz:4
	v_add_f32_dpp v176, v176, v176 quad_perm:[1,0,3,2] row_mask:0xf bank_mask:0xf bound_ctrl:1
	v_add_f32_dpp v180, v180, v180 quad_perm:[1,0,3,2] row_mask:0xf bank_mask:0xf bound_ctrl:1
	v_add_f32_dpp v184, v184, v184 quad_perm:[1,0,3,2] row_mask:0xf bank_mask:0xf bound_ctrl:1
	v_mfma_scale_f32_16x16x128_f8f6f4 v[164:167], v[76:79], v[136:143], v[164:167], v240, v242 op_sel_hi:[0,0,0] cbsz:4
	v_add_f32_dpp v188, v188, v188 quad_perm:[1,0,3,2] row_mask:0xf bank_mask:0xf bound_ctrl:1
	v_add_f32_dpp v176, v176, v176 quad_perm:[2,3,0,1] row_mask:0xf bank_mask:0xf bound_ctrl:1
	v_add_f32_dpp v180, v180, v180 quad_perm:[2,3,0,1] row_mask:0xf bank_mask:0xf bound_ctrl:1
	v_mfma_scale_f32_16x16x128_f8f6f4 v[168:171], v[84:87], v[136:143], v[168:171], v240, v242 op_sel_hi:[0,0,0] cbsz:4
	v_add_f32_dpp v184, v184, v184 quad_perm:[2,3,0,1] row_mask:0xf bank_mask:0xf bound_ctrl:1
	v_add_f32_dpp v188, v188, v188 quad_perm:[2,3,0,1] row_mask:0xf bank_mask:0xf bound_ctrl:1
	v_cndmask_b32_e64 v176, v176, v180, s[4:5]
	v_mfma_scale_f32_16x16x128_f8f6f4 v[172:175], v[92:95], v[136:143], v[172:175], v240, v242 op_sel_hi:[0,0,0] cbsz:4
	v_cndmask_b32_e64 v176, v176, v184, s[6:7]
	v_cndmask_b32_e64 v176, v176, v188, s[8:9]
	v_add_f32_e32 v205, v205, v176
	s_waitcnt lgkmcnt(0)
	v_lshl_or_b32 v144, v144, 7, v236
	v_lshl_or_b32 v145, v145, 7, v236
	v_lshl_or_b32 v146, v146, 7, v236
	v_lshl_or_b32 v147, v147, 7, v236
	v_lshl_or_b32 v148, v148, 7, v236
	v_lshl_or_b32 v149, v149, 7, v236
	v_lshl_or_b32 v150, v150, 7, v236
	v_lshl_or_b32 v151, v151, 7, v236
	buffer_load_dwordx4 v[64:67], v144, s[16:19], s1 offen
	buffer_load_dwordx4 v[68:71], v145, s[16:19], s1 offen
	buffer_load_dwordx4 v[72:75], v146, s[16:19], s1 offen
	buffer_load_dwordx4 v[76:79], v147, s[16:19], s1 offen
	buffer_load_dwordx4 v[80:83], v148, s[16:19], s1 offen
	buffer_load_dwordx4 v[84:87], v149, s[16:19], s1 offen
	buffer_load_dwordx4 v[88:91], v150, s[16:19], s1 offen
	buffer_load_dwordx4 v[92:95], v151, s[16:19], s1 offen
	ds_read_b32 v144, v237 offset:1792
	ds_read_b32 v145, v237 offset:1824
	ds_read_b32 v146, v237 offset:1856
	ds_read_b32 v147, v237 offset:1888
	ds_read_b32 v148, v237 offset:1920
	ds_read_b32 v149, v237 offset:1952
	ds_read_b32 v150, v237 offset:1984
	ds_read_b32 v151, v237 offset:2016
	s_waitcnt vmcnt(26)
	v_mfma_scale_f32_16x16x128_f8f6f4 v[176:179], v[96:99], v[136:143], 0, v240, v241 op_sel_hi:[0,0,0] cbsz:4
	v_cndmask_b32_e64 v160, v160, v161, s[4:5]
	v_cndmask_b32_e64 v164, v164, v165, s[4:5]
	v_cndmask_b32_e64 v168, v168, v169, s[4:5]
	v_mfma_scale_f32_16x16x128_f8f6f4 v[180:183], v[104:107], v[136:143], 0, v240, v241 op_sel_hi:[0,0,0] cbsz:4
	v_cndmask_b32_e64 v172, v172, v173, s[4:5]
	v_cndmask_b32_e64 v160, v160, v162, s[6:7]
	v_cndmask_b32_e64 v164, v164, v166, s[6:7]
	v_mfma_scale_f32_16x16x128_f8f6f4 v[184:187], v[112:115], v[136:143], 0, v240, v241 op_sel_hi:[0,0,0] cbsz:4
	v_cndmask_b32_e64 v168, v168, v170, s[6:7]
	v_cndmask_b32_e64 v172, v172, v174, s[6:7]
	v_cndmask_b32_e64 v160, v160, v163, s[8:9]
	v_mfma_scale_f32_16x16x128_f8f6f4 v[188:191], v[120:123], v[136:143], 0, v240, v241 op_sel_hi:[0,0,0] cbsz:4
	v_cndmask_b32_e64 v164, v164, v167, s[8:9]
	v_cndmask_b32_e64 v168, v168, v171, s[8:9]
	v_cndmask_b32_e64 v172, v172, v175, s[8:9]
	v_mfma_scale_f32_16x16x128_f8f6f4 v[176:179], v[100:103], v[136:143], v[176:179], v240, v242 op_sel_hi:[0,0,0] cbsz:4
	v_add_f32_dpp v160, v160, v160 quad_perm:[1,0,3,2] row_mask:0xf bank_mask:0xf bound_ctrl:1
	v_add_f32_dpp v164, v164, v164 quad_perm:[1,0,3,2] row_mask:0xf bank_mask:0xf bound_ctrl:1
	v_add_f32_dpp v168, v168, v168 quad_perm:[1,0,3,2] row_mask:0xf bank_mask:0xf bound_ctrl:1
	v_mfma_scale_f32_16x16x128_f8f6f4 v[180:183], v[108:111], v[136:143], v[180:183], v240, v242 op_sel_hi:[0,0,0] cbsz:4
	v_add_f32_dpp v172, v172, v172 quad_perm:[1,0,3,2] row_mask:0xf bank_mask:0xf bound_ctrl:1
	v_add_f32_dpp v160, v160, v160 quad_perm:[2,3,0,1] row_mask:0xf bank_mask:0xf bound_ctrl:1
	v_add_f32_dpp v164, v164, v164 quad_perm:[2,3,0,1] row_mask:0xf bank_mask:0xf bound_ctrl:1
	v_mfma_scale_f32_16x16x128_f8f6f4 v[184:187], v[116:119], v[136:143], v[184:187], v240, v242 op_sel_hi:[0,0,0] cbsz:4
	v_add_f32_dpp v168, v168, v168 quad_perm:[2,3,0,1] row_mask:0xf bank_mask:0xf bound_ctrl:1
	v_add_f32_dpp v172, v172, v172 quad_perm:[2,3,0,1] row_mask:0xf bank_mask:0xf bound_ctrl:1
	v_cndmask_b32_e64 v160, v160, v164, s[4:5]
	v_mfma_scale_f32_16x16x128_f8f6f4 v[188:191], v[124:127], v[136:143], v[188:191], v240, v242 op_sel_hi:[0,0,0] cbsz:4
	v_cndmask_b32_e64 v160, v160, v168, s[6:7]
	v_cndmask_b32_e64 v160, v160, v172, s[8:9]
	v_add_f32_e32 v206, v206, v160
	s_add_u32 s80, s61, 0x1800
	buffer_load_dwordx4 v[136:139], v238, s[12:15], s80 offen
	buffer_load_dwordx4 v[140:143], v239, s[12:15], s80 offen
	s_waitcnt lgkmcnt(0)
	v_lshl_or_b32 v144, v144, 7, v236
	v_lshl_or_b32 v145, v145, 7, v236
	v_lshl_or_b32 v146, v146, 7, v236
	v_lshl_or_b32 v147, v147, 7, v236
	v_lshl_or_b32 v148, v148, 7, v236
	v_lshl_or_b32 v149, v149, 7, v236
	v_lshl_or_b32 v150, v150, 7, v236
	v_lshl_or_b32 v151, v151, 7, v236
	buffer_load_dwordx4 v[96:99], v144, s[16:19], s1 offen
	buffer_load_dwordx4 v[100:103], v145, s[16:19], s1 offen
	buffer_load_dwordx4 v[104:107], v146, s[16:19], s1 offen
	buffer_load_dwordx4 v[108:111], v147, s[16:19], s1 offen
	buffer_load_dwordx4 v[112:115], v148, s[16:19], s1 offen
	buffer_load_dwordx4 v[116:119], v149, s[16:19], s1 offen
	buffer_load_dwordx4 v[120:123], v150, s[16:19], s1 offen
	buffer_load_dwordx4 v[124:127], v151, s[16:19], s1 offen
	ds_read_b32 v144, v237 offset:2048
	ds_read_b32 v145, v237 offset:2080
	ds_read_b32 v146, v237 offset:2112
	ds_read_b32 v147, v237 offset:2144
	ds_read_b32 v148, v237 offset:2176
	ds_read_b32 v149, v237 offset:2208
	ds_read_b32 v150, v237 offset:2240
	ds_read_b32 v151, v237 offset:2272
	s_waitcnt vmcnt(26)
	v_mfma_scale_f32_16x16x128_f8f6f4 v[160:163], v[0:3], v[128:135], 0, v240, v241 op_sel_hi:[0,0,0] cbsz:4
	v_cndmask_b32_e64 v176, v176, v177, s[4:5]
	v_cndmask_b32_e64 v180, v180, v181, s[4:5]
	v_cndmask_b32_e64 v184, v184, v185, s[4:5]
	v_mfma_scale_f32_16x16x128_f8f6f4 v[164:167], v[8:11], v[128:135], 0, v240, v241 op_sel_hi:[0,0,0] cbsz:4
	v_cndmask_b32_e64 v188, v188, v189, s[4:5]
	v_cndmask_b32_e64 v176, v176, v178, s[6:7]
	v_cndmask_b32_e64 v180, v180, v182, s[6:7]
	v_mfma_scale_f32_16x16x128_f8f6f4 v[168:171], v[16:19], v[128:135], 0, v240, v241 op_sel_hi:[0,0,0] cbsz:4
	v_cndmask_b32_e64 v184, v184, v186, s[6:7]
	v_cndmask_b32_e64 v188, v188, v190, s[6:7]
	v_cndmask_b32_e64 v176, v176, v179, s[8:9]
	v_mfma_scale_f32_16x16x128_f8f6f4 v[172:175], v[24:27], v[128:135], 0, v240, v241 op_sel_hi:[0,0,0] cbsz:4
	v_cndmask_b32_e64 v180, v180, v183, s[8:9]
	v_cndmask_b32_e64 v184, v184, v187, s[8:9]
	v_cndmask_b32_e64 v188, v188, v191, s[8:9]
	v_mfma_scale_f32_16x16x128_f8f6f4 v[160:163], v[4:7], v[128:135], v[160:163], v240, v242 op_sel_hi:[0,0,0] cbsz:4
	v_add_f32_dpp v176, v176, v176 quad_perm:[1,0,3,2] row_mask:0xf bank_mask:0xf bound_ctrl:1
	v_add_f32_dpp v180, v180, v180 quad_perm:[1,0,3,2] row_mask:0xf bank_mask:0xf bound_ctrl:1
	v_add_f32_dpp v184, v184, v184 quad_perm:[1,0,3,2] row_mask:0xf bank_mask:0xf bound_ctrl:1
	v_mfma_scale_f32_16x16x128_f8f6f4 v[164:167], v[12:15], v[128:135], v[164:167], v240, v242 op_sel_hi:[0,0,0] cbsz:4
	v_add_f32_dpp v188, v188, v188 quad_perm:[1,0,3,2] row_mask:0xf bank_mask:0xf bound_ctrl:1
	v_add_f32_dpp v176, v176, v176 quad_perm:[2,3,0,1] row_mask:0xf bank_mask:0xf bound_ctrl:1
	v_add_f32_dpp v180, v180, v180 quad_perm:[2,3,0,1] row_mask:0xf bank_mask:0xf bound_ctrl:1
	v_mfma_scale_f32_16x16x128_f8f6f4 v[168:171], v[20:23], v[128:135], v[168:171], v240, v242 op_sel_hi:[0,0,0] cbsz:4
	v_add_f32_dpp v184, v184, v184 quad_perm:[2,3,0,1] row_mask:0xf bank_mask:0xf bound_ctrl:1
	v_add_f32_dpp v188, v188, v188 quad_perm:[2,3,0,1] row_mask:0xf bank_mask:0xf bound_ctrl:1
	v_cndmask_b32_e64 v176, v176, v180, s[4:5]
	v_mfma_scale_f32_16x16x128_f8f6f4 v[172:175], v[28:31], v[128:135], v[172:175], v240, v242 op_sel_hi:[0,0,0] cbsz:4
	v_cndmask_b32_e64 v176, v176, v184, s[6:7]
	v_cndmask_b32_e64 v176, v176, v188, s[8:9]
	v_add_f32_e32 v207, v207, v176
	s_waitcnt lgkmcnt(0)
	v_lshl_or_b32 v144, v144, 7, v236
	v_lshl_or_b32 v145, v145, 7, v236
	v_lshl_or_b32 v146, v146, 7, v236
	v_lshl_or_b32 v147, v147, 7, v236
	v_lshl_or_b32 v148, v148, 7, v236
	v_lshl_or_b32 v149, v149, 7, v236
	v_lshl_or_b32 v150, v150, 7, v236
	v_lshl_or_b32 v151, v151, 7, v236
	buffer_load_dwordx4 v[0:3], v144, s[16:19], s1 offen
	buffer_load_dwordx4 v[4:7], v145, s[16:19], s1 offen
	buffer_load_dwordx4 v[8:11], v146, s[16:19], s1 offen
	buffer_load_dwordx4 v[12:15], v147, s[16:19], s1 offen
	buffer_load_dwordx4 v[16:19], v148, s[16:19], s1 offen
	buffer_load_dwordx4 v[20:23], v149, s[16:19], s1 offen
	buffer_load_dwordx4 v[24:27], v150, s[16:19], s1 offen
	buffer_load_dwordx4 v[28:31], v151, s[16:19], s1 offen
	ds_read_b32 v144, v237 offset:2304
	ds_read_b32 v145, v237 offset:2336
	ds_read_b32 v146, v237 offset:2368
	ds_read_b32 v147, v237 offset:2400
	ds_read_b32 v148, v237 offset:2432
	ds_read_b32 v149, v237 offset:2464
	ds_read_b32 v150, v237 offset:2496
	ds_read_b32 v151, v237 offset:2528
	s_waitcnt vmcnt(26)
	v_mfma_scale_f32_16x16x128_f8f6f4 v[176:179], v[32:35], v[128:135], 0, v240, v241 op_sel_hi:[0,0,0] cbsz:4
	v_cndmask_b32_e64 v160, v160, v161, s[4:5]
	v_cndmask_b32_e64 v164, v164, v165, s[4:5]
	v_cndmask_b32_e64 v168, v168, v169, s[4:5]
	v_mfma_scale_f32_16x16x128_f8f6f4 v[180:183], v[40:43], v[128:135], 0, v240, v241 op_sel_hi:[0,0,0] cbsz:4
	v_cndmask_b32_e64 v172, v172, v173, s[4:5]
	v_cndmask_b32_e64 v160, v160, v162, s[6:7]
	v_cndmask_b32_e64 v164, v164, v166, s[6:7]
	v_mfma_scale_f32_16x16x128_f8f6f4 v[184:187], v[48:51], v[128:135], 0, v240, v241 op_sel_hi:[0,0,0] cbsz:4
	v_cndmask_b32_e64 v168, v168, v170, s[6:7]
	v_cndmask_b32_e64 v172, v172, v174, s[6:7]
	v_cndmask_b32_e64 v160, v160, v163, s[8:9]
	v_mfma_scale_f32_16x16x128_f8f6f4 v[188:191], v[56:59], v[128:135], 0, v240, v241 op_sel_hi:[0,0,0] cbsz:4
	v_cndmask_b32_e64 v164, v164, v167, s[8:9]
	v_cndmask_b32_e64 v168, v168, v171, s[8:9]
	v_cndmask_b32_e64 v172, v172, v175, s[8:9]
	v_mfma_scale_f32_16x16x128_f8f6f4 v[176:179], v[36:39], v[128:135], v[176:179], v240, v242 op_sel_hi:[0,0,0] cbsz:4
	v_add_f32_dpp v160, v160, v160 quad_perm:[1,0,3,2] row_mask:0xf bank_mask:0xf bound_ctrl:1
	v_add_f32_dpp v164, v164, v164 quad_perm:[1,0,3,2] row_mask:0xf bank_mask:0xf bound_ctrl:1
	v_add_f32_dpp v168, v168, v168 quad_perm:[1,0,3,2] row_mask:0xf bank_mask:0xf bound_ctrl:1
	v_mfma_scale_f32_16x16x128_f8f6f4 v[180:183], v[44:47], v[128:135], v[180:183], v240, v242 op_sel_hi:[0,0,0] cbsz:4
	v_add_f32_dpp v172, v172, v172 quad_perm:[1,0,3,2] row_mask:0xf bank_mask:0xf bound_ctrl:1
	v_add_f32_dpp v160, v160, v160 quad_perm:[2,3,0,1] row_mask:0xf bank_mask:0xf bound_ctrl:1
	v_add_f32_dpp v164, v164, v164 quad_perm:[2,3,0,1] row_mask:0xf bank_mask:0xf bound_ctrl:1
	v_mfma_scale_f32_16x16x128_f8f6f4 v[184:187], v[52:55], v[128:135], v[184:187], v240, v242 op_sel_hi:[0,0,0] cbsz:4
	v_add_f32_dpp v168, v168, v168 quad_perm:[2,3,0,1] row_mask:0xf bank_mask:0xf bound_ctrl:1
	v_add_f32_dpp v172, v172, v172 quad_perm:[2,3,0,1] row_mask:0xf bank_mask:0xf bound_ctrl:1
	v_cndmask_b32_e64 v160, v160, v164, s[4:5]
	v_mfma_scale_f32_16x16x128_f8f6f4 v[188:191], v[60:63], v[128:135], v[188:191], v240, v242 op_sel_hi:[0,0,0] cbsz:4
	v_cndmask_b32_e64 v160, v160, v168, s[6:7]
	v_cndmask_b32_e64 v160, v160, v172, s[8:9]
	v_add_f32_e32 v208, v208, v160
	s_add_u32 s80, s61, 0x2000
	buffer_load_dwordx4 v[128:131], v238, s[12:15], s80 offen
	buffer_load_dwordx4 v[132:135], v239, s[12:15], s80 offen
	s_waitcnt lgkmcnt(0)
	v_lshl_or_b32 v144, v144, 7, v236
	v_lshl_or_b32 v145, v145, 7, v236
	v_lshl_or_b32 v146, v146, 7, v236
	v_lshl_or_b32 v147, v147, 7, v236
	v_lshl_or_b32 v148, v148, 7, v236
	v_lshl_or_b32 v149, v149, 7, v236
	v_lshl_or_b32 v150, v150, 7, v236
	v_lshl_or_b32 v151, v151, 7, v236
	buffer_load_dwordx4 v[32:35], v144, s[16:19], s1 offen
	buffer_load_dwordx4 v[36:39], v145, s[16:19], s1 offen
	buffer_load_dwordx4 v[40:43], v146, s[16:19], s1 offen
	buffer_load_dwordx4 v[44:47], v147, s[16:19], s1 offen
	buffer_load_dwordx4 v[48:51], v148, s[16:19], s1 offen
	buffer_load_dwordx4 v[52:55], v149, s[16:19], s1 offen
	buffer_load_dwordx4 v[56:59], v150, s[16:19], s1 offen
	buffer_load_dwordx4 v[60:63], v151, s[16:19], s1 offen
	ds_read_b32 v144, v237 offset:2560
	ds_read_b32 v145, v237 offset:2592
	ds_read_b32 v146, v237 offset:2624
	ds_read_b32 v147, v237 offset:2656
	ds_read_b32 v148, v237 offset:2688
	ds_read_b32 v149, v237 offset:2720
	ds_read_b32 v150, v237 offset:2752
	ds_read_b32 v151, v237 offset:2784
	s_waitcnt vmcnt(26)
	v_mfma_scale_f32_16x16x128_f8f6f4 v[160:163], v[64:67], v[136:143], 0, v240, v241 op_sel_hi:[0,0,0] cbsz:4
	v_cndmask_b32_e64 v176, v176, v177, s[4:5]
	v_cndmask_b32_e64 v180, v180, v181, s[4:5]
	v_cndmask_b32_e64 v184, v184, v185, s[4:5]
	v_mfma_scale_f32_16x16x128_f8f6f4 v[164:167], v[72:75], v[136:143], 0, v240, v241 op_sel_hi:[0,0,0] cbsz:4
	v_cndmask_b32_e64 v188, v188, v189, s[4:5]
	v_cndmask_b32_e64 v176, v176, v178, s[6:7]
	v_cndmask_b32_e64 v180, v180, v182, s[6:7]
	v_mfma_scale_f32_16x16x128_f8f6f4 v[168:171], v[80:83], v[136:143], 0, v240, v241 op_sel_hi:[0,0,0] cbsz:4
	v_cndmask_b32_e64 v184, v184, v186, s[6:7]
	v_cndmask_b32_e64 v188, v188, v190, s[6:7]
	v_cndmask_b32_e64 v176, v176, v179, s[8:9]
	v_mfma_scale_f32_16x16x128_f8f6f4 v[172:175], v[88:91], v[136:143], 0, v240, v241 op_sel_hi:[0,0,0] cbsz:4
	v_cndmask_b32_e64 v180, v180, v183, s[8:9]
	v_cndmask_b32_e64 v184, v184, v187, s[8:9]
	v_cndmask_b32_e64 v188, v188, v191, s[8:9]
	v_mfma_scale_f32_16x16x128_f8f6f4 v[160:163], v[68:71], v[136:143], v[160:163], v240, v242 op_sel_hi:[0,0,0] cbsz:4
	v_add_f32_dpp v176, v176, v176 quad_perm:[1,0,3,2] row_mask:0xf bank_mask:0xf bound_ctrl:1
	v_add_f32_dpp v180, v180, v180 quad_perm:[1,0,3,2] row_mask:0xf bank_mask:0xf bound_ctrl:1
	v_add_f32_dpp v184, v184, v184 quad_perm:[1,0,3,2] row_mask:0xf bank_mask:0xf bound_ctrl:1
	v_mfma_scale_f32_16x16x128_f8f6f4 v[164:167], v[76:79], v[136:143], v[164:167], v240, v242 op_sel_hi:[0,0,0] cbsz:4
	v_add_f32_dpp v188, v188, v188 quad_perm:[1,0,3,2] row_mask:0xf bank_mask:0xf bound_ctrl:1
	v_add_f32_dpp v176, v176, v176 quad_perm:[2,3,0,1] row_mask:0xf bank_mask:0xf bound_ctrl:1
	v_add_f32_dpp v180, v180, v180 quad_perm:[2,3,0,1] row_mask:0xf bank_mask:0xf bound_ctrl:1
	v_mfma_scale_f32_16x16x128_f8f6f4 v[168:171], v[84:87], v[136:143], v[168:171], v240, v242 op_sel_hi:[0,0,0] cbsz:4
	v_add_f32_dpp v184, v184, v184 quad_perm:[2,3,0,1] row_mask:0xf bank_mask:0xf bound_ctrl:1
	v_add_f32_dpp v188, v188, v188 quad_perm:[2,3,0,1] row_mask:0xf bank_mask:0xf bound_ctrl:1
	v_cndmask_b32_e64 v176, v176, v180, s[4:5]
	v_mfma_scale_f32_16x16x128_f8f6f4 v[172:175], v[92:95], v[136:143], v[172:175], v240, v242 op_sel_hi:[0,0,0] cbsz:4
	v_cndmask_b32_e64 v176, v176, v184, s[6:7]
	v_cndmask_b32_e64 v176, v176, v188, s[8:9]
	v_add_f32_e32 v209, v209, v176
	s_waitcnt lgkmcnt(0)
	v_lshl_or_b32 v144, v144, 7, v236
	v_lshl_or_b32 v145, v145, 7, v236
	v_lshl_or_b32 v146, v146, 7, v236
	v_lshl_or_b32 v147, v147, 7, v236
	v_lshl_or_b32 v148, v148, 7, v236
	v_lshl_or_b32 v149, v149, 7, v236
	v_lshl_or_b32 v150, v150, 7, v236
	v_lshl_or_b32 v151, v151, 7, v236
	buffer_load_dwordx4 v[64:67], v144, s[16:19], s1 offen
	buffer_load_dwordx4 v[68:71], v145, s[16:19], s1 offen
	buffer_load_dwordx4 v[72:75], v146, s[16:19], s1 offen
	buffer_load_dwordx4 v[76:79], v147, s[16:19], s1 offen
	buffer_load_dwordx4 v[80:83], v148, s[16:19], s1 offen
	buffer_load_dwordx4 v[84:87], v149, s[16:19], s1 offen
	buffer_load_dwordx4 v[88:91], v150, s[16:19], s1 offen
	buffer_load_dwordx4 v[92:95], v151, s[16:19], s1 offen
	ds_read_b32 v144, v237 offset:2816
	ds_read_b32 v145, v237 offset:2848
	ds_read_b32 v146, v237 offset:2880
	ds_read_b32 v147, v237 offset:2912
	ds_read_b32 v148, v237 offset:2944
	ds_read_b32 v149, v237 offset:2976
	ds_read_b32 v150, v237 offset:3008
	ds_read_b32 v151, v237 offset:3040
	s_waitcnt vmcnt(26)
	v_mfma_scale_f32_16x16x128_f8f6f4 v[176:179], v[96:99], v[136:143], 0, v240, v241 op_sel_hi:[0,0,0] cbsz:4
	v_cndmask_b32_e64 v160, v160, v161, s[4:5]
	v_cndmask_b32_e64 v164, v164, v165, s[4:5]
	v_cndmask_b32_e64 v168, v168, v169, s[4:5]
	v_mfma_scale_f32_16x16x128_f8f6f4 v[180:183], v[104:107], v[136:143], 0, v240, v241 op_sel_hi:[0,0,0] cbsz:4
	v_cndmask_b32_e64 v172, v172, v173, s[4:5]
	v_cndmask_b32_e64 v160, v160, v162, s[6:7]
	v_cndmask_b32_e64 v164, v164, v166, s[6:7]
	v_mfma_scale_f32_16x16x128_f8f6f4 v[184:187], v[112:115], v[136:143], 0, v240, v241 op_sel_hi:[0,0,0] cbsz:4
	v_cndmask_b32_e64 v168, v168, v170, s[6:7]
	v_cndmask_b32_e64 v172, v172, v174, s[6:7]
	v_cndmask_b32_e64 v160, v160, v163, s[8:9]
	v_mfma_scale_f32_16x16x128_f8f6f4 v[188:191], v[120:123], v[136:143], 0, v240, v241 op_sel_hi:[0,0,0] cbsz:4
	v_cndmask_b32_e64 v164, v164, v167, s[8:9]
	v_cndmask_b32_e64 v168, v168, v171, s[8:9]
	v_cndmask_b32_e64 v172, v172, v175, s[8:9]
	v_mfma_scale_f32_16x16x128_f8f6f4 v[176:179], v[100:103], v[136:143], v[176:179], v240, v242 op_sel_hi:[0,0,0] cbsz:4
	v_add_f32_dpp v160, v160, v160 quad_perm:[1,0,3,2] row_mask:0xf bank_mask:0xf bound_ctrl:1
	v_add_f32_dpp v164, v164, v164 quad_perm:[1,0,3,2] row_mask:0xf bank_mask:0xf bound_ctrl:1
	v_add_f32_dpp v168, v168, v168 quad_perm:[1,0,3,2] row_mask:0xf bank_mask:0xf bound_ctrl:1
	v_mfma_scale_f32_16x16x128_f8f6f4 v[180:183], v[108:111], v[136:143], v[180:183], v240, v242 op_sel_hi:[0,0,0] cbsz:4
	v_add_f32_dpp v172, v172, v172 quad_perm:[1,0,3,2] row_mask:0xf bank_mask:0xf bound_ctrl:1
	v_add_f32_dpp v160, v160, v160 quad_perm:[2,3,0,1] row_mask:0xf bank_mask:0xf bound_ctrl:1
	v_add_f32_dpp v164, v164, v164 quad_perm:[2,3,0,1] row_mask:0xf bank_mask:0xf bound_ctrl:1
	v_mfma_scale_f32_16x16x128_f8f6f4 v[184:187], v[116:119], v[136:143], v[184:187], v240, v242 op_sel_hi:[0,0,0] cbsz:4
	v_add_f32_dpp v168, v168, v168 quad_perm:[2,3,0,1] row_mask:0xf bank_mask:0xf bound_ctrl:1
	v_add_f32_dpp v172, v172, v172 quad_perm:[2,3,0,1] row_mask:0xf bank_mask:0xf bound_ctrl:1
	v_cndmask_b32_e64 v160, v160, v164, s[4:5]
	v_mfma_scale_f32_16x16x128_f8f6f4 v[188:191], v[124:127], v[136:143], v[188:191], v240, v242 op_sel_hi:[0,0,0] cbsz:4
	v_cndmask_b32_e64 v160, v160, v168, s[6:7]
	v_cndmask_b32_e64 v160, v160, v172, s[8:9]
	v_add_f32_e32 v210, v210, v160
	s_add_u32 s80, s61, 0x2800
	buffer_load_dwordx4 v[136:139], v238, s[12:15], s80 offen
	buffer_load_dwordx4 v[140:143], v239, s[12:15], s80 offen
	s_waitcnt lgkmcnt(0)
	v_lshl_or_b32 v144, v144, 7, v236
	v_lshl_or_b32 v145, v145, 7, v236
	v_lshl_or_b32 v146, v146, 7, v236
	v_lshl_or_b32 v147, v147, 7, v236
	v_lshl_or_b32 v148, v148, 7, v236
	v_lshl_or_b32 v149, v149, 7, v236
	v_lshl_or_b32 v150, v150, 7, v236
	v_lshl_or_b32 v151, v151, 7, v236
	buffer_load_dwordx4 v[96:99], v144, s[16:19], s1 offen
	buffer_load_dwordx4 v[100:103], v145, s[16:19], s1 offen
	buffer_load_dwordx4 v[104:107], v146, s[16:19], s1 offen
	buffer_load_dwordx4 v[108:111], v147, s[16:19], s1 offen
	buffer_load_dwordx4 v[112:115], v148, s[16:19], s1 offen
	buffer_load_dwordx4 v[116:119], v149, s[16:19], s1 offen
	buffer_load_dwordx4 v[120:123], v150, s[16:19], s1 offen
	buffer_load_dwordx4 v[124:127], v151, s[16:19], s1 offen
	ds_read_b32 v144, v237 offset:3072
	ds_read_b32 v145, v237 offset:3104
	ds_read_b32 v146, v237 offset:3136
	ds_read_b32 v147, v237 offset:3168
	ds_read_b32 v148, v237 offset:3200
	ds_read_b32 v149, v237 offset:3232
	ds_read_b32 v150, v237 offset:3264
	ds_read_b32 v151, v237 offset:3296
	s_waitcnt vmcnt(26)
	v_mfma_scale_f32_16x16x128_f8f6f4 v[160:163], v[0:3], v[128:135], 0, v240, v241 op_sel_hi:[0,0,0] cbsz:4
	v_cndmask_b32_e64 v176, v176, v177, s[4:5]
	v_cndmask_b32_e64 v180, v180, v181, s[4:5]
	v_cndmask_b32_e64 v184, v184, v185, s[4:5]
	v_mfma_scale_f32_16x16x128_f8f6f4 v[164:167], v[8:11], v[128:135], 0, v240, v241 op_sel_hi:[0,0,0] cbsz:4
	v_cndmask_b32_e64 v188, v188, v189, s[4:5]
	v_cndmask_b32_e64 v176, v176, v178, s[6:7]
	v_cndmask_b32_e64 v180, v180, v182, s[6:7]
	v_mfma_scale_f32_16x16x128_f8f6f4 v[168:171], v[16:19], v[128:135], 0, v240, v241 op_sel_hi:[0,0,0] cbsz:4
	v_cndmask_b32_e64 v184, v184, v186, s[6:7]
	v_cndmask_b32_e64 v188, v188, v190, s[6:7]
	v_cndmask_b32_e64 v176, v176, v179, s[8:9]
	v_mfma_scale_f32_16x16x128_f8f6f4 v[172:175], v[24:27], v[128:135], 0, v240, v241 op_sel_hi:[0,0,0] cbsz:4
	v_cndmask_b32_e64 v180, v180, v183, s[8:9]
	v_cndmask_b32_e64 v184, v184, v187, s[8:9]
	v_cndmask_b32_e64 v188, v188, v191, s[8:9]
	v_mfma_scale_f32_16x16x128_f8f6f4 v[160:163], v[4:7], v[128:135], v[160:163], v240, v242 op_sel_hi:[0,0,0] cbsz:4
	v_add_f32_dpp v176, v176, v176 quad_perm:[1,0,3,2] row_mask:0xf bank_mask:0xf bound_ctrl:1
	v_add_f32_dpp v180, v180, v180 quad_perm:[1,0,3,2] row_mask:0xf bank_mask:0xf bound_ctrl:1
	v_add_f32_dpp v184, v184, v184 quad_perm:[1,0,3,2] row_mask:0xf bank_mask:0xf bound_ctrl:1
	v_mfma_scale_f32_16x16x128_f8f6f4 v[164:167], v[12:15], v[128:135], v[164:167], v240, v242 op_sel_hi:[0,0,0] cbsz:4
	v_add_f32_dpp v188, v188, v188 quad_perm:[1,0,3,2] row_mask:0xf bank_mask:0xf bound_ctrl:1
	v_add_f32_dpp v176, v176, v176 quad_perm:[2,3,0,1] row_mask:0xf bank_mask:0xf bound_ctrl:1
	v_add_f32_dpp v180, v180, v180 quad_perm:[2,3,0,1] row_mask:0xf bank_mask:0xf bound_ctrl:1
	v_mfma_scale_f32_16x16x128_f8f6f4 v[168:171], v[20:23], v[128:135], v[168:171], v240, v242 op_sel_hi:[0,0,0] cbsz:4
	v_add_f32_dpp v184, v184, v184 quad_perm:[2,3,0,1] row_mask:0xf bank_mask:0xf bound_ctrl:1
	v_add_f32_dpp v188, v188, v188 quad_perm:[2,3,0,1] row_mask:0xf bank_mask:0xf bound_ctrl:1
	v_cndmask_b32_e64 v176, v176, v180, s[4:5]
	v_mfma_scale_f32_16x16x128_f8f6f4 v[172:175], v[28:31], v[128:135], v[172:175], v240, v242 op_sel_hi:[0,0,0] cbsz:4
	v_cndmask_b32_e64 v176, v176, v184, s[6:7]
	v_cndmask_b32_e64 v176, v176, v188, s[8:9]
	v_add_f32_e32 v211, v211, v176
	s_waitcnt lgkmcnt(0)
	v_lshl_or_b32 v144, v144, 7, v236
	v_lshl_or_b32 v145, v145, 7, v236
	v_lshl_or_b32 v146, v146, 7, v236
	v_lshl_or_b32 v147, v147, 7, v236
	v_lshl_or_b32 v148, v148, 7, v236
	v_lshl_or_b32 v149, v149, 7, v236
	v_lshl_or_b32 v150, v150, 7, v236
	v_lshl_or_b32 v151, v151, 7, v236
	buffer_load_dwordx4 v[0:3], v144, s[16:19], s1 offen
	buffer_load_dwordx4 v[4:7], v145, s[16:19], s1 offen
	buffer_load_dwordx4 v[8:11], v146, s[16:19], s1 offen
	buffer_load_dwordx4 v[12:15], v147, s[16:19], s1 offen
	buffer_load_dwordx4 v[16:19], v148, s[16:19], s1 offen
	buffer_load_dwordx4 v[20:23], v149, s[16:19], s1 offen
	buffer_load_dwordx4 v[24:27], v150, s[16:19], s1 offen
	buffer_load_dwordx4 v[28:31], v151, s[16:19], s1 offen
	ds_read_b32 v144, v237 offset:3328
	ds_read_b32 v145, v237 offset:3360
	ds_read_b32 v146, v237 offset:3392
	ds_read_b32 v147, v237 offset:3424
	ds_read_b32 v148, v237 offset:3456
	ds_read_b32 v149, v237 offset:3488
	ds_read_b32 v150, v237 offset:3520
	ds_read_b32 v151, v237 offset:3552
	s_waitcnt vmcnt(26)
	v_mfma_scale_f32_16x16x128_f8f6f4 v[176:179], v[32:35], v[128:135], 0, v240, v241 op_sel_hi:[0,0,0] cbsz:4
	v_cndmask_b32_e64 v160, v160, v161, s[4:5]
	v_cndmask_b32_e64 v164, v164, v165, s[4:5]
	v_cndmask_b32_e64 v168, v168, v169, s[4:5]
	v_mfma_scale_f32_16x16x128_f8f6f4 v[180:183], v[40:43], v[128:135], 0, v240, v241 op_sel_hi:[0,0,0] cbsz:4
	v_cndmask_b32_e64 v172, v172, v173, s[4:5]
	v_cndmask_b32_e64 v160, v160, v162, s[6:7]
	v_cndmask_b32_e64 v164, v164, v166, s[6:7]
	v_mfma_scale_f32_16x16x128_f8f6f4 v[184:187], v[48:51], v[128:135], 0, v240, v241 op_sel_hi:[0,0,0] cbsz:4
	v_cndmask_b32_e64 v168, v168, v170, s[6:7]
	v_cndmask_b32_e64 v172, v172, v174, s[6:7]
	v_cndmask_b32_e64 v160, v160, v163, s[8:9]
	v_mfma_scale_f32_16x16x128_f8f6f4 v[188:191], v[56:59], v[128:135], 0, v240, v241 op_sel_hi:[0,0,0] cbsz:4
	v_cndmask_b32_e64 v164, v164, v167, s[8:9]
	v_cndmask_b32_e64 v168, v168, v171, s[8:9]
	v_cndmask_b32_e64 v172, v172, v175, s[8:9]
	v_mfma_scale_f32_16x16x128_f8f6f4 v[176:179], v[36:39], v[128:135], v[176:179], v240, v242 op_sel_hi:[0,0,0] cbsz:4
	v_add_f32_dpp v160, v160, v160 quad_perm:[1,0,3,2] row_mask:0xf bank_mask:0xf bound_ctrl:1
	v_add_f32_dpp v164, v164, v164 quad_perm:[1,0,3,2] row_mask:0xf bank_mask:0xf bound_ctrl:1
	v_add_f32_dpp v168, v168, v168 quad_perm:[1,0,3,2] row_mask:0xf bank_mask:0xf bound_ctrl:1
	v_mfma_scale_f32_16x16x128_f8f6f4 v[180:183], v[44:47], v[128:135], v[180:183], v240, v242 op_sel_hi:[0,0,0] cbsz:4
	v_add_f32_dpp v172, v172, v172 quad_perm:[1,0,3,2] row_mask:0xf bank_mask:0xf bound_ctrl:1
	v_add_f32_dpp v160, v160, v160 quad_perm:[2,3,0,1] row_mask:0xf bank_mask:0xf bound_ctrl:1
	v_add_f32_dpp v164, v164, v164 quad_perm:[2,3,0,1] row_mask:0xf bank_mask:0xf bound_ctrl:1
	v_mfma_scale_f32_16x16x128_f8f6f4 v[184:187], v[52:55], v[128:135], v[184:187], v240, v242 op_sel_hi:[0,0,0] cbsz:4
	v_add_f32_dpp v168, v168, v168 quad_perm:[2,3,0,1] row_mask:0xf bank_mask:0xf bound_ctrl:1
	v_add_f32_dpp v172, v172, v172 quad_perm:[2,3,0,1] row_mask:0xf bank_mask:0xf bound_ctrl:1
	v_cndmask_b32_e64 v160, v160, v164, s[4:5]
	v_mfma_scale_f32_16x16x128_f8f6f4 v[188:191], v[60:63], v[128:135], v[188:191], v240, v242 op_sel_hi:[0,0,0] cbsz:4
	v_cndmask_b32_e64 v160, v160, v168, s[6:7]
	v_cndmask_b32_e64 v160, v160, v172, s[8:9]
	v_add_f32_e32 v212, v212, v160
	s_add_u32 s80, s61, 0x3000
	buffer_load_dwordx4 v[128:131], v238, s[12:15], s80 offen
	buffer_load_dwordx4 v[132:135], v239, s[12:15], s80 offen
	s_waitcnt lgkmcnt(0)
	v_lshl_or_b32 v144, v144, 7, v236
	v_lshl_or_b32 v145, v145, 7, v236
	v_lshl_or_b32 v146, v146, 7, v236
	v_lshl_or_b32 v147, v147, 7, v236
	v_lshl_or_b32 v148, v148, 7, v236
	v_lshl_or_b32 v149, v149, 7, v236
	v_lshl_or_b32 v150, v150, 7, v236
	v_lshl_or_b32 v151, v151, 7, v236
	buffer_load_dwordx4 v[32:35], v144, s[16:19], s1 offen
	buffer_load_dwordx4 v[36:39], v145, s[16:19], s1 offen
	buffer_load_dwordx4 v[40:43], v146, s[16:19], s1 offen
	buffer_load_dwordx4 v[44:47], v147, s[16:19], s1 offen
	buffer_load_dwordx4 v[48:51], v148, s[16:19], s1 offen
	buffer_load_dwordx4 v[52:55], v149, s[16:19], s1 offen
	buffer_load_dwordx4 v[56:59], v150, s[16:19], s1 offen
	buffer_load_dwordx4 v[60:63], v151, s[16:19], s1 offen
	ds_read_b32 v144, v237 offset:3584
	ds_read_b32 v145, v237 offset:3616
	ds_read_b32 v146, v237 offset:3648
	ds_read_b32 v147, v237 offset:3680
	ds_read_b32 v148, v237 offset:3712
	ds_read_b32 v149, v237 offset:3744
	ds_read_b32 v150, v237 offset:3776
	ds_read_b32 v151, v237 offset:3808
	s_waitcnt vmcnt(26)
	v_mfma_scale_f32_16x16x128_f8f6f4 v[160:163], v[64:67], v[136:143], 0, v240, v241 op_sel_hi:[0,0,0] cbsz:4
	v_cndmask_b32_e64 v176, v176, v177, s[4:5]
	v_cndmask_b32_e64 v180, v180, v181, s[4:5]
	v_cndmask_b32_e64 v184, v184, v185, s[4:5]
	v_mfma_scale_f32_16x16x128_f8f6f4 v[164:167], v[72:75], v[136:143], 0, v240, v241 op_sel_hi:[0,0,0] cbsz:4
	v_cndmask_b32_e64 v188, v188, v189, s[4:5]
	v_cndmask_b32_e64 v176, v176, v178, s[6:7]
	v_cndmask_b32_e64 v180, v180, v182, s[6:7]
	v_mfma_scale_f32_16x16x128_f8f6f4 v[168:171], v[80:83], v[136:143], 0, v240, v241 op_sel_hi:[0,0,0] cbsz:4
	v_cndmask_b32_e64 v184, v184, v186, s[6:7]
	v_cndmask_b32_e64 v188, v188, v190, s[6:7]
	v_cndmask_b32_e64 v176, v176, v179, s[8:9]
	v_mfma_scale_f32_16x16x128_f8f6f4 v[172:175], v[88:91], v[136:143], 0, v240, v241 op_sel_hi:[0,0,0] cbsz:4
	v_cndmask_b32_e64 v180, v180, v183, s[8:9]
	v_cndmask_b32_e64 v184, v184, v187, s[8:9]
	v_cndmask_b32_e64 v188, v188, v191, s[8:9]
	v_mfma_scale_f32_16x16x128_f8f6f4 v[160:163], v[68:71], v[136:143], v[160:163], v240, v242 op_sel_hi:[0,0,0] cbsz:4
	v_add_f32_dpp v176, v176, v176 quad_perm:[1,0,3,2] row_mask:0xf bank_mask:0xf bound_ctrl:1
	v_add_f32_dpp v180, v180, v180 quad_perm:[1,0,3,2] row_mask:0xf bank_mask:0xf bound_ctrl:1
	v_add_f32_dpp v184, v184, v184 quad_perm:[1,0,3,2] row_mask:0xf bank_mask:0xf bound_ctrl:1
	v_mfma_scale_f32_16x16x128_f8f6f4 v[164:167], v[76:79], v[136:143], v[164:167], v240, v242 op_sel_hi:[0,0,0] cbsz:4
	v_add_f32_dpp v188, v188, v188 quad_perm:[1,0,3,2] row_mask:0xf bank_mask:0xf bound_ctrl:1
	v_add_f32_dpp v176, v176, v176 quad_perm:[2,3,0,1] row_mask:0xf bank_mask:0xf bound_ctrl:1
	v_add_f32_dpp v180, v180, v180 quad_perm:[2,3,0,1] row_mask:0xf bank_mask:0xf bound_ctrl:1
	v_mfma_scale_f32_16x16x128_f8f6f4 v[168:171], v[84:87], v[136:143], v[168:171], v240, v242 op_sel_hi:[0,0,0] cbsz:4
	v_add_f32_dpp v184, v184, v184 quad_perm:[2,3,0,1] row_mask:0xf bank_mask:0xf bound_ctrl:1
	v_add_f32_dpp v188, v188, v188 quad_perm:[2,3,0,1] row_mask:0xf bank_mask:0xf bound_ctrl:1
	v_cndmask_b32_e64 v176, v176, v180, s[4:5]
	v_mfma_scale_f32_16x16x128_f8f6f4 v[172:175], v[92:95], v[136:143], v[172:175], v240, v242 op_sel_hi:[0,0,0] cbsz:4
	v_cndmask_b32_e64 v176, v176, v184, s[6:7]
	v_cndmask_b32_e64 v176, v176, v188, s[8:9]
	v_add_f32_e32 v213, v213, v176
	s_waitcnt lgkmcnt(0)
	v_lshl_or_b32 v144, v144, 7, v236
	v_lshl_or_b32 v145, v145, 7, v236
	v_lshl_or_b32 v146, v146, 7, v236
	v_lshl_or_b32 v147, v147, 7, v236
	v_lshl_or_b32 v148, v148, 7, v236
	v_lshl_or_b32 v149, v149, 7, v236
	v_lshl_or_b32 v150, v150, 7, v236
	v_lshl_or_b32 v151, v151, 7, v236
	buffer_load_dwordx4 v[64:67], v144, s[16:19], s1 offen
	buffer_load_dwordx4 v[68:71], v145, s[16:19], s1 offen
	buffer_load_dwordx4 v[72:75], v146, s[16:19], s1 offen
	buffer_load_dwordx4 v[76:79], v147, s[16:19], s1 offen
	buffer_load_dwordx4 v[80:83], v148, s[16:19], s1 offen
	buffer_load_dwordx4 v[84:87], v149, s[16:19], s1 offen
	buffer_load_dwordx4 v[88:91], v150, s[16:19], s1 offen
	buffer_load_dwordx4 v[92:95], v151, s[16:19], s1 offen
	ds_read_b32 v144, v237 offset:3840
	ds_read_b32 v145, v237 offset:3872
	ds_read_b32 v146, v237 offset:3904
	ds_read_b32 v147, v237 offset:3936
	ds_read_b32 v148, v237 offset:3968
	ds_read_b32 v149, v237 offset:4000
	ds_read_b32 v150, v237 offset:4032
	ds_read_b32 v151, v237 offset:4064
	s_waitcnt vmcnt(26)
	v_mfma_scale_f32_16x16x128_f8f6f4 v[176:179], v[96:99], v[136:143], 0, v240, v241 op_sel_hi:[0,0,0] cbsz:4
	v_cndmask_b32_e64 v160, v160, v161, s[4:5]
	v_cndmask_b32_e64 v164, v164, v165, s[4:5]
	v_cndmask_b32_e64 v168, v168, v169, s[4:5]
	v_mfma_scale_f32_16x16x128_f8f6f4 v[180:183], v[104:107], v[136:143], 0, v240, v241 op_sel_hi:[0,0,0] cbsz:4
	v_cndmask_b32_e64 v172, v172, v173, s[4:5]
	v_cndmask_b32_e64 v160, v160, v162, s[6:7]
	v_cndmask_b32_e64 v164, v164, v166, s[6:7]
	v_mfma_scale_f32_16x16x128_f8f6f4 v[184:187], v[112:115], v[136:143], 0, v240, v241 op_sel_hi:[0,0,0] cbsz:4
	v_cndmask_b32_e64 v168, v168, v170, s[6:7]
	v_cndmask_b32_e64 v172, v172, v174, s[6:7]
	v_cndmask_b32_e64 v160, v160, v163, s[8:9]
	v_mfma_scale_f32_16x16x128_f8f6f4 v[188:191], v[120:123], v[136:143], 0, v240, v241 op_sel_hi:[0,0,0] cbsz:4
	v_cndmask_b32_e64 v164, v164, v167, s[8:9]
	v_cndmask_b32_e64 v168, v168, v171, s[8:9]
	v_cndmask_b32_e64 v172, v172, v175, s[8:9]
	v_mfma_scale_f32_16x16x128_f8f6f4 v[176:179], v[100:103], v[136:143], v[176:179], v240, v242 op_sel_hi:[0,0,0] cbsz:4
	v_add_f32_dpp v160, v160, v160 quad_perm:[1,0,3,2] row_mask:0xf bank_mask:0xf bound_ctrl:1
	v_add_f32_dpp v164, v164, v164 quad_perm:[1,0,3,2] row_mask:0xf bank_mask:0xf bound_ctrl:1
	v_add_f32_dpp v168, v168, v168 quad_perm:[1,0,3,2] row_mask:0xf bank_mask:0xf bound_ctrl:1
	v_mfma_scale_f32_16x16x128_f8f6f4 v[180:183], v[108:111], v[136:143], v[180:183], v240, v242 op_sel_hi:[0,0,0] cbsz:4
	v_add_f32_dpp v172, v172, v172 quad_perm:[1,0,3,2] row_mask:0xf bank_mask:0xf bound_ctrl:1
	v_add_f32_dpp v160, v160, v160 quad_perm:[2,3,0,1] row_mask:0xf bank_mask:0xf bound_ctrl:1
	v_add_f32_dpp v164, v164, v164 quad_perm:[2,3,0,1] row_mask:0xf bank_mask:0xf bound_ctrl:1
	v_mfma_scale_f32_16x16x128_f8f6f4 v[184:187], v[116:119], v[136:143], v[184:187], v240, v242 op_sel_hi:[0,0,0] cbsz:4
	v_add_f32_dpp v168, v168, v168 quad_perm:[2,3,0,1] row_mask:0xf bank_mask:0xf bound_ctrl:1
	v_add_f32_dpp v172, v172, v172 quad_perm:[2,3,0,1] row_mask:0xf bank_mask:0xf bound_ctrl:1
	v_cndmask_b32_e64 v160, v160, v164, s[4:5]
	v_mfma_scale_f32_16x16x128_f8f6f4 v[188:191], v[124:127], v[136:143], v[188:191], v240, v242 op_sel_hi:[0,0,0] cbsz:4
	v_cndmask_b32_e64 v160, v160, v168, s[6:7]
	v_cndmask_b32_e64 v160, v160, v172, s[8:9]
	v_add_f32_e32 v214, v214, v160
	s_add_u32 s80, s61, 0x3800
	buffer_load_dwordx4 v[136:139], v238, s[12:15], s80 offen
	buffer_load_dwordx4 v[140:143], v239, s[12:15], s80 offen
	s_waitcnt lgkmcnt(0)
	v_lshl_or_b32 v144, v144, 7, v236
	v_lshl_or_b32 v145, v145, 7, v236
	v_lshl_or_b32 v146, v146, 7, v236
	v_lshl_or_b32 v147, v147, 7, v236
	v_lshl_or_b32 v148, v148, 7, v236
	v_lshl_or_b32 v149, v149, 7, v236
	v_lshl_or_b32 v150, v150, 7, v236
	v_lshl_or_b32 v151, v151, 7, v236
	buffer_load_dwordx4 v[96:99], v144, s[16:19], s1 offen
	buffer_load_dwordx4 v[100:103], v145, s[16:19], s1 offen
	buffer_load_dwordx4 v[104:107], v146, s[16:19], s1 offen
	buffer_load_dwordx4 v[108:111], v147, s[16:19], s1 offen
	buffer_load_dwordx4 v[112:115], v148, s[16:19], s1 offen
	buffer_load_dwordx4 v[116:119], v149, s[16:19], s1 offen
	buffer_load_dwordx4 v[120:123], v150, s[16:19], s1 offen
	buffer_load_dwordx4 v[124:127], v151, s[16:19], s1 offen
	ds_read_b32 v144, v237 offset:0
	ds_read_b32 v145, v237 offset:32
	ds_read_b32 v146, v237 offset:64
	ds_read_b32 v147, v237 offset:96
	ds_read_b32 v148, v237 offset:128
	ds_read_b32 v149, v237 offset:160
	ds_read_b32 v150, v237 offset:192
	ds_read_b32 v151, v237 offset:224
	s_waitcnt vmcnt(26)
	v_mfma_scale_f32_16x16x128_f8f6f4 v[160:163], v[0:3], v[128:135], 0, v240, v241 op_sel_hi:[0,0,0] cbsz:4
	v_cndmask_b32_e64 v176, v176, v177, s[4:5]
	v_cndmask_b32_e64 v180, v180, v181, s[4:5]
	v_cndmask_b32_e64 v184, v184, v185, s[4:5]
	v_mfma_scale_f32_16x16x128_f8f6f4 v[164:167], v[8:11], v[128:135], 0, v240, v241 op_sel_hi:[0,0,0] cbsz:4
	v_cndmask_b32_e64 v188, v188, v189, s[4:5]
	v_cndmask_b32_e64 v176, v176, v178, s[6:7]
	v_cndmask_b32_e64 v180, v180, v182, s[6:7]
	v_mfma_scale_f32_16x16x128_f8f6f4 v[168:171], v[16:19], v[128:135], 0, v240, v241 op_sel_hi:[0,0,0] cbsz:4
	v_cndmask_b32_e64 v184, v184, v186, s[6:7]
	v_cndmask_b32_e64 v188, v188, v190, s[6:7]
	v_cndmask_b32_e64 v176, v176, v179, s[8:9]
	v_mfma_scale_f32_16x16x128_f8f6f4 v[172:175], v[24:27], v[128:135], 0, v240, v241 op_sel_hi:[0,0,0] cbsz:4
	v_cndmask_b32_e64 v180, v180, v183, s[8:9]
	v_cndmask_b32_e64 v184, v184, v187, s[8:9]
	v_cndmask_b32_e64 v188, v188, v191, s[8:9]
	v_mfma_scale_f32_16x16x128_f8f6f4 v[160:163], v[4:7], v[128:135], v[160:163], v240, v242 op_sel_hi:[0,0,0] cbsz:4
	v_add_f32_dpp v176, v176, v176 quad_perm:[1,0,3,2] row_mask:0xf bank_mask:0xf bound_ctrl:1
	v_add_f32_dpp v180, v180, v180 quad_perm:[1,0,3,2] row_mask:0xf bank_mask:0xf bound_ctrl:1
	v_add_f32_dpp v184, v184, v184 quad_perm:[1,0,3,2] row_mask:0xf bank_mask:0xf bound_ctrl:1
	v_mfma_scale_f32_16x16x128_f8f6f4 v[164:167], v[12:15], v[128:135], v[164:167], v240, v242 op_sel_hi:[0,0,0] cbsz:4
	v_add_f32_dpp v188, v188, v188 quad_perm:[1,0,3,2] row_mask:0xf bank_mask:0xf bound_ctrl:1
	v_add_f32_dpp v176, v176, v176 quad_perm:[2,3,0,1] row_mask:0xf bank_mask:0xf bound_ctrl:1
	v_add_f32_dpp v180, v180, v180 quad_perm:[2,3,0,1] row_mask:0xf bank_mask:0xf bound_ctrl:1
	v_mfma_scale_f32_16x16x128_f8f6f4 v[168:171], v[20:23], v[128:135], v[168:171], v240, v242 op_sel_hi:[0,0,0] cbsz:4
	v_add_f32_dpp v184, v184, v184 quad_perm:[2,3,0,1] row_mask:0xf bank_mask:0xf bound_ctrl:1
	v_add_f32_dpp v188, v188, v188 quad_perm:[2,3,0,1] row_mask:0xf bank_mask:0xf bound_ctrl:1
	v_cndmask_b32_e64 v176, v176, v180, s[4:5]
	v_mfma_scale_f32_16x16x128_f8f6f4 v[172:175], v[28:31], v[128:135], v[172:175], v240, v242 op_sel_hi:[0,0,0] cbsz:4
	v_cndmask_b32_e64 v176, v176, v184, s[6:7]
	v_cndmask_b32_e64 v176, v176, v188, s[8:9]
	v_add_f32_e32 v215, v215, v176
	s_waitcnt lgkmcnt(0)
	v_lshl_or_b32 v144, v144, 7, v236
	v_lshl_or_b32 v145, v145, 7, v236
	v_lshl_or_b32 v146, v146, 7, v236
	v_lshl_or_b32 v147, v147, 7, v236
	v_lshl_or_b32 v148, v148, 7, v236
	v_lshl_or_b32 v149, v149, 7, v236
	v_lshl_or_b32 v150, v150, 7, v236
	v_lshl_or_b32 v151, v151, 7, v236
	buffer_load_dwordx4 v[0:3], v144, s[16:19], s60 offen
	buffer_load_dwordx4 v[4:7], v145, s[16:19], s60 offen
	buffer_load_dwordx4 v[8:11], v146, s[16:19], s60 offen
	buffer_load_dwordx4 v[12:15], v147, s[16:19], s60 offen
	buffer_load_dwordx4 v[16:19], v148, s[16:19], s60 offen
	buffer_load_dwordx4 v[20:23], v149, s[16:19], s60 offen
	buffer_load_dwordx4 v[24:27], v150, s[16:19], s60 offen
	buffer_load_dwordx4 v[28:31], v151, s[16:19], s60 offen
	ds_read_b32 v144, v237 offset:256
	ds_read_b32 v145, v237 offset:288
	ds_read_b32 v146, v237 offset:320
	ds_read_b32 v147, v237 offset:352
	ds_read_b32 v148, v237 offset:384
	ds_read_b32 v149, v237 offset:416
	ds_read_b32 v150, v237 offset:448
	ds_read_b32 v151, v237 offset:480
	s_waitcnt vmcnt(26)
	v_mfma_scale_f32_16x16x128_f8f6f4 v[176:179], v[32:35], v[128:135], 0, v240, v241 op_sel_hi:[0,0,0] cbsz:4
	v_cndmask_b32_e64 v160, v160, v161, s[4:5]
	v_cndmask_b32_e64 v164, v164, v165, s[4:5]
	v_cndmask_b32_e64 v168, v168, v169, s[4:5]
	v_mfma_scale_f32_16x16x128_f8f6f4 v[180:183], v[40:43], v[128:135], 0, v240, v241 op_sel_hi:[0,0,0] cbsz:4
	v_cndmask_b32_e64 v172, v172, v173, s[4:5]
	v_cndmask_b32_e64 v160, v160, v162, s[6:7]
	v_cndmask_b32_e64 v164, v164, v166, s[6:7]
	v_mfma_scale_f32_16x16x128_f8f6f4 v[184:187], v[48:51], v[128:135], 0, v240, v241 op_sel_hi:[0,0,0] cbsz:4
	v_cndmask_b32_e64 v168, v168, v170, s[6:7]
	v_cndmask_b32_e64 v172, v172, v174, s[6:7]
	v_cndmask_b32_e64 v160, v160, v163, s[8:9]
	v_mfma_scale_f32_16x16x128_f8f6f4 v[188:191], v[56:59], v[128:135], 0, v240, v241 op_sel_hi:[0,0,0] cbsz:4
	v_cndmask_b32_e64 v164, v164, v167, s[8:9]
	v_cndmask_b32_e64 v168, v168, v171, s[8:9]
	v_cndmask_b32_e64 v172, v172, v175, s[8:9]
	v_mfma_scale_f32_16x16x128_f8f6f4 v[176:179], v[36:39], v[128:135], v[176:179], v240, v242 op_sel_hi:[0,0,0] cbsz:4
	v_add_f32_dpp v160, v160, v160 quad_perm:[1,0,3,2] row_mask:0xf bank_mask:0xf bound_ctrl:1
	v_add_f32_dpp v164, v164, v164 quad_perm:[1,0,3,2] row_mask:0xf bank_mask:0xf bound_ctrl:1
	v_add_f32_dpp v168, v168, v168 quad_perm:[1,0,3,2] row_mask:0xf bank_mask:0xf bound_ctrl:1
	v_mfma_scale_f32_16x16x128_f8f6f4 v[180:183], v[44:47], v[128:135], v[180:183], v240, v242 op_sel_hi:[0,0,0] cbsz:4
	v_add_f32_dpp v172, v172, v172 quad_perm:[1,0,3,2] row_mask:0xf bank_mask:0xf bound_ctrl:1
	v_add_f32_dpp v160, v160, v160 quad_perm:[2,3,0,1] row_mask:0xf bank_mask:0xf bound_ctrl:1
	v_add_f32_dpp v164, v164, v164 quad_perm:[2,3,0,1] row_mask:0xf bank_mask:0xf bound_ctrl:1
	v_mfma_scale_f32_16x16x128_f8f6f4 v[184:187], v[52:55], v[128:135], v[184:187], v240, v242 op_sel_hi:[0,0,0] cbsz:4
	v_add_f32_dpp v168, v168, v168 quad_perm:[2,3,0,1] row_mask:0xf bank_mask:0xf bound_ctrl:1
	v_add_f32_dpp v172, v172, v172 quad_perm:[2,3,0,1] row_mask:0xf bank_mask:0xf bound_ctrl:1
	v_cndmask_b32_e64 v160, v160, v164, s[4:5]
	v_mfma_scale_f32_16x16x128_f8f6f4 v[188:191], v[60:63], v[128:135], v[188:191], v240, v242 op_sel_hi:[0,0,0] cbsz:4
	v_cndmask_b32_e64 v160, v160, v168, s[6:7]
	v_cndmask_b32_e64 v160, v160, v172, s[8:9]
	v_add_f32_e32 v216, v216, v160
	s_add_u32 s80, s62, 0x0
	buffer_load_dwordx4 v[128:131], v238, s[12:15], s80 offen
	buffer_load_dwordx4 v[132:135], v239, s[12:15], s80 offen
	s_waitcnt lgkmcnt(0)
	v_lshl_or_b32 v144, v144, 7, v236
	v_lshl_or_b32 v145, v145, 7, v236
	v_lshl_or_b32 v146, v146, 7, v236
	v_lshl_or_b32 v147, v147, 7, v236
	v_lshl_or_b32 v148, v148, 7, v236
	v_lshl_or_b32 v149, v149, 7, v236
	v_lshl_or_b32 v150, v150, 7, v236
	v_lshl_or_b32 v151, v151, 7, v236
	buffer_load_dwordx4 v[32:35], v144, s[16:19], s60 offen
	buffer_load_dwordx4 v[36:39], v145, s[16:19], s60 offen
	buffer_load_dwordx4 v[40:43], v146, s[16:19], s60 offen
	buffer_load_dwordx4 v[44:47], v147, s[16:19], s60 offen
	buffer_load_dwordx4 v[48:51], v148, s[16:19], s60 offen
	buffer_load_dwordx4 v[52:55], v149, s[16:19], s60 offen
	buffer_load_dwordx4 v[56:59], v150, s[16:19], s60 offen
	buffer_load_dwordx4 v[60:63], v151, s[16:19], s60 offen
	ds_read_b32 v144, v237 offset:512
	ds_read_b32 v145, v237 offset:544
	ds_read_b32 v146, v237 offset:576
	ds_read_b32 v147, v237 offset:608
	ds_read_b32 v148, v237 offset:640
	ds_read_b32 v149, v237 offset:672
	ds_read_b32 v150, v237 offset:704
	ds_read_b32 v151, v237 offset:736
	s_waitcnt vmcnt(26)
	v_mfma_scale_f32_16x16x128_f8f6f4 v[160:163], v[64:67], v[136:143], 0, v240, v241 op_sel_hi:[0,0,0] cbsz:4
	v_cndmask_b32_e64 v176, v176, v177, s[4:5]
	v_cndmask_b32_e64 v180, v180, v181, s[4:5]
	v_cndmask_b32_e64 v184, v184, v185, s[4:5]
	v_mfma_scale_f32_16x16x128_f8f6f4 v[164:167], v[72:75], v[136:143], 0, v240, v241 op_sel_hi:[0,0,0] cbsz:4
	v_cndmask_b32_e64 v188, v188, v189, s[4:5]
	v_cndmask_b32_e64 v176, v176, v178, s[6:7]
	v_cndmask_b32_e64 v180, v180, v182, s[6:7]
	v_mfma_scale_f32_16x16x128_f8f6f4 v[168:171], v[80:83], v[136:143], 0, v240, v241 op_sel_hi:[0,0,0] cbsz:4
	v_cndmask_b32_e64 v184, v184, v186, s[6:7]
	v_cndmask_b32_e64 v188, v188, v190, s[6:7]
	v_cndmask_b32_e64 v176, v176, v179, s[8:9]
	v_mfma_scale_f32_16x16x128_f8f6f4 v[172:175], v[88:91], v[136:143], 0, v240, v241 op_sel_hi:[0,0,0] cbsz:4
	v_cndmask_b32_e64 v180, v180, v183, s[8:9]
	v_cndmask_b32_e64 v184, v184, v187, s[8:9]
	v_cndmask_b32_e64 v188, v188, v191, s[8:9]
	v_mfma_scale_f32_16x16x128_f8f6f4 v[160:163], v[68:71], v[136:143], v[160:163], v240, v242 op_sel_hi:[0,0,0] cbsz:4
	v_add_f32_dpp v176, v176, v176 quad_perm:[1,0,3,2] row_mask:0xf bank_mask:0xf bound_ctrl:1
	v_add_f32_dpp v180, v180, v180 quad_perm:[1,0,3,2] row_mask:0xf bank_mask:0xf bound_ctrl:1
	v_add_f32_dpp v184, v184, v184 quad_perm:[1,0,3,2] row_mask:0xf bank_mask:0xf bound_ctrl:1
	v_mfma_scale_f32_16x16x128_f8f6f4 v[164:167], v[76:79], v[136:143], v[164:167], v240, v242 op_sel_hi:[0,0,0] cbsz:4
	v_add_f32_dpp v188, v188, v188 quad_perm:[1,0,3,2] row_mask:0xf bank_mask:0xf bound_ctrl:1
	v_add_f32_dpp v176, v176, v176 quad_perm:[2,3,0,1] row_mask:0xf bank_mask:0xf bound_ctrl:1
	v_add_f32_dpp v180, v180, v180 quad_perm:[2,3,0,1] row_mask:0xf bank_mask:0xf bound_ctrl:1
	v_mfma_scale_f32_16x16x128_f8f6f4 v[168:171], v[84:87], v[136:143], v[168:171], v240, v242 op_sel_hi:[0,0,0] cbsz:4
	v_add_f32_dpp v184, v184, v184 quad_perm:[2,3,0,1] row_mask:0xf bank_mask:0xf bound_ctrl:1
	v_add_f32_dpp v188, v188, v188 quad_perm:[2,3,0,1] row_mask:0xf bank_mask:0xf bound_ctrl:1
	v_cndmask_b32_e64 v176, v176, v180, s[4:5]
	v_mfma_scale_f32_16x16x128_f8f6f4 v[172:175], v[92:95], v[136:143], v[172:175], v240, v242 op_sel_hi:[0,0,0] cbsz:4
	v_cndmask_b32_e64 v176, v176, v184, s[6:7]
	v_cndmask_b32_e64 v176, v176, v188, s[8:9]
	v_add_f32_e32 v217, v217, v176
	s_waitcnt lgkmcnt(0)
	v_lshl_or_b32 v144, v144, 7, v236
	v_lshl_or_b32 v145, v145, 7, v236
	v_lshl_or_b32 v146, v146, 7, v236
	v_lshl_or_b32 v147, v147, 7, v236
	v_lshl_or_b32 v148, v148, 7, v236
	v_lshl_or_b32 v149, v149, 7, v236
	v_lshl_or_b32 v150, v150, 7, v236
	v_lshl_or_b32 v151, v151, 7, v236
	buffer_load_dwordx4 v[64:67], v144, s[16:19], s60 offen
	buffer_load_dwordx4 v[68:71], v145, s[16:19], s60 offen
	buffer_load_dwordx4 v[72:75], v146, s[16:19], s60 offen
	buffer_load_dwordx4 v[76:79], v147, s[16:19], s60 offen
	buffer_load_dwordx4 v[80:83], v148, s[16:19], s60 offen
	buffer_load_dwordx4 v[84:87], v149, s[16:19], s60 offen
	buffer_load_dwordx4 v[88:91], v150, s[16:19], s60 offen
	buffer_load_dwordx4 v[92:95], v151, s[16:19], s60 offen
	ds_read_b32 v144, v237 offset:768
	ds_read_b32 v145, v237 offset:800
	ds_read_b32 v146, v237 offset:832
	ds_read_b32 v147, v237 offset:864
	ds_read_b32 v148, v237 offset:896
	ds_read_b32 v149, v237 offset:928
	ds_read_b32 v150, v237 offset:960
	ds_read_b32 v151, v237 offset:992
	s_waitcnt vmcnt(26)
	v_mfma_scale_f32_16x16x128_f8f6f4 v[176:179], v[96:99], v[136:143], 0, v240, v241 op_sel_hi:[0,0,0] cbsz:4
	v_cndmask_b32_e64 v160, v160, v161, s[4:5]
	v_cndmask_b32_e64 v164, v164, v165, s[4:5]
	v_cndmask_b32_e64 v168, v168, v169, s[4:5]
	v_mfma_scale_f32_16x16x128_f8f6f4 v[180:183], v[104:107], v[136:143], 0, v240, v241 op_sel_hi:[0,0,0] cbsz:4
	v_cndmask_b32_e64 v172, v172, v173, s[4:5]
	v_cndmask_b32_e64 v160, v160, v162, s[6:7]
	v_cndmask_b32_e64 v164, v164, v166, s[6:7]
	v_mfma_scale_f32_16x16x128_f8f6f4 v[184:187], v[112:115], v[136:143], 0, v240, v241 op_sel_hi:[0,0,0] cbsz:4
	v_cndmask_b32_e64 v168, v168, v170, s[6:7]
	v_cndmask_b32_e64 v172, v172, v174, s[6:7]
	v_cndmask_b32_e64 v160, v160, v163, s[8:9]
	v_mfma_scale_f32_16x16x128_f8f6f4 v[188:191], v[120:123], v[136:143], 0, v240, v241 op_sel_hi:[0,0,0] cbsz:4
	v_cndmask_b32_e64 v164, v164, v167, s[8:9]
	v_cndmask_b32_e64 v168, v168, v171, s[8:9]
	v_cndmask_b32_e64 v172, v172, v175, s[8:9]
	v_mfma_scale_f32_16x16x128_f8f6f4 v[176:179], v[100:103], v[136:143], v[176:179], v240, v242 op_sel_hi:[0,0,0] cbsz:4
	v_add_f32_dpp v160, v160, v160 quad_perm:[1,0,3,2] row_mask:0xf bank_mask:0xf bound_ctrl:1
	v_add_f32_dpp v164, v164, v164 quad_perm:[1,0,3,2] row_mask:0xf bank_mask:0xf bound_ctrl:1
	v_add_f32_dpp v168, v168, v168 quad_perm:[1,0,3,2] row_mask:0xf bank_mask:0xf bound_ctrl:1
	v_mfma_scale_f32_16x16x128_f8f6f4 v[180:183], v[108:111], v[136:143], v[180:183], v240, v242 op_sel_hi:[0,0,0] cbsz:4
	v_add_f32_dpp v172, v172, v172 quad_perm:[1,0,3,2] row_mask:0xf bank_mask:0xf bound_ctrl:1
	v_add_f32_dpp v160, v160, v160 quad_perm:[2,3,0,1] row_mask:0xf bank_mask:0xf bound_ctrl:1
	v_add_f32_dpp v164, v164, v164 quad_perm:[2,3,0,1] row_mask:0xf bank_mask:0xf bound_ctrl:1
	v_mfma_scale_f32_16x16x128_f8f6f4 v[184:187], v[116:119], v[136:143], v[184:187], v240, v242 op_sel_hi:[0,0,0] cbsz:4
	v_add_f32_dpp v168, v168, v168 quad_perm:[2,3,0,1] row_mask:0xf bank_mask:0xf bound_ctrl:1
	v_add_f32_dpp v172, v172, v172 quad_perm:[2,3,0,1] row_mask:0xf bank_mask:0xf bound_ctrl:1
	v_cndmask_b32_e64 v160, v160, v164, s[4:5]
	v_mfma_scale_f32_16x16x128_f8f6f4 v[188:191], v[124:127], v[136:143], v[188:191], v240, v242 op_sel_hi:[0,0,0] cbsz:4
	v_cndmask_b32_e64 v160, v160, v168, s[6:7]
	v_cndmask_b32_e64 v160, v160, v172, s[8:9]
	v_add_f32_e32 v218, v218, v160
	s_add_u32 s0, s0, 1
	s_lshl_b32 s1, s0, 21
	s_add_u32 s60, s1, 0x200000
	s_add_u32 s61, s61, 0x100
	s_add_u32 s62, s61, 0x100
	s_cmp_eq_u32 s0, 4
	s_cbranch_scc0 .LpgL0_unoflush
	s_nop 15
	v_cndmask_b32_e64 v176, v176, v177, s[4:5]
	v_cndmask_b32_e64 v180, v180, v181, s[4:5]
	v_cndmask_b32_e64 v184, v184, v185, s[4:5]
	v_cndmask_b32_e64 v188, v188, v189, s[4:5]
	v_cndmask_b32_e64 v176, v176, v178, s[6:7]
	v_cndmask_b32_e64 v180, v180, v182, s[6:7]
	v_cndmask_b32_e64 v184, v184, v186, s[6:7]
	v_cndmask_b32_e64 v188, v188, v190, s[6:7]
	v_cndmask_b32_e64 v176, v176, v179, s[8:9]
	v_cndmask_b32_e64 v180, v180, v183, s[8:9]
	v_cndmask_b32_e64 v184, v184, v187, s[8:9]
	v_cndmask_b32_e64 v188, v188, v191, s[8:9]
	v_add_f32_dpp v176, v176, v176 quad_perm:[1,0,3,2] row_mask:0xf bank_mask:0xf bound_ctrl:1
	v_add_f32_dpp v180, v180, v180 quad_perm:[1,0,3,2] row_mask:0xf bank_mask:0xf bound_ctrl:1
	v_add_f32_dpp v184, v184, v184 quad_perm:[1,0,3,2] row_mask:0xf bank_mask:0xf bound_ctrl:1
	v_add_f32_dpp v188, v188, v188 quad_perm:[1,0,3,2] row_mask:0xf bank_mask:0xf bound_ctrl:1
	v_add_f32_dpp v176, v176, v176 quad_perm:[2,3,0,1] row_mask:0xf bank_mask:0xf bound_ctrl:1
	v_add_f32_dpp v180, v180, v180 quad_perm:[2,3,0,1] row_mask:0xf bank_mask:0xf bound_ctrl:1
	v_add_f32_dpp v184, v184, v184 quad_perm:[2,3,0,1] row_mask:0xf bank_mask:0xf bound_ctrl:1
	v_add_f32_dpp v188, v188, v188 quad_perm:[2,3,0,1] row_mask:0xf bank_mask:0xf bound_ctrl:1
	v_cndmask_b32_e64 v176, v176, v180, s[4:5]
	v_cndmask_b32_e64 v176, v176, v184, s[6:7]
	v_cndmask_b32_e64 v176, v176, v188, s[8:9]
	v_add_f32_e32 v219, v219, v176
	v_mov_b32_e32 v220, v204
	v_mov_b32_e32 v221, v205
	v_mov_b32_e32 v222, v206
	v_mov_b32_e32 v223, v207
	v_mov_b32_e32 v224, v208
	v_mov_b32_e32 v225, v209
	v_mov_b32_e32 v226, v210
	v_mov_b32_e32 v227, v211
	v_mov_b32_e32 v228, v212
	v_mov_b32_e32 v229, v213
	v_mov_b32_e32 v230, v214
	v_mov_b32_e32 v231, v215
	v_mov_b32_e32 v232, v216
	v_mov_b32_e32 v233, v217
	v_mov_b32_e32 v234, v218
	v_mov_b32_e32 v235, v219
	v_mov_b32_e32 v204, 0
	v_mov_b32_e32 v205, 0
	v_mov_b32_e32 v206, 0
	v_mov_b32_e32 v207, 0
	v_mov_b32_e32 v208, 0
	v_mov_b32_e32 v209, 0
	v_mov_b32_e32 v210, 0
	v_mov_b32_e32 v211, 0
	v_mov_b32_e32 v212, 0
	v_mov_b32_e32 v213, 0
	v_mov_b32_e32 v214, 0
	v_mov_b32_e32 v215, 0
	v_mov_b32_e32 v216, 0
	v_mov_b32_e32 v217, 0
	v_mov_b32_e32 v218, 0
	v_mov_b32_e32 v219, 0
	v_mov_b32_e32 v176, 0
	v_mov_b32_e32 v177, 0
	v_mov_b32_e32 v178, 0
	v_mov_b32_e32 v179, 0
	v_mov_b32_e32 v180, 0
	v_mov_b32_e32 v181, 0
	v_mov_b32_e32 v182, 0
	v_mov_b32_e32 v183, 0
	v_mov_b32_e32 v184, 0
	v_mov_b32_e32 v185, 0
	v_mov_b32_e32 v186, 0
	v_mov_b32_e32 v187, 0
	v_mov_b32_e32 v188, 0
	v_mov_b32_e32 v189, 0
	v_mov_b32_e32 v190, 0
	v_mov_b32_e32 v191, 0
.LpgL0_unoflush:
	s_cmp_lt_u32 s0, 8
	s_cbranch_scc1 .LpgL0_uloop
	s_waitcnt vmcnt(0)
	s_nop 15
	v_cndmask_b32_e64 v176, v176, v177, s[4:5]
	v_cndmask_b32_e64 v180, v180, v181, s[4:5]
	v_cndmask_b32_e64 v184, v184, v185, s[4:5]
	v_cndmask_b32_e64 v188, v188, v189, s[4:5]
	v_cndmask_b32_e64 v176, v176, v178, s[6:7]
	v_cndmask_b32_e64 v180, v180, v182, s[6:7]
	v_cndmask_b32_e64 v184, v184, v186, s[6:7]
	v_cndmask_b32_e64 v188, v188, v190, s[6:7]
	v_cndmask_b32_e64 v176, v176, v179, s[8:9]
	v_cndmask_b32_e64 v180, v180, v183, s[8:9]
	v_cndmask_b32_e64 v184, v184, v187, s[8:9]
	v_cndmask_b32_e64 v188, v188, v191, s[8:9]
	v_add_f32_dpp v176, v176, v176 quad_perm:[1,0,3,2] row_mask:0xf bank_mask:0xf bound_ctrl:1
	v_add_f32_dpp v180, v180, v180 quad_perm:[1,0,3,2] row_mask:0xf bank_mask:0xf bound_ctrl:1
	v_add_f32_dpp v184, v184, v184 quad_perm:[1,0,3,2] row_mask:0xf bank_mask:0xf bound_ctrl:1
	v_add_f32_dpp v188, v188, v188 quad_perm:[1,0,3,2] row_mask:0xf bank_mask:0xf bound_ctrl:1
	v_add_f32_dpp v176, v176, v176 quad_perm:[2,3,0,1] row_mask:0xf bank_mask:0xf bound_ctrl:1
	v_add_f32_dpp v180, v180, v180 quad_perm:[2,3,0,1] row_mask:0xf bank_mask:0xf bound_ctrl:1
	v_add_f32_dpp v184, v184, v184 quad_perm:[2,3,0,1] row_mask:0xf bank_mask:0xf bound_ctrl:1
	v_add_f32_dpp v188, v188, v188 quad_perm:[2,3,0,1] row_mask:0xf bank_mask:0xf bound_ctrl:1
	v_cndmask_b32_e64 v176, v176, v180, s[4:5]
	v_cndmask_b32_e64 v176, v176, v184, s[6:7]
	v_cndmask_b32_e64 v176, v176, v188, s[8:9]
	v_add_f32_e32 v219, v219, v176
	ds_read_b32 v0, v243 offset:0
	ds_read_b32 v1, v243 offset:256
	ds_read_b32 v2, v243 offset:512
	ds_read_b32 v3, v243 offset:768
	ds_read_b32 v4, v243 offset:1024
	ds_read_b32 v5, v243 offset:1280
	ds_read_b32 v6, v243 offset:1536
	ds_read_b32 v7, v243 offset:1792
	ds_read_b32 v8, v243 offset:2048
	ds_read_b32 v9, v243 offset:2304
	ds_read_b32 v10, v243 offset:2560
	ds_read_b32 v11, v243 offset:2816
	ds_read_b32 v12, v243 offset:3072
	ds_read_b32 v13, v243 offset:3328
	ds_read_b32 v14, v243 offset:3584
	ds_read_b32 v15, v243 offset:3840
	global_load_dword v96, v246, s[40:41] offset:0
	global_load_dword v97, v246, s[40:41] offset:4
	global_load_dword v98, v246, s[40:41] offset:8
	global_load_dword v99, v246, s[40:41] offset:12
	global_load_dword v100, v246, s[40:41] offset:16
	global_load_dword v101, v246, s[40:41] offset:20
	global_load_dword v102, v246, s[40:41] offset:24
	global_load_dword v103, v246, s[40:41] offset:28
	global_load_dword v16, v244, s[26:27] offset:0
	global_load_dword v17, v244, s[26:27] offset:256
	global_load_dword v18, v244, s[26:27] offset:512
	global_load_dword v19, v244, s[26:27] offset:768
	global_load_dword v20, v244, s[26:27] offset:1024
	global_load_dword v21, v244, s[26:27] offset:1280
	global_load_dword v22, v244, s[26:27] offset:1536
	global_load_dword v23, v244, s[26:27] offset:1792
	global_load_dword v24, v244, s[26:27] offset:2048
	global_load_dword v25, v244, s[26:27] offset:2304
	global_load_dword v26, v244, s[26:27] offset:2560
	global_load_dword v27, v244, s[26:27] offset:2816
	global_load_dword v28, v244, s[26:27] offset:3072
	global_load_dword v29, v244, s[26:27] offset:3328
	global_load_dword v30, v244, s[26:27] offset:3584
	global_load_dword v31, v244, s[26:27] offset:3840
	s_waitcnt lgkmcnt(0)
	v_lshlrev_b32_e32 v0, 3, v0
	global_load_dwordx2 v[32:33], v0, s[30:31]
	global_load_dwordx2 v[64:65], v0, s[34:35]
	v_lshlrev_b32_e32 v1, 3, v1
	global_load_dwordx2 v[34:35], v1, s[30:31]
	global_load_dwordx2 v[66:67], v1, s[34:35]
	v_lshlrev_b32_e32 v2, 3, v2
	global_load_dwordx2 v[36:37], v2, s[30:31]
	global_load_dwordx2 v[68:69], v2, s[34:35]
	v_lshlrev_b32_e32 v3, 3, v3
	global_load_dwordx2 v[38:39], v3, s[30:31]
	global_load_dwordx2 v[70:71], v3, s[34:35]
	v_lshlrev_b32_e32 v4, 3, v4
	global_load_dwordx2 v[40:41], v4, s[30:31]
	global_load_dwordx2 v[72:73], v4, s[34:35]
	v_lshlrev_b32_e32 v5, 3, v5
	global_load_dwordx2 v[42:43], v5, s[30:31]
	global_load_dwordx2 v[74:75], v5, s[34:35]
	v_lshlrev_b32_e32 v6, 3, v6
	global_load_dwordx2 v[44:45], v6, s[30:31]
	global_load_dwordx2 v[76:77], v6, s[34:35]
	v_lshlrev_b32_e32 v7, 3, v7
	global_load_dwordx2 v[46:47], v7, s[30:31]
	global_load_dwordx2 v[78:79], v7, s[34:35]
	v_lshlrev_b32_e32 v8, 3, v8
	global_load_dwordx2 v[48:49], v8, s[30:31]
	global_load_dwordx2 v[80:81], v8, s[34:35]
	v_lshlrev_b32_e32 v9, 3, v9
	global_load_dwordx2 v[50:51], v9, s[30:31]
	global_load_dwordx2 v[82:83], v9, s[34:35]
	v_lshlrev_b32_e32 v10, 3, v10
	global_load_dwordx2 v[52:53], v10, s[30:31]
	global_load_dwordx2 v[84:85], v10, s[34:35]
	v_lshlrev_b32_e32 v11, 3, v11
	global_load_dwordx2 v[54:55], v11, s[30:31]
	global_load_dwordx2 v[86:87], v11, s[34:35]
	v_lshlrev_b32_e32 v12, 3, v12
	global_load_dwordx2 v[56:57], v12, s[30:31]
	global_load_dwordx2 v[88:89], v12, s[34:35]
	v_lshlrev_b32_e32 v13, 3, v13
	global_load_dwordx2 v[58:59], v13, s[30:31]
	global_load_dwordx2 v[90:91], v13, s[34:35]
	v_lshlrev_b32_e32 v14, 3, v14
	global_load_dwordx2 v[60:61], v14, s[30:31]
	global_load_dwordx2 v[92:93], v14, s[34:35]
	v_lshlrev_b32_e32 v15, 3, v15
	global_load_dwordx2 v[62:63], v15, s[30:31]
	global_load_dwordx2 v[94:95], v15, s[34:35]
	s_waitcnt vmcnt(0)
	v_mov_b32_e32 v120, 0x358637bd
	v_fmamk_f32 v96, v96, 0x3a000000, v120
	v_cmp_gt_f32_e32 vcc, s96, v96
	v_mul_f32_e32 v121, 0x4b800000, v96
	s_nop 0
	v_cndmask_b32_e32 v96, v96, v121, vcc
	v_rsq_f32_e32 v96, v96
	s_nop 0
	v_mul_f32_e32 v121, 0x45800000, v96
	v_cndmask_b32_e32 v96, v96, v121, vcc
	v_fmamk_f32 v97, v97, 0x3a000000, v120
	v_cmp_gt_f32_e32 vcc, s96, v97
	v_mul_f32_e32 v121, 0x4b800000, v97
	s_nop 0
	v_cndmask_b32_e32 v97, v97, v121, vcc
	v_rsq_f32_e32 v97, v97
	s_nop 0
	v_mul_f32_e32 v121, 0x45800000, v97
	v_cndmask_b32_e32 v97, v97, v121, vcc
	v_fmamk_f32 v98, v98, 0x3a000000, v120
	v_cmp_gt_f32_e32 vcc, s96, v98
	v_mul_f32_e32 v121, 0x4b800000, v98
	s_nop 0
	v_cndmask_b32_e32 v98, v98, v121, vcc
	v_rsq_f32_e32 v98, v98
	s_nop 0
	v_mul_f32_e32 v121, 0x45800000, v98
	v_cndmask_b32_e32 v98, v98, v121, vcc
	v_fmamk_f32 v99, v99, 0x3a000000, v120
	v_cmp_gt_f32_e32 vcc, s96, v99
	v_mul_f32_e32 v121, 0x4b800000, v99
	s_nop 0
	v_cndmask_b32_e32 v99, v99, v121, vcc
	v_rsq_f32_e32 v99, v99
	s_nop 0
	v_mul_f32_e32 v121, 0x45800000, v99
	v_cndmask_b32_e32 v99, v99, v121, vcc
	v_fmamk_f32 v100, v100, 0x3a000000, v120
	v_cmp_gt_f32_e32 vcc, s96, v100
	v_mul_f32_e32 v121, 0x4b800000, v100
	s_nop 0
	v_cndmask_b32_e32 v100, v100, v121, vcc
	v_rsq_f32_e32 v100, v100
	s_nop 0
	v_mul_f32_e32 v121, 0x45800000, v100
	v_cndmask_b32_e32 v100, v100, v121, vcc
	v_fmamk_f32 v101, v101, 0x3a000000, v120
	v_cmp_gt_f32_e32 vcc, s96, v101
	v_mul_f32_e32 v121, 0x4b800000, v101
	s_nop 0
	v_cndmask_b32_e32 v101, v101, v121, vcc
	v_rsq_f32_e32 v101, v101
	s_nop 0
	v_mul_f32_e32 v121, 0x45800000, v101
	v_cndmask_b32_e32 v101, v101, v121, vcc
	v_fmamk_f32 v102, v102, 0x3a000000, v120
	v_cmp_gt_f32_e32 vcc, s96, v102
	v_mul_f32_e32 v121, 0x4b800000, v102
	s_nop 0
	v_cndmask_b32_e32 v102, v102, v121, vcc
	v_rsq_f32_e32 v102, v102
	s_nop 0
	v_mul_f32_e32 v121, 0x45800000, v102
	v_cndmask_b32_e32 v102, v102, v121, vcc
	v_fmamk_f32 v103, v103, 0x3a000000, v120
	v_cmp_gt_f32_e32 vcc, s96, v103
	v_mul_f32_e32 v121, 0x4b800000, v103
	s_nop 0
	v_cndmask_b32_e32 v103, v103, v121, vcc
	v_rsq_f32_e32 v103, v103
	s_nop 0
	v_mul_f32_e32 v121, 0x45800000, v103
	v_cndmask_b32_e32 v103, v103, v121, vcc
	v_mul_f32_e32 v104, v220, v32
	v_fmac_f32_e32 v104, v204, v33
	v_mul_f32_e32 v104, v104, v96
	v_mul_f32_e32 v105, 0x3d372713, v104
	v_mul_f32_e32 v105, v104, v105
	v_fma_f32 v105, v104, v105, v104
	v_mul_f32_e32 v105, 0x3f4c422a, v105
	v_add_f32_e32 v105, v105, v105
	v_mul_f32_e32 v105, 0x3fb8aa3b, v105
	v_exp_f32_e32 v105, v105
	v_mul_f32_e32 v104, 0.5, v104
	v_add_f32_e32 v105, 1.0, v105
	v_div_scale_f32 v106, s[70:71], v105, v105, 2.0
	v_rcp_f32_e32 v107, v106
	s_nop 0
	v_fma_f32 v108, -v106, v107, 1.0
	v_fmac_f32_e32 v107, v108, v107
	v_div_scale_f32 v108, vcc, 2.0, v105, 2.0
	v_mul_f32_e32 v109, v108, v107
	v_fma_f32 v110, -v106, v109, v108
	v_fmac_f32_e32 v109, v110, v107
	v_fma_f32 v106, -v106, v109, v108
	v_div_fmas_f32 v106, v106, v107, v109
	v_div_fixup_f32 v105, v106, v105, 2.0
	v_sub_f32_e32 v105, 1.0, v105
	v_add_f32_e32 v105, 1.0, v105
	v_mul_f32_e32 v104, v104, v105
	v_mul_f32_e32 v104, v16, v104
	v_mul_f32_e32 v105, v64, v104
	v_mul_f32_e32 v105, 0x43800000, v105
	v_mov_b32_e32 v106, 0x43e00000
	v_med3_f32 v105, v105, s94, v106
	v_mov_b32_e32 v106, 0
	v_cvt_pk_fp8_f32 v106, v105, 0
	s_nop 0
	v_and_b32_e32 v106, 0xff, v106
	v_mul_lo_u32 v106, v106, s81
	ds_write_b32 v245, v106 offset:0
	v_mul_f32_e32 v105, v65, v104
	v_mul_f32_e32 v105, 0x43800000, v105
	v_mov_b32_e32 v106, 0x43e00000
	v_med3_f32 v105, v105, s94, v106
	v_mov_b32_e32 v106, 0
	v_cvt_pk_fp8_f32 v106, v105, 0
	s_nop 0
	v_and_b32_e32 v106, 0xff, v106
	v_mul_lo_u32 v106, v106, s81
	ds_write_b32 v245, v106 offset:4096
	v_mul_f32_e32 v104, v221, v34
	v_fmac_f32_e32 v104, v205, v35
	v_mul_f32_e32 v104, v104, v96
	v_mul_f32_e32 v105, 0x3d372713, v104
	v_mul_f32_e32 v105, v104, v105
	v_fma_f32 v105, v104, v105, v104
	v_mul_f32_e32 v105, 0x3f4c422a, v105
	v_add_f32_e32 v105, v105, v105
	v_mul_f32_e32 v105, 0x3fb8aa3b, v105
	v_exp_f32_e32 v105, v105
	v_mul_f32_e32 v104, 0.5, v104
	v_add_f32_e32 v105, 1.0, v105
	v_div_scale_f32 v106, s[70:71], v105, v105, 2.0
	v_rcp_f32_e32 v107, v106
	s_nop 0
	v_fma_f32 v108, -v106, v107, 1.0
	v_fmac_f32_e32 v107, v108, v107
	v_div_scale_f32 v108, vcc, 2.0, v105, 2.0
	v_mul_f32_e32 v109, v108, v107
	v_fma_f32 v110, -v106, v109, v108
	v_fmac_f32_e32 v109, v110, v107
	v_fma_f32 v106, -v106, v109, v108
	v_div_fmas_f32 v106, v106, v107, v109
	v_div_fixup_f32 v105, v106, v105, 2.0
	v_sub_f32_e32 v105, 1.0, v105
	v_add_f32_e32 v105, 1.0, v105
	v_mul_f32_e32 v104, v104, v105
	v_mul_f32_e32 v104, v17, v104
	v_mul_f32_e32 v105, v66, v104
	v_mul_f32_e32 v105, 0x43800000, v105
	v_mov_b32_e32 v106, 0x43e00000
	v_med3_f32 v105, v105, s94, v106
	v_mov_b32_e32 v106, 0
	v_cvt_pk_fp8_f32 v106, v105, 0
	s_nop 0
	v_and_b32_e32 v106, 0xff, v106
	v_mul_lo_u32 v106, v106, s81
	ds_write_b32 v245, v106 offset:256
	v_mul_f32_e32 v105, v67, v104
	v_mul_f32_e32 v105, 0x43800000, v105
	v_mov_b32_e32 v106, 0x43e00000
	v_med3_f32 v105, v105, s94, v106
	v_mov_b32_e32 v106, 0
	v_cvt_pk_fp8_f32 v106, v105, 0
	s_nop 0
	v_and_b32_e32 v106, 0xff, v106
	v_mul_lo_u32 v106, v106, s81
	ds_write_b32 v245, v106 offset:4352
	v_mul_f32_e32 v104, v222, v36
	v_fmac_f32_e32 v104, v206, v37
	v_mul_f32_e32 v104, v104, v97
	v_mul_f32_e32 v105, 0x3d372713, v104
	v_mul_f32_e32 v105, v104, v105
	v_fma_f32 v105, v104, v105, v104
	v_mul_f32_e32 v105, 0x3f4c422a, v105
	v_add_f32_e32 v105, v105, v105
	v_mul_f32_e32 v105, 0x3fb8aa3b, v105
	v_exp_f32_e32 v105, v105
	v_mul_f32_e32 v104, 0.5, v104
	v_add_f32_e32 v105, 1.0, v105
	v_div_scale_f32 v106, s[70:71], v105, v105, 2.0
	v_rcp_f32_e32 v107, v106
	s_nop 0
	v_fma_f32 v108, -v106, v107, 1.0
	v_fmac_f32_e32 v107, v108, v107
	v_div_scale_f32 v108, vcc, 2.0, v105, 2.0
	v_mul_f32_e32 v109, v108, v107
	v_fma_f32 v110, -v106, v109, v108
	v_fmac_f32_e32 v109, v110, v107
	v_fma_f32 v106, -v106, v109, v108
	v_div_fmas_f32 v106, v106, v107, v109
	v_div_fixup_f32 v105, v106, v105, 2.0
	v_sub_f32_e32 v105, 1.0, v105
	v_add_f32_e32 v105, 1.0, v105
	v_mul_f32_e32 v104, v104, v105
	v_mul_f32_e32 v104, v18, v104
	v_mul_f32_e32 v105, v68, v104
	v_mul_f32_e32 v105, 0x43800000, v105
	v_mov_b32_e32 v106, 0x43e00000
	v_med3_f32 v105, v105, s94, v106
	v_mov_b32_e32 v106, 0
	v_cvt_pk_fp8_f32 v106, v105, 0
	s_nop 0
	v_and_b32_e32 v106, 0xff, v106
	v_mul_lo_u32 v106, v106, s81
	ds_write_b32 v245, v106 offset:512
	v_mul_f32_e32 v105, v69, v104
	v_mul_f32_e32 v105, 0x43800000, v105
	v_mov_b32_e32 v106, 0x43e00000
	v_med3_f32 v105, v105, s94, v106
	v_mov_b32_e32 v106, 0
	v_cvt_pk_fp8_f32 v106, v105, 0
	s_nop 0
	v_and_b32_e32 v106, 0xff, v106
	v_mul_lo_u32 v106, v106, s81
	ds_write_b32 v245, v106 offset:4608
	v_mul_f32_e32 v104, v223, v38
	v_fmac_f32_e32 v104, v207, v39
	v_mul_f32_e32 v104, v104, v97
	v_mul_f32_e32 v105, 0x3d372713, v104
	v_mul_f32_e32 v105, v104, v105
	v_fma_f32 v105, v104, v105, v104
	v_mul_f32_e32 v105, 0x3f4c422a, v105
	v_add_f32_e32 v105, v105, v105
	v_mul_f32_e32 v105, 0x3fb8aa3b, v105
	v_exp_f32_e32 v105, v105
	v_mul_f32_e32 v104, 0.5, v104
	v_add_f32_e32 v105, 1.0, v105
	v_div_scale_f32 v106, s[70:71], v105, v105, 2.0
	v_rcp_f32_e32 v107, v106
	s_nop 0
	v_fma_f32 v108, -v106, v107, 1.0
	v_fmac_f32_e32 v107, v108, v107
	v_div_scale_f32 v108, vcc, 2.0, v105, 2.0
	v_mul_f32_e32 v109, v108, v107
	v_fma_f32 v110, -v106, v109, v108
	v_fmac_f32_e32 v109, v110, v107
	v_fma_f32 v106, -v106, v109, v108
	v_div_fmas_f32 v106, v106, v107, v109
	v_div_fixup_f32 v105, v106, v105, 2.0
	v_sub_f32_e32 v105, 1.0, v105
	v_add_f32_e32 v105, 1.0, v105
	v_mul_f32_e32 v104, v104, v105
	v_mul_f32_e32 v104, v19, v104
	v_mul_f32_e32 v105, v70, v104
	v_mul_f32_e32 v105, 0x43800000, v105
	v_mov_b32_e32 v106, 0x43e00000
	v_med3_f32 v105, v105, s94, v106
	v_mov_b32_e32 v106, 0
	v_cvt_pk_fp8_f32 v106, v105, 0
	s_nop 0
	v_and_b32_e32 v106, 0xff, v106
	v_mul_lo_u32 v106, v106, s81
	ds_write_b32 v245, v106 offset:768
	v_mul_f32_e32 v105, v71, v104
	v_mul_f32_e32 v105, 0x43800000, v105
	v_mov_b32_e32 v106, 0x43e00000
	v_med3_f32 v105, v105, s94, v106
	v_mov_b32_e32 v106, 0
	v_cvt_pk_fp8_f32 v106, v105, 0
	s_nop 0
	v_and_b32_e32 v106, 0xff, v106
	v_mul_lo_u32 v106, v106, s81
	ds_write_b32 v245, v106 offset:4864
	v_mul_f32_e32 v104, v224, v40
	v_fmac_f32_e32 v104, v208, v41
	v_mul_f32_e32 v104, v104, v98
	v_mul_f32_e32 v105, 0x3d372713, v104
	v_mul_f32_e32 v105, v104, v105
	v_fma_f32 v105, v104, v105, v104
	v_mul_f32_e32 v105, 0x3f4c422a, v105
	v_add_f32_e32 v105, v105, v105
	v_mul_f32_e32 v105, 0x3fb8aa3b, v105
	v_exp_f32_e32 v105, v105
	v_mul_f32_e32 v104, 0.5, v104
	v_add_f32_e32 v105, 1.0, v105
	v_div_scale_f32 v106, s[70:71], v105, v105, 2.0
	v_rcp_f32_e32 v107, v106
	s_nop 0
	v_fma_f32 v108, -v106, v107, 1.0
	v_fmac_f32_e32 v107, v108, v107
	v_div_scale_f32 v108, vcc, 2.0, v105, 2.0
	v_mul_f32_e32 v109, v108, v107
	v_fma_f32 v110, -v106, v109, v108
	v_fmac_f32_e32 v109, v110, v107
	v_fma_f32 v106, -v106, v109, v108
	v_div_fmas_f32 v106, v106, v107, v109
	v_div_fixup_f32 v105, v106, v105, 2.0
	v_sub_f32_e32 v105, 1.0, v105
	v_add_f32_e32 v105, 1.0, v105
	v_mul_f32_e32 v104, v104, v105
	v_mul_f32_e32 v104, v20, v104
	v_mul_f32_e32 v105, v72, v104
	v_mul_f32_e32 v105, 0x43800000, v105
	v_mov_b32_e32 v106, 0x43e00000
	v_med3_f32 v105, v105, s94, v106
	v_mov_b32_e32 v106, 0
	v_cvt_pk_fp8_f32 v106, v105, 0
	s_nop 0
	v_and_b32_e32 v106, 0xff, v106
	v_mul_lo_u32 v106, v106, s81
	ds_write_b32 v245, v106 offset:1024
	v_mul_f32_e32 v105, v73, v104
	v_mul_f32_e32 v105, 0x43800000, v105
	v_mov_b32_e32 v106, 0x43e00000
	v_med3_f32 v105, v105, s94, v106
	v_mov_b32_e32 v106, 0
	v_cvt_pk_fp8_f32 v106, v105, 0
	s_nop 0
	v_and_b32_e32 v106, 0xff, v106
	v_mul_lo_u32 v106, v106, s81
	ds_write_b32 v245, v106 offset:5120
	v_mul_f32_e32 v104, v225, v42
	v_fmac_f32_e32 v104, v209, v43
	v_mul_f32_e32 v104, v104, v98
	v_mul_f32_e32 v105, 0x3d372713, v104
	v_mul_f32_e32 v105, v104, v105
	v_fma_f32 v105, v104, v105, v104
	v_mul_f32_e32 v105, 0x3f4c422a, v105
	v_add_f32_e32 v105, v105, v105
	v_mul_f32_e32 v105, 0x3fb8aa3b, v105
	v_exp_f32_e32 v105, v105
	v_mul_f32_e32 v104, 0.5, v104
	v_add_f32_e32 v105, 1.0, v105
	v_div_scale_f32 v106, s[70:71], v105, v105, 2.0
	v_rcp_f32_e32 v107, v106
	s_nop 0
	v_fma_f32 v108, -v106, v107, 1.0
	v_fmac_f32_e32 v107, v108, v107
	v_div_scale_f32 v108, vcc, 2.0, v105, 2.0
	v_mul_f32_e32 v109, v108, v107
	v_fma_f32 v110, -v106, v109, v108
	v_fmac_f32_e32 v109, v110, v107
	v_fma_f32 v106, -v106, v109, v108
	v_div_fmas_f32 v106, v106, v107, v109
	v_div_fixup_f32 v105, v106, v105, 2.0
	v_sub_f32_e32 v105, 1.0, v105
	v_add_f32_e32 v105, 1.0, v105
	v_mul_f32_e32 v104, v104, v105
	v_mul_f32_e32 v104, v21, v104
	v_mul_f32_e32 v105, v74, v104
	v_mul_f32_e32 v105, 0x43800000, v105
	v_mov_b32_e32 v106, 0x43e00000
	v_med3_f32 v105, v105, s94, v106
	v_mov_b32_e32 v106, 0
	v_cvt_pk_fp8_f32 v106, v105, 0
	s_nop 0
	v_and_b32_e32 v106, 0xff, v106
	v_mul_lo_u32 v106, v106, s81
	ds_write_b32 v245, v106 offset:1280
	v_mul_f32_e32 v105, v75, v104
	v_mul_f32_e32 v105, 0x43800000, v105
	v_mov_b32_e32 v106, 0x43e00000
	v_med3_f32 v105, v105, s94, v106
	v_mov_b32_e32 v106, 0
	v_cvt_pk_fp8_f32 v106, v105, 0
	s_nop 0
	v_and_b32_e32 v106, 0xff, v106
	v_mul_lo_u32 v106, v106, s81
	ds_write_b32 v245, v106 offset:5376
	v_mul_f32_e32 v104, v226, v44
	v_fmac_f32_e32 v104, v210, v45
	v_mul_f32_e32 v104, v104, v99
	v_mul_f32_e32 v105, 0x3d372713, v104
	v_mul_f32_e32 v105, v104, v105
	v_fma_f32 v105, v104, v105, v104
	v_mul_f32_e32 v105, 0x3f4c422a, v105
	v_add_f32_e32 v105, v105, v105
	v_mul_f32_e32 v105, 0x3fb8aa3b, v105
	v_exp_f32_e32 v105, v105
	v_mul_f32_e32 v104, 0.5, v104
	v_add_f32_e32 v105, 1.0, v105
	v_div_scale_f32 v106, s[70:71], v105, v105, 2.0
	v_rcp_f32_e32 v107, v106
	s_nop 0
	v_fma_f32 v108, -v106, v107, 1.0
	v_fmac_f32_e32 v107, v108, v107
	v_div_scale_f32 v108, vcc, 2.0, v105, 2.0
	v_mul_f32_e32 v109, v108, v107
	v_fma_f32 v110, -v106, v109, v108
	v_fmac_f32_e32 v109, v110, v107
	v_fma_f32 v106, -v106, v109, v108
	v_div_fmas_f32 v106, v106, v107, v109
	v_div_fixup_f32 v105, v106, v105, 2.0
	v_sub_f32_e32 v105, 1.0, v105
	v_add_f32_e32 v105, 1.0, v105
	v_mul_f32_e32 v104, v104, v105
	v_mul_f32_e32 v104, v22, v104
	v_mul_f32_e32 v105, v76, v104
	v_mul_f32_e32 v105, 0x43800000, v105
	v_mov_b32_e32 v106, 0x43e00000
	v_med3_f32 v105, v105, s94, v106
	v_mov_b32_e32 v106, 0
	v_cvt_pk_fp8_f32 v106, v105, 0
	s_nop 0
	v_and_b32_e32 v106, 0xff, v106
	v_mul_lo_u32 v106, v106, s81
	ds_write_b32 v245, v106 offset:1536
	v_mul_f32_e32 v105, v77, v104
	v_mul_f32_e32 v105, 0x43800000, v105
	v_mov_b32_e32 v106, 0x43e00000
	v_med3_f32 v105, v105, s94, v106
	v_mov_b32_e32 v106, 0
	v_cvt_pk_fp8_f32 v106, v105, 0
	s_nop 0
	v_and_b32_e32 v106, 0xff, v106
	v_mul_lo_u32 v106, v106, s81
	ds_write_b32 v245, v106 offset:5632
	v_mul_f32_e32 v104, v227, v46
	v_fmac_f32_e32 v104, v211, v47
	v_mul_f32_e32 v104, v104, v99
	v_mul_f32_e32 v105, 0x3d372713, v104
	v_mul_f32_e32 v105, v104, v105
	v_fma_f32 v105, v104, v105, v104
	v_mul_f32_e32 v105, 0x3f4c422a, v105
	v_add_f32_e32 v105, v105, v105
	v_mul_f32_e32 v105, 0x3fb8aa3b, v105
	v_exp_f32_e32 v105, v105
	v_mul_f32_e32 v104, 0.5, v104
	v_add_f32_e32 v105, 1.0, v105
	v_div_scale_f32 v106, s[70:71], v105, v105, 2.0
	v_rcp_f32_e32 v107, v106
	s_nop 0
	v_fma_f32 v108, -v106, v107, 1.0
	v_fmac_f32_e32 v107, v108, v107
	v_div_scale_f32 v108, vcc, 2.0, v105, 2.0
	v_mul_f32_e32 v109, v108, v107
	v_fma_f32 v110, -v106, v109, v108
	v_fmac_f32_e32 v109, v110, v107
	v_fma_f32 v106, -v106, v109, v108
	v_div_fmas_f32 v106, v106, v107, v109
	v_div_fixup_f32 v105, v106, v105, 2.0
	v_sub_f32_e32 v105, 1.0, v105
	v_add_f32_e32 v105, 1.0, v105
	v_mul_f32_e32 v104, v104, v105
	v_mul_f32_e32 v104, v23, v104
	v_mul_f32_e32 v105, v78, v104
	v_mul_f32_e32 v105, 0x43800000, v105
	v_mov_b32_e32 v106, 0x43e00000
	v_med3_f32 v105, v105, s94, v106
	v_mov_b32_e32 v106, 0
	v_cvt_pk_fp8_f32 v106, v105, 0
	s_nop 0
	v_and_b32_e32 v106, 0xff, v106
	v_mul_lo_u32 v106, v106, s81
	ds_write_b32 v245, v106 offset:1792
	v_mul_f32_e32 v105, v79, v104
	v_mul_f32_e32 v105, 0x43800000, v105
	v_mov_b32_e32 v106, 0x43e00000
	v_med3_f32 v105, v105, s94, v106
	v_mov_b32_e32 v106, 0
	v_cvt_pk_fp8_f32 v106, v105, 0
	s_nop 0
	v_and_b32_e32 v106, 0xff, v106
	v_mul_lo_u32 v106, v106, s81
	ds_write_b32 v245, v106 offset:5888
	v_mul_f32_e32 v104, v228, v48
	v_fmac_f32_e32 v104, v212, v49
	v_mul_f32_e32 v104, v104, v100
	v_mul_f32_e32 v105, 0x3d372713, v104
	v_mul_f32_e32 v105, v104, v105
	v_fma_f32 v105, v104, v105, v104
	v_mul_f32_e32 v105, 0x3f4c422a, v105
	v_add_f32_e32 v105, v105, v105
	v_mul_f32_e32 v105, 0x3fb8aa3b, v105
	v_exp_f32_e32 v105, v105
	v_mul_f32_e32 v104, 0.5, v104
	v_add_f32_e32 v105, 1.0, v105
	v_div_scale_f32 v106, s[70:71], v105, v105, 2.0
	v_rcp_f32_e32 v107, v106
	s_nop 0
	v_fma_f32 v108, -v106, v107, 1.0
	v_fmac_f32_e32 v107, v108, v107
	v_div_scale_f32 v108, vcc, 2.0, v105, 2.0
	v_mul_f32_e32 v109, v108, v107
	v_fma_f32 v110, -v106, v109, v108
	v_fmac_f32_e32 v109, v110, v107
	v_fma_f32 v106, -v106, v109, v108
	v_div_fmas_f32 v106, v106, v107, v109
	v_div_fixup_f32 v105, v106, v105, 2.0
	v_sub_f32_e32 v105, 1.0, v105
	v_add_f32_e32 v105, 1.0, v105
	v_mul_f32_e32 v104, v104, v105
	v_mul_f32_e32 v104, v24, v104
	v_mul_f32_e32 v105, v80, v104
	v_mul_f32_e32 v105, 0x43800000, v105
	v_mov_b32_e32 v106, 0x43e00000
	v_med3_f32 v105, v105, s94, v106
	v_mov_b32_e32 v106, 0
	v_cvt_pk_fp8_f32 v106, v105, 0
	s_nop 0
	v_and_b32_e32 v106, 0xff, v106
	v_mul_lo_u32 v106, v106, s81
	ds_write_b32 v245, v106 offset:2048
	v_mul_f32_e32 v105, v81, v104
	v_mul_f32_e32 v105, 0x43800000, v105
	v_mov_b32_e32 v106, 0x43e00000
	v_med3_f32 v105, v105, s94, v106
	v_mov_b32_e32 v106, 0
	v_cvt_pk_fp8_f32 v106, v105, 0
	s_nop 0
	v_and_b32_e32 v106, 0xff, v106
	v_mul_lo_u32 v106, v106, s81
	ds_write_b32 v245, v106 offset:6144
	v_mul_f32_e32 v104, v229, v50
	v_fmac_f32_e32 v104, v213, v51
	v_mul_f32_e32 v104, v104, v100
	v_mul_f32_e32 v105, 0x3d372713, v104
	v_mul_f32_e32 v105, v104, v105
	v_fma_f32 v105, v104, v105, v104
	v_mul_f32_e32 v105, 0x3f4c422a, v105
	v_add_f32_e32 v105, v105, v105
	v_mul_f32_e32 v105, 0x3fb8aa3b, v105
	v_exp_f32_e32 v105, v105
	v_mul_f32_e32 v104, 0.5, v104
	v_add_f32_e32 v105, 1.0, v105
	v_div_scale_f32 v106, s[70:71], v105, v105, 2.0
	v_rcp_f32_e32 v107, v106
	s_nop 0
	v_fma_f32 v108, -v106, v107, 1.0
	v_fmac_f32_e32 v107, v108, v107
	v_div_scale_f32 v108, vcc, 2.0, v105, 2.0
	v_mul_f32_e32 v109, v108, v107
	v_fma_f32 v110, -v106, v109, v108
	v_fmac_f32_e32 v109, v110, v107
	v_fma_f32 v106, -v106, v109, v108
	v_div_fmas_f32 v106, v106, v107, v109
	v_div_fixup_f32 v105, v106, v105, 2.0
	v_sub_f32_e32 v105, 1.0, v105
	v_add_f32_e32 v105, 1.0, v105
	v_mul_f32_e32 v104, v104, v105
	v_mul_f32_e32 v104, v25, v104
	v_mul_f32_e32 v105, v82, v104
	v_mul_f32_e32 v105, 0x43800000, v105
	v_mov_b32_e32 v106, 0x43e00000
	v_med3_f32 v105, v105, s94, v106
	v_mov_b32_e32 v106, 0
	v_cvt_pk_fp8_f32 v106, v105, 0
	s_nop 0
	v_and_b32_e32 v106, 0xff, v106
	v_mul_lo_u32 v106, v106, s81
	ds_write_b32 v245, v106 offset:2304
	v_mul_f32_e32 v105, v83, v104
	v_mul_f32_e32 v105, 0x43800000, v105
	v_mov_b32_e32 v106, 0x43e00000
	v_med3_f32 v105, v105, s94, v106
	v_mov_b32_e32 v106, 0
	v_cvt_pk_fp8_f32 v106, v105, 0
	s_nop 0
	v_and_b32_e32 v106, 0xff, v106
	v_mul_lo_u32 v106, v106, s81
	ds_write_b32 v245, v106 offset:6400
	v_mul_f32_e32 v104, v230, v52
	v_fmac_f32_e32 v104, v214, v53
	v_mul_f32_e32 v104, v104, v101
	v_mul_f32_e32 v105, 0x3d372713, v104
	v_mul_f32_e32 v105, v104, v105
	v_fma_f32 v105, v104, v105, v104
	v_mul_f32_e32 v105, 0x3f4c422a, v105
	v_add_f32_e32 v105, v105, v105
	v_mul_f32_e32 v105, 0x3fb8aa3b, v105
	v_exp_f32_e32 v105, v105
	v_mul_f32_e32 v104, 0.5, v104
	v_add_f32_e32 v105, 1.0, v105
	v_div_scale_f32 v106, s[70:71], v105, v105, 2.0
	v_rcp_f32_e32 v107, v106
	s_nop 0
	v_fma_f32 v108, -v106, v107, 1.0
	v_fmac_f32_e32 v107, v108, v107
	v_div_scale_f32 v108, vcc, 2.0, v105, 2.0
	v_mul_f32_e32 v109, v108, v107
	v_fma_f32 v110, -v106, v109, v108
	v_fmac_f32_e32 v109, v110, v107
	v_fma_f32 v106, -v106, v109, v108
	v_div_fmas_f32 v106, v106, v107, v109
	v_div_fixup_f32 v105, v106, v105, 2.0
	v_sub_f32_e32 v105, 1.0, v105
	v_add_f32_e32 v105, 1.0, v105
	v_mul_f32_e32 v104, v104, v105
	v_mul_f32_e32 v104, v26, v104
	v_mul_f32_e32 v105, v84, v104
	v_mul_f32_e32 v105, 0x43800000, v105
	v_mov_b32_e32 v106, 0x43e00000
	v_med3_f32 v105, v105, s94, v106
	v_mov_b32_e32 v106, 0
	v_cvt_pk_fp8_f32 v106, v105, 0
	s_nop 0
	v_and_b32_e32 v106, 0xff, v106
	v_mul_lo_u32 v106, v106, s81
	ds_write_b32 v245, v106 offset:2560
	v_mul_f32_e32 v105, v85, v104
	v_mul_f32_e32 v105, 0x43800000, v105
	v_mov_b32_e32 v106, 0x43e00000
	v_med3_f32 v105, v105, s94, v106
	v_mov_b32_e32 v106, 0
	v_cvt_pk_fp8_f32 v106, v105, 0
	s_nop 0
	v_and_b32_e32 v106, 0xff, v106
	v_mul_lo_u32 v106, v106, s81
	ds_write_b32 v245, v106 offset:6656
	v_mul_f32_e32 v104, v231, v54
	v_fmac_f32_e32 v104, v215, v55
	v_mul_f32_e32 v104, v104, v101
	v_mul_f32_e32 v105, 0x3d372713, v104
	v_mul_f32_e32 v105, v104, v105
	v_fma_f32 v105, v104, v105, v104
	v_mul_f32_e32 v105, 0x3f4c422a, v105
	v_add_f32_e32 v105, v105, v105
	v_mul_f32_e32 v105, 0x3fb8aa3b, v105
	v_exp_f32_e32 v105, v105
	v_mul_f32_e32 v104, 0.5, v104
	v_add_f32_e32 v105, 1.0, v105
	v_div_scale_f32 v106, s[70:71], v105, v105, 2.0
	v_rcp_f32_e32 v107, v106
	s_nop 0
	v_fma_f32 v108, -v106, v107, 1.0
	v_fmac_f32_e32 v107, v108, v107
	v_div_scale_f32 v108, vcc, 2.0, v105, 2.0
	v_mul_f32_e32 v109, v108, v107
	v_fma_f32 v110, -v106, v109, v108
	v_fmac_f32_e32 v109, v110, v107
	v_fma_f32 v106, -v106, v109, v108
	v_div_fmas_f32 v106, v106, v107, v109
	v_div_fixup_f32 v105, v106, v105, 2.0
	v_sub_f32_e32 v105, 1.0, v105
	v_add_f32_e32 v105, 1.0, v105
	v_mul_f32_e32 v104, v104, v105
	v_mul_f32_e32 v104, v27, v104
	v_mul_f32_e32 v105, v86, v104
	v_mul_f32_e32 v105, 0x43800000, v105
	v_mov_b32_e32 v106, 0x43e00000
	v_med3_f32 v105, v105, s94, v106
	v_mov_b32_e32 v106, 0
	v_cvt_pk_fp8_f32 v106, v105, 0
	s_nop 0
	v_and_b32_e32 v106, 0xff, v106
	v_mul_lo_u32 v106, v106, s81
	ds_write_b32 v245, v106 offset:2816
	v_mul_f32_e32 v105, v87, v104
	v_mul_f32_e32 v105, 0x43800000, v105
	v_mov_b32_e32 v106, 0x43e00000
	v_med3_f32 v105, v105, s94, v106
	v_mov_b32_e32 v106, 0
	v_cvt_pk_fp8_f32 v106, v105, 0
	s_nop 0
	v_and_b32_e32 v106, 0xff, v106
	v_mul_lo_u32 v106, v106, s81
	ds_write_b32 v245, v106 offset:6912
	v_mul_f32_e32 v104, v232, v56
	v_fmac_f32_e32 v104, v216, v57
	v_mul_f32_e32 v104, v104, v102
	v_mul_f32_e32 v105, 0x3d372713, v104
	v_mul_f32_e32 v105, v104, v105
	v_fma_f32 v105, v104, v105, v104
	v_mul_f32_e32 v105, 0x3f4c422a, v105
	v_add_f32_e32 v105, v105, v105
	v_mul_f32_e32 v105, 0x3fb8aa3b, v105
	v_exp_f32_e32 v105, v105
	v_mul_f32_e32 v104, 0.5, v104
	v_add_f32_e32 v105, 1.0, v105
	v_div_scale_f32 v106, s[70:71], v105, v105, 2.0
	v_rcp_f32_e32 v107, v106
	s_nop 0
	v_fma_f32 v108, -v106, v107, 1.0
	v_fmac_f32_e32 v107, v108, v107
	v_div_scale_f32 v108, vcc, 2.0, v105, 2.0
	v_mul_f32_e32 v109, v108, v107
	v_fma_f32 v110, -v106, v109, v108
	v_fmac_f32_e32 v109, v110, v107
	v_fma_f32 v106, -v106, v109, v108
	v_div_fmas_f32 v106, v106, v107, v109
	v_div_fixup_f32 v105, v106, v105, 2.0
	v_sub_f32_e32 v105, 1.0, v105
	v_add_f32_e32 v105, 1.0, v105
	v_mul_f32_e32 v104, v104, v105
	v_mul_f32_e32 v104, v28, v104
	v_mul_f32_e32 v105, v88, v104
	v_mul_f32_e32 v105, 0x43800000, v105
	v_mov_b32_e32 v106, 0x43e00000
	v_med3_f32 v105, v105, s94, v106
	v_mov_b32_e32 v106, 0
	v_cvt_pk_fp8_f32 v106, v105, 0
	s_nop 0
	v_and_b32_e32 v106, 0xff, v106
	v_mul_lo_u32 v106, v106, s81
	ds_write_b32 v245, v106 offset:3072
	v_mul_f32_e32 v105, v89, v104
	v_mul_f32_e32 v105, 0x43800000, v105
	v_mov_b32_e32 v106, 0x43e00000
	v_med3_f32 v105, v105, s94, v106
	v_mov_b32_e32 v106, 0
	v_cvt_pk_fp8_f32 v106, v105, 0
	s_nop 0
	v_and_b32_e32 v106, 0xff, v106
	v_mul_lo_u32 v106, v106, s81
	ds_write_b32 v245, v106 offset:7168
	v_mul_f32_e32 v104, v233, v58
	v_fmac_f32_e32 v104, v217, v59
	v_mul_f32_e32 v104, v104, v102
	v_mul_f32_e32 v105, 0x3d372713, v104
	v_mul_f32_e32 v105, v104, v105
	v_fma_f32 v105, v104, v105, v104
	v_mul_f32_e32 v105, 0x3f4c422a, v105
	v_add_f32_e32 v105, v105, v105
	v_mul_f32_e32 v105, 0x3fb8aa3b, v105
	v_exp_f32_e32 v105, v105
	v_mul_f32_e32 v104, 0.5, v104
	v_add_f32_e32 v105, 1.0, v105
	v_div_scale_f32 v106, s[70:71], v105, v105, 2.0
	v_rcp_f32_e32 v107, v106
	s_nop 0
	v_fma_f32 v108, -v106, v107, 1.0
	v_fmac_f32_e32 v107, v108, v107
	v_div_scale_f32 v108, vcc, 2.0, v105, 2.0
	v_mul_f32_e32 v109, v108, v107
	v_fma_f32 v110, -v106, v109, v108
	v_fmac_f32_e32 v109, v110, v107
	v_fma_f32 v106, -v106, v109, v108
	v_div_fmas_f32 v106, v106, v107, v109
	v_div_fixup_f32 v105, v106, v105, 2.0
	v_sub_f32_e32 v105, 1.0, v105
	v_add_f32_e32 v105, 1.0, v105
	v_mul_f32_e32 v104, v104, v105
	v_mul_f32_e32 v104, v29, v104
	v_mul_f32_e32 v105, v90, v104
	v_mul_f32_e32 v105, 0x43800000, v105
	v_mov_b32_e32 v106, 0x43e00000
	v_med3_f32 v105, v105, s94, v106
	v_mov_b32_e32 v106, 0
	v_cvt_pk_fp8_f32 v106, v105, 0
	s_nop 0
	v_and_b32_e32 v106, 0xff, v106
	v_mul_lo_u32 v106, v106, s81
	ds_write_b32 v245, v106 offset:3328
	v_mul_f32_e32 v105, v91, v104
	v_mul_f32_e32 v105, 0x43800000, v105
	v_mov_b32_e32 v106, 0x43e00000
	v_med3_f32 v105, v105, s94, v106
	v_mov_b32_e32 v106, 0
	v_cvt_pk_fp8_f32 v106, v105, 0
	s_nop 0
	v_and_b32_e32 v106, 0xff, v106
	v_mul_lo_u32 v106, v106, s81
	ds_write_b32 v245, v106 offset:7424
	v_mul_f32_e32 v104, v234, v60
	v_fmac_f32_e32 v104, v218, v61
	v_mul_f32_e32 v104, v104, v103
	v_mul_f32_e32 v105, 0x3d372713, v104
	v_mul_f32_e32 v105, v104, v105
	v_fma_f32 v105, v104, v105, v104
	v_mul_f32_e32 v105, 0x3f4c422a, v105
	v_add_f32_e32 v105, v105, v105
	v_mul_f32_e32 v105, 0x3fb8aa3b, v105
	v_exp_f32_e32 v105, v105
	v_mul_f32_e32 v104, 0.5, v104
	v_add_f32_e32 v105, 1.0, v105
	v_div_scale_f32 v106, s[70:71], v105, v105, 2.0
	v_rcp_f32_e32 v107, v106
	s_nop 0
	v_fma_f32 v108, -v106, v107, 1.0
	v_fmac_f32_e32 v107, v108, v107
	v_div_scale_f32 v108, vcc, 2.0, v105, 2.0
	v_mul_f32_e32 v109, v108, v107
	v_fma_f32 v110, -v106, v109, v108
	v_fmac_f32_e32 v109, v110, v107
	v_fma_f32 v106, -v106, v109, v108
	v_div_fmas_f32 v106, v106, v107, v109
	v_div_fixup_f32 v105, v106, v105, 2.0
	v_sub_f32_e32 v105, 1.0, v105
	v_add_f32_e32 v105, 1.0, v105
	v_mul_f32_e32 v104, v104, v105
	v_mul_f32_e32 v104, v30, v104
	v_mul_f32_e32 v105, v92, v104
	v_mul_f32_e32 v105, 0x43800000, v105
	v_mov_b32_e32 v106, 0x43e00000
	v_med3_f32 v105, v105, s94, v106
	v_mov_b32_e32 v106, 0
	v_cvt_pk_fp8_f32 v106, v105, 0
	s_nop 0
	v_and_b32_e32 v106, 0xff, v106
	v_mul_lo_u32 v106, v106, s81
	ds_write_b32 v245, v106 offset:3584
	v_mul_f32_e32 v105, v93, v104
	v_mul_f32_e32 v105, 0x43800000, v105
	v_mov_b32_e32 v106, 0x43e00000
	v_med3_f32 v105, v105, s94, v106
	v_mov_b32_e32 v106, 0
	v_cvt_pk_fp8_f32 v106, v105, 0
	s_nop 0
	v_and_b32_e32 v106, 0xff, v106
	v_mul_lo_u32 v106, v106, s81
	ds_write_b32 v245, v106 offset:7680
	v_mul_f32_e32 v104, v235, v62
	v_fmac_f32_e32 v104, v219, v63
	v_mul_f32_e32 v104, v104, v103
	v_mul_f32_e32 v105, 0x3d372713, v104
	v_mul_f32_e32 v105, v104, v105
	v_fma_f32 v105, v104, v105, v104
	v_mul_f32_e32 v105, 0x3f4c422a, v105
	v_add_f32_e32 v105, v105, v105
	v_mul_f32_e32 v105, 0x3fb8aa3b, v105
	v_exp_f32_e32 v105, v105
	v_mul_f32_e32 v104, 0.5, v104
	v_add_f32_e32 v105, 1.0, v105
	v_div_scale_f32 v106, s[70:71], v105, v105, 2.0
	v_rcp_f32_e32 v107, v106
	s_nop 0
	v_fma_f32 v108, -v106, v107, 1.0
	v_fmac_f32_e32 v107, v108, v107
	v_div_scale_f32 v108, vcc, 2.0, v105, 2.0
	v_mul_f32_e32 v109, v108, v107
	v_fma_f32 v110, -v106, v109, v108
	v_fmac_f32_e32 v109, v110, v107
	v_fma_f32 v106, -v106, v109, v108
	v_div_fmas_f32 v106, v106, v107, v109
	v_div_fixup_f32 v105, v106, v105, 2.0
	v_sub_f32_e32 v105, 1.0, v105
	v_add_f32_e32 v105, 1.0, v105
	v_mul_f32_e32 v104, v104, v105
	v_mul_f32_e32 v104, v31, v104
	v_mul_f32_e32 v105, v94, v104
	v_mul_f32_e32 v105, 0x43800000, v105
	v_mov_b32_e32 v106, 0x43e00000
	v_med3_f32 v105, v105, s94, v106
	v_mov_b32_e32 v106, 0
	v_cvt_pk_fp8_f32 v106, v105, 0
	s_nop 0
	v_and_b32_e32 v106, 0xff, v106
	v_mul_lo_u32 v106, v106, s81
	ds_write_b32 v245, v106 offset:3840
	v_mul_f32_e32 v105, v95, v104
	v_mul_f32_e32 v105, 0x43800000, v105
	v_mov_b32_e32 v106, 0x43e00000
	v_med3_f32 v105, v105, s94, v106
	v_mov_b32_e32 v106, 0
	v_cvt_pk_fp8_f32 v106, v105, 0
	s_nop 0
	v_and_b32_e32 v106, 0xff, v106
	v_mul_lo_u32 v106, v106, s81
	ds_write_b32 v245, v106 offset:7936
	s_waitcnt lgkmcnt(0)
	v_mbcnt_lo_u32_b32 v249, -1, 0
	v_mbcnt_hi_u32_b32 v249, -1, v249
	v_and_b32_e32 v250, 15, v249
	v_lshrrev_b32_e32 v251, 4, v249
	v_and_b32_e32 v252, 3, v250
	v_lshlrev_b32_e32 v232, 3, v250
	v_lshl_add_u32 v233, v251, 3, s91
	v_lshlrev_b32_e32 v239, 3, v249
	v_mov_b32_e32 v241, 0x77777777
	v_lshlrev_b32_e32 v253, 3, v252
	v_mov_b32_e32 v254, 0xff
	v_lshlrev_b32_e32 v254, v253, v254
	v_lshrrev_b32_e32 v253, 2, v250
	v_cmp_eq_u32_e32 vcc, 0, v253
	s_nop 1
	v_cndmask_b32_e32 v235, 0, v254, vcc
	v_cmp_eq_u32_e32 vcc, 1, v253
	s_nop 1
	v_cndmask_b32_e32 v236, 0, v254, vcc
	v_cmp_eq_u32_e32 vcc, 2, v253
	s_nop 1
	v_cndmask_b32_e32 v237, 0, v254, vcc
	v_cmp_eq_u32_e32 vcc, 3, v253
	s_nop 1
	v_cndmask_b32_e32 v238, 0, v254, vcc
	v_add_u32_e32 v234, 0x1000, v233
	v_add_u32_e32 v247, 0x1000, v233
	v_mov_b32_e32 v220, 0
	v_mov_b32_e32 v221, 0
	v_mov_b32_e32 v222, 0
	v_mov_b32_e32 v223, 0
	v_mov_b32_e32 v224, 0
	v_mov_b32_e32 v225, 0
	v_mov_b32_e32 v226, 0
	v_mov_b32_e32 v227, 0
	s_mov_b32 s0, 0
	s_mov_b32 s1, 0
	s_mov_b32 s60, 0x200000
	ds_read_b64 v[128:129], v233 offset:0
	ds_read_b64 v[130:131], v233 offset:32
	ds_read_b64 v[132:133], v233 offset:64
	ds_read_b64 v[134:135], v233 offset:96
	ds_read_b64 v[136:137], v233 offset:128
	ds_read_b64 v[138:139], v233 offset:160
	ds_read_b64 v[140:141], v233 offset:192
	ds_read_b64 v[142:143], v233 offset:224
	s_waitcnt lgkmcnt(0)
	v_lshl_or_b32 v128, v128, 7, v232
	v_lshl_or_b32 v129, v129, 7, v232
	v_lshl_or_b32 v130, v130, 7, v232
	v_lshl_or_b32 v131, v131, 7, v232
	v_lshl_or_b32 v132, v132, 7, v232
	v_lshl_or_b32 v133, v133, 7, v232
	v_lshl_or_b32 v134, v134, 7, v232
	v_lshl_or_b32 v135, v135, 7, v232
	v_lshl_or_b32 v136, v136, 7, v232
	v_lshl_or_b32 v137, v137, 7, v232
	v_lshl_or_b32 v138, v138, 7, v232
	v_lshl_or_b32 v139, v139, 7, v232
	v_lshl_or_b32 v140, v140, 7, v232
	v_lshl_or_b32 v141, v141, 7, v232
	v_lshl_or_b32 v142, v142, 7, v232
	v_lshl_or_b32 v143, v143, 7, v232
	buffer_load_dwordx2 v[0:1], v128, s[20:23], s1 offen
	buffer_load_dwordx2 v[2:3], v129, s[20:23], s1 offen
	buffer_load_dwordx2 v[4:5], v130, s[20:23], s1 offen
	buffer_load_dwordx2 v[6:7], v131, s[20:23], s1 offen
	buffer_load_dwordx2 v[8:9], v132, s[20:23], s1 offen
	buffer_load_dwordx2 v[10:11], v133, s[20:23], s1 offen
	buffer_load_dwordx2 v[12:13], v134, s[20:23], s1 offen
	buffer_load_dwordx2 v[14:15], v135, s[20:23], s1 offen
	buffer_load_dwordx2 v[16:17], v136, s[20:23], s1 offen
	buffer_load_dwordx2 v[18:19], v137, s[20:23], s1 offen
	buffer_load_dwordx2 v[20:21], v138, s[20:23], s1 offen
	buffer_load_dwordx2 v[22:23], v139, s[20:23], s1 offen
	buffer_load_dwordx2 v[24:25], v140, s[20:23], s1 offen
	buffer_load_dwordx2 v[26:27], v141, s[20:23], s1 offen
	buffer_load_dwordx2 v[28:29], v142, s[20:23], s1 offen
	buffer_load_dwordx2 v[30:31], v143, s[20:23], s1 offen
	ds_read_b64 v[128:129], v233 offset:256
	ds_read_b64 v[130:131], v233 offset:288
	ds_read_b64 v[132:133], v233 offset:320
	ds_read_b64 v[134:135], v233 offset:352
	ds_read_b64 v[136:137], v233 offset:384
	ds_read_b64 v[138:139], v233 offset:416
	ds_read_b64 v[140:141], v233 offset:448
	ds_read_b64 v[142:143], v233 offset:480
	global_load_dword v242, v246, s[40:41]
	global_load_dword v242, v246, s[40:41]
	s_waitcnt lgkmcnt(0)
	v_lshl_or_b32 v128, v128, 7, v232
	v_lshl_or_b32 v129, v129, 7, v232
	v_lshl_or_b32 v130, v130, 7, v232
	v_lshl_or_b32 v131, v131, 7, v232
	v_lshl_or_b32 v132, v132, 7, v232
	v_lshl_or_b32 v133, v133, 7, v232
	v_lshl_or_b32 v134, v134, 7, v232
	v_lshl_or_b32 v135, v135, 7, v232
	v_lshl_or_b32 v136, v136, 7, v232
	v_lshl_or_b32 v137, v137, 7, v232
	v_lshl_or_b32 v138, v138, 7, v232
	v_lshl_or_b32 v139, v139, 7, v232
	v_lshl_or_b32 v140, v140, 7, v232
	v_lshl_or_b32 v141, v141, 7, v232
	v_lshl_or_b32 v142, v142, 7, v232
	v_lshl_or_b32 v143, v143, 7, v232
	buffer_load_dwordx2 v[32:33], v128, s[20:23], s1 offen
	buffer_load_dwordx2 v[34:35], v129, s[20:23], s1 offen
	buffer_load_dwordx2 v[36:37], v130, s[20:23], s1 offen
	buffer_load_dwordx2 v[38:39], v131, s[20:23], s1 offen
	buffer_load_dwordx2 v[40:41], v132, s[20:23], s1 offen
	buffer_load_dwordx2 v[42:43], v133, s[20:23], s1 offen
	buffer_load_dwordx2 v[44:45], v134, s[20:23], s1 offen
	buffer_load_dwordx2 v[46:47], v135, s[20:23], s1 offen
	buffer_load_dwordx2 v[48:49], v136, s[20:23], s1 offen
	buffer_load_dwordx2 v[50:51], v137, s[20:23], s1 offen
	buffer_load_dwordx2 v[52:53], v138, s[20:23], s1 offen
	buffer_load_dwordx2 v[54:55], v139, s[20:23], s1 offen
	buffer_load_dwordx2 v[56:57], v140, s[20:23], s1 offen
	buffer_load_dwordx2 v[58:59], v141, s[20:23], s1 offen
	buffer_load_dwordx2 v[60:61], v142, s[20:23], s1 offen
	buffer_load_dwordx2 v[62:63], v143, s[20:23], s1 offen
	ds_read_b64 v[128:129], v233 offset:512
	ds_read_b64 v[130:131], v233 offset:544
	ds_read_b64 v[132:133], v233 offset:576
	ds_read_b64 v[134:135], v233 offset:608
	ds_read_b64 v[136:137], v233 offset:640
	ds_read_b64 v[138:139], v233 offset:672
	ds_read_b64 v[140:141], v233 offset:704
	ds_read_b64 v[142:143], v233 offset:736
	s_waitcnt lgkmcnt(0)
	v_lshl_or_b32 v128, v128, 7, v232
	v_lshl_or_b32 v129, v129, 7, v232
	v_lshl_or_b32 v130, v130, 7, v232
	v_lshl_or_b32 v131, v131, 7, v232
	v_lshl_or_b32 v132, v132, 7, v232
	v_lshl_or_b32 v133, v133, 7, v232
	v_lshl_or_b32 v134, v134, 7, v232
	v_lshl_or_b32 v135, v135, 7, v232
	v_lshl_or_b32 v136, v136, 7, v232
	v_lshl_or_b32 v137, v137, 7, v232
	v_lshl_or_b32 v138, v138, 7, v232
	v_lshl_or_b32 v139, v139, 7, v232
	v_lshl_or_b32 v140, v140, 7, v232
	v_lshl_or_b32 v141, v141, 7, v232
	v_lshl_or_b32 v142, v142, 7, v232
	v_lshl_or_b32 v143, v143, 7, v232
	buffer_load_dwordx2 v[64:65], v128, s[20:23], s1 offen
	buffer_load_dwordx2 v[66:67], v129, s[20:23], s1 offen
	buffer_load_dwordx2 v[68:69], v130, s[20:23], s1 offen
	buffer_load_dwordx2 v[70:71], v131, s[20:23], s1 offen
	buffer_load_dwordx2 v[72:73], v132, s[20:23], s1 offen
	buffer_load_dwordx2 v[74:75], v133, s[20:23], s1 offen
	buffer_load_dwordx2 v[76:77], v134, s[20:23], s1 offen
	buffer_load_dwordx2 v[78:79], v135, s[20:23], s1 offen
	buffer_load_dwordx2 v[80:81], v136, s[20:23], s1 offen
	buffer_load_dwordx2 v[82:83], v137, s[20:23], s1 offen
	buffer_load_dwordx2 v[84:85], v138, s[20:23], s1 offen
	buffer_load_dwordx2 v[86:87], v139, s[20:23], s1 offen
	buffer_load_dwordx2 v[88:89], v140, s[20:23], s1 offen
	buffer_load_dwordx2 v[90:91], v141, s[20:23], s1 offen
	buffer_load_dwordx2 v[92:93], v142, s[20:23], s1 offen
	buffer_load_dwordx2 v[94:95], v143, s[20:23], s1 offen
	ds_read_b64 v[128:129], v233 offset:768
	ds_read_b64 v[130:131], v233 offset:800
	ds_read_b64 v[132:133], v233 offset:832
	ds_read_b64 v[134:135], v233 offset:864
	ds_read_b64 v[136:137], v233 offset:896
	ds_read_b64 v[138:139], v233 offset:928
	ds_read_b64 v[140:141], v233 offset:960
	ds_read_b64 v[142:143], v233 offset:992
	ds_read_b64 v[160:161], v234 offset:0
	ds_read_b64 v[162:163], v234 offset:32
	ds_read_b64 v[164:165], v234 offset:64
	ds_read_b64 v[166:167], v234 offset:96
	ds_read_b64 v[168:169], v234 offset:128
	ds_read_b64 v[170:171], v234 offset:160
	ds_read_b64 v[172:173], v234 offset:192
	ds_read_b64 v[174:175], v234 offset:224
	global_load_dword v242, v246, s[40:41]
.LpgL0_vloop:
	s_lshl_b32 s64, s0, 9
	s_add_u32 s64, s64, 0x0
	s_add_u32 s70, s28, s64
	s_addc_u32 s71, s29, 0
	global_load_dwordx2 v[228:229], v239, s[70:71]
	s_waitcnt lgkmcnt(0)
	v_lshl_or_b32 v128, v128, 7, v232
	v_lshl_or_b32 v129, v129, 7, v232
	v_lshl_or_b32 v130, v130, 7, v232
	v_lshl_or_b32 v131, v131, 7, v232
	v_lshl_or_b32 v132, v132, 7, v232
	v_lshl_or_b32 v133, v133, 7, v232
	v_lshl_or_b32 v134, v134, 7, v232
	v_lshl_or_b32 v135, v135, 7, v232
	v_lshl_or_b32 v136, v136, 7, v232
	v_lshl_or_b32 v137, v137, 7, v232
	v_lshl_or_b32 v138, v138, 7, v232
	v_lshl_or_b32 v139, v139, 7, v232
	v_lshl_or_b32 v140, v140, 7, v232
	v_lshl_or_b32 v141, v141, 7, v232
	v_lshl_or_b32 v142, v142, 7, v232
	v_lshl_or_b32 v143, v143, 7, v232
	buffer_load_dwordx2 v[96:97], v128, s[20:23], s1 offen
	buffer_load_dwordx2 v[98:99], v129, s[20:23], s1 offen
	buffer_load_dwordx2 v[100:101], v130, s[20:23], s1 offen
	buffer_load_dwordx2 v[102:103], v131, s[20:23], s1 offen
	buffer_load_dwordx2 v[104:105], v132, s[20:23], s1 offen
	buffer_load_dwordx2 v[106:107], v133, s[20:23], s1 offen
	buffer_load_dwordx2 v[108:109], v134, s[20:23], s1 offen
	buffer_load_dwordx2 v[110:111], v135, s[20:23], s1 offen
	buffer_load_dwordx2 v[112:113], v136, s[20:23], s1 offen
	buffer_load_dwordx2 v[114:115], v137, s[20:23], s1 offen
	buffer_load_dwordx2 v[116:117], v138, s[20:23], s1 offen
	buffer_load_dwordx2 v[118:119], v139, s[20:23], s1 offen
	buffer_load_dwordx2 v[120:121], v140, s[20:23], s1 offen
	buffer_load_dwordx2 v[122:123], v141, s[20:23], s1 offen
	buffer_load_dwordx2 v[124:125], v142, s[20:23], s1 offen
	buffer_load_dwordx2 v[126:127], v143, s[20:23], s1 offen
	ds_read_b64 v[128:129], v233 offset:1024
	ds_read_b64 v[130:131], v233 offset:1056
	ds_read_b64 v[132:133], v233 offset:1088
	ds_read_b64 v[134:135], v233 offset:1120
	ds_read_b64 v[136:137], v233 offset:1152
	ds_read_b64 v[138:139], v233 offset:1184
	ds_read_b64 v[140:141], v233 offset:1216
	ds_read_b64 v[142:143], v233 offset:1248
	ds_read_b64 v[176:177], v234 offset:256
	ds_read_b64 v[178:179], v234 offset:288
	ds_read_b64 v[180:181], v234 offset:320
	ds_read_b64 v[182:183], v234 offset:352
	ds_read_b64 v[184:185], v234 offset:384
	ds_read_b64 v[186:187], v234 offset:416
	ds_read_b64 v[188:189], v234 offset:448
	ds_read_b64 v[190:191], v234 offset:480
	s_waitcnt vmcnt(52)
	v_and_b32_e32 v144, v160, v235
	v_and_b32_e32 v145, v160, v236
	v_and_b32_e32 v146, v160, v237
	v_and_b32_e32 v147, v160, v238
	v_and_b32_e32 v148, v161, v235
	v_and_b32_e32 v149, v161, v236
	v_and_b32_e32 v150, v161, v237
	v_and_b32_e32 v151, v161, v238
	v_and_b32_e32 v204, v162, v235
	v_and_b32_e32 v205, v162, v236
	v_and_b32_e32 v206, v162, v237
	v_and_b32_e32 v207, v162, v238
	v_and_b32_e32 v208, v163, v235
	v_and_b32_e32 v209, v163, v236
	v_and_b32_e32 v210, v163, v237
	v_and_b32_e32 v211, v163, v238
	v_mfma_scale_f32_16x16x128_f8f6f4 v[212:215], v[0:3], v[144:151], 0, v240, v241 op_sel_hi:[0,0,0] cbsz:4
	v_and_b32_e32 v144, v164, v235
	v_and_b32_e32 v145, v164, v236
	v_and_b32_e32 v146, v164, v237
	v_and_b32_e32 v147, v164, v238
	v_and_b32_e32 v148, v165, v235
	v_and_b32_e32 v149, v165, v236
	v_and_b32_e32 v150, v165, v237
	v_and_b32_e32 v151, v165, v238
	v_mfma_scale_f32_16x16x128_f8f6f4 v[212:215], v[4:7], v[204:211], v[212:215], v240, v241 op_sel_hi:[0,0,0] cbsz:4
	v_and_b32_e32 v204, v166, v235
	v_and_b32_e32 v205, v166, v236
	v_and_b32_e32 v206, v166, v237
	v_and_b32_e32 v207, v166, v238
	v_and_b32_e32 v208, v167, v235
	v_and_b32_e32 v209, v167, v236
	v_and_b32_e32 v210, v167, v237
	v_and_b32_e32 v211, v167, v238
	v_mfma_scale_f32_16x16x128_f8f6f4 v[212:215], v[8:11], v[144:151], v[212:215], v240, v241 op_sel_hi:[0,0,0] cbsz:4
	v_and_b32_e32 v144, v168, v235
	v_and_b32_e32 v145, v168, v236
	v_and_b32_e32 v146, v168, v237
	v_and_b32_e32 v147, v168, v238
	v_and_b32_e32 v148, v169, v235
	v_and_b32_e32 v149, v169, v236
	v_and_b32_e32 v150, v169, v237
	v_and_b32_e32 v151, v169, v238
	v_mfma_scale_f32_16x16x128_f8f6f4 v[212:215], v[12:15], v[204:211], v[212:215], v240, v241 op_sel_hi:[0,0,0] cbsz:4
	v_and_b32_e32 v204, v170, v235
	v_and_b32_e32 v205, v170, v236
	v_and_b32_e32 v206, v170, v237
	v_and_b32_e32 v207, v170, v238
	v_and_b32_e32 v208, v171, v235
	v_and_b32_e32 v209, v171, v236
	v_and_b32_e32 v210, v171, v237
	v_and_b32_e32 v211, v171, v238
	v_mfma_scale_f32_16x16x128_f8f6f4 v[212:215], v[16:19], v[144:151], v[212:215], v240, v241 op_sel_hi:[0,0,0] cbsz:4
	v_and_b32_e32 v144, v172, v235
	v_and_b32_e32 v145, v172, v236
	v_and_b32_e32 v146, v172, v237
	v_and_b32_e32 v147, v172, v238
	v_and_b32_e32 v148, v173, v235
	v_and_b32_e32 v149, v173, v236
	v_and_b32_e32 v150, v173, v237
	v_and_b32_e32 v151, v173, v238
	v_mfma_scale_f32_16x16x128_f8f6f4 v[212:215], v[20:23], v[204:211], v[212:215], v240, v241 op_sel_hi:[0,0,0] cbsz:4
	v_and_b32_e32 v204, v174, v235
	v_and_b32_e32 v205, v174, v236
	v_and_b32_e32 v206, v174, v237
	v_and_b32_e32 v207, v174, v238
	v_and_b32_e32 v208, v175, v235
	v_and_b32_e32 v209, v175, v236
	v_and_b32_e32 v210, v175, v237
	v_and_b32_e32 v211, v175, v238
	v_mfma_scale_f32_16x16x128_f8f6f4 v[212:215], v[24:27], v[144:151], v[212:215], v240, v241 op_sel_hi:[0,0,0] cbsz:4
	s_nop 0
	v_mfma_scale_f32_16x16x128_f8f6f4 v[212:215], v[28:31], v[204:211], v[212:215], v240, v241 op_sel_hi:[0,0,0] cbsz:4
	s_waitcnt lgkmcnt(0)
	v_lshl_or_b32 v128, v128, 7, v232
	v_lshl_or_b32 v129, v129, 7, v232
	v_lshl_or_b32 v130, v130, 7, v232
	v_lshl_or_b32 v131, v131, 7, v232
	v_lshl_or_b32 v132, v132, 7, v232
	v_lshl_or_b32 v133, v133, 7, v232
	v_lshl_or_b32 v134, v134, 7, v232
	v_lshl_or_b32 v135, v135, 7, v232
	v_lshl_or_b32 v136, v136, 7, v232
	v_lshl_or_b32 v137, v137, 7, v232
	v_lshl_or_b32 v138, v138, 7, v232
	v_lshl_or_b32 v139, v139, 7, v232
	v_lshl_or_b32 v140, v140, 7, v232
	v_lshl_or_b32 v141, v141, 7, v232
	v_lshl_or_b32 v142, v142, 7, v232
	v_lshl_or_b32 v143, v143, 7, v232
	buffer_load_dwordx2 v[0:1], v128, s[20:23], s1 offen
	buffer_load_dwordx2 v[2:3], v129, s[20:23], s1 offen
	buffer_load_dwordx2 v[4:5], v130, s[20:23], s1 offen
	buffer_load_dwordx2 v[6:7], v131, s[20:23], s1 offen
	buffer_load_dwordx2 v[8:9], v132, s[20:23], s1 offen
	buffer_load_dwordx2 v[10:11], v133, s[20:23], s1 offen
	buffer_load_dwordx2 v[12:13], v134, s[20:23], s1 offen
	buffer_load_dwordx2 v[14:15], v135, s[20:23], s1 offen
	buffer_load_dwordx2 v[16:17], v136, s[20:23], s1 offen
	buffer_load_dwordx2 v[18:19], v137, s[20:23], s1 offen
	buffer_load_dwordx2 v[20:21], v138, s[20:23], s1 offen
	buffer_load_dwordx2 v[22:23], v139, s[20:23], s1 offen
	buffer_load_dwordx2 v[24:25], v140, s[20:23], s1 offen
	buffer_load_dwordx2 v[26:27], v141, s[20:23], s1 offen
	buffer_load_dwordx2 v[28:29], v142, s[20:23], s1 offen
	buffer_load_dwordx2 v[30:31], v143, s[20:23], s1 offen
	ds_read_b64 v[128:129], v233 offset:1280
	ds_read_b64 v[130:131], v233 offset:1312
	ds_read_b64 v[132:133], v233 offset:1344
	ds_read_b64 v[134:135], v233 offset:1376
	ds_read_b64 v[136:137], v233 offset:1408
	ds_read_b64 v[138:139], v233 offset:1440
	ds_read_b64 v[140:141], v233 offset:1472
	ds_read_b64 v[142:143], v233 offset:1504
	ds_read_b64 v[160:161], v234 offset:512
	ds_read_b64 v[162:163], v234 offset:544
	ds_read_b64 v[164:165], v234 offset:576
	ds_read_b64 v[166:167], v234 offset:608
	ds_read_b64 v[168:169], v234 offset:640
	ds_read_b64 v[170:171], v234 offset:672
	ds_read_b64 v[172:173], v234 offset:704
	ds_read_b64 v[174:175], v234 offset:736
	s_waitcnt vmcnt(50)
	s_cmp_eq_u32 s0, 0
	s_cbranch_scc1 .LpgL0_vdummy
	v_and_b32_e32 v144, v176, v235
	v_and_b32_e32 v145, v176, v236
	v_and_b32_e32 v146, v176, v237
	v_and_b32_e32 v147, v176, v238
	v_and_b32_e32 v148, v177, v235
	v_and_b32_e32 v149, v177, v236
	v_and_b32_e32 v150, v177, v237
	v_and_b32_e32 v151, v177, v238
	v_and_b32_e32 v204, v178, v235
	v_and_b32_e32 v205, v178, v236
	v_and_b32_e32 v206, v178, v237
	v_and_b32_e32 v207, v178, v238
	v_and_b32_e32 v208, v179, v235
	v_and_b32_e32 v209, v179, v236
	v_and_b32_e32 v210, v179, v237
	v_and_b32_e32 v211, v179, v238
	v_mfma_scale_f32_16x16x128_f8f6f4 v[212:215], v[32:35], v[144:151], v[212:215], v240, v241 op_sel_hi:[0,0,0] cbsz:4
	v_lshlrev_b32_e32 v252, 16, v230
	v_and_b32_e32 v253, 0xffff0000, v230
	v_lshlrev_b32_e32 v254, 16, v231
	v_and_b32_e32 v144, v180, v235
	v_and_b32_e32 v145, v180, v236
	v_and_b32_e32 v146, v180, v237
	v_and_b32_e32 v147, v180, v238
	v_and_b32_e32 v148, v181, v235
	v_and_b32_e32 v149, v181, v236
	v_and_b32_e32 v150, v181, v237
	v_and_b32_e32 v151, v181, v238
	v_mfma_scale_f32_16x16x128_f8f6f4 v[212:215], v[36:39], v[204:211], v[212:215], v240, v241 op_sel_hi:[0,0,0] cbsz:4
	v_and_b32_e32 v255, 0xffff0000, v231
	v_add_f32_e32 v252, v216, v252
	v_add_f32_e32 v253, v217, v253
	v_and_b32_e32 v204, v182, v235
	v_and_b32_e32 v205, v182, v236
	v_and_b32_e32 v206, v182, v237
	v_and_b32_e32 v207, v182, v238
	v_and_b32_e32 v208, v183, v235
	v_and_b32_e32 v209, v183, v236
	v_and_b32_e32 v210, v183, v237
	v_and_b32_e32 v211, v183, v238
	v_mfma_scale_f32_16x16x128_f8f6f4 v[212:215], v[40:43], v[144:151], v[212:215], v240, v241 op_sel_hi:[0,0,0] cbsz:4
	v_add_f32_e32 v254, v218, v254
	v_add_f32_e32 v255, v219, v255
	v_mul_f32_e32 v192, v252, v252
	v_and_b32_e32 v144, v184, v235
	v_and_b32_e32 v145, v184, v236
	v_and_b32_e32 v146, v184, v237
	v_and_b32_e32 v147, v184, v238
	v_and_b32_e32 v148, v185, v235
	v_and_b32_e32 v149, v185, v236
	v_and_b32_e32 v150, v185, v237
	v_and_b32_e32 v151, v185, v238
	v_mfma_scale_f32_16x16x128_f8f6f4 v[212:215], v[44:47], v[204:211], v[212:215], v240, v241 op_sel_hi:[0,0,0] cbsz:4
	v_mul_f32_e32 v193, v254, v254
	v_fmac_f32_e32 v192, v253, v253
	v_fmac_f32_e32 v193, v255, v255
	v_and_b32_e32 v204, v186, v235
	v_and_b32_e32 v205, v186, v236
	v_and_b32_e32 v206, v186, v237
	v_and_b32_e32 v207, v186, v238
	v_and_b32_e32 v208, v187, v235
	v_and_b32_e32 v209, v187, v236
	v_and_b32_e32 v210, v187, v237
	v_and_b32_e32 v211, v187, v238
	v_mfma_scale_f32_16x16x128_f8f6f4 v[212:215], v[48:51], v[144:151], v[212:215], v240, v241 op_sel_hi:[0,0,0] cbsz:4
	v_cvt_pk_bf16_f32 v250, v252, v253
	v_cvt_pk_bf16_f32 v251, v254, v255
	v_add_f32_e32 v192, v192, v193
	v_and_b32_e32 v144, v188, v235
	v_and_b32_e32 v145, v188, v236
	v_and_b32_e32 v146, v188, v237
	v_and_b32_e32 v147, v188, v238
	v_and_b32_e32 v148, v189, v235
	v_and_b32_e32 v149, v189, v236
	v_and_b32_e32 v150, v189, v237
	v_and_b32_e32 v151, v189, v238
	v_mfma_scale_f32_16x16x128_f8f6f4 v[212:215], v[52:55], v[204:211], v[212:215], v240, v241 op_sel_hi:[0,0,0] cbsz:4
	v_add_f32_e32 v227, v227, v192
	v_and_b32_e32 v204, v190, v235
	v_and_b32_e32 v205, v190, v236
	v_and_b32_e32 v206, v190, v237
	v_and_b32_e32 v207, v190, v238
	v_and_b32_e32 v208, v191, v235
	v_and_b32_e32 v209, v191, v236
	v_and_b32_e32 v210, v191, v237
	v_and_b32_e32 v211, v191, v238
	v_mfma_scale_f32_16x16x128_f8f6f4 v[212:215], v[56:59], v[144:151], v[212:215], v240, v241 op_sel_hi:[0,0,0] cbsz:4
	s_nop 0
	v_mfma_scale_f32_16x16x128_f8f6f4 v[212:215], v[60:63], v[204:211], v[212:215], v240, v241 op_sel_hi:[0,0,0] cbsz:4
	s_lshl_b32 s64, s0, 9
	s_add_u32 s64, s64, 0x6e00
	s_add_u32 s76, s28, s64
	s_addc_u32 s77, s29, 0
	global_store_dwordx2 v239, v[250:251], s[76:77]
	s_branch .LpgL0_vjoin
.LpgL0_vdummy:
	v_and_b32_e32 v144, v176, v235
	v_and_b32_e32 v145, v176, v236
	v_and_b32_e32 v146, v176, v237
	v_and_b32_e32 v147, v176, v238
	v_and_b32_e32 v148, v177, v235
	v_and_b32_e32 v149, v177, v236
	v_and_b32_e32 v150, v177, v237
	v_and_b32_e32 v151, v177, v238
	v_and_b32_e32 v204, v178, v235
	v_and_b32_e32 v205, v178, v236
	v_and_b32_e32 v206, v178, v237
	v_and_b32_e32 v207, v178, v238
	v_and_b32_e32 v208, v179, v235
	v_and_b32_e32 v209, v179, v236
	v_and_b32_e32 v210, v179, v237
	v_and_b32_e32 v211, v179, v238
	v_mfma_scale_f32_16x16x128_f8f6f4 v[212:215], v[32:35], v[144:151], v[212:215], v240, v241 op_sel_hi:[0,0,0] cbsz:4
	v_and_b32_e32 v144, v180, v235
	v_and_b32_e32 v145, v180, v236
	v_and_b32_e32 v146, v180, v237
	v_and_b32_e32 v147, v180, v238
	v_and_b32_e32 v148, v181, v235
	v_and_b32_e32 v149, v181, v236
	v_and_b32_e32 v150, v181, v237
	v_and_b32_e32 v151, v181, v238
	v_mfma_scale_f32_16x16x128_f8f6f4 v[212:215], v[36:39], v[204:211], v[212:215], v240, v241 op_sel_hi:[0,0,0] cbsz:4
	v_and_b32_e32 v204, v182, v235
	v_and_b32_e32 v205, v182, v236
	v_and_b32_e32 v206, v182, v237
	v_and_b32_e32 v207, v182, v238
	v_and_b32_e32 v208, v183, v235
	v_and_b32_e32 v209, v183, v236
	v_and_b32_e32 v210, v183, v237
	v_and_b32_e32 v211, v183, v238
	v_mfma_scale_f32_16x16x128_f8f6f4 v[212:215], v[40:43], v[144:151], v[212:215], v240, v241 op_sel_hi:[0,0,0] cbsz:4
	v_and_b32_e32 v144, v184, v235
	v_and_b32_e32 v145, v184, v236
	v_and_b32_e32 v146, v184, v237
	v_and_b32_e32 v147, v184, v238
	v_and_b32_e32 v148, v185, v235
	v_and_b32_e32 v149, v185, v236
	v_and_b32_e32 v150, v185, v237
	v_and_b32_e32 v151, v185, v238
	v_mfma_scale_f32_16x16x128_f8f6f4 v[212:215], v[44:47], v[204:211], v[212:215], v240, v241 op_sel_hi:[0,0,0] cbsz:4
	v_and_b32_e32 v204, v186, v235
	v_and_b32_e32 v205, v186, v236
	v_and_b32_e32 v206, v186, v237
	v_and_b32_e32 v207, v186, v238
	v_and_b32_e32 v208, v187, v235
	v_and_b32_e32 v209, v187, v236
	v_and_b32_e32 v210, v187, v237
	v_and_b32_e32 v211, v187, v238
	v_mfma_scale_f32_16x16x128_f8f6f4 v[212:215], v[48:51], v[144:151], v[212:215], v240, v241 op_sel_hi:[0,0,0] cbsz:4
	v_and_b32_e32 v144, v188, v235
	v_and_b32_e32 v145, v188, v236
	v_and_b32_e32 v146, v188, v237
	v_and_b32_e32 v147, v188, v238
	v_and_b32_e32 v148, v189, v235
	v_and_b32_e32 v149, v189, v236
	v_and_b32_e32 v150, v189, v237
	v_and_b32_e32 v151, v189, v238
	v_mfma_scale_f32_16x16x128_f8f6f4 v[212:215], v[52:55], v[204:211], v[212:215], v240, v241 op_sel_hi:[0,0,0] cbsz:4
	v_and_b32_e32 v204, v190, v235
	v_and_b32_e32 v205, v190, v236
	v_and_b32_e32 v206, v190, v237
	v_and_b32_e32 v207, v190, v238
	v_and_b32_e32 v208, v191, v235
	v_and_b32_e32 v209, v191, v236
	v_and_b32_e32 v210, v191, v237
	v_and_b32_e32 v211, v191, v238
	v_mfma_scale_f32_16x16x128_f8f6f4 v[212:215], v[56:59], v[144:151], v[212:215], v240, v241 op_sel_hi:[0,0,0] cbsz:4
	s_nop 0
	v_mfma_scale_f32_16x16x128_f8f6f4 v[212:215], v[60:63], v[204:211], v[212:215], v240, v241 op_sel_hi:[0,0,0] cbsz:4
	global_load_dword v242, v246, s[40:41]
.LpgL0_vjoin:
	s_lshl_b32 s64, s0, 9
	s_add_u32 s64, s64, 0x1000
	s_add_u32 s70, s28, s64
	s_addc_u32 s71, s29, 0
	global_load_dwordx2 v[230:231], v239, s[70:71]
	s_waitcnt lgkmcnt(0)
	v_lshl_or_b32 v128, v128, 7, v232
	v_lshl_or_b32 v129, v129, 7, v232
	v_lshl_or_b32 v130, v130, 7, v232
	v_lshl_or_b32 v131, v131, 7, v232
	v_lshl_or_b32 v132, v132, 7, v232
	v_lshl_or_b32 v133, v133, 7, v232
	v_lshl_or_b32 v134, v134, 7, v232
	v_lshl_or_b32 v135, v135, 7, v232
	v_lshl_or_b32 v136, v136, 7, v232
	v_lshl_or_b32 v137, v137, 7, v232
	v_lshl_or_b32 v138, v138, 7, v232
	v_lshl_or_b32 v139, v139, 7, v232
	v_lshl_or_b32 v140, v140, 7, v232
	v_lshl_or_b32 v141, v141, 7, v232
	v_lshl_or_b32 v142, v142, 7, v232
	v_lshl_or_b32 v143, v143, 7, v232
	buffer_load_dwordx2 v[32:33], v128, s[20:23], s1 offen
	buffer_load_dwordx2 v[34:35], v129, s[20:23], s1 offen
	buffer_load_dwordx2 v[36:37], v130, s[20:23], s1 offen
	buffer_load_dwordx2 v[38:39], v131, s[20:23], s1 offen
	buffer_load_dwordx2 v[40:41], v132, s[20:23], s1 offen
	buffer_load_dwordx2 v[42:43], v133, s[20:23], s1 offen
	buffer_load_dwordx2 v[44:45], v134, s[20:23], s1 offen
	buffer_load_dwordx2 v[46:47], v135, s[20:23], s1 offen
	buffer_load_dwordx2 v[48:49], v136, s[20:23], s1 offen
	buffer_load_dwordx2 v[50:51], v137, s[20:23], s1 offen
	buffer_load_dwordx2 v[52:53], v138, s[20:23], s1 offen
	buffer_load_dwordx2 v[54:55], v139, s[20:23], s1 offen
	buffer_load_dwordx2 v[56:57], v140, s[20:23], s1 offen
	buffer_load_dwordx2 v[58:59], v141, s[20:23], s1 offen
	buffer_load_dwordx2 v[60:61], v142, s[20:23], s1 offen
	buffer_load_dwordx2 v[62:63], v143, s[20:23], s1 offen
	ds_read_b64 v[128:129], v233 offset:1536
	ds_read_b64 v[130:131], v233 offset:1568
	ds_read_b64 v[132:133], v233 offset:1600
	ds_read_b64 v[134:135], v233 offset:1632
	ds_read_b64 v[136:137], v233 offset:1664
	ds_read_b64 v[138:139], v233 offset:1696
	ds_read_b64 v[140:141], v233 offset:1728
	ds_read_b64 v[142:143], v233 offset:1760
	ds_read_b64 v[176:177], v234 offset:768
	ds_read_b64 v[178:179], v234 offset:800
	ds_read_b64 v[180:181], v234 offset:832
	ds_read_b64 v[182:183], v234 offset:864
	ds_read_b64 v[184:185], v234 offset:896
	ds_read_b64 v[186:187], v234 offset:928
	ds_read_b64 v[188:189], v234 offset:960
	ds_read_b64 v[190:191], v234 offset:992
	s_waitcnt vmcnt(52)
	v_and_b32_e32 v144, v160, v235
	v_and_b32_e32 v145, v160, v236
	v_and_b32_e32 v146, v160, v237
	v_and_b32_e32 v147, v160, v238
	v_and_b32_e32 v148, v161, v235
	v_and_b32_e32 v149, v161, v236
	v_and_b32_e32 v150, v161, v237
	v_and_b32_e32 v151, v161, v238
	v_and_b32_e32 v204, v162, v235
	v_and_b32_e32 v205, v162, v236
	v_and_b32_e32 v206, v162, v237
	v_and_b32_e32 v207, v162, v238
	v_and_b32_e32 v208, v163, v235
	v_and_b32_e32 v209, v163, v236
	v_and_b32_e32 v210, v163, v237
	v_and_b32_e32 v211, v163, v238
	v_mfma_scale_f32_16x16x128_f8f6f4 v[216:219], v[64:67], v[144:151], 0, v240, v241 op_sel_hi:[0,0,0] cbsz:4
	v_and_b32_e32 v144, v164, v235
	v_and_b32_e32 v145, v164, v236
	v_and_b32_e32 v146, v164, v237
	v_and_b32_e32 v147, v164, v238
	v_and_b32_e32 v148, v165, v235
	v_and_b32_e32 v149, v165, v236
	v_and_b32_e32 v150, v165, v237
	v_and_b32_e32 v151, v165, v238
	v_mfma_scale_f32_16x16x128_f8f6f4 v[216:219], v[68:71], v[204:211], v[216:219], v240, v241 op_sel_hi:[0,0,0] cbsz:4
	v_and_b32_e32 v204, v166, v235
	v_and_b32_e32 v205, v166, v236
	v_and_b32_e32 v206, v166, v237
	v_and_b32_e32 v207, v166, v238
	v_and_b32_e32 v208, v167, v235
	v_and_b32_e32 v209, v167, v236
	v_and_b32_e32 v210, v167, v237
	v_and_b32_e32 v211, v167, v238
	v_mfma_scale_f32_16x16x128_f8f6f4 v[216:219], v[72:75], v[144:151], v[216:219], v240, v241 op_sel_hi:[0,0,0] cbsz:4
	v_and_b32_e32 v144, v168, v235
	v_and_b32_e32 v145, v168, v236
	v_and_b32_e32 v146, v168, v237
	v_and_b32_e32 v147, v168, v238
	v_and_b32_e32 v148, v169, v235
	v_and_b32_e32 v149, v169, v236
	v_and_b32_e32 v150, v169, v237
	v_and_b32_e32 v151, v169, v238
	v_mfma_scale_f32_16x16x128_f8f6f4 v[216:219], v[76:79], v[204:211], v[216:219], v240, v241 op_sel_hi:[0,0,0] cbsz:4
	v_and_b32_e32 v204, v170, v235
	v_and_b32_e32 v205, v170, v236
	v_and_b32_e32 v206, v170, v237
	v_and_b32_e32 v207, v170, v238
	v_and_b32_e32 v208, v171, v235
	v_and_b32_e32 v209, v171, v236
	v_and_b32_e32 v210, v171, v237
	v_and_b32_e32 v211, v171, v238
	v_mfma_scale_f32_16x16x128_f8f6f4 v[216:219], v[80:83], v[144:151], v[216:219], v240, v241 op_sel_hi:[0,0,0] cbsz:4
	v_and_b32_e32 v144, v172, v235
	v_and_b32_e32 v145, v172, v236
	v_and_b32_e32 v146, v172, v237
	v_and_b32_e32 v147, v172, v238
	v_and_b32_e32 v148, v173, v235
	v_and_b32_e32 v149, v173, v236
	v_and_b32_e32 v150, v173, v237
	v_and_b32_e32 v151, v173, v238
	v_mfma_scale_f32_16x16x128_f8f6f4 v[216:219], v[84:87], v[204:211], v[216:219], v240, v241 op_sel_hi:[0,0,0] cbsz:4
	v_and_b32_e32 v204, v174, v235
	v_and_b32_e32 v205, v174, v236
	v_and_b32_e32 v206, v174, v237
	v_and_b32_e32 v207, v174, v238
	v_and_b32_e32 v208, v175, v235
	v_and_b32_e32 v209, v175, v236
	v_and_b32_e32 v210, v175, v237
	v_and_b32_e32 v211, v175, v238
	v_mfma_scale_f32_16x16x128_f8f6f4 v[216:219], v[88:91], v[144:151], v[216:219], v240, v241 op_sel_hi:[0,0,0] cbsz:4
	s_nop 0
	v_mfma_scale_f32_16x16x128_f8f6f4 v[216:219], v[92:95], v[204:211], v[216:219], v240, v241 op_sel_hi:[0,0,0] cbsz:4
	s_waitcnt lgkmcnt(0)
	v_lshl_or_b32 v128, v128, 7, v232
	v_lshl_or_b32 v129, v129, 7, v232
	v_lshl_or_b32 v130, v130, 7, v232
	v_lshl_or_b32 v131, v131, 7, v232
	v_lshl_or_b32 v132, v132, 7, v232
	v_lshl_or_b32 v133, v133, 7, v232
	v_lshl_or_b32 v134, v134, 7, v232
	v_lshl_or_b32 v135, v135, 7, v232
	v_lshl_or_b32 v136, v136, 7, v232
	v_lshl_or_b32 v137, v137, 7, v232
	v_lshl_or_b32 v138, v138, 7, v232
	v_lshl_or_b32 v139, v139, 7, v232
	v_lshl_or_b32 v140, v140, 7, v232
	v_lshl_or_b32 v141, v141, 7, v232
	v_lshl_or_b32 v142, v142, 7, v232
	v_lshl_or_b32 v143, v143, 7, v232
	buffer_load_dwordx2 v[64:65], v128, s[20:23], s1 offen
	buffer_load_dwordx2 v[66:67], v129, s[20:23], s1 offen
	buffer_load_dwordx2 v[68:69], v130, s[20:23], s1 offen
	buffer_load_dwordx2 v[70:71], v131, s[20:23], s1 offen
	buffer_load_dwordx2 v[72:73], v132, s[20:23], s1 offen
	buffer_load_dwordx2 v[74:75], v133, s[20:23], s1 offen
	buffer_load_dwordx2 v[76:77], v134, s[20:23], s1 offen
	buffer_load_dwordx2 v[78:79], v135, s[20:23], s1 offen
	buffer_load_dwordx2 v[80:81], v136, s[20:23], s1 offen
	buffer_load_dwordx2 v[82:83], v137, s[20:23], s1 offen
	buffer_load_dwordx2 v[84:85], v138, s[20:23], s1 offen
	buffer_load_dwordx2 v[86:87], v139, s[20:23], s1 offen
	buffer_load_dwordx2 v[88:89], v140, s[20:23], s1 offen
	buffer_load_dwordx2 v[90:91], v141, s[20:23], s1 offen
	buffer_load_dwordx2 v[92:93], v142, s[20:23], s1 offen
	buffer_load_dwordx2 v[94:95], v143, s[20:23], s1 offen
	ds_read_b64 v[128:129], v233 offset:1792
	ds_read_b64 v[130:131], v233 offset:1824
	ds_read_b64 v[132:133], v233 offset:1856
	ds_read_b64 v[134:135], v233 offset:1888
	ds_read_b64 v[136:137], v233 offset:1920
	ds_read_b64 v[138:139], v233 offset:1952
	ds_read_b64 v[140:141], v233 offset:1984
	ds_read_b64 v[142:143], v233 offset:2016
	ds_read_b64 v[160:161], v234 offset:1024
	ds_read_b64 v[162:163], v234 offset:1056
	ds_read_b64 v[164:165], v234 offset:1088
	ds_read_b64 v[166:167], v234 offset:1120
	ds_read_b64 v[168:169], v234 offset:1152
	ds_read_b64 v[170:171], v234 offset:1184
	ds_read_b64 v[172:173], v234 offset:1216
	ds_read_b64 v[174:175], v234 offset:1248
	s_waitcnt vmcnt(50)
	v_and_b32_e32 v144, v176, v235
	v_and_b32_e32 v145, v176, v236
	v_and_b32_e32 v146, v176, v237
	v_and_b32_e32 v147, v176, v238
	v_and_b32_e32 v148, v177, v235
	v_and_b32_e32 v149, v177, v236
	v_and_b32_e32 v150, v177, v237
	v_and_b32_e32 v151, v177, v238
	v_and_b32_e32 v204, v178, v235
	v_and_b32_e32 v205, v178, v236
	v_and_b32_e32 v206, v178, v237
	v_and_b32_e32 v207, v178, v238
	v_and_b32_e32 v208, v179, v235
	v_and_b32_e32 v209, v179, v236
	v_and_b32_e32 v210, v179, v237
	v_and_b32_e32 v211, v179, v238
	v_mfma_scale_f32_16x16x128_f8f6f4 v[216:219], v[96:99], v[144:151], v[216:219], v240, v241 op_sel_hi:[0,0,0] cbsz:4
	v_lshlrev_b32_e32 v252, 16, v228
	v_and_b32_e32 v253, 0xffff0000, v228
	v_lshlrev_b32_e32 v254, 16, v229
	v_and_b32_e32 v144, v180, v235
	v_and_b32_e32 v145, v180, v236
	v_and_b32_e32 v146, v180, v237
	v_and_b32_e32 v147, v180, v238
	v_and_b32_e32 v148, v181, v235
	v_and_b32_e32 v149, v181, v236
	v_and_b32_e32 v150, v181, v237
	v_and_b32_e32 v151, v181, v238
	v_mfma_scale_f32_16x16x128_f8f6f4 v[216:219], v[100:103], v[204:211], v[216:219], v240, v241 op_sel_hi:[0,0,0] cbsz:4
	v_and_b32_e32 v255, 0xffff0000, v229
	v_add_f32_e32 v252, v212, v252
	v_add_f32_e32 v253, v213, v253
	v_and_b32_e32 v204, v182, v235
	v_and_b32_e32 v205, v182, v236
	v_and_b32_e32 v206, v182, v237
	v_and_b32_e32 v207, v182, v238
	v_and_b32_e32 v208, v183, v235
	v_and_b32_e32 v209, v183, v236
	v_and_b32_e32 v210, v183, v237
	v_and_b32_e32 v211, v183, v238
	v_mfma_scale_f32_16x16x128_f8f6f4 v[216:219], v[104:107], v[144:151], v[216:219], v240, v241 op_sel_hi:[0,0,0] cbsz:4
	v_add_f32_e32 v254, v214, v254
	v_add_f32_e32 v255, v215, v255
	v_mul_f32_e32 v192, v252, v252
	v_and_b32_e32 v144, v184, v235
	v_and_b32_e32 v145, v184, v236
	v_and_b32_e32 v146, v184, v237
	v_and_b32_e32 v147, v184, v238
	v_and_b32_e32 v148, v185, v235
	v_and_b32_e32 v149, v185, v236
	v_and_b32_e32 v150, v185, v237
	v_and_b32_e32 v151, v185, v238
	v_mfma_scale_f32_16x16x128_f8f6f4 v[216:219], v[108:111], v[204:211], v[216:219], v240, v241 op_sel_hi:[0,0,0] cbsz:4
	v_mul_f32_e32 v193, v254, v254
	v_fmac_f32_e32 v192, v253, v253
	v_fmac_f32_e32 v193, v255, v255
	v_and_b32_e32 v204, v186, v235
	v_and_b32_e32 v205, v186, v236
	v_and_b32_e32 v206, v186, v237
	v_and_b32_e32 v207, v186, v238
	v_and_b32_e32 v208, v187, v235
	v_and_b32_e32 v209, v187, v236
	v_and_b32_e32 v210, v187, v237
	v_and_b32_e32 v211, v187, v238
	v_mfma_scale_f32_16x16x128_f8f6f4 v[216:219], v[112:115], v[144:151], v[216:219], v240, v241 op_sel_hi:[0,0,0] cbsz:4
	v_cvt_pk_bf16_f32 v250, v252, v253
	v_cvt_pk_bf16_f32 v251, v254, v255
	v_add_f32_e32 v192, v192, v193
	v_and_b32_e32 v144, v188, v235
	v_and_b32_e32 v145, v188, v236
	v_and_b32_e32 v146, v188, v237
	v_and_b32_e32 v147, v188, v238
	v_and_b32_e32 v148, v189, v235
	v_and_b32_e32 v149, v189, v236
	v_and_b32_e32 v150, v189, v237
	v_and_b32_e32 v151, v189, v238
	v_mfma_scale_f32_16x16x128_f8f6f4 v[216:219], v[116:119], v[204:211], v[216:219], v240, v241 op_sel_hi:[0,0,0] cbsz:4
	v_add_f32_e32 v220, v220, v192
	v_and_b32_e32 v204, v190, v235
	v_and_b32_e32 v205, v190, v236
	v_and_b32_e32 v206, v190, v237
	v_and_b32_e32 v207, v190, v238
	v_and_b32_e32 v208, v191, v235
	v_and_b32_e32 v209, v191, v236
	v_and_b32_e32 v210, v191, v237
	v_and_b32_e32 v211, v191, v238
	v_mfma_scale_f32_16x16x128_f8f6f4 v[216:219], v[120:123], v[144:151], v[216:219], v240, v241 op_sel_hi:[0,0,0] cbsz:4
	s_nop 0
	v_mfma_scale_f32_16x16x128_f8f6f4 v[216:219], v[124:127], v[204:211], v[216:219], v240, v241 op_sel_hi:[0,0,0] cbsz:4
	s_lshl_b32 s64, s0, 9
	s_add_u32 s64, s64, 0x0
	s_add_u32 s76, s28, s64
	s_addc_u32 s77, s29, 0
	global_store_dwordx2 v239, v[250:251], s[76:77]
	s_lshl_b32 s64, s0, 9
	s_add_u32 s64, s64, 0x2000
	s_add_u32 s70, s28, s64
	s_addc_u32 s71, s29, 0
	global_load_dwordx2 v[228:229], v239, s[70:71]
	s_waitcnt lgkmcnt(0)
	v_lshl_or_b32 v128, v128, 7, v232
	v_lshl_or_b32 v129, v129, 7, v232
	v_lshl_or_b32 v130, v130, 7, v232
	v_lshl_or_b32 v131, v131, 7, v232
	v_lshl_or_b32 v132, v132, 7, v232
	v_lshl_or_b32 v133, v133, 7, v232
	v_lshl_or_b32 v134, v134, 7, v232
	v_lshl_or_b32 v135, v135, 7, v232
	v_lshl_or_b32 v136, v136, 7, v232
	v_lshl_or_b32 v137, v137, 7, v232
	v_lshl_or_b32 v138, v138, 7, v232
	v_lshl_or_b32 v139, v139, 7, v232
	v_lshl_or_b32 v140, v140, 7, v232
	v_lshl_or_b32 v141, v141, 7, v232
	v_lshl_or_b32 v142, v142, 7, v232
	v_lshl_or_b32 v143, v143, 7, v232
	buffer_load_dwordx2 v[96:97], v128, s[20:23], s1 offen
	buffer_load_dwordx2 v[98:99], v129, s[20:23], s1 offen
	buffer_load_dwordx2 v[100:101], v130, s[20:23], s1 offen
	buffer_load_dwordx2 v[102:103], v131, s[20:23], s1 offen
	buffer_load_dwordx2 v[104:105], v132, s[20:23], s1 offen
	buffer_load_dwordx2 v[106:107], v133, s[20:23], s1 offen
	buffer_load_dwordx2 v[108:109], v134, s[20:23], s1 offen
	buffer_load_dwordx2 v[110:111], v135, s[20:23], s1 offen
	buffer_load_dwordx2 v[112:113], v136, s[20:23], s1 offen
	buffer_load_dwordx2 v[114:115], v137, s[20:23], s1 offen
	buffer_load_dwordx2 v[116:117], v138, s[20:23], s1 offen
	buffer_load_dwordx2 v[118:119], v139, s[20:23], s1 offen
	buffer_load_dwordx2 v[120:121], v140, s[20:23], s1 offen
	buffer_load_dwordx2 v[122:123], v141, s[20:23], s1 offen
	buffer_load_dwordx2 v[124:125], v142, s[20:23], s1 offen
	buffer_load_dwordx2 v[126:127], v143, s[20:23], s1 offen
	ds_read_b64 v[128:129], v233 offset:2048
	ds_read_b64 v[130:131], v233 offset:2080
	ds_read_b64 v[132:133], v233 offset:2112
	ds_read_b64 v[134:135], v233 offset:2144
	ds_read_b64 v[136:137], v233 offset:2176
	ds_read_b64 v[138:139], v233 offset:2208
	ds_read_b64 v[140:141], v233 offset:2240
	ds_read_b64 v[142:143], v233 offset:2272
	ds_read_b64 v[176:177], v234 offset:1280
	ds_read_b64 v[178:179], v234 offset:1312
	ds_read_b64 v[180:181], v234 offset:1344
	ds_read_b64 v[182:183], v234 offset:1376
	ds_read_b64 v[184:185], v234 offset:1408
	ds_read_b64 v[186:187], v234 offset:1440
	ds_read_b64 v[188:189], v234 offset:1472
	ds_read_b64 v[190:191], v234 offset:1504
	s_waitcnt vmcnt(52)
	v_and_b32_e32 v144, v160, v235
	v_and_b32_e32 v145, v160, v236
	v_and_b32_e32 v146, v160, v237
	v_and_b32_e32 v147, v160, v238
	v_and_b32_e32 v148, v161, v235
	v_and_b32_e32 v149, v161, v236
	v_and_b32_e32 v150, v161, v237
	v_and_b32_e32 v151, v161, v238
	v_and_b32_e32 v204, v162, v235
	v_and_b32_e32 v205, v162, v236
	v_and_b32_e32 v206, v162, v237
	v_and_b32_e32 v207, v162, v238
	v_and_b32_e32 v208, v163, v235
	v_and_b32_e32 v209, v163, v236
	v_and_b32_e32 v210, v163, v237
	v_and_b32_e32 v211, v163, v238
	v_mfma_scale_f32_16x16x128_f8f6f4 v[212:215], v[0:3], v[144:151], 0, v240, v241 op_sel_hi:[0,0,0] cbsz:4
	v_and_b32_e32 v144, v164, v235
	v_and_b32_e32 v145, v164, v236
	v_and_b32_e32 v146, v164, v237
	v_and_b32_e32 v147, v164, v238
	v_and_b32_e32 v148, v165, v235
	v_and_b32_e32 v149, v165, v236
	v_and_b32_e32 v150, v165, v237
	v_and_b32_e32 v151, v165, v238
	v_mfma_scale_f32_16x16x128_f8f6f4 v[212:215], v[4:7], v[204:211], v[212:215], v240, v241 op_sel_hi:[0,0,0] cbsz:4
	v_and_b32_e32 v204, v166, v235
	v_and_b32_e32 v205, v166, v236
	v_and_b32_e32 v206, v166, v237
	v_and_b32_e32 v207, v166, v238
	v_and_b32_e32 v208, v167, v235
	v_and_b32_e32 v209, v167, v236
	v_and_b32_e32 v210, v167, v237
	v_and_b32_e32 v211, v167, v238
	v_mfma_scale_f32_16x16x128_f8f6f4 v[212:215], v[8:11], v[144:151], v[212:215], v240, v241 op_sel_hi:[0,0,0] cbsz:4
	v_and_b32_e32 v144, v168, v235
	v_and_b32_e32 v145, v168, v236
	v_and_b32_e32 v146, v168, v237
	v_and_b32_e32 v147, v168, v238
	v_and_b32_e32 v148, v169, v235
	v_and_b32_e32 v149, v169, v236
	v_and_b32_e32 v150, v169, v237
	v_and_b32_e32 v151, v169, v238
	v_mfma_scale_f32_16x16x128_f8f6f4 v[212:215], v[12:15], v[204:211], v[212:215], v240, v241 op_sel_hi:[0,0,0] cbsz:4
	v_and_b32_e32 v204, v170, v235
	v_and_b32_e32 v205, v170, v236
	v_and_b32_e32 v206, v170, v237
	v_and_b32_e32 v207, v170, v238
	v_and_b32_e32 v208, v171, v235
	v_and_b32_e32 v209, v171, v236
	v_and_b32_e32 v210, v171, v237
	v_and_b32_e32 v211, v171, v238
	v_mfma_scale_f32_16x16x128_f8f6f4 v[212:215], v[16:19], v[144:151], v[212:215], v240, v241 op_sel_hi:[0,0,0] cbsz:4
	v_and_b32_e32 v144, v172, v235
	v_and_b32_e32 v145, v172, v236
	v_and_b32_e32 v146, v172, v237
	v_and_b32_e32 v147, v172, v238
	v_and_b32_e32 v148, v173, v235
	v_and_b32_e32 v149, v173, v236
	v_and_b32_e32 v150, v173, v237
	v_and_b32_e32 v151, v173, v238
	v_mfma_scale_f32_16x16x128_f8f6f4 v[212:215], v[20:23], v[204:211], v[212:215], v240, v241 op_sel_hi:[0,0,0] cbsz:4
	v_and_b32_e32 v204, v174, v235
	v_and_b32_e32 v205, v174, v236
	v_and_b32_e32 v206, v174, v237
	v_and_b32_e32 v207, v174, v238
	v_and_b32_e32 v208, v175, v235
	v_and_b32_e32 v209, v175, v236
	v_and_b32_e32 v210, v175, v237
	v_and_b32_e32 v211, v175, v238
	v_mfma_scale_f32_16x16x128_f8f6f4 v[212:215], v[24:27], v[144:151], v[212:215], v240, v241 op_sel_hi:[0,0,0] cbsz:4
	s_nop 0
	v_mfma_scale_f32_16x16x128_f8f6f4 v[212:215], v[28:31], v[204:211], v[212:215], v240, v241 op_sel_hi:[0,0,0] cbsz:4
	s_waitcnt lgkmcnt(0)
	v_lshl_or_b32 v128, v128, 7, v232
	v_lshl_or_b32 v129, v129, 7, v232
	v_lshl_or_b32 v130, v130, 7, v232
	v_lshl_or_b32 v131, v131, 7, v232
	v_lshl_or_b32 v132, v132, 7, v232
	v_lshl_or_b32 v133, v133, 7, v232
	v_lshl_or_b32 v134, v134, 7, v232
	v_lshl_or_b32 v135, v135, 7, v232
	v_lshl_or_b32 v136, v136, 7, v232
	v_lshl_or_b32 v137, v137, 7, v232
	v_lshl_or_b32 v138, v138, 7, v232
	v_lshl_or_b32 v139, v139, 7, v232
	v_lshl_or_b32 v140, v140, 7, v232
	v_lshl_or_b32 v141, v141, 7, v232
	v_lshl_or_b32 v142, v142, 7, v232
	v_lshl_or_b32 v143, v143, 7, v232
	buffer_load_dwordx2 v[0:1], v128, s[20:23], s1 offen
	buffer_load_dwordx2 v[2:3], v129, s[20:23], s1 offen
	buffer_load_dwordx2 v[4:5], v130, s[20:23], s1 offen
	buffer_load_dwordx2 v[6:7], v131, s[20:23], s1 offen
	buffer_load_dwordx2 v[8:9], v132, s[20:23], s1 offen
	buffer_load_dwordx2 v[10:11], v133, s[20:23], s1 offen
	buffer_load_dwordx2 v[12:13], v134, s[20:23], s1 offen
	buffer_load_dwordx2 v[14:15], v135, s[20:23], s1 offen
	buffer_load_dwordx2 v[16:17], v136, s[20:23], s1 offen
	buffer_load_dwordx2 v[18:19], v137, s[20:23], s1 offen
	buffer_load_dwordx2 v[20:21], v138, s[20:23], s1 offen
	buffer_load_dwordx2 v[22:23], v139, s[20:23], s1 offen
	buffer_load_dwordx2 v[24:25], v140, s[20:23], s1 offen
	buffer_load_dwordx2 v[26:27], v141, s[20:23], s1 offen
	buffer_load_dwordx2 v[28:29], v142, s[20:23], s1 offen
	buffer_load_dwordx2 v[30:31], v143, s[20:23], s1 offen
	ds_read_b64 v[128:129], v233 offset:2304
	ds_read_b64 v[130:131], v233 offset:2336
	ds_read_b64 v[132:133], v233 offset:2368
	ds_read_b64 v[134:135], v233 offset:2400
	ds_read_b64 v[136:137], v233 offset:2432
	ds_read_b64 v[138:139], v233 offset:2464
	ds_read_b64 v[140:141], v233 offset:2496
	ds_read_b64 v[142:143], v233 offset:2528
	ds_read_b64 v[160:161], v234 offset:1536
	ds_read_b64 v[162:163], v234 offset:1568
	ds_read_b64 v[164:165], v234 offset:1600
	ds_read_b64 v[166:167], v234 offset:1632
	ds_read_b64 v[168:169], v234 offset:1664
	ds_read_b64 v[170:171], v234 offset:1696
	ds_read_b64 v[172:173], v234 offset:1728
	ds_read_b64 v[174:175], v234 offset:1760
	s_waitcnt vmcnt(50)
	v_and_b32_e32 v144, v176, v235
	v_and_b32_e32 v145, v176, v236
	v_and_b32_e32 v146, v176, v237
	v_and_b32_e32 v147, v176, v238
	v_and_b32_e32 v148, v177, v235
	v_and_b32_e32 v149, v177, v236
	v_and_b32_e32 v150, v177, v237
	v_and_b32_e32 v151, v177, v238
	v_and_b32_e32 v204, v178, v235
	v_and_b32_e32 v205, v178, v236
	v_and_b32_e32 v206, v178, v237
	v_and_b32_e32 v207, v178, v238
	v_and_b32_e32 v208, v179, v235
	v_and_b32_e32 v209, v179, v236
	v_and_b32_e32 v210, v179, v237
	v_and_b32_e32 v211, v179, v238
	v_mfma_scale_f32_16x16x128_f8f6f4 v[212:215], v[32:35], v[144:151], v[212:215], v240, v241 op_sel_hi:[0,0,0] cbsz:4
	v_lshlrev_b32_e32 v252, 16, v230
	v_and_b32_e32 v253, 0xffff0000, v230
	v_lshlrev_b32_e32 v254, 16, v231
	v_and_b32_e32 v144, v180, v235
	v_and_b32_e32 v145, v180, v236
	v_and_b32_e32 v146, v180, v237
	v_and_b32_e32 v147, v180, v238
	v_and_b32_e32 v148, v181, v235
	v_and_b32_e32 v149, v181, v236
	v_and_b32_e32 v150, v181, v237
	v_and_b32_e32 v151, v181, v238
	v_mfma_scale_f32_16x16x128_f8f6f4 v[212:215], v[36:39], v[204:211], v[212:215], v240, v241 op_sel_hi:[0,0,0] cbsz:4
	v_and_b32_e32 v255, 0xffff0000, v231
	v_add_f32_e32 v252, v216, v252
	v_add_f32_e32 v253, v217, v253
	v_and_b32_e32 v204, v182, v235
	v_and_b32_e32 v205, v182, v236
	v_and_b32_e32 v206, v182, v237
	v_and_b32_e32 v207, v182, v238
	v_and_b32_e32 v208, v183, v235
	v_and_b32_e32 v209, v183, v236
	v_and_b32_e32 v210, v183, v237
	v_and_b32_e32 v211, v183, v238
	v_mfma_scale_f32_16x16x128_f8f6f4 v[212:215], v[40:43], v[144:151], v[212:215], v240, v241 op_sel_hi:[0,0,0] cbsz:4
	v_add_f32_e32 v254, v218, v254
	v_add_f32_e32 v255, v219, v255
	v_mul_f32_e32 v192, v252, v252
	v_and_b32_e32 v144, v184, v235
	v_and_b32_e32 v145, v184, v236
	v_and_b32_e32 v146, v184, v237
	v_and_b32_e32 v147, v184, v238
	v_and_b32_e32 v148, v185, v235
	v_and_b32_e32 v149, v185, v236
	v_and_b32_e32 v150, v185, v237
	v_and_b32_e32 v151, v185, v238
	v_mfma_scale_f32_16x16x128_f8f6f4 v[212:215], v[44:47], v[204:211], v[212:215], v240, v241 op_sel_hi:[0,0,0] cbsz:4
	v_mul_f32_e32 v193, v254, v254
	v_fmac_f32_e32 v192, v253, v253
	v_fmac_f32_e32 v193, v255, v255
	v_and_b32_e32 v204, v186, v235
	v_and_b32_e32 v205, v186, v236
	v_and_b32_e32 v206, v186, v237
	v_and_b32_e32 v207, v186, v238
	v_and_b32_e32 v208, v187, v235
	v_and_b32_e32 v209, v187, v236
	v_and_b32_e32 v210, v187, v237
	v_and_b32_e32 v211, v187, v238
	v_mfma_scale_f32_16x16x128_f8f6f4 v[212:215], v[48:51], v[144:151], v[212:215], v240, v241 op_sel_hi:[0,0,0] cbsz:4
	v_cvt_pk_bf16_f32 v250, v252, v253
	v_cvt_pk_bf16_f32 v251, v254, v255
	v_add_f32_e32 v192, v192, v193
	v_and_b32_e32 v144, v188, v235
	v_and_b32_e32 v145, v188, v236
	v_and_b32_e32 v146, v188, v237
	v_and_b32_e32 v147, v188, v238
	v_and_b32_e32 v148, v189, v235
	v_and_b32_e32 v149, v189, v236
	v_and_b32_e32 v150, v189, v237
	v_and_b32_e32 v151, v189, v238
	v_mfma_scale_f32_16x16x128_f8f6f4 v[212:215], v[52:55], v[204:211], v[212:215], v240, v241 op_sel_hi:[0,0,0] cbsz:4
	v_add_f32_e32 v221, v221, v192
	v_and_b32_e32 v204, v190, v235
	v_and_b32_e32 v205, v190, v236
	v_and_b32_e32 v206, v190, v237
	v_and_b32_e32 v207, v190, v238
	v_and_b32_e32 v208, v191, v235
	v_and_b32_e32 v209, v191, v236
	v_and_b32_e32 v210, v191, v237
	v_and_b32_e32 v211, v191, v238
	v_mfma_scale_f32_16x16x128_f8f6f4 v[212:215], v[56:59], v[144:151], v[212:215], v240, v241 op_sel_hi:[0,0,0] cbsz:4
	s_nop 0
	v_mfma_scale_f32_16x16x128_f8f6f4 v[212:215], v[60:63], v[204:211], v[212:215], v240, v241 op_sel_hi:[0,0,0] cbsz:4
	s_lshl_b32 s64, s0, 9
	s_add_u32 s64, s64, 0x1000
	s_add_u32 s76, s28, s64
	s_addc_u32 s77, s29, 0
	global_store_dwordx2 v239, v[250:251], s[76:77]
	s_lshl_b32 s64, s0, 9
	s_add_u32 s64, s64, 0x3000
	s_add_u32 s70, s28, s64
	s_addc_u32 s71, s29, 0
	global_load_dwordx2 v[230:231], v239, s[70:71]
	s_waitcnt lgkmcnt(0)
	v_lshl_or_b32 v128, v128, 7, v232
	v_lshl_or_b32 v129, v129, 7, v232
	v_lshl_or_b32 v130, v130, 7, v232
	v_lshl_or_b32 v131, v131, 7, v232
	v_lshl_or_b32 v132, v132, 7, v232
	v_lshl_or_b32 v133, v133, 7, v232
	v_lshl_or_b32 v134, v134, 7, v232
	v_lshl_or_b32 v135, v135, 7, v232
	v_lshl_or_b32 v136, v136, 7, v232
	v_lshl_or_b32 v137, v137, 7, v232
	v_lshl_or_b32 v138, v138, 7, v232
	v_lshl_or_b32 v139, v139, 7, v232
	v_lshl_or_b32 v140, v140, 7, v232
	v_lshl_or_b32 v141, v141, 7, v232
	v_lshl_or_b32 v142, v142, 7, v232
	v_lshl_or_b32 v143, v143, 7, v232
	buffer_load_dwordx2 v[32:33], v128, s[20:23], s1 offen
	buffer_load_dwordx2 v[34:35], v129, s[20:23], s1 offen
	buffer_load_dwordx2 v[36:37], v130, s[20:23], s1 offen
	buffer_load_dwordx2 v[38:39], v131, s[20:23], s1 offen
	buffer_load_dwordx2 v[40:41], v132, s[20:23], s1 offen
	buffer_load_dwordx2 v[42:43], v133, s[20:23], s1 offen
	buffer_load_dwordx2 v[44:45], v134, s[20:23], s1 offen
	buffer_load_dwordx2 v[46:47], v135, s[20:23], s1 offen
	buffer_load_dwordx2 v[48:49], v136, s[20:23], s1 offen
	buffer_load_dwordx2 v[50:51], v137, s[20:23], s1 offen
	buffer_load_dwordx2 v[52:53], v138, s[20:23], s1 offen
	buffer_load_dwordx2 v[54:55], v139, s[20:23], s1 offen
	buffer_load_dwordx2 v[56:57], v140, s[20:23], s1 offen
	buffer_load_dwordx2 v[58:59], v141, s[20:23], s1 offen
	buffer_load_dwordx2 v[60:61], v142, s[20:23], s1 offen
	buffer_load_dwordx2 v[62:63], v143, s[20:23], s1 offen
	ds_read_b64 v[128:129], v233 offset:2560
	ds_read_b64 v[130:131], v233 offset:2592
	ds_read_b64 v[132:133], v233 offset:2624
	ds_read_b64 v[134:135], v233 offset:2656
	ds_read_b64 v[136:137], v233 offset:2688
	ds_read_b64 v[138:139], v233 offset:2720
	ds_read_b64 v[140:141], v233 offset:2752
	ds_read_b64 v[142:143], v233 offset:2784
	ds_read_b64 v[176:177], v234 offset:1792
	ds_read_b64 v[178:179], v234 offset:1824
	ds_read_b64 v[180:181], v234 offset:1856
	ds_read_b64 v[182:183], v234 offset:1888
	ds_read_b64 v[184:185], v234 offset:1920
	ds_read_b64 v[186:187], v234 offset:1952
	ds_read_b64 v[188:189], v234 offset:1984
	ds_read_b64 v[190:191], v234 offset:2016
	s_waitcnt vmcnt(52)
	v_and_b32_e32 v144, v160, v235
	v_and_b32_e32 v145, v160, v236
	v_and_b32_e32 v146, v160, v237
	v_and_b32_e32 v147, v160, v238
	v_and_b32_e32 v148, v161, v235
	v_and_b32_e32 v149, v161, v236
	v_and_b32_e32 v150, v161, v237
	v_and_b32_e32 v151, v161, v238
	v_and_b32_e32 v204, v162, v235
	v_and_b32_e32 v205, v162, v236
	v_and_b32_e32 v206, v162, v237
	v_and_b32_e32 v207, v162, v238
	v_and_b32_e32 v208, v163, v235
	v_and_b32_e32 v209, v163, v236
	v_and_b32_e32 v210, v163, v237
	v_and_b32_e32 v211, v163, v238
	v_mfma_scale_f32_16x16x128_f8f6f4 v[216:219], v[64:67], v[144:151], 0, v240, v241 op_sel_hi:[0,0,0] cbsz:4
	v_and_b32_e32 v144, v164, v235
	v_and_b32_e32 v145, v164, v236
	v_and_b32_e32 v146, v164, v237
	v_and_b32_e32 v147, v164, v238
	v_and_b32_e32 v148, v165, v235
	v_and_b32_e32 v149, v165, v236
	v_and_b32_e32 v150, v165, v237
	v_and_b32_e32 v151, v165, v238
	v_mfma_scale_f32_16x16x128_f8f6f4 v[216:219], v[68:71], v[204:211], v[216:219], v240, v241 op_sel_hi:[0,0,0] cbsz:4
	v_and_b32_e32 v204, v166, v235
	v_and_b32_e32 v205, v166, v236
	v_and_b32_e32 v206, v166, v237
	v_and_b32_e32 v207, v166, v238
	v_and_b32_e32 v208, v167, v235
	v_and_b32_e32 v209, v167, v236
	v_and_b32_e32 v210, v167, v237
	v_and_b32_e32 v211, v167, v238
	v_mfma_scale_f32_16x16x128_f8f6f4 v[216:219], v[72:75], v[144:151], v[216:219], v240, v241 op_sel_hi:[0,0,0] cbsz:4
	v_and_b32_e32 v144, v168, v235
	v_and_b32_e32 v145, v168, v236
	v_and_b32_e32 v146, v168, v237
	v_and_b32_e32 v147, v168, v238
	v_and_b32_e32 v148, v169, v235
	v_and_b32_e32 v149, v169, v236
	v_and_b32_e32 v150, v169, v237
	v_and_b32_e32 v151, v169, v238
	v_mfma_scale_f32_16x16x128_f8f6f4 v[216:219], v[76:79], v[204:211], v[216:219], v240, v241 op_sel_hi:[0,0,0] cbsz:4
	v_and_b32_e32 v204, v170, v235
	v_and_b32_e32 v205, v170, v236
	v_and_b32_e32 v206, v170, v237
	v_and_b32_e32 v207, v170, v238
	v_and_b32_e32 v208, v171, v235
	v_and_b32_e32 v209, v171, v236
	v_and_b32_e32 v210, v171, v237
	v_and_b32_e32 v211, v171, v238
	v_mfma_scale_f32_16x16x128_f8f6f4 v[216:219], v[80:83], v[144:151], v[216:219], v240, v241 op_sel_hi:[0,0,0] cbsz:4
	v_and_b32_e32 v144, v172, v235
	v_and_b32_e32 v145, v172, v236
	v_and_b32_e32 v146, v172, v237
	v_and_b32_e32 v147, v172, v238
	v_and_b32_e32 v148, v173, v235
	v_and_b32_e32 v149, v173, v236
	v_and_b32_e32 v150, v173, v237
	v_and_b32_e32 v151, v173, v238
	v_mfma_scale_f32_16x16x128_f8f6f4 v[216:219], v[84:87], v[204:211], v[216:219], v240, v241 op_sel_hi:[0,0,0] cbsz:4
	v_and_b32_e32 v204, v174, v235
	v_and_b32_e32 v205, v174, v236
	v_and_b32_e32 v206, v174, v237
	v_and_b32_e32 v207, v174, v238
	v_and_b32_e32 v208, v175, v235
	v_and_b32_e32 v209, v175, v236
	v_and_b32_e32 v210, v175, v237
	v_and_b32_e32 v211, v175, v238
	v_mfma_scale_f32_16x16x128_f8f6f4 v[216:219], v[88:91], v[144:151], v[216:219], v240, v241 op_sel_hi:[0,0,0] cbsz:4
	s_nop 0
	v_mfma_scale_f32_16x16x128_f8f6f4 v[216:219], v[92:95], v[204:211], v[216:219], v240, v241 op_sel_hi:[0,0,0] cbsz:4
	s_waitcnt lgkmcnt(0)
	v_lshl_or_b32 v128, v128, 7, v232
	v_lshl_or_b32 v129, v129, 7, v232
	v_lshl_or_b32 v130, v130, 7, v232
	v_lshl_or_b32 v131, v131, 7, v232
	v_lshl_or_b32 v132, v132, 7, v232
	v_lshl_or_b32 v133, v133, 7, v232
	v_lshl_or_b32 v134, v134, 7, v232
	v_lshl_or_b32 v135, v135, 7, v232
	v_lshl_or_b32 v136, v136, 7, v232
	v_lshl_or_b32 v137, v137, 7, v232
	v_lshl_or_b32 v138, v138, 7, v232
	v_lshl_or_b32 v139, v139, 7, v232
	v_lshl_or_b32 v140, v140, 7, v232
	v_lshl_or_b32 v141, v141, 7, v232
	v_lshl_or_b32 v142, v142, 7, v232
	v_lshl_or_b32 v143, v143, 7, v232
	buffer_load_dwordx2 v[64:65], v128, s[20:23], s1 offen
	buffer_load_dwordx2 v[66:67], v129, s[20:23], s1 offen
	buffer_load_dwordx2 v[68:69], v130, s[20:23], s1 offen
	buffer_load_dwordx2 v[70:71], v131, s[20:23], s1 offen
	buffer_load_dwordx2 v[72:73], v132, s[20:23], s1 offen
	buffer_load_dwordx2 v[74:75], v133, s[20:23], s1 offen
	buffer_load_dwordx2 v[76:77], v134, s[20:23], s1 offen
	buffer_load_dwordx2 v[78:79], v135, s[20:23], s1 offen
	buffer_load_dwordx2 v[80:81], v136, s[20:23], s1 offen
	buffer_load_dwordx2 v[82:83], v137, s[20:23], s1 offen
	buffer_load_dwordx2 v[84:85], v138, s[20:23], s1 offen
	buffer_load_dwordx2 v[86:87], v139, s[20:23], s1 offen
	buffer_load_dwordx2 v[88:89], v140, s[20:23], s1 offen
	buffer_load_dwordx2 v[90:91], v141, s[20:23], s1 offen
	buffer_load_dwordx2 v[92:93], v142, s[20:23], s1 offen
	buffer_load_dwordx2 v[94:95], v143, s[20:23], s1 offen
	ds_read_b64 v[128:129], v233 offset:2816
	ds_read_b64 v[130:131], v233 offset:2848
	ds_read_b64 v[132:133], v233 offset:2880
	ds_read_b64 v[134:135], v233 offset:2912
	ds_read_b64 v[136:137], v233 offset:2944
	ds_read_b64 v[138:139], v233 offset:2976
	ds_read_b64 v[140:141], v233 offset:3008
	ds_read_b64 v[142:143], v233 offset:3040
	ds_read_b64 v[160:161], v234 offset:2048
	ds_read_b64 v[162:163], v234 offset:2080
	ds_read_b64 v[164:165], v234 offset:2112
	ds_read_b64 v[166:167], v234 offset:2144
	ds_read_b64 v[168:169], v234 offset:2176
	ds_read_b64 v[170:171], v234 offset:2208
	ds_read_b64 v[172:173], v234 offset:2240
	ds_read_b64 v[174:175], v234 offset:2272
	s_waitcnt vmcnt(50)
	v_and_b32_e32 v144, v176, v235
	v_and_b32_e32 v145, v176, v236
	v_and_b32_e32 v146, v176, v237
	v_and_b32_e32 v147, v176, v238
	v_and_b32_e32 v148, v177, v235
	v_and_b32_e32 v149, v177, v236
	v_and_b32_e32 v150, v177, v237
	v_and_b32_e32 v151, v177, v238
	v_and_b32_e32 v204, v178, v235
	v_and_b32_e32 v205, v178, v236
	v_and_b32_e32 v206, v178, v237
	v_and_b32_e32 v207, v178, v238
	v_and_b32_e32 v208, v179, v235
	v_and_b32_e32 v209, v179, v236
	v_and_b32_e32 v210, v179, v237
	v_and_b32_e32 v211, v179, v238
	v_mfma_scale_f32_16x16x128_f8f6f4 v[216:219], v[96:99], v[144:151], v[216:219], v240, v241 op_sel_hi:[0,0,0] cbsz:4
	v_lshlrev_b32_e32 v252, 16, v228
	v_and_b32_e32 v253, 0xffff0000, v228
	v_lshlrev_b32_e32 v254, 16, v229
	v_and_b32_e32 v144, v180, v235
	v_and_b32_e32 v145, v180, v236
	v_and_b32_e32 v146, v180, v237
	v_and_b32_e32 v147, v180, v238
	v_and_b32_e32 v148, v181, v235
	v_and_b32_e32 v149, v181, v236
	v_and_b32_e32 v150, v181, v237
	v_and_b32_e32 v151, v181, v238
	v_mfma_scale_f32_16x16x128_f8f6f4 v[216:219], v[100:103], v[204:211], v[216:219], v240, v241 op_sel_hi:[0,0,0] cbsz:4
	v_and_b32_e32 v255, 0xffff0000, v229
	v_add_f32_e32 v252, v212, v252
	v_add_f32_e32 v253, v213, v253
	v_and_b32_e32 v204, v182, v235
	v_and_b32_e32 v205, v182, v236
	v_and_b32_e32 v206, v182, v237
	v_and_b32_e32 v207, v182, v238
	v_and_b32_e32 v208, v183, v235
	v_and_b32_e32 v209, v183, v236
	v_and_b32_e32 v210, v183, v237
	v_and_b32_e32 v211, v183, v238
	v_mfma_scale_f32_16x16x128_f8f6f4 v[216:219], v[104:107], v[144:151], v[216:219], v240, v241 op_sel_hi:[0,0,0] cbsz:4
	v_add_f32_e32 v254, v214, v254
	v_add_f32_e32 v255, v215, v255
	v_mul_f32_e32 v192, v252, v252
	v_and_b32_e32 v144, v184, v235
	v_and_b32_e32 v145, v184, v236
	v_and_b32_e32 v146, v184, v237
	v_and_b32_e32 v147, v184, v238
	v_and_b32_e32 v148, v185, v235
	v_and_b32_e32 v149, v185, v236
	v_and_b32_e32 v150, v185, v237
	v_and_b32_e32 v151, v185, v238
	v_mfma_scale_f32_16x16x128_f8f6f4 v[216:219], v[108:111], v[204:211], v[216:219], v240, v241 op_sel_hi:[0,0,0] cbsz:4
	v_mul_f32_e32 v193, v254, v254
	v_fmac_f32_e32 v192, v253, v253
	v_fmac_f32_e32 v193, v255, v255
	v_and_b32_e32 v204, v186, v235
	v_and_b32_e32 v205, v186, v236
	v_and_b32_e32 v206, v186, v237
	v_and_b32_e32 v207, v186, v238
	v_and_b32_e32 v208, v187, v235
	v_and_b32_e32 v209, v187, v236
	v_and_b32_e32 v210, v187, v237
	v_and_b32_e32 v211, v187, v238
	v_mfma_scale_f32_16x16x128_f8f6f4 v[216:219], v[112:115], v[144:151], v[216:219], v240, v241 op_sel_hi:[0,0,0] cbsz:4
	v_cvt_pk_bf16_f32 v250, v252, v253
	v_cvt_pk_bf16_f32 v251, v254, v255
	v_add_f32_e32 v192, v192, v193
	v_and_b32_e32 v144, v188, v235
	v_and_b32_e32 v145, v188, v236
	v_and_b32_e32 v146, v188, v237
	v_and_b32_e32 v147, v188, v238
	v_and_b32_e32 v148, v189, v235
	v_and_b32_e32 v149, v189, v236
	v_and_b32_e32 v150, v189, v237
	v_and_b32_e32 v151, v189, v238
	v_mfma_scale_f32_16x16x128_f8f6f4 v[216:219], v[116:119], v[204:211], v[216:219], v240, v241 op_sel_hi:[0,0,0] cbsz:4
	v_add_f32_e32 v222, v222, v192
	v_and_b32_e32 v204, v190, v235
	v_and_b32_e32 v205, v190, v236
	v_and_b32_e32 v206, v190, v237
	v_and_b32_e32 v207, v190, v238
	v_and_b32_e32 v208, v191, v235
	v_and_b32_e32 v209, v191, v236
	v_and_b32_e32 v210, v191, v237
	v_and_b32_e32 v211, v191, v238
	v_mfma_scale_f32_16x16x128_f8f6f4 v[216:219], v[120:123], v[144:151], v[216:219], v240, v241 op_sel_hi:[0,0,0] cbsz:4
	s_nop 0
	v_mfma_scale_f32_16x16x128_f8f6f4 v[216:219], v[124:127], v[204:211], v[216:219], v240, v241 op_sel_hi:[0,0,0] cbsz:4
	s_lshl_b32 s64, s0, 9
	s_add_u32 s64, s64, 0x2000
	s_add_u32 s76, s28, s64
	s_addc_u32 s77, s29, 0
	global_store_dwordx2 v239, v[250:251], s[76:77]
	s_lshl_b32 s64, s0, 9
	s_add_u32 s64, s64, 0x4000
	s_add_u32 s70, s28, s64
	s_addc_u32 s71, s29, 0
	global_load_dwordx2 v[228:229], v239, s[70:71]
	s_waitcnt lgkmcnt(0)
	v_lshl_or_b32 v128, v128, 7, v232
	v_lshl_or_b32 v129, v129, 7, v232
	v_lshl_or_b32 v130, v130, 7, v232
	v_lshl_or_b32 v131, v131, 7, v232
	v_lshl_or_b32 v132, v132, 7, v232
	v_lshl_or_b32 v133, v133, 7, v232
	v_lshl_or_b32 v134, v134, 7, v232
	v_lshl_or_b32 v135, v135, 7, v232
	v_lshl_or_b32 v136, v136, 7, v232
	v_lshl_or_b32 v137, v137, 7, v232
	v_lshl_or_b32 v138, v138, 7, v232
	v_lshl_or_b32 v139, v139, 7, v232
	v_lshl_or_b32 v140, v140, 7, v232
	v_lshl_or_b32 v141, v141, 7, v232
	v_lshl_or_b32 v142, v142, 7, v232
	v_lshl_or_b32 v143, v143, 7, v232
	buffer_load_dwordx2 v[96:97], v128, s[20:23], s1 offen
	buffer_load_dwordx2 v[98:99], v129, s[20:23], s1 offen
	buffer_load_dwordx2 v[100:101], v130, s[20:23], s1 offen
	buffer_load_dwordx2 v[102:103], v131, s[20:23], s1 offen
	buffer_load_dwordx2 v[104:105], v132, s[20:23], s1 offen
	buffer_load_dwordx2 v[106:107], v133, s[20:23], s1 offen
	buffer_load_dwordx2 v[108:109], v134, s[20:23], s1 offen
	buffer_load_dwordx2 v[110:111], v135, s[20:23], s1 offen
	buffer_load_dwordx2 v[112:113], v136, s[20:23], s1 offen
	buffer_load_dwordx2 v[114:115], v137, s[20:23], s1 offen
	buffer_load_dwordx2 v[116:117], v138, s[20:23], s1 offen
	buffer_load_dwordx2 v[118:119], v139, s[20:23], s1 offen
	buffer_load_dwordx2 v[120:121], v140, s[20:23], s1 offen
	buffer_load_dwordx2 v[122:123], v141, s[20:23], s1 offen
	buffer_load_dwordx2 v[124:125], v142, s[20:23], s1 offen
	buffer_load_dwordx2 v[126:127], v143, s[20:23], s1 offen
	ds_read_b64 v[128:129], v233 offset:3072
	ds_read_b64 v[130:131], v233 offset:3104
	ds_read_b64 v[132:133], v233 offset:3136
	ds_read_b64 v[134:135], v233 offset:3168
	ds_read_b64 v[136:137], v233 offset:3200
	ds_read_b64 v[138:139], v233 offset:3232
	ds_read_b64 v[140:141], v233 offset:3264
	ds_read_b64 v[142:143], v233 offset:3296
	ds_read_b64 v[176:177], v234 offset:2304
	ds_read_b64 v[178:179], v234 offset:2336
	ds_read_b64 v[180:181], v234 offset:2368
	ds_read_b64 v[182:183], v234 offset:2400
	ds_read_b64 v[184:185], v234 offset:2432
	ds_read_b64 v[186:187], v234 offset:2464
	ds_read_b64 v[188:189], v234 offset:2496
	ds_read_b64 v[190:191], v234 offset:2528
	s_waitcnt vmcnt(52)
	v_and_b32_e32 v144, v160, v235
	v_and_b32_e32 v145, v160, v236
	v_and_b32_e32 v146, v160, v237
	v_and_b32_e32 v147, v160, v238
	v_and_b32_e32 v148, v161, v235
	v_and_b32_e32 v149, v161, v236
	v_and_b32_e32 v150, v161, v237
	v_and_b32_e32 v151, v161, v238
	v_and_b32_e32 v204, v162, v235
	v_and_b32_e32 v205, v162, v236
	v_and_b32_e32 v206, v162, v237
	v_and_b32_e32 v207, v162, v238
	v_and_b32_e32 v208, v163, v235
	v_and_b32_e32 v209, v163, v236
	v_and_b32_e32 v210, v163, v237
	v_and_b32_e32 v211, v163, v238
	v_mfma_scale_f32_16x16x128_f8f6f4 v[212:215], v[0:3], v[144:151], 0, v240, v241 op_sel_hi:[0,0,0] cbsz:4
	v_and_b32_e32 v144, v164, v235
	v_and_b32_e32 v145, v164, v236
	v_and_b32_e32 v146, v164, v237
	v_and_b32_e32 v147, v164, v238
	v_and_b32_e32 v148, v165, v235
	v_and_b32_e32 v149, v165, v236
	v_and_b32_e32 v150, v165, v237
	v_and_b32_e32 v151, v165, v238
	v_mfma_scale_f32_16x16x128_f8f6f4 v[212:215], v[4:7], v[204:211], v[212:215], v240, v241 op_sel_hi:[0,0,0] cbsz:4
	v_and_b32_e32 v204, v166, v235
	v_and_b32_e32 v205, v166, v236
	v_and_b32_e32 v206, v166, v237
	v_and_b32_e32 v207, v166, v238
	v_and_b32_e32 v208, v167, v235
	v_and_b32_e32 v209, v167, v236
	v_and_b32_e32 v210, v167, v237
	v_and_b32_e32 v211, v167, v238
	v_mfma_scale_f32_16x16x128_f8f6f4 v[212:215], v[8:11], v[144:151], v[212:215], v240, v241 op_sel_hi:[0,0,0] cbsz:4
	v_and_b32_e32 v144, v168, v235
	v_and_b32_e32 v145, v168, v236
	v_and_b32_e32 v146, v168, v237
	v_and_b32_e32 v147, v168, v238
	v_and_b32_e32 v148, v169, v235
	v_and_b32_e32 v149, v169, v236
	v_and_b32_e32 v150, v169, v237
	v_and_b32_e32 v151, v169, v238
	v_mfma_scale_f32_16x16x128_f8f6f4 v[212:215], v[12:15], v[204:211], v[212:215], v240, v241 op_sel_hi:[0,0,0] cbsz:4
	v_and_b32_e32 v204, v170, v235
	v_and_b32_e32 v205, v170, v236
	v_and_b32_e32 v206, v170, v237
	v_and_b32_e32 v207, v170, v238
	v_and_b32_e32 v208, v171, v235
	v_and_b32_e32 v209, v171, v236
	v_and_b32_e32 v210, v171, v237
	v_and_b32_e32 v211, v171, v238
	v_mfma_scale_f32_16x16x128_f8f6f4 v[212:215], v[16:19], v[144:151], v[212:215], v240, v241 op_sel_hi:[0,0,0] cbsz:4
	v_and_b32_e32 v144, v172, v235
	v_and_b32_e32 v145, v172, v236
	v_and_b32_e32 v146, v172, v237
	v_and_b32_e32 v147, v172, v238
	v_and_b32_e32 v148, v173, v235
	v_and_b32_e32 v149, v173, v236
	v_and_b32_e32 v150, v173, v237
	v_and_b32_e32 v151, v173, v238
	v_mfma_scale_f32_16x16x128_f8f6f4 v[212:215], v[20:23], v[204:211], v[212:215], v240, v241 op_sel_hi:[0,0,0] cbsz:4
	v_and_b32_e32 v204, v174, v235
	v_and_b32_e32 v205, v174, v236
	v_and_b32_e32 v206, v174, v237
	v_and_b32_e32 v207, v174, v238
	v_and_b32_e32 v208, v175, v235
	v_and_b32_e32 v209, v175, v236
	v_and_b32_e32 v210, v175, v237
	v_and_b32_e32 v211, v175, v238
	v_mfma_scale_f32_16x16x128_f8f6f4 v[212:215], v[24:27], v[144:151], v[212:215], v240, v241 op_sel_hi:[0,0,0] cbsz:4
	s_nop 0
	v_mfma_scale_f32_16x16x128_f8f6f4 v[212:215], v[28:31], v[204:211], v[212:215], v240, v241 op_sel_hi:[0,0,0] cbsz:4
	s_waitcnt lgkmcnt(0)
	v_lshl_or_b32 v128, v128, 7, v232
	v_lshl_or_b32 v129, v129, 7, v232
	v_lshl_or_b32 v130, v130, 7, v232
	v_lshl_or_b32 v131, v131, 7, v232
	v_lshl_or_b32 v132, v132, 7, v232
	v_lshl_or_b32 v133, v133, 7, v232
	v_lshl_or_b32 v134, v134, 7, v232
	v_lshl_or_b32 v135, v135, 7, v232
	v_lshl_or_b32 v136, v136, 7, v232
	v_lshl_or_b32 v137, v137, 7, v232
	v_lshl_or_b32 v138, v138, 7, v232
	v_lshl_or_b32 v139, v139, 7, v232
	v_lshl_or_b32 v140, v140, 7, v232
	v_lshl_or_b32 v141, v141, 7, v232
	v_lshl_or_b32 v142, v142, 7, v232
	v_lshl_or_b32 v143, v143, 7, v232
	buffer_load_dwordx2 v[0:1], v128, s[20:23], s1 offen
	buffer_load_dwordx2 v[2:3], v129, s[20:23], s1 offen
	buffer_load_dwordx2 v[4:5], v130, s[20:23], s1 offen
	buffer_load_dwordx2 v[6:7], v131, s[20:23], s1 offen
	buffer_load_dwordx2 v[8:9], v132, s[20:23], s1 offen
	buffer_load_dwordx2 v[10:11], v133, s[20:23], s1 offen
	buffer_load_dwordx2 v[12:13], v134, s[20:23], s1 offen
	buffer_load_dwordx2 v[14:15], v135, s[20:23], s1 offen
	buffer_load_dwordx2 v[16:17], v136, s[20:23], s1 offen
	buffer_load_dwordx2 v[18:19], v137, s[20:23], s1 offen
	buffer_load_dwordx2 v[20:21], v138, s[20:23], s1 offen
	buffer_load_dwordx2 v[22:23], v139, s[20:23], s1 offen
	buffer_load_dwordx2 v[24:25], v140, s[20:23], s1 offen
	buffer_load_dwordx2 v[26:27], v141, s[20:23], s1 offen
	buffer_load_dwordx2 v[28:29], v142, s[20:23], s1 offen
	buffer_load_dwordx2 v[30:31], v143, s[20:23], s1 offen
	ds_read_b64 v[128:129], v233 offset:3328
	ds_read_b64 v[130:131], v233 offset:3360
	ds_read_b64 v[132:133], v233 offset:3392
	ds_read_b64 v[134:135], v233 offset:3424
	ds_read_b64 v[136:137], v233 offset:3456
	ds_read_b64 v[138:139], v233 offset:3488
	ds_read_b64 v[140:141], v233 offset:3520
	ds_read_b64 v[142:143], v233 offset:3552
	ds_read_b64 v[160:161], v234 offset:2560
	ds_read_b64 v[162:163], v234 offset:2592
	ds_read_b64 v[164:165], v234 offset:2624
	ds_read_b64 v[166:167], v234 offset:2656
	ds_read_b64 v[168:169], v234 offset:2688
	ds_read_b64 v[170:171], v234 offset:2720
	ds_read_b64 v[172:173], v234 offset:2752
	ds_read_b64 v[174:175], v234 offset:2784
	s_waitcnt vmcnt(50)
	v_and_b32_e32 v144, v176, v235
	v_and_b32_e32 v145, v176, v236
	v_and_b32_e32 v146, v176, v237
	v_and_b32_e32 v147, v176, v238
	v_and_b32_e32 v148, v177, v235
	v_and_b32_e32 v149, v177, v236
	v_and_b32_e32 v150, v177, v237
	v_and_b32_e32 v151, v177, v238
	v_and_b32_e32 v204, v178, v235
	v_and_b32_e32 v205, v178, v236
	v_and_b32_e32 v206, v178, v237
	v_and_b32_e32 v207, v178, v238
	v_and_b32_e32 v208, v179, v235
	v_and_b32_e32 v209, v179, v236
	v_and_b32_e32 v210, v179, v237
	v_and_b32_e32 v211, v179, v238
	v_mfma_scale_f32_16x16x128_f8f6f4 v[212:215], v[32:35], v[144:151], v[212:215], v240, v241 op_sel_hi:[0,0,0] cbsz:4
	v_lshlrev_b32_e32 v252, 16, v230
	v_and_b32_e32 v253, 0xffff0000, v230
	v_lshlrev_b32_e32 v254, 16, v231
	v_and_b32_e32 v144, v180, v235
	v_and_b32_e32 v145, v180, v236
	v_and_b32_e32 v146, v180, v237
	v_and_b32_e32 v147, v180, v238
	v_and_b32_e32 v148, v181, v235
	v_and_b32_e32 v149, v181, v236
	v_and_b32_e32 v150, v181, v237
	v_and_b32_e32 v151, v181, v238
	v_mfma_scale_f32_16x16x128_f8f6f4 v[212:215], v[36:39], v[204:211], v[212:215], v240, v241 op_sel_hi:[0,0,0] cbsz:4
	v_and_b32_e32 v255, 0xffff0000, v231
	v_add_f32_e32 v252, v216, v252
	v_add_f32_e32 v253, v217, v253
	v_and_b32_e32 v204, v182, v235
	v_and_b32_e32 v205, v182, v236
	v_and_b32_e32 v206, v182, v237
	v_and_b32_e32 v207, v182, v238
	v_and_b32_e32 v208, v183, v235
	v_and_b32_e32 v209, v183, v236
	v_and_b32_e32 v210, v183, v237
	v_and_b32_e32 v211, v183, v238
	v_mfma_scale_f32_16x16x128_f8f6f4 v[212:215], v[40:43], v[144:151], v[212:215], v240, v241 op_sel_hi:[0,0,0] cbsz:4
	v_add_f32_e32 v254, v218, v254
	v_add_f32_e32 v255, v219, v255
	v_mul_f32_e32 v192, v252, v252
	v_and_b32_e32 v144, v184, v235
	v_and_b32_e32 v145, v184, v236
	v_and_b32_e32 v146, v184, v237
	v_and_b32_e32 v147, v184, v238
	v_and_b32_e32 v148, v185, v235
	v_and_b32_e32 v149, v185, v236
	v_and_b32_e32 v150, v185, v237
	v_and_b32_e32 v151, v185, v238
	v_mfma_scale_f32_16x16x128_f8f6f4 v[212:215], v[44:47], v[204:211], v[212:215], v240, v241 op_sel_hi:[0,0,0] cbsz:4
	v_mul_f32_e32 v193, v254, v254
	v_fmac_f32_e32 v192, v253, v253
	v_fmac_f32_e32 v193, v255, v255
	v_and_b32_e32 v204, v186, v235
	v_and_b32_e32 v205, v186, v236
	v_and_b32_e32 v206, v186, v237
	v_and_b32_e32 v207, v186, v238
	v_and_b32_e32 v208, v187, v235
	v_and_b32_e32 v209, v187, v236
	v_and_b32_e32 v210, v187, v237
	v_and_b32_e32 v211, v187, v238
	v_mfma_scale_f32_16x16x128_f8f6f4 v[212:215], v[48:51], v[144:151], v[212:215], v240, v241 op_sel_hi:[0,0,0] cbsz:4
	v_cvt_pk_bf16_f32 v250, v252, v253
	v_cvt_pk_bf16_f32 v251, v254, v255
	v_add_f32_e32 v192, v192, v193
	v_and_b32_e32 v144, v188, v235
	v_and_b32_e32 v145, v188, v236
	v_and_b32_e32 v146, v188, v237
	v_and_b32_e32 v147, v188, v238
	v_and_b32_e32 v148, v189, v235
	v_and_b32_e32 v149, v189, v236
	v_and_b32_e32 v150, v189, v237
	v_and_b32_e32 v151, v189, v238
	v_mfma_scale_f32_16x16x128_f8f6f4 v[212:215], v[52:55], v[204:211], v[212:215], v240, v241 op_sel_hi:[0,0,0] cbsz:4
	v_add_f32_e32 v223, v223, v192
	v_and_b32_e32 v204, v190, v235
	v_and_b32_e32 v205, v190, v236
	v_and_b32_e32 v206, v190, v237
	v_and_b32_e32 v207, v190, v238
	v_and_b32_e32 v208, v191, v235
	v_and_b32_e32 v209, v191, v236
	v_and_b32_e32 v210, v191, v237
	v_and_b32_e32 v211, v191, v238
	v_mfma_scale_f32_16x16x128_f8f6f4 v[212:215], v[56:59], v[144:151], v[212:215], v240, v241 op_sel_hi:[0,0,0] cbsz:4
	s_nop 0
	v_mfma_scale_f32_16x16x128_f8f6f4 v[212:215], v[60:63], v[204:211], v[212:215], v240, v241 op_sel_hi:[0,0,0] cbsz:4
	s_lshl_b32 s64, s0, 9
	s_add_u32 s64, s64, 0x3000
	s_add_u32 s76, s28, s64
	s_addc_u32 s77, s29, 0
	global_store_dwordx2 v239, v[250:251], s[76:77]
	s_lshl_b32 s64, s0, 9
	s_add_u32 s64, s64, 0x5000
	s_add_u32 s70, s28, s64
	s_addc_u32 s71, s29, 0
	global_load_dwordx2 v[230:231], v239, s[70:71]
	s_waitcnt lgkmcnt(0)
	v_lshl_or_b32 v128, v128, 7, v232
	v_lshl_or_b32 v129, v129, 7, v232
	v_lshl_or_b32 v130, v130, 7, v232
	v_lshl_or_b32 v131, v131, 7, v232
	v_lshl_or_b32 v132, v132, 7, v232
	v_lshl_or_b32 v133, v133, 7, v232
	v_lshl_or_b32 v134, v134, 7, v232
	v_lshl_or_b32 v135, v135, 7, v232
	v_lshl_or_b32 v136, v136, 7, v232
	v_lshl_or_b32 v137, v137, 7, v232
	v_lshl_or_b32 v138, v138, 7, v232
	v_lshl_or_b32 v139, v139, 7, v232
	v_lshl_or_b32 v140, v140, 7, v232
	v_lshl_or_b32 v141, v141, 7, v232
	v_lshl_or_b32 v142, v142, 7, v232
	v_lshl_or_b32 v143, v143, 7, v232
	buffer_load_dwordx2 v[32:33], v128, s[20:23], s1 offen
	buffer_load_dwordx2 v[34:35], v129, s[20:23], s1 offen
	buffer_load_dwordx2 v[36:37], v130, s[20:23], s1 offen
	buffer_load_dwordx2 v[38:39], v131, s[20:23], s1 offen
	buffer_load_dwordx2 v[40:41], v132, s[20:23], s1 offen
	buffer_load_dwordx2 v[42:43], v133, s[20:23], s1 offen
	buffer_load_dwordx2 v[44:45], v134, s[20:23], s1 offen
	buffer_load_dwordx2 v[46:47], v135, s[20:23], s1 offen
	buffer_load_dwordx2 v[48:49], v136, s[20:23], s1 offen
	buffer_load_dwordx2 v[50:51], v137, s[20:23], s1 offen
	buffer_load_dwordx2 v[52:53], v138, s[20:23], s1 offen
	buffer_load_dwordx2 v[54:55], v139, s[20:23], s1 offen
	buffer_load_dwordx2 v[56:57], v140, s[20:23], s1 offen
	buffer_load_dwordx2 v[58:59], v141, s[20:23], s1 offen
	buffer_load_dwordx2 v[60:61], v142, s[20:23], s1 offen
	buffer_load_dwordx2 v[62:63], v143, s[20:23], s1 offen
	ds_read_b64 v[128:129], v233 offset:3584
	ds_read_b64 v[130:131], v233 offset:3616
	ds_read_b64 v[132:133], v233 offset:3648
	ds_read_b64 v[134:135], v233 offset:3680
	ds_read_b64 v[136:137], v233 offset:3712
	ds_read_b64 v[138:139], v233 offset:3744
	ds_read_b64 v[140:141], v233 offset:3776
	ds_read_b64 v[142:143], v233 offset:3808
	ds_read_b64 v[176:177], v234 offset:2816
	ds_read_b64 v[178:179], v234 offset:2848
	ds_read_b64 v[180:181], v234 offset:2880
	ds_read_b64 v[182:183], v234 offset:2912
	ds_read_b64 v[184:185], v234 offset:2944
	ds_read_b64 v[186:187], v234 offset:2976
	ds_read_b64 v[188:189], v234 offset:3008
	ds_read_b64 v[190:191], v234 offset:3040
	s_waitcnt vmcnt(52)
	v_and_b32_e32 v144, v160, v235
	v_and_b32_e32 v145, v160, v236
	v_and_b32_e32 v146, v160, v237
	v_and_b32_e32 v147, v160, v238
	v_and_b32_e32 v148, v161, v235
	v_and_b32_e32 v149, v161, v236
	v_and_b32_e32 v150, v161, v237
	v_and_b32_e32 v151, v161, v238
	v_and_b32_e32 v204, v162, v235
	v_and_b32_e32 v205, v162, v236
	v_and_b32_e32 v206, v162, v237
	v_and_b32_e32 v207, v162, v238
	v_and_b32_e32 v208, v163, v235
	v_and_b32_e32 v209, v163, v236
	v_and_b32_e32 v210, v163, v237
	v_and_b32_e32 v211, v163, v238
	v_mfma_scale_f32_16x16x128_f8f6f4 v[216:219], v[64:67], v[144:151], 0, v240, v241 op_sel_hi:[0,0,0] cbsz:4
	v_and_b32_e32 v144, v164, v235
	v_and_b32_e32 v145, v164, v236
	v_and_b32_e32 v146, v164, v237
	v_and_b32_e32 v147, v164, v238
	v_and_b32_e32 v148, v165, v235
	v_and_b32_e32 v149, v165, v236
	v_and_b32_e32 v150, v165, v237
	v_and_b32_e32 v151, v165, v238
	v_mfma_scale_f32_16x16x128_f8f6f4 v[216:219], v[68:71], v[204:211], v[216:219], v240, v241 op_sel_hi:[0,0,0] cbsz:4
	v_and_b32_e32 v204, v166, v235
	v_and_b32_e32 v205, v166, v236
	v_and_b32_e32 v206, v166, v237
	v_and_b32_e32 v207, v166, v238
	v_and_b32_e32 v208, v167, v235
	v_and_b32_e32 v209, v167, v236
	v_and_b32_e32 v210, v167, v237
	v_and_b32_e32 v211, v167, v238
	v_mfma_scale_f32_16x16x128_f8f6f4 v[216:219], v[72:75], v[144:151], v[216:219], v240, v241 op_sel_hi:[0,0,0] cbsz:4
	v_and_b32_e32 v144, v168, v235
	v_and_b32_e32 v145, v168, v236
	v_and_b32_e32 v146, v168, v237
	v_and_b32_e32 v147, v168, v238
	v_and_b32_e32 v148, v169, v235
	v_and_b32_e32 v149, v169, v236
	v_and_b32_e32 v150, v169, v237
	v_and_b32_e32 v151, v169, v238
	v_mfma_scale_f32_16x16x128_f8f6f4 v[216:219], v[76:79], v[204:211], v[216:219], v240, v241 op_sel_hi:[0,0,0] cbsz:4
	v_and_b32_e32 v204, v170, v235
	v_and_b32_e32 v205, v170, v236
	v_and_b32_e32 v206, v170, v237
	v_and_b32_e32 v207, v170, v238
	v_and_b32_e32 v208, v171, v235
	v_and_b32_e32 v209, v171, v236
	v_and_b32_e32 v210, v171, v237
	v_and_b32_e32 v211, v171, v238
	v_mfma_scale_f32_16x16x128_f8f6f4 v[216:219], v[80:83], v[144:151], v[216:219], v240, v241 op_sel_hi:[0,0,0] cbsz:4
	v_and_b32_e32 v144, v172, v235
	v_and_b32_e32 v145, v172, v236
	v_and_b32_e32 v146, v172, v237
	v_and_b32_e32 v147, v172, v238
	v_and_b32_e32 v148, v173, v235
	v_and_b32_e32 v149, v173, v236
	v_and_b32_e32 v150, v173, v237
	v_and_b32_e32 v151, v173, v238
	v_mfma_scale_f32_16x16x128_f8f6f4 v[216:219], v[84:87], v[204:211], v[216:219], v240, v241 op_sel_hi:[0,0,0] cbsz:4
	v_and_b32_e32 v204, v174, v235
	v_and_b32_e32 v205, v174, v236
	v_and_b32_e32 v206, v174, v237
	v_and_b32_e32 v207, v174, v238
	v_and_b32_e32 v208, v175, v235
	v_and_b32_e32 v209, v175, v236
	v_and_b32_e32 v210, v175, v237
	v_and_b32_e32 v211, v175, v238
	v_mfma_scale_f32_16x16x128_f8f6f4 v[216:219], v[88:91], v[144:151], v[216:219], v240, v241 op_sel_hi:[0,0,0] cbsz:4
	s_nop 0
	v_mfma_scale_f32_16x16x128_f8f6f4 v[216:219], v[92:95], v[204:211], v[216:219], v240, v241 op_sel_hi:[0,0,0] cbsz:4
	s_waitcnt lgkmcnt(0)
	v_lshl_or_b32 v128, v128, 7, v232
	v_lshl_or_b32 v129, v129, 7, v232
	v_lshl_or_b32 v130, v130, 7, v232
	v_lshl_or_b32 v131, v131, 7, v232
	v_lshl_or_b32 v132, v132, 7, v232
	v_lshl_or_b32 v133, v133, 7, v232
	v_lshl_or_b32 v134, v134, 7, v232
	v_lshl_or_b32 v135, v135, 7, v232
	v_lshl_or_b32 v136, v136, 7, v232
	v_lshl_or_b32 v137, v137, 7, v232
	v_lshl_or_b32 v138, v138, 7, v232
	v_lshl_or_b32 v139, v139, 7, v232
	v_lshl_or_b32 v140, v140, 7, v232
	v_lshl_or_b32 v141, v141, 7, v232
	v_lshl_or_b32 v142, v142, 7, v232
	v_lshl_or_b32 v143, v143, 7, v232
	buffer_load_dwordx2 v[64:65], v128, s[20:23], s1 offen
	buffer_load_dwordx2 v[66:67], v129, s[20:23], s1 offen
	buffer_load_dwordx2 v[68:69], v130, s[20:23], s1 offen
	buffer_load_dwordx2 v[70:71], v131, s[20:23], s1 offen
	buffer_load_dwordx2 v[72:73], v132, s[20:23], s1 offen
	buffer_load_dwordx2 v[74:75], v133, s[20:23], s1 offen
	buffer_load_dwordx2 v[76:77], v134, s[20:23], s1 offen
	buffer_load_dwordx2 v[78:79], v135, s[20:23], s1 offen
	buffer_load_dwordx2 v[80:81], v136, s[20:23], s1 offen
	buffer_load_dwordx2 v[82:83], v137, s[20:23], s1 offen
	buffer_load_dwordx2 v[84:85], v138, s[20:23], s1 offen
	buffer_load_dwordx2 v[86:87], v139, s[20:23], s1 offen
	buffer_load_dwordx2 v[88:89], v140, s[20:23], s1 offen
	buffer_load_dwordx2 v[90:91], v141, s[20:23], s1 offen
	buffer_load_dwordx2 v[92:93], v142, s[20:23], s1 offen
	buffer_load_dwordx2 v[94:95], v143, s[20:23], s1 offen
	ds_read_b64 v[128:129], v233 offset:3840
	ds_read_b64 v[130:131], v233 offset:3872
	ds_read_b64 v[132:133], v233 offset:3904
	ds_read_b64 v[134:135], v233 offset:3936
	ds_read_b64 v[136:137], v233 offset:3968
	ds_read_b64 v[138:139], v233 offset:4000
	ds_read_b64 v[140:141], v233 offset:4032
	ds_read_b64 v[142:143], v233 offset:4064
	ds_read_b64 v[160:161], v234 offset:3072
	ds_read_b64 v[162:163], v234 offset:3104
	ds_read_b64 v[164:165], v234 offset:3136
	ds_read_b64 v[166:167], v234 offset:3168
	ds_read_b64 v[168:169], v234 offset:3200
	ds_read_b64 v[170:171], v234 offset:3232
	ds_read_b64 v[172:173], v234 offset:3264
	ds_read_b64 v[174:175], v234 offset:3296
	s_waitcnt vmcnt(50)
	v_and_b32_e32 v144, v176, v235
	v_and_b32_e32 v145, v176, v236
	v_and_b32_e32 v146, v176, v237
	v_and_b32_e32 v147, v176, v238
	v_and_b32_e32 v148, v177, v235
	v_and_b32_e32 v149, v177, v236
	v_and_b32_e32 v150, v177, v237
	v_and_b32_e32 v151, v177, v238
	v_and_b32_e32 v204, v178, v235
	v_and_b32_e32 v205, v178, v236
	v_and_b32_e32 v206, v178, v237
	v_and_b32_e32 v207, v178, v238
	v_and_b32_e32 v208, v179, v235
	v_and_b32_e32 v209, v179, v236
	v_and_b32_e32 v210, v179, v237
	v_and_b32_e32 v211, v179, v238
	v_mfma_scale_f32_16x16x128_f8f6f4 v[216:219], v[96:99], v[144:151], v[216:219], v240, v241 op_sel_hi:[0,0,0] cbsz:4
	v_lshlrev_b32_e32 v252, 16, v228
	v_and_b32_e32 v253, 0xffff0000, v228
	v_lshlrev_b32_e32 v254, 16, v229
	v_and_b32_e32 v144, v180, v235
	v_and_b32_e32 v145, v180, v236
	v_and_b32_e32 v146, v180, v237
	v_and_b32_e32 v147, v180, v238
	v_and_b32_e32 v148, v181, v235
	v_and_b32_e32 v149, v181, v236
	v_and_b32_e32 v150, v181, v237
	v_and_b32_e32 v151, v181, v238
	v_mfma_scale_f32_16x16x128_f8f6f4 v[216:219], v[100:103], v[204:211], v[216:219], v240, v241 op_sel_hi:[0,0,0] cbsz:4
	v_and_b32_e32 v255, 0xffff0000, v229
	v_add_f32_e32 v252, v212, v252
	v_add_f32_e32 v253, v213, v253
	v_and_b32_e32 v204, v182, v235
	v_and_b32_e32 v205, v182, v236
	v_and_b32_e32 v206, v182, v237
	v_and_b32_e32 v207, v182, v238
	v_and_b32_e32 v208, v183, v235
	v_and_b32_e32 v209, v183, v236
	v_and_b32_e32 v210, v183, v237
	v_and_b32_e32 v211, v183, v238
	v_mfma_scale_f32_16x16x128_f8f6f4 v[216:219], v[104:107], v[144:151], v[216:219], v240, v241 op_sel_hi:[0,0,0] cbsz:4
	v_add_f32_e32 v254, v214, v254
	v_add_f32_e32 v255, v215, v255
	v_mul_f32_e32 v192, v252, v252
	v_and_b32_e32 v144, v184, v235
	v_and_b32_e32 v145, v184, v236
	v_and_b32_e32 v146, v184, v237
	v_and_b32_e32 v147, v184, v238
	v_and_b32_e32 v148, v185, v235
	v_and_b32_e32 v149, v185, v236
	v_and_b32_e32 v150, v185, v237
	v_and_b32_e32 v151, v185, v238
	v_mfma_scale_f32_16x16x128_f8f6f4 v[216:219], v[108:111], v[204:211], v[216:219], v240, v241 op_sel_hi:[0,0,0] cbsz:4
	v_mul_f32_e32 v193, v254, v254
	v_fmac_f32_e32 v192, v253, v253
	v_fmac_f32_e32 v193, v255, v255
	v_and_b32_e32 v204, v186, v235
	v_and_b32_e32 v205, v186, v236
	v_and_b32_e32 v206, v186, v237
	v_and_b32_e32 v207, v186, v238
	v_and_b32_e32 v208, v187, v235
	v_and_b32_e32 v209, v187, v236
	v_and_b32_e32 v210, v187, v237
	v_and_b32_e32 v211, v187, v238
	v_mfma_scale_f32_16x16x128_f8f6f4 v[216:219], v[112:115], v[144:151], v[216:219], v240, v241 op_sel_hi:[0,0,0] cbsz:4
	v_cvt_pk_bf16_f32 v250, v252, v253
	v_cvt_pk_bf16_f32 v251, v254, v255
	v_add_f32_e32 v192, v192, v193
	v_and_b32_e32 v144, v188, v235
	v_and_b32_e32 v145, v188, v236
	v_and_b32_e32 v146, v188, v237
	v_and_b32_e32 v147, v188, v238
	v_and_b32_e32 v148, v189, v235
	v_and_b32_e32 v149, v189, v236
	v_and_b32_e32 v150, v189, v237
	v_and_b32_e32 v151, v189, v238
	v_mfma_scale_f32_16x16x128_f8f6f4 v[216:219], v[116:119], v[204:211], v[216:219], v240, v241 op_sel_hi:[0,0,0] cbsz:4
	v_add_f32_e32 v224, v224, v192
	v_and_b32_e32 v204, v190, v235
	v_and_b32_e32 v205, v190, v236
	v_and_b32_e32 v206, v190, v237
	v_and_b32_e32 v207, v190, v238
	v_and_b32_e32 v208, v191, v235
	v_and_b32_e32 v209, v191, v236
	v_and_b32_e32 v210, v191, v237
	v_and_b32_e32 v211, v191, v238
	v_mfma_scale_f32_16x16x128_f8f6f4 v[216:219], v[120:123], v[144:151], v[216:219], v240, v241 op_sel_hi:[0,0,0] cbsz:4
	s_nop 0
	v_mfma_scale_f32_16x16x128_f8f6f4 v[216:219], v[124:127], v[204:211], v[216:219], v240, v241 op_sel_hi:[0,0,0] cbsz:4
	s_lshl_b32 s64, s0, 9
	s_add_u32 s64, s64, 0x4000
	s_add_u32 s76, s28, s64
	s_addc_u32 s77, s29, 0
	global_store_dwordx2 v239, v[250:251], s[76:77]
	s_lshl_b32 s64, s0, 9
	s_add_u32 s64, s64, 0x6000
	s_add_u32 s70, s28, s64
	s_addc_u32 s71, s29, 0
	global_load_dwordx2 v[228:229], v239, s[70:71]
	s_waitcnt lgkmcnt(0)
	v_lshl_or_b32 v128, v128, 7, v232
	v_lshl_or_b32 v129, v129, 7, v232
	v_lshl_or_b32 v130, v130, 7, v232
	v_lshl_or_b32 v131, v131, 7, v232
	v_lshl_or_b32 v132, v132, 7, v232
	v_lshl_or_b32 v133, v133, 7, v232
	v_lshl_or_b32 v134, v134, 7, v232
	v_lshl_or_b32 v135, v135, 7, v232
	v_lshl_or_b32 v136, v136, 7, v232
	v_lshl_or_b32 v137, v137, 7, v232
	v_lshl_or_b32 v138, v138, 7, v232
	v_lshl_or_b32 v139, v139, 7, v232
	v_lshl_or_b32 v140, v140, 7, v232
	v_lshl_or_b32 v141, v141, 7, v232
	v_lshl_or_b32 v142, v142, 7, v232
	v_lshl_or_b32 v143, v143, 7, v232
	buffer_load_dwordx2 v[96:97], v128, s[20:23], s1 offen
	buffer_load_dwordx2 v[98:99], v129, s[20:23], s1 offen
	buffer_load_dwordx2 v[100:101], v130, s[20:23], s1 offen
	buffer_load_dwordx2 v[102:103], v131, s[20:23], s1 offen
	buffer_load_dwordx2 v[104:105], v132, s[20:23], s1 offen
	buffer_load_dwordx2 v[106:107], v133, s[20:23], s1 offen
	buffer_load_dwordx2 v[108:109], v134, s[20:23], s1 offen
	buffer_load_dwordx2 v[110:111], v135, s[20:23], s1 offen
	buffer_load_dwordx2 v[112:113], v136, s[20:23], s1 offen
	buffer_load_dwordx2 v[114:115], v137, s[20:23], s1 offen
	buffer_load_dwordx2 v[116:117], v138, s[20:23], s1 offen
	buffer_load_dwordx2 v[118:119], v139, s[20:23], s1 offen
	buffer_load_dwordx2 v[120:121], v140, s[20:23], s1 offen
	buffer_load_dwordx2 v[122:123], v141, s[20:23], s1 offen
	buffer_load_dwordx2 v[124:125], v142, s[20:23], s1 offen
	buffer_load_dwordx2 v[126:127], v143, s[20:23], s1 offen
	ds_read_b64 v[128:129], v233 offset:0
	ds_read_b64 v[130:131], v233 offset:32
	ds_read_b64 v[132:133], v233 offset:64
	ds_read_b64 v[134:135], v233 offset:96
	ds_read_b64 v[136:137], v233 offset:128
	ds_read_b64 v[138:139], v233 offset:160
	ds_read_b64 v[140:141], v233 offset:192
	ds_read_b64 v[142:143], v233 offset:224
	ds_read_b64 v[176:177], v234 offset:3328
	ds_read_b64 v[178:179], v234 offset:3360
	ds_read_b64 v[180:181], v234 offset:3392
	ds_read_b64 v[182:183], v234 offset:3424
	ds_read_b64 v[184:185], v234 offset:3456
	ds_read_b64 v[186:187], v234 offset:3488
	ds_read_b64 v[188:189], v234 offset:3520
	ds_read_b64 v[190:191], v234 offset:3552
	s_waitcnt vmcnt(52)
	v_and_b32_e32 v144, v160, v235
	v_and_b32_e32 v145, v160, v236
	v_and_b32_e32 v146, v160, v237
	v_and_b32_e32 v147, v160, v238
	v_and_b32_e32 v148, v161, v235
	v_and_b32_e32 v149, v161, v236
	v_and_b32_e32 v150, v161, v237
	v_and_b32_e32 v151, v161, v238
	v_and_b32_e32 v204, v162, v235
	v_and_b32_e32 v205, v162, v236
	v_and_b32_e32 v206, v162, v237
	v_and_b32_e32 v207, v162, v238
	v_and_b32_e32 v208, v163, v235
	v_and_b32_e32 v209, v163, v236
	v_and_b32_e32 v210, v163, v237
	v_and_b32_e32 v211, v163, v238
	v_mfma_scale_f32_16x16x128_f8f6f4 v[212:215], v[0:3], v[144:151], 0, v240, v241 op_sel_hi:[0,0,0] cbsz:4
	v_and_b32_e32 v144, v164, v235
	v_and_b32_e32 v145, v164, v236
	v_and_b32_e32 v146, v164, v237
	v_and_b32_e32 v147, v164, v238
	v_and_b32_e32 v148, v165, v235
	v_and_b32_e32 v149, v165, v236
	v_and_b32_e32 v150, v165, v237
	v_and_b32_e32 v151, v165, v238
	v_mfma_scale_f32_16x16x128_f8f6f4 v[212:215], v[4:7], v[204:211], v[212:215], v240, v241 op_sel_hi:[0,0,0] cbsz:4
	v_and_b32_e32 v204, v166, v235
	v_and_b32_e32 v205, v166, v236
	v_and_b32_e32 v206, v166, v237
	v_and_b32_e32 v207, v166, v238
	v_and_b32_e32 v208, v167, v235
	v_and_b32_e32 v209, v167, v236
	v_and_b32_e32 v210, v167, v237
	v_and_b32_e32 v211, v167, v238
	v_mfma_scale_f32_16x16x128_f8f6f4 v[212:215], v[8:11], v[144:151], v[212:215], v240, v241 op_sel_hi:[0,0,0] cbsz:4
	v_and_b32_e32 v144, v168, v235
	v_and_b32_e32 v145, v168, v236
	v_and_b32_e32 v146, v168, v237
	v_and_b32_e32 v147, v168, v238
	v_and_b32_e32 v148, v169, v235
	v_and_b32_e32 v149, v169, v236
	v_and_b32_e32 v150, v169, v237
	v_and_b32_e32 v151, v169, v238
	v_mfma_scale_f32_16x16x128_f8f6f4 v[212:215], v[12:15], v[204:211], v[212:215], v240, v241 op_sel_hi:[0,0,0] cbsz:4
	v_and_b32_e32 v204, v170, v235
	v_and_b32_e32 v205, v170, v236
	v_and_b32_e32 v206, v170, v237
	v_and_b32_e32 v207, v170, v238
	v_and_b32_e32 v208, v171, v235
	v_and_b32_e32 v209, v171, v236
	v_and_b32_e32 v210, v171, v237
	v_and_b32_e32 v211, v171, v238
	v_mfma_scale_f32_16x16x128_f8f6f4 v[212:215], v[16:19], v[144:151], v[212:215], v240, v241 op_sel_hi:[0,0,0] cbsz:4
	v_and_b32_e32 v144, v172, v235
	v_and_b32_e32 v145, v172, v236
	v_and_b32_e32 v146, v172, v237
	v_and_b32_e32 v147, v172, v238
	v_and_b32_e32 v148, v173, v235
	v_and_b32_e32 v149, v173, v236
	v_and_b32_e32 v150, v173, v237
	v_and_b32_e32 v151, v173, v238
	v_mfma_scale_f32_16x16x128_f8f6f4 v[212:215], v[20:23], v[204:211], v[212:215], v240, v241 op_sel_hi:[0,0,0] cbsz:4
	v_and_b32_e32 v204, v174, v235
	v_and_b32_e32 v205, v174, v236
	v_and_b32_e32 v206, v174, v237
	v_and_b32_e32 v207, v174, v238
	v_and_b32_e32 v208, v175, v235
	v_and_b32_e32 v209, v175, v236
	v_and_b32_e32 v210, v175, v237
	v_and_b32_e32 v211, v175, v238
	v_mfma_scale_f32_16x16x128_f8f6f4 v[212:215], v[24:27], v[144:151], v[212:215], v240, v241 op_sel_hi:[0,0,0] cbsz:4
	s_nop 0
	v_mfma_scale_f32_16x16x128_f8f6f4 v[212:215], v[28:31], v[204:211], v[212:215], v240, v241 op_sel_hi:[0,0,0] cbsz:4
	s_waitcnt lgkmcnt(0)
	v_lshl_or_b32 v128, v128, 7, v232
	v_lshl_or_b32 v129, v129, 7, v232
	v_lshl_or_b32 v130, v130, 7, v232
	v_lshl_or_b32 v131, v131, 7, v232
	v_lshl_or_b32 v132, v132, 7, v232
	v_lshl_or_b32 v133, v133, 7, v232
	v_lshl_or_b32 v134, v134, 7, v232
	v_lshl_or_b32 v135, v135, 7, v232
	v_lshl_or_b32 v136, v136, 7, v232
	v_lshl_or_b32 v137, v137, 7, v232
	v_lshl_or_b32 v138, v138, 7, v232
	v_lshl_or_b32 v139, v139, 7, v232
	v_lshl_or_b32 v140, v140, 7, v232
	v_lshl_or_b32 v141, v141, 7, v232
	v_lshl_or_b32 v142, v142, 7, v232
	v_lshl_or_b32 v143, v143, 7, v232
	buffer_load_dwordx2 v[0:1], v128, s[20:23], s60 offen
	buffer_load_dwordx2 v[2:3], v129, s[20:23], s60 offen
	buffer_load_dwordx2 v[4:5], v130, s[20:23], s60 offen
	buffer_load_dwordx2 v[6:7], v131, s[20:23], s60 offen
	buffer_load_dwordx2 v[8:9], v132, s[20:23], s60 offen
	buffer_load_dwordx2 v[10:11], v133, s[20:23], s60 offen
	buffer_load_dwordx2 v[12:13], v134, s[20:23], s60 offen
	buffer_load_dwordx2 v[14:15], v135, s[20:23], s60 offen
	buffer_load_dwordx2 v[16:17], v136, s[20:23], s60 offen
	buffer_load_dwordx2 v[18:19], v137, s[20:23], s60 offen
	buffer_load_dwordx2 v[20:21], v138, s[20:23], s60 offen
	buffer_load_dwordx2 v[22:23], v139, s[20:23], s60 offen
	buffer_load_dwordx2 v[24:25], v140, s[20:23], s60 offen
	buffer_load_dwordx2 v[26:27], v141, s[20:23], s60 offen
	buffer_load_dwordx2 v[28:29], v142, s[20:23], s60 offen
	buffer_load_dwordx2 v[30:31], v143, s[20:23], s60 offen
	ds_read_b64 v[128:129], v233 offset:256
	ds_read_b64 v[130:131], v233 offset:288
	ds_read_b64 v[132:133], v233 offset:320
	ds_read_b64 v[134:135], v233 offset:352
	ds_read_b64 v[136:137], v233 offset:384
	ds_read_b64 v[138:139], v233 offset:416
	ds_read_b64 v[140:141], v233 offset:448
	ds_read_b64 v[142:143], v233 offset:480
	ds_read_b64 v[160:161], v234 offset:3584
	ds_read_b64 v[162:163], v234 offset:3616
	ds_read_b64 v[164:165], v234 offset:3648
	ds_read_b64 v[166:167], v234 offset:3680
	ds_read_b64 v[168:169], v234 offset:3712
	ds_read_b64 v[170:171], v234 offset:3744
	ds_read_b64 v[172:173], v234 offset:3776
	ds_read_b64 v[174:175], v234 offset:3808
	s_waitcnt vmcnt(50)
	v_and_b32_e32 v144, v176, v235
	v_and_b32_e32 v145, v176, v236
	v_and_b32_e32 v146, v176, v237
	v_and_b32_e32 v147, v176, v238
	v_and_b32_e32 v148, v177, v235
	v_and_b32_e32 v149, v177, v236
	v_and_b32_e32 v150, v177, v237
	v_and_b32_e32 v151, v177, v238
	v_and_b32_e32 v204, v178, v235
	v_and_b32_e32 v205, v178, v236
	v_and_b32_e32 v206, v178, v237
	v_and_b32_e32 v207, v178, v238
	v_and_b32_e32 v208, v179, v235
	v_and_b32_e32 v209, v179, v236
	v_and_b32_e32 v210, v179, v237
	v_and_b32_e32 v211, v179, v238
	v_mfma_scale_f32_16x16x128_f8f6f4 v[212:215], v[32:35], v[144:151], v[212:215], v240, v241 op_sel_hi:[0,0,0] cbsz:4
	v_lshlrev_b32_e32 v252, 16, v230
	v_and_b32_e32 v253, 0xffff0000, v230
	v_lshlrev_b32_e32 v254, 16, v231
	v_and_b32_e32 v144, v180, v235
	v_and_b32_e32 v145, v180, v236
	v_and_b32_e32 v146, v180, v237
	v_and_b32_e32 v147, v180, v238
	v_and_b32_e32 v148, v181, v235
	v_and_b32_e32 v149, v181, v236
	v_and_b32_e32 v150, v181, v237
	v_and_b32_e32 v151, v181, v238
	v_mfma_scale_f32_16x16x128_f8f6f4 v[212:215], v[36:39], v[204:211], v[212:215], v240, v241 op_sel_hi:[0,0,0] cbsz:4
	v_and_b32_e32 v255, 0xffff0000, v231
	v_add_f32_e32 v252, v216, v252
	v_add_f32_e32 v253, v217, v253
	v_and_b32_e32 v204, v182, v235
	v_and_b32_e32 v205, v182, v236
	v_and_b32_e32 v206, v182, v237
	v_and_b32_e32 v207, v182, v238
	v_and_b32_e32 v208, v183, v235
	v_and_b32_e32 v209, v183, v236
	v_and_b32_e32 v210, v183, v237
	v_and_b32_e32 v211, v183, v238
	v_mfma_scale_f32_16x16x128_f8f6f4 v[212:215], v[40:43], v[144:151], v[212:215], v240, v241 op_sel_hi:[0,0,0] cbsz:4
	v_add_f32_e32 v254, v218, v254
	v_add_f32_e32 v255, v219, v255
	v_mul_f32_e32 v192, v252, v252
	v_and_b32_e32 v144, v184, v235
	v_and_b32_e32 v145, v184, v236
	v_and_b32_e32 v146, v184, v237
	v_and_b32_e32 v147, v184, v238
	v_and_b32_e32 v148, v185, v235
	v_and_b32_e32 v149, v185, v236
	v_and_b32_e32 v150, v185, v237
	v_and_b32_e32 v151, v185, v238
	v_mfma_scale_f32_16x16x128_f8f6f4 v[212:215], v[44:47], v[204:211], v[212:215], v240, v241 op_sel_hi:[0,0,0] cbsz:4
	v_mul_f32_e32 v193, v254, v254
	v_fmac_f32_e32 v192, v253, v253
	v_fmac_f32_e32 v193, v255, v255
	v_and_b32_e32 v204, v186, v235
	v_and_b32_e32 v205, v186, v236
	v_and_b32_e32 v206, v186, v237
	v_and_b32_e32 v207, v186, v238
	v_and_b32_e32 v208, v187, v235
	v_and_b32_e32 v209, v187, v236
	v_and_b32_e32 v210, v187, v237
	v_and_b32_e32 v211, v187, v238
	v_mfma_scale_f32_16x16x128_f8f6f4 v[212:215], v[48:51], v[144:151], v[212:215], v240, v241 op_sel_hi:[0,0,0] cbsz:4
	v_cvt_pk_bf16_f32 v250, v252, v253
	v_cvt_pk_bf16_f32 v251, v254, v255
	v_add_f32_e32 v192, v192, v193
	v_and_b32_e32 v144, v188, v235
	v_and_b32_e32 v145, v188, v236
	v_and_b32_e32 v146, v188, v237
	v_and_b32_e32 v147, v188, v238
	v_and_b32_e32 v148, v189, v235
	v_and_b32_e32 v149, v189, v236
	v_and_b32_e32 v150, v189, v237
	v_and_b32_e32 v151, v189, v238
	v_mfma_scale_f32_16x16x128_f8f6f4 v[212:215], v[52:55], v[204:211], v[212:215], v240, v241 op_sel_hi:[0,0,0] cbsz:4
	v_add_f32_e32 v225, v225, v192
	v_and_b32_e32 v204, v190, v235
	v_and_b32_e32 v205, v190, v236
	v_and_b32_e32 v206, v190, v237
	v_and_b32_e32 v207, v190, v238
	v_and_b32_e32 v208, v191, v235
	v_and_b32_e32 v209, v191, v236
	v_and_b32_e32 v210, v191, v237
	v_and_b32_e32 v211, v191, v238
	v_mfma_scale_f32_16x16x128_f8f6f4 v[212:215], v[56:59], v[144:151], v[212:215], v240, v241 op_sel_hi:[0,0,0] cbsz:4
	s_nop 0
	v_mfma_scale_f32_16x16x128_f8f6f4 v[212:215], v[60:63], v[204:211], v[212:215], v240, v241 op_sel_hi:[0,0,0] cbsz:4
	s_lshl_b32 s64, s0, 9
	s_add_u32 s64, s64, 0x5000
	s_add_u32 s76, s28, s64
	s_addc_u32 s77, s29, 0
	global_store_dwordx2 v239, v[250:251], s[76:77]
	s_lshl_b32 s64, s0, 9
	s_add_u32 s64, s64, 0x7000
	s_add_u32 s70, s28, s64
	s_addc_u32 s71, s29, 0
	global_load_dwordx2 v[230:231], v239, s[70:71]
	s_waitcnt lgkmcnt(0)
	v_lshl_or_b32 v128, v128, 7, v232
	v_lshl_or_b32 v129, v129, 7, v232
	v_lshl_or_b32 v130, v130, 7, v232
	v_lshl_or_b32 v131, v131, 7, v232
	v_lshl_or_b32 v132, v132, 7, v232
	v_lshl_or_b32 v133, v133, 7, v232
	v_lshl_or_b32 v134, v134, 7, v232
	v_lshl_or_b32 v135, v135, 7, v232
	v_lshl_or_b32 v136, v136, 7, v232
	v_lshl_or_b32 v137, v137, 7, v232
	v_lshl_or_b32 v138, v138, 7, v232
	v_lshl_or_b32 v139, v139, 7, v232
	v_lshl_or_b32 v140, v140, 7, v232
	v_lshl_or_b32 v141, v141, 7, v232
	v_lshl_or_b32 v142, v142, 7, v232
	v_lshl_or_b32 v143, v143, 7, v232
	buffer_load_dwordx2 v[32:33], v128, s[20:23], s60 offen
	buffer_load_dwordx2 v[34:35], v129, s[20:23], s60 offen
	buffer_load_dwordx2 v[36:37], v130, s[20:23], s60 offen
	buffer_load_dwordx2 v[38:39], v131, s[20:23], s60 offen
	buffer_load_dwordx2 v[40:41], v132, s[20:23], s60 offen
	buffer_load_dwordx2 v[42:43], v133, s[20:23], s60 offen
	buffer_load_dwordx2 v[44:45], v134, s[20:23], s60 offen
	buffer_load_dwordx2 v[46:47], v135, s[20:23], s60 offen
	buffer_load_dwordx2 v[48:49], v136, s[20:23], s60 offen
	buffer_load_dwordx2 v[50:51], v137, s[20:23], s60 offen
	buffer_load_dwordx2 v[52:53], v138, s[20:23], s60 offen
	buffer_load_dwordx2 v[54:55], v139, s[20:23], s60 offen
	buffer_load_dwordx2 v[56:57], v140, s[20:23], s60 offen
	buffer_load_dwordx2 v[58:59], v141, s[20:23], s60 offen
	buffer_load_dwordx2 v[60:61], v142, s[20:23], s60 offen
	buffer_load_dwordx2 v[62:63], v143, s[20:23], s60 offen
	ds_read_b64 v[128:129], v233 offset:512
	ds_read_b64 v[130:131], v233 offset:544
	ds_read_b64 v[132:133], v233 offset:576
	ds_read_b64 v[134:135], v233 offset:608
	ds_read_b64 v[136:137], v233 offset:640
	ds_read_b64 v[138:139], v233 offset:672
	ds_read_b64 v[140:141], v233 offset:704
	ds_read_b64 v[142:143], v233 offset:736
	ds_read_b64 v[176:177], v234 offset:3840
	ds_read_b64 v[178:179], v234 offset:3872
	ds_read_b64 v[180:181], v234 offset:3904
	ds_read_b64 v[182:183], v234 offset:3936
	ds_read_b64 v[184:185], v234 offset:3968
	ds_read_b64 v[186:187], v234 offset:4000
	ds_read_b64 v[188:189], v234 offset:4032
	ds_read_b64 v[190:191], v234 offset:4064
	s_waitcnt vmcnt(52)
	v_and_b32_e32 v144, v160, v235
	v_and_b32_e32 v145, v160, v236
	v_and_b32_e32 v146, v160, v237
	v_and_b32_e32 v147, v160, v238
	v_and_b32_e32 v148, v161, v235
	v_and_b32_e32 v149, v161, v236
	v_and_b32_e32 v150, v161, v237
	v_and_b32_e32 v151, v161, v238
	v_and_b32_e32 v204, v162, v235
	v_and_b32_e32 v205, v162, v236
	v_and_b32_e32 v206, v162, v237
	v_and_b32_e32 v207, v162, v238
	v_and_b32_e32 v208, v163, v235
	v_and_b32_e32 v209, v163, v236
	v_and_b32_e32 v210, v163, v237
	v_and_b32_e32 v211, v163, v238
	v_mfma_scale_f32_16x16x128_f8f6f4 v[216:219], v[64:67], v[144:151], 0, v240, v241 op_sel_hi:[0,0,0] cbsz:4
	v_and_b32_e32 v144, v164, v235
	v_and_b32_e32 v145, v164, v236
	v_and_b32_e32 v146, v164, v237
	v_and_b32_e32 v147, v164, v238
	v_and_b32_e32 v148, v165, v235
	v_and_b32_e32 v149, v165, v236
	v_and_b32_e32 v150, v165, v237
	v_and_b32_e32 v151, v165, v238
	v_mfma_scale_f32_16x16x128_f8f6f4 v[216:219], v[68:71], v[204:211], v[216:219], v240, v241 op_sel_hi:[0,0,0] cbsz:4
	v_and_b32_e32 v204, v166, v235
	v_and_b32_e32 v205, v166, v236
	v_and_b32_e32 v206, v166, v237
	v_and_b32_e32 v207, v166, v238
	v_and_b32_e32 v208, v167, v235
	v_and_b32_e32 v209, v167, v236
	v_and_b32_e32 v210, v167, v237
	v_and_b32_e32 v211, v167, v238
	v_mfma_scale_f32_16x16x128_f8f6f4 v[216:219], v[72:75], v[144:151], v[216:219], v240, v241 op_sel_hi:[0,0,0] cbsz:4
	v_and_b32_e32 v144, v168, v235
	v_and_b32_e32 v145, v168, v236
	v_and_b32_e32 v146, v168, v237
	v_and_b32_e32 v147, v168, v238
	v_and_b32_e32 v148, v169, v235
	v_and_b32_e32 v149, v169, v236
	v_and_b32_e32 v150, v169, v237
	v_and_b32_e32 v151, v169, v238
	v_mfma_scale_f32_16x16x128_f8f6f4 v[216:219], v[76:79], v[204:211], v[216:219], v240, v241 op_sel_hi:[0,0,0] cbsz:4
	v_and_b32_e32 v204, v170, v235
	v_and_b32_e32 v205, v170, v236
	v_and_b32_e32 v206, v170, v237
	v_and_b32_e32 v207, v170, v238
	v_and_b32_e32 v208, v171, v235
	v_and_b32_e32 v209, v171, v236
	v_and_b32_e32 v210, v171, v237
	v_and_b32_e32 v211, v171, v238
	v_mfma_scale_f32_16x16x128_f8f6f4 v[216:219], v[80:83], v[144:151], v[216:219], v240, v241 op_sel_hi:[0,0,0] cbsz:4
	v_and_b32_e32 v144, v172, v235
	v_and_b32_e32 v145, v172, v236
	v_and_b32_e32 v146, v172, v237
	v_and_b32_e32 v147, v172, v238
	v_and_b32_e32 v148, v173, v235
	v_and_b32_e32 v149, v173, v236
	v_and_b32_e32 v150, v173, v237
	v_and_b32_e32 v151, v173, v238
	v_mfma_scale_f32_16x16x128_f8f6f4 v[216:219], v[84:87], v[204:211], v[216:219], v240, v241 op_sel_hi:[0,0,0] cbsz:4
	v_and_b32_e32 v204, v174, v235
	v_and_b32_e32 v205, v174, v236
	v_and_b32_e32 v206, v174, v237
	v_and_b32_e32 v207, v174, v238
	v_and_b32_e32 v208, v175, v235
	v_and_b32_e32 v209, v175, v236
	v_and_b32_e32 v210, v175, v237
	v_and_b32_e32 v211, v175, v238
	v_mfma_scale_f32_16x16x128_f8f6f4 v[216:219], v[88:91], v[144:151], v[216:219], v240, v241 op_sel_hi:[0,0,0] cbsz:4
	s_nop 0
	v_mfma_scale_f32_16x16x128_f8f6f4 v[216:219], v[92:95], v[204:211], v[216:219], v240, v241 op_sel_hi:[0,0,0] cbsz:4
	s_waitcnt lgkmcnt(0)
	v_lshl_or_b32 v128, v128, 7, v232
	v_lshl_or_b32 v129, v129, 7, v232
	v_lshl_or_b32 v130, v130, 7, v232
	v_lshl_or_b32 v131, v131, 7, v232
	v_lshl_or_b32 v132, v132, 7, v232
	v_lshl_or_b32 v133, v133, 7, v232
	v_lshl_or_b32 v134, v134, 7, v232
	v_lshl_or_b32 v135, v135, 7, v232
	v_lshl_or_b32 v136, v136, 7, v232
	v_lshl_or_b32 v137, v137, 7, v232
	v_lshl_or_b32 v138, v138, 7, v232
	v_lshl_or_b32 v139, v139, 7, v232
	v_lshl_or_b32 v140, v140, 7, v232
	v_lshl_or_b32 v141, v141, 7, v232
	v_lshl_or_b32 v142, v142, 7, v232
	v_lshl_or_b32 v143, v143, 7, v232
	buffer_load_dwordx2 v[64:65], v128, s[20:23], s60 offen
	buffer_load_dwordx2 v[66:67], v129, s[20:23], s60 offen
	buffer_load_dwordx2 v[68:69], v130, s[20:23], s60 offen
	buffer_load_dwordx2 v[70:71], v131, s[20:23], s60 offen
	buffer_load_dwordx2 v[72:73], v132, s[20:23], s60 offen
	buffer_load_dwordx2 v[74:75], v133, s[20:23], s60 offen
	buffer_load_dwordx2 v[76:77], v134, s[20:23], s60 offen
	buffer_load_dwordx2 v[78:79], v135, s[20:23], s60 offen
	buffer_load_dwordx2 v[80:81], v136, s[20:23], s60 offen
	buffer_load_dwordx2 v[82:83], v137, s[20:23], s60 offen
	buffer_load_dwordx2 v[84:85], v138, s[20:23], s60 offen
	buffer_load_dwordx2 v[86:87], v139, s[20:23], s60 offen
	buffer_load_dwordx2 v[88:89], v140, s[20:23], s60 offen
	buffer_load_dwordx2 v[90:91], v141, s[20:23], s60 offen
	buffer_load_dwordx2 v[92:93], v142, s[20:23], s60 offen
	buffer_load_dwordx2 v[94:95], v143, s[20:23], s60 offen
	ds_read_b64 v[128:129], v233 offset:768
	ds_read_b64 v[130:131], v233 offset:800
	ds_read_b64 v[132:133], v233 offset:832
	ds_read_b64 v[134:135], v233 offset:864
	ds_read_b64 v[136:137], v233 offset:896
	ds_read_b64 v[138:139], v233 offset:928
	ds_read_b64 v[140:141], v233 offset:960
	ds_read_b64 v[142:143], v233 offset:992
	ds_read_b64 v[160:161], v247 offset:0
	ds_read_b64 v[162:163], v247 offset:32
	ds_read_b64 v[164:165], v247 offset:64
	ds_read_b64 v[166:167], v247 offset:96
	ds_read_b64 v[168:169], v247 offset:128
	ds_read_b64 v[170:171], v247 offset:160
	ds_read_b64 v[172:173], v247 offset:192
	ds_read_b64 v[174:175], v247 offset:224
	s_waitcnt vmcnt(50)
	v_and_b32_e32 v144, v176, v235
	v_and_b32_e32 v145, v176, v236
	v_and_b32_e32 v146, v176, v237
	v_and_b32_e32 v147, v176, v238
	v_and_b32_e32 v148, v177, v235
	v_and_b32_e32 v149, v177, v236
	v_and_b32_e32 v150, v177, v237
	v_and_b32_e32 v151, v177, v238
	v_and_b32_e32 v204, v178, v235
	v_and_b32_e32 v205, v178, v236
	v_and_b32_e32 v206, v178, v237
	v_and_b32_e32 v207, v178, v238
	v_and_b32_e32 v208, v179, v235
	v_and_b32_e32 v209, v179, v236
	v_and_b32_e32 v210, v179, v237
	v_and_b32_e32 v211, v179, v238
	v_mfma_scale_f32_16x16x128_f8f6f4 v[216:219], v[96:99], v[144:151], v[216:219], v240, v241 op_sel_hi:[0,0,0] cbsz:4
	v_lshlrev_b32_e32 v252, 16, v228
	v_and_b32_e32 v253, 0xffff0000, v228
	v_lshlrev_b32_e32 v254, 16, v229
	v_and_b32_e32 v144, v180, v235
	v_and_b32_e32 v145, v180, v236
	v_and_b32_e32 v146, v180, v237
	v_and_b32_e32 v147, v180, v238
	v_and_b32_e32 v148, v181, v235
	v_and_b32_e32 v149, v181, v236
	v_and_b32_e32 v150, v181, v237
	v_and_b32_e32 v151, v181, v238
	v_mfma_scale_f32_16x16x128_f8f6f4 v[216:219], v[100:103], v[204:211], v[216:219], v240, v241 op_sel_hi:[0,0,0] cbsz:4
	v_and_b32_e32 v255, 0xffff0000, v229
	v_add_f32_e32 v252, v212, v252
	v_add_f32_e32 v253, v213, v253
	v_and_b32_e32 v204, v182, v235
	v_and_b32_e32 v205, v182, v236
	v_and_b32_e32 v206, v182, v237
	v_and_b32_e32 v207, v182, v238
	v_and_b32_e32 v208, v183, v235
	v_and_b32_e32 v209, v183, v236
	v_and_b32_e32 v210, v183, v237
	v_and_b32_e32 v211, v183, v238
	v_mfma_scale_f32_16x16x128_f8f6f4 v[216:219], v[104:107], v[144:151], v[216:219], v240, v241 op_sel_hi:[0,0,0] cbsz:4
	v_add_f32_e32 v254, v214, v254
	v_add_f32_e32 v255, v215, v255
	v_mul_f32_e32 v192, v252, v252
	v_and_b32_e32 v144, v184, v235
	v_and_b32_e32 v145, v184, v236
	v_and_b32_e32 v146, v184, v237
	v_and_b32_e32 v147, v184, v238
	v_and_b32_e32 v148, v185, v235
	v_and_b32_e32 v149, v185, v236
	v_and_b32_e32 v150, v185, v237
	v_and_b32_e32 v151, v185, v238
	v_mfma_scale_f32_16x16x128_f8f6f4 v[216:219], v[108:111], v[204:211], v[216:219], v240, v241 op_sel_hi:[0,0,0] cbsz:4
	v_mul_f32_e32 v193, v254, v254
	v_fmac_f32_e32 v192, v253, v253
	v_fmac_f32_e32 v193, v255, v255
	v_and_b32_e32 v204, v186, v235
	v_and_b32_e32 v205, v186, v236
	v_and_b32_e32 v206, v186, v237
	v_and_b32_e32 v207, v186, v238
	v_and_b32_e32 v208, v187, v235
	v_and_b32_e32 v209, v187, v236
	v_and_b32_e32 v210, v187, v237
	v_and_b32_e32 v211, v187, v238
	v_mfma_scale_f32_16x16x128_f8f6f4 v[216:219], v[112:115], v[144:151], v[216:219], v240, v241 op_sel_hi:[0,0,0] cbsz:4
	v_cvt_pk_bf16_f32 v250, v252, v253
	v_cvt_pk_bf16_f32 v251, v254, v255
	v_add_f32_e32 v192, v192, v193
	v_and_b32_e32 v144, v188, v235
	v_and_b32_e32 v145, v188, v236
	v_and_b32_e32 v146, v188, v237
	v_and_b32_e32 v147, v188, v238
	v_and_b32_e32 v148, v189, v235
	v_and_b32_e32 v149, v189, v236
	v_and_b32_e32 v150, v189, v237
	v_and_b32_e32 v151, v189, v238
	v_mfma_scale_f32_16x16x128_f8f6f4 v[216:219], v[116:119], v[204:211], v[216:219], v240, v241 op_sel_hi:[0,0,0] cbsz:4
	v_add_f32_e32 v226, v226, v192
	v_and_b32_e32 v204, v190, v235
	v_and_b32_e32 v205, v190, v236
	v_and_b32_e32 v206, v190, v237
	v_and_b32_e32 v207, v190, v238
	v_and_b32_e32 v208, v191, v235
	v_and_b32_e32 v209, v191, v236
	v_and_b32_e32 v210, v191, v237
	v_and_b32_e32 v211, v191, v238
	v_mfma_scale_f32_16x16x128_f8f6f4 v[216:219], v[120:123], v[144:151], v[216:219], v240, v241 op_sel_hi:[0,0,0] cbsz:4
	s_nop 0
	v_mfma_scale_f32_16x16x128_f8f6f4 v[216:219], v[124:127], v[204:211], v[216:219], v240, v241 op_sel_hi:[0,0,0] cbsz:4
	s_lshl_b32 s64, s0, 9
	s_add_u32 s64, s64, 0x6000
	s_add_u32 s76, s28, s64
	s_addc_u32 s77, s29, 0
	global_store_dwordx2 v239, v[250:251], s[76:77]
	s_add_u32 s0, s0, 1
	s_lshl_b32 s1, s0, 21
	s_add_u32 s60, s1, 0x200000
	s_cmp_ge_u32 s0, 3
	s_movk_i32 s65, 0x2000
	s_cselect_b32 s64, s65, 0x1000
	v_mov_b32_e32 v234, v247
	v_add_u32_e32 v247, s64, v233
	s_cmp_lt_u32 s0, 8
	s_cbranch_scc1 .LpgL0_vloop
	s_waitcnt vmcnt(0)
	s_nop 15
	v_lshlrev_b32_e32 v252, 16, v230
	v_and_b32_e32 v253, 0xffff0000, v230
	v_lshlrev_b32_e32 v254, 16, v231
	v_and_b32_e32 v255, 0xffff0000, v231
	v_add_f32_e32 v252, v216, v252
	v_add_f32_e32 v253, v217, v253
	v_add_f32_e32 v254, v218, v254
	v_add_f32_e32 v255, v219, v255
	v_mul_f32_e32 v192, v252, v252
	v_mul_f32_e32 v193, v254, v254
	v_fmac_f32_e32 v192, v253, v253
	v_fmac_f32_e32 v193, v255, v255
	v_cvt_pk_bf16_f32 v250, v252, v253
	v_cvt_pk_bf16_f32 v251, v254, v255
	v_add_f32_e32 v192, v192, v193
	v_add_f32_e32 v227, v227, v192
	s_lshl_b32 s64, s0, 9
	s_add_u32 s64, s64, 0x6e00
	s_add_u32 s76, s28, s64
	s_addc_u32 s77, s29, 0
	global_store_dwordx2 v239, v[250:251], s[76:77]
	s_nop 1
	v_add_f32_dpp v220, v220, v220 quad_perm:[1,0,3,2] row_mask:0xf bank_mask:0xf bound_ctrl:1
	s_nop 1
	v_add_f32_dpp v220, v220, v220 quad_perm:[2,3,0,1] row_mask:0xf bank_mask:0xf bound_ctrl:1
	s_nop 1
	v_add_f32_dpp v220, v220, v220 row_half_mirror row_mask:0xf bank_mask:0xf bound_ctrl:1
	s_nop 1
	v_add_f32_dpp v220, v220, v220 row_mirror row_mask:0xf bank_mask:0xf bound_ctrl:1
	v_mov_b32_e32 v249, v220
	s_nop 1
	v_permlane16_swap_b32_e32 v220, v249
	v_add_f32_e32 v220, v220, v249
	v_mov_b32_e32 v249, v220
	s_nop 1
	v_permlane32_swap_b32_e32 v220, v249
	v_add_f32_e32 v220, v220, v249
	s_nop 1
	v_add_f32_dpp v221, v221, v221 quad_perm:[1,0,3,2] row_mask:0xf bank_mask:0xf bound_ctrl:1
	s_nop 1
	v_add_f32_dpp v221, v221, v221 quad_perm:[2,3,0,1] row_mask:0xf bank_mask:0xf bound_ctrl:1
	s_nop 1
	v_add_f32_dpp v221, v221, v221 row_half_mirror row_mask:0xf bank_mask:0xf bound_ctrl:1
	s_nop 1
	v_add_f32_dpp v221, v221, v221 row_mirror row_mask:0xf bank_mask:0xf bound_ctrl:1
	v_mov_b32_e32 v249, v221
	s_nop 1
	v_permlane16_swap_b32_e32 v221, v249
	v_add_f32_e32 v221, v221, v249
	v_mov_b32_e32 v249, v221
	s_nop 1
	v_permlane32_swap_b32_e32 v221, v249
	v_add_f32_e32 v221, v221, v249
	s_nop 1
	v_add_f32_dpp v222, v222, v222 quad_perm:[1,0,3,2] row_mask:0xf bank_mask:0xf bound_ctrl:1
	s_nop 1
	v_add_f32_dpp v222, v222, v222 quad_perm:[2,3,0,1] row_mask:0xf bank_mask:0xf bound_ctrl:1
	s_nop 1
	v_add_f32_dpp v222, v222, v222 row_half_mirror row_mask:0xf bank_mask:0xf bound_ctrl:1
	s_nop 1
	v_add_f32_dpp v222, v222, v222 row_mirror row_mask:0xf bank_mask:0xf bound_ctrl:1
	v_mov_b32_e32 v249, v222
	s_nop 1
	v_permlane16_swap_b32_e32 v222, v249
	v_add_f32_e32 v222, v222, v249
	v_mov_b32_e32 v249, v222
	s_nop 1
	v_permlane32_swap_b32_e32 v222, v249
	v_add_f32_e32 v222, v222, v249
	s_nop 1
	v_add_f32_dpp v223, v223, v223 quad_perm:[1,0,3,2] row_mask:0xf bank_mask:0xf bound_ctrl:1
	s_nop 1
	v_add_f32_dpp v223, v223, v223 quad_perm:[2,3,0,1] row_mask:0xf bank_mask:0xf bound_ctrl:1
	s_nop 1
	v_add_f32_dpp v223, v223, v223 row_half_mirror row_mask:0xf bank_mask:0xf bound_ctrl:1
	s_nop 1
	v_add_f32_dpp v223, v223, v223 row_mirror row_mask:0xf bank_mask:0xf bound_ctrl:1
	v_mov_b32_e32 v249, v223
	s_nop 1
	v_permlane16_swap_b32_e32 v223, v249
	v_add_f32_e32 v223, v223, v249
	v_mov_b32_e32 v249, v223
	s_nop 1
	v_permlane32_swap_b32_e32 v223, v249
	v_add_f32_e32 v223, v223, v249
	s_nop 1
	v_add_f32_dpp v224, v224, v224 quad_perm:[1,0,3,2] row_mask:0xf bank_mask:0xf bound_ctrl:1
	s_nop 1
	v_add_f32_dpp v224, v224, v224 quad_perm:[2,3,0,1] row_mask:0xf bank_mask:0xf bound_ctrl:1
	s_nop 1
	v_add_f32_dpp v224, v224, v224 row_half_mirror row_mask:0xf bank_mask:0xf bound_ctrl:1
	s_nop 1
	v_add_f32_dpp v224, v224, v224 row_mirror row_mask:0xf bank_mask:0xf bound_ctrl:1
	v_mov_b32_e32 v249, v224
	s_nop 1
	v_permlane16_swap_b32_e32 v224, v249
	v_add_f32_e32 v224, v224, v249
	v_mov_b32_e32 v249, v224
	s_nop 1
	v_permlane32_swap_b32_e32 v224, v249
	v_add_f32_e32 v224, v224, v249
	s_nop 1
	v_add_f32_dpp v225, v225, v225 quad_perm:[1,0,3,2] row_mask:0xf bank_mask:0xf bound_ctrl:1
	s_nop 1
	v_add_f32_dpp v225, v225, v225 quad_perm:[2,3,0,1] row_mask:0xf bank_mask:0xf bound_ctrl:1
	s_nop 1
	v_add_f32_dpp v225, v225, v225 row_half_mirror row_mask:0xf bank_mask:0xf bound_ctrl:1
	s_nop 1
	v_add_f32_dpp v225, v225, v225 row_mirror row_mask:0xf bank_mask:0xf bound_ctrl:1
	v_mov_b32_e32 v249, v225
	s_nop 1
	v_permlane16_swap_b32_e32 v225, v249
	v_add_f32_e32 v225, v225, v249
	v_mov_b32_e32 v249, v225
	s_nop 1
	v_permlane32_swap_b32_e32 v225, v249
	v_add_f32_e32 v225, v225, v249
	s_nop 1
	v_add_f32_dpp v226, v226, v226 quad_perm:[1,0,3,2] row_mask:0xf bank_mask:0xf bound_ctrl:1
	s_nop 1
	v_add_f32_dpp v226, v226, v226 quad_perm:[2,3,0,1] row_mask:0xf bank_mask:0xf bound_ctrl:1
	s_nop 1
	v_add_f32_dpp v226, v226, v226 row_half_mirror row_mask:0xf bank_mask:0xf bound_ctrl:1
	s_nop 1
	v_add_f32_dpp v226, v226, v226 row_mirror row_mask:0xf bank_mask:0xf bound_ctrl:1
	v_mov_b32_e32 v249, v226
	s_nop 1
	v_permlane16_swap_b32_e32 v226, v249
	v_add_f32_e32 v226, v226, v249
	v_mov_b32_e32 v249, v226
	s_nop 1
	v_permlane32_swap_b32_e32 v226, v249
	v_add_f32_e32 v226, v226, v249
	s_nop 1
	v_add_f32_dpp v227, v227, v227 quad_perm:[1,0,3,2] row_mask:0xf bank_mask:0xf bound_ctrl:1
	s_nop 1
	v_add_f32_dpp v227, v227, v227 quad_perm:[2,3,0,1] row_mask:0xf bank_mask:0xf bound_ctrl:1
	s_nop 1
	v_add_f32_dpp v227, v227, v227 row_half_mirror row_mask:0xf bank_mask:0xf bound_ctrl:1
	s_nop 1
	v_add_f32_dpp v227, v227, v227 row_mirror row_mask:0xf bank_mask:0xf bound_ctrl:1
	v_mov_b32_e32 v249, v227
	s_nop 1
	v_permlane16_swap_b32_e32 v227, v249
	v_add_f32_e32 v227, v227, v249
	v_mov_b32_e32 v249, v227
	s_nop 1
	v_permlane32_swap_b32_e32 v227, v249
	v_add_f32_e32 v227, v227, v249
	s_mov_b64 s[78:79], exec
	s_mov_b64 exec, s[10:11]
	global_store_dword v246, v220, s[44:45] offset:0
	global_store_dword v246, v221, s[44:45] offset:4
	global_store_dword v246, v222, s[44:45] offset:8
	global_store_dword v246, v223, s[44:45] offset:12
	global_store_dword v246, v224, s[44:45] offset:16
	global_store_dword v246, v225, s[44:45] offset:20
	global_store_dword v246, v226, s[44:45] offset:24
	global_store_dword v246, v227, s[44:45] offset:28
	s_mov_b64 exec, s[78:79]
	s_add_u32 s63, s63, s90
	s_cmpk_lt_i32 s63, 0x800
	s_cbranch_scc1 .LpgL0_group

.LBB0_1075:
	s_cmp_lt_i32 s56, 16
	s_cselect_b64 s[0:1], -1, 0
	s_and_b64 s[0:1], s[0:1], s[4:5]
	s_andn2_b64 vcc, exec, s[0:1]
	s_cbranch_vccnz .LBB0_1083
	s_cmpk_gt_i32 s33, 0x7ff
	v_mbcnt_lo_u32_b32 v0, -1, 0
	v_mbcnt_hi_u32_b32 v0, -1, v0
	s_cbranch_scc1 .LBB0_1083
	s_mov_b32 s63, s33
.LpgL1_group:
	v_mbcnt_lo_u32_b32 v249, -1, 0
	v_mbcnt_hi_u32_b32 v249, -1, v249
	v_and_b32_e32 v250, 15, v249
	v_lshrrev_b32_e32 v251, 4, v249
	v_and_b32_e32 v252, 3, v250
	v_cmp_eq_u32_e64 s[4:5], 1, v252
	v_cmp_eq_u32_e64 s[6:7], 2, v252
	v_cmp_eq_u32_e64 s[8:9], 3, v252
	v_cmp_eq_u32_e64 s[10:11], 0, v249
	s_add_u32 s12, s54, 0x29800000
	s_addc_u32 s13, s55, 0
	s_and_b32 s13, s13, 0xffff
	s_mov_b32 s14, 0x2000000
	s_mov_b32 s15, 0x20000
	s_add_u32 s16, s54, 0x10000000
	s_addc_u32 s17, s55, 0
	s_and_b32 s17, s17, 0xffff
	s_mov_b32 s18, 0x1000000
	s_mov_b32 s19, 0x20000
	s_add_u32 s20, s54, 0x14000000
	s_addc_u32 s21, s55, 0
	s_and_b32 s21, s21, 0xffff
	s_mov_b32 s22, 0x1000000
	s_mov_b32 s23, 0x20000
	s_add_u32 s30, s54, 0xa0000
	s_addc_u32 s31, s55, 0
	s_add_u32 s34, s54, 0xe0000
	s_addc_u32 s35, s55, 0
	s_mov_b32 s94, 0xc3e00000
	s_mov_b32 s96, 0x800000
	s_mov_b32 s81, 0x1010101
	v_lshrrev_b32_e32 v253, 2, v250
	v_lshrrev_b32_e32 v254, 1, v251
	v_lshl_add_u32 v255, v253, 1, v254
	v_lshl_add_u32 v237, v255, 2, s91
	v_and_b32_e32 v255, 1, v251
	v_lshl_add_u32 v236, v255, 2, v252
	v_lshlrev_b32_e32 v236, 4, v236
	v_lshlrev_b32_e32 v254, 7, v254
	v_lshl_add_u32 v254, v252, 5, v254
	v_lshl_add_u32 v254, v255, 4, v254
	v_and_b32_e32 v253, 1, v253
	v_mov_b32_e32 v255, 0x7fff0000
	v_cmp_eq_u32_e32 vcc, 0, v253
	s_nop 1
	v_cndmask_b32_e32 v238, v255, v254, vcc
	v_cndmask_b32_e32 v239, v254, v255, vcc
	v_mov_b32_e32 v240, 0x7f7f7f7f
	v_mov_b32_e32 v255, 0x20202020
	v_cmp_gt_u32_e32 vcc, 8, v250
	s_nop 1
	v_cndmask_b32_e32 v241, v255, v240, vcc
	v_cndmask_b32_e32 v242, v240, v255, vcc
	v_lshrrev_b32_e32 v254, 3, v250
	v_lshl_add_u32 v254, v252, 1, v254
	v_lshl_add_u32 v255, v251, 1, v253
	v_lshl_add_u32 v244, v254, 3, v255
	v_lshlrev_b32_e32 v244, 2, v244
	v_add_u32_e32 v243, s91, v244
	v_and_b32_e32 v253, 3, v255
	v_lshrrev_b32_e32 v255, 2, v255
	v_lshl_add_u32 v253, v253, 1, v255
	v_lshl_add_u32 v253, v254, 3, v253
	v_lshlrev_b32_e32 v253, 2, v253
	v_add_u32_e32 v245, s91, v253
	v_add_u32_e32 v245, 0x1000, v245
	v_mov_b32_e32 v246, 0
	s_lshl_b32 s64, s63, 12
	s_add_u32 s24, s54, 0x28000000
	s_addc_u32 s25, s55, 0
	s_add_u32 s24, s24, s64
	s_addc_u32 s25, s25, 0
	s_lshl_b32 s64, s63, 12
	s_add_u32 s26, s54, 0x28800000
	s_addc_u32 s27, s55, 0
	s_add_u32 s26, s26, s64
	s_addc_u32 s27, s27, 0
	s_lshl_b32 s64, s63, 15
	s_add_u32 s28, s54, 0x18000000
	s_addc_u32 s29, s55, 0
	s_add_u32 s28, s28, s64
	s_addc_u32 s29, s29, 0
	s_lshl_b32 s64, s63, 5
	s_add_u32 s40, s54, 0x60000
	s_addc_u32 s41, s55, 0
	s_add_u32 s40, s40, s64
	s_addc_u32 s41, s41, 0
	s_lshl_b32 s64, s63, 5
	s_add_u32 s44, s54, 0x70000
	s_addc_u32 s45, s55, 0
	s_add_u32 s44, s44, s64
	s_addc_u32 s45, s45, 0
	s_lshl_b32 s64, s63, 16
	s_mov_b32 s46, s52
	s_mov_b32 s47, s53
	s_add_u32 s46, s46, s64
	s_addc_u32 s47, s47, 0
	s_lshl_b32 s61, s63, 14
	s_add_u32 s62, s61, 0x100
	v_mbcnt_lo_u32_b32 v253, -1, 0
	v_mbcnt_hi_u32_b32 v253, -1, v253
	v_lshlrev_b32_e32 v253, 2, v253
	global_load_dword v0, v253, s[24:25] offset:0
	global_load_dword v1, v253, s[24:25] offset:256
	global_load_dword v2, v253, s[24:25] offset:512
	global_load_dword v3, v253, s[24:25] offset:768
	global_load_dword v4, v253, s[24:25] offset:1024
	global_load_dword v5, v253, s[24:25] offset:1280
	global_load_dword v6, v253, s[24:25] offset:1536
	global_load_dword v7, v253, s[24:25] offset:1792
	global_load_dword v8, v253, s[24:25] offset:2048
	global_load_dword v9, v253, s[24:25] offset:2304
	global_load_dword v10, v253, s[24:25] offset:2560
	global_load_dword v11, v253, s[24:25] offset:2816
	global_load_dword v12, v253, s[24:25] offset:3072
	global_load_dword v13, v253, s[24:25] offset:3328
	global_load_dword v14, v253, s[24:25] offset:3584
	global_load_dword v15, v253, s[24:25] offset:3840
	v_add_u32_e32 v254, s91, v253
	s_waitcnt vmcnt(0)
	ds_write_b32 v254, v0 offset:0
	ds_write_b32 v254, v1 offset:256
	ds_write_b32 v254, v2 offset:512
	ds_write_b32 v254, v3 offset:768
	ds_write_b32 v254, v4 offset:1024
	ds_write_b32 v254, v5 offset:1280
	ds_write_b32 v254, v6 offset:1536
	ds_write_b32 v254, v7 offset:1792
	ds_write_b32 v254, v8 offset:2048
	ds_write_b32 v254, v9 offset:2304
	ds_write_b32 v254, v10 offset:2560
	ds_write_b32 v254, v11 offset:2816
	ds_write_b32 v254, v12 offset:3072
	ds_write_b32 v254, v13 offset:3328
	ds_write_b32 v254, v14 offset:3584
	ds_write_b32 v254, v15 offset:3840
	s_waitcnt lgkmcnt(0)
	v_mov_b32_e32 v204, 0
	v_mov_b32_e32 v205, 0
	v_mov_b32_e32 v206, 0
	v_mov_b32_e32 v207, 0
	v_mov_b32_e32 v208, 0
	v_mov_b32_e32 v209, 0
	v_mov_b32_e32 v210, 0
	v_mov_b32_e32 v211, 0
	v_mov_b32_e32 v212, 0
	v_mov_b32_e32 v213, 0
	v_mov_b32_e32 v214, 0
	v_mov_b32_e32 v215, 0
	v_mov_b32_e32 v216, 0
	v_mov_b32_e32 v217, 0
	v_mov_b32_e32 v218, 0
	v_mov_b32_e32 v219, 0
	v_mov_b32_e32 v176, 0
	v_mov_b32_e32 v177, 0
	v_mov_b32_e32 v178, 0
	v_mov_b32_e32 v179, 0
	v_mov_b32_e32 v180, 0
	v_mov_b32_e32 v181, 0
	v_mov_b32_e32 v182, 0
	v_mov_b32_e32 v183, 0
	v_mov_b32_e32 v184, 0
	v_mov_b32_e32 v185, 0
	v_mov_b32_e32 v186, 0
	v_mov_b32_e32 v187, 0
	v_mov_b32_e32 v188, 0
	v_mov_b32_e32 v189, 0
	v_mov_b32_e32 v190, 0
	v_mov_b32_e32 v191, 0
	s_mov_b32 s0, 0
	s_mov_b32 s1, 0
	s_mov_b32 s60, 0x200000
	ds_read_b32 v144, v237 offset:0
	ds_read_b32 v145, v237 offset:32
	ds_read_b32 v146, v237 offset:64
	ds_read_b32 v147, v237 offset:96
	ds_read_b32 v148, v237 offset:128
	ds_read_b32 v149, v237 offset:160
	ds_read_b32 v150, v237 offset:192
	ds_read_b32 v151, v237 offset:224
	s_waitcnt lgkmcnt(0)
	v_lshl_or_b32 v144, v144, 7, v236
	v_lshl_or_b32 v145, v145, 7, v236
	v_lshl_or_b32 v146, v146, 7, v236
	v_lshl_or_b32 v147, v147, 7, v236
	v_lshl_or_b32 v148, v148, 7, v236
	v_lshl_or_b32 v149, v149, 7, v236
	v_lshl_or_b32 v150, v150, 7, v236
	v_lshl_or_b32 v151, v151, 7, v236
	buffer_load_dwordx4 v[0:3], v144, s[16:19], s1 offen
	buffer_load_dwordx4 v[4:7], v145, s[16:19], s1 offen
	buffer_load_dwordx4 v[8:11], v146, s[16:19], s1 offen
	buffer_load_dwordx4 v[12:15], v147, s[16:19], s1 offen
	buffer_load_dwordx4 v[16:19], v148, s[16:19], s1 offen
	buffer_load_dwordx4 v[20:23], v149, s[16:19], s1 offen
	buffer_load_dwordx4 v[24:27], v150, s[16:19], s1 offen
	buffer_load_dwordx4 v[28:31], v151, s[16:19], s1 offen
	ds_read_b32 v144, v237 offset:256
	ds_read_b32 v145, v237 offset:288
	ds_read_b32 v146, v237 offset:320
	ds_read_b32 v147, v237 offset:352
	ds_read_b32 v148, v237 offset:384
	ds_read_b32 v149, v237 offset:416
	ds_read_b32 v150, v237 offset:448
	ds_read_b32 v151, v237 offset:480
	s_add_u32 s80, s61, 0x0
	buffer_load_dwordx4 v[128:131], v238, s[12:15], s80 offen
	buffer_load_dwordx4 v[132:135], v239, s[12:15], s80 offen
	s_waitcnt lgkmcnt(0)
	v_lshl_or_b32 v144, v144, 7, v236
	v_lshl_or_b32 v145, v145, 7, v236
	v_lshl_or_b32 v146, v146, 7, v236
	v_lshl_or_b32 v147, v147, 7, v236
	v_lshl_or_b32 v148, v148, 7, v236
	v_lshl_or_b32 v149, v149, 7, v236
	v_lshl_or_b32 v150, v150, 7, v236
	v_lshl_or_b32 v151, v151, 7, v236
	buffer_load_dwordx4 v[32:35], v144, s[16:19], s1 offen
	buffer_load_dwordx4 v[36:39], v145, s[16:19], s1 offen
	buffer_load_dwordx4 v[40:43], v146, s[16:19], s1 offen
	buffer_load_dwordx4 v[44:47], v147, s[16:19], s1 offen
	buffer_load_dwordx4 v[48:51], v148, s[16:19], s1 offen
	buffer_load_dwordx4 v[52:55], v149, s[16:19], s1 offen
	buffer_load_dwordx4 v[56:59], v150, s[16:19], s1 offen
	buffer_load_dwordx4 v[60:63], v151, s[16:19], s1 offen
	ds_read_b32 v144, v237 offset:512
	ds_read_b32 v145, v237 offset:544
	ds_read_b32 v146, v237 offset:576
	ds_read_b32 v147, v237 offset:608
	ds_read_b32 v148, v237 offset:640
	ds_read_b32 v149, v237 offset:672
	ds_read_b32 v150, v237 offset:704
	ds_read_b32 v151, v237 offset:736
	s_waitcnt lgkmcnt(0)
	v_lshl_or_b32 v144, v144, 7, v236
	v_lshl_or_b32 v145, v145, 7, v236
	v_lshl_or_b32 v146, v146, 7, v236
	v_lshl_or_b32 v147, v147, 7, v236
	v_lshl_or_b32 v148, v148, 7, v236
	v_lshl_or_b32 v149, v149, 7, v236
	v_lshl_or_b32 v150, v150, 7, v236
	v_lshl_or_b32 v151, v151, 7, v236
	buffer_load_dwordx4 v[64:67], v144, s[16:19], s1 offen
	buffer_load_dwordx4 v[68:71], v145, s[16:19], s1 offen
	buffer_load_dwordx4 v[72:75], v146, s[16:19], s1 offen
	buffer_load_dwordx4 v[76:79], v147, s[16:19], s1 offen
	buffer_load_dwordx4 v[80:83], v148, s[16:19], s1 offen
	buffer_load_dwordx4 v[84:87], v149, s[16:19], s1 offen
	buffer_load_dwordx4 v[88:91], v150, s[16:19], s1 offen
	buffer_load_dwordx4 v[92:95], v151, s[16:19], s1 offen
	ds_read_b32 v144, v237 offset:768
	ds_read_b32 v145, v237 offset:800
	ds_read_b32 v146, v237 offset:832
	ds_read_b32 v147, v237 offset:864
	ds_read_b32 v148, v237 offset:896
	ds_read_b32 v149, v237 offset:928
	ds_read_b32 v150, v237 offset:960
	ds_read_b32 v151, v237 offset:992

.LpgL1_vjoin:
	s_lshl_b32 s64, s0, 9
	s_add_u32 s64, s64, 0x1000
	s_add_u32 s70, s28, s64
	s_addc_u32 s71, s29, 0
	global_load_dwordx2 v[230:231], v239, s[70:71]
	s_waitcnt lgkmcnt(0)
	v_lshl_or_b32 v128, v128, 7, v232
	v_lshl_or_b32 v129, v129, 7, v232
	v_lshl_or_b32 v130, v130, 7, v232
	v_lshl_or_b32 v131, v131, 7, v232
	v_lshl_or_b32 v132, v132, 7, v232
	v_lshl_or_b32 v133, v133, 7, v232
	v_lshl_or_b32 v134, v134, 7, v232
	v_lshl_or_b32 v135, v135, 7, v232
	v_lshl_or_b32 v136, v136, 7, v232
	v_lshl_or_b32 v137, v137, 7, v232
	v_lshl_or_b32 v138, v138, 7, v232
	v_lshl_or_b32 v139, v139, 7, v232
	v_lshl_or_b32 v140, v140, 7, v232
	v_lshl_or_b32 v141, v141, 7, v232
	v_lshl_or_b32 v142, v142, 7, v232
	v_lshl_or_b32 v143, v143, 7, v232
	buffer_load_dwordx2 v[32:33], v128, s[20:23], s1 offen
	buffer_load_dwordx2 v[34:35], v129, s[20:23], s1 offen
	buffer_load_dwordx2 v[36:37], v130, s[20:23], s1 offen
	buffer_load_dwordx2 v[38:39], v131, s[20:23], s1 offen
	buffer_load_dwordx2 v[40:41], v132, s[20:23], s1 offen
	buffer_load_dwordx2 v[42:43], v133, s[20:23], s1 offen
	buffer_load_dwordx2 v[44:45], v134, s[20:23], s1 offen
	buffer_load_dwordx2 v[46:47], v135, s[20:23], s1 offen
	buffer_load_dwordx2 v[48:49], v136, s[20:23], s1 offen
	buffer_load_dwordx2 v[50:51], v137, s[20:23], s1 offen
	buffer_load_dwordx2 v[52:53], v138, s[20:23], s1 offen
	buffer_load_dwordx2 v[54:55], v139, s[20:23], s1 offen
	buffer_load_dwordx2 v[56:57], v140, s[20:23], s1 offen
	buffer_load_dwordx2 v[58:59], v141, s[20:23], s1 offen
	buffer_load_dwordx2 v[60:61], v142, s[20:23], s1 offen
	buffer_load_dwordx2 v[62:63], v143, s[20:23], s1 offen
	ds_read_b64 v[128:129], v233 offset:1536
	ds_read_b64 v[130:131], v233 offset:1568
	ds_read_b64 v[132:133], v233 offset:1600
	ds_read_b64 v[134:135], v233 offset:1632
	ds_read_b64 v[136:137], v233 offset:1664
	ds_read_b64 v[138:139], v233 offset:1696
	ds_read_b64 v[140:141], v233 offset:1728
	ds_read_b64 v[142:143], v233 offset:1760
	ds_read_b64 v[176:177], v234 offset:768
	ds_read_b64 v[178:179], v234 offset:800
	ds_read_b64 v[180:181], v234 offset:832
	ds_read_b64 v[182:183], v234 offset:864
	ds_read_b64 v[184:185], v234 offset:896
	ds_read_b64 v[186:187], v234 offset:928
	ds_read_b64 v[188:189], v234 offset:960
	ds_read_b64 v[190:191], v234 offset:992
	s_waitcnt vmcnt(52)
	v_and_b32_e32 v144, v160, v235
	v_and_b32_e32 v145, v160, v236
	v_and_b32_e32 v146, v160, v237
	v_and_b32_e32 v147, v160, v238
	v_and_b32_e32 v148, v161, v235
	v_and_b32_e32 v149, v161, v236
	v_and_b32_e32 v150, v161, v237
	v_and_b32_e32 v151, v161, v238
	v_and_b32_e32 v204, v162, v235
	v_and_b32_e32 v205, v162, v236
	v_and_b32_e32 v206, v162, v237
	v_and_b32_e32 v207, v162, v238
	v_and_b32_e32 v208, v163, v235
	v_and_b32_e32 v209, v163, v236
	v_and_b32_e32 v210, v163, v237
	v_and_b32_e32 v211, v163, v238
	v_mfma_scale_f32_16x16x128_f8f6f4 v[216:219], v[64:67], v[144:151], 0, v240, v241 op_sel_hi:[0,0,0] cbsz:4
	v_and_b32_e32 v144, v164, v235
	v_and_b32_e32 v145, v164, v236
	v_and_b32_e32 v146, v164, v237
	v_and_b32_e32 v147, v164, v238
	v_and_b32_e32 v148, v165, v235
	v_and_b32_e32 v149, v165, v236
	v_and_b32_e32 v150, v165, v237
	v_and_b32_e32 v151, v165, v238
	v_mfma_scale_f32_16x16x128_f8f6f4 v[216:219], v[68:71], v[204:211], v[216:219], v240, v241 op_sel_hi:[0,0,0] cbsz:4
	v_and_b32_e32 v204, v166, v235
	v_and_b32_e32 v205, v166, v236
	v_and_b32_e32 v206, v166, v237
	v_and_b32_e32 v207, v166, v238
	v_and_b32_e32 v208, v167, v235
	v_and_b32_e32 v209, v167, v236
	v_and_b32_e32 v210, v167, v237
	v_and_b32_e32 v211, v167, v238
	v_mfma_scale_f32_16x16x128_f8f6f4 v[216:219], v[72:75], v[144:151], v[216:219], v240, v241 op_sel_hi:[0,0,0] cbsz:4
	v_and_b32_e32 v144, v168, v235
	v_and_b32_e32 v145, v168, v236
	v_and_b32_e32 v146, v168, v237
	v_and_b32_e32 v147, v168, v238
	v_and_b32_e32 v148, v169, v235
	v_and_b32_e32 v149, v169, v236
	v_and_b32_e32 v150, v169, v237
	v_and_b32_e32 v151, v169, v238
	v_mfma_scale_f32_16x16x128_f8f6f4 v[216:219], v[76:79], v[204:211], v[216:219], v240, v241 op_sel_hi:[0,0,0] cbsz:4
	v_and_b32_e32 v204, v170, v235
	v_and_b32_e32 v205, v170, v236
	v_and_b32_e32 v206, v170, v237
	v_and_b32_e32 v207, v170, v238
	v_and_b32_e32 v208, v171, v235
	v_and_b32_e32 v209, v171, v236
	v_and_b32_e32 v210, v171, v237
	v_and_b32_e32 v211, v171, v238
	v_mfma_scale_f32_16x16x128_f8f6f4 v[216:219], v[80:83], v[144:151], v[216:219], v240, v241 op_sel_hi:[0,0,0] cbsz:4
	v_and_b32_e32 v144, v172, v235
	v_and_b32_e32 v145, v172, v236
	v_and_b32_e32 v146, v172, v237
	v_and_b32_e32 v147, v172, v238
	v_and_b32_e32 v148, v173, v235
	v_and_b32_e32 v149, v173, v236
	v_and_b32_e32 v150, v173, v237
	v_and_b32_e32 v151, v173, v238
	v_mfma_scale_f32_16x16x128_f8f6f4 v[216:219], v[84:87], v[204:211], v[216:219], v240, v241 op_sel_hi:[0,0,0] cbsz:4
	v_and_b32_e32 v204, v174, v235
	v_and_b32_e32 v205, v174, v236
	v_and_b32_e32 v206, v174, v237
	v_and_b32_e32 v207, v174, v238
	v_and_b32_e32 v208, v175, v235
	v_and_b32_e32 v209, v175, v236
	v_and_b32_e32 v210, v175, v237
	v_and_b32_e32 v211, v175, v238
	v_mfma_scale_f32_16x16x128_f8f6f4 v[216:219], v[88:91], v[144:151], v[216:219], v240, v241 op_sel_hi:[0,0,0] cbsz:4
	s_nop 0
	v_mfma_scale_f32_16x16x128_f8f6f4 v[216:219], v[92:95], v[204:211], v[216:219], v240, v241 op_sel_hi:[0,0,0] cbsz:4
	s_waitcnt lgkmcnt(0)
	v_lshl_or_b32 v128, v128, 7, v232
	v_lshl_or_b32 v129, v129, 7, v232
	v_lshl_or_b32 v130, v130, 7, v232
	v_lshl_or_b32 v131, v131, 7, v232
	v_lshl_or_b32 v132, v132, 7, v232
	v_lshl_or_b32 v133, v133, 7, v232
	v_lshl_or_b32 v134, v134, 7, v232
	v_lshl_or_b32 v135, v135, 7, v232
	v_lshl_or_b32 v136, v136, 7, v232
	v_lshl_or_b32 v137, v137, 7, v232
	v_lshl_or_b32 v138, v138, 7, v232
	v_lshl_or_b32 v139, v139, 7, v232
	v_lshl_or_b32 v140, v140, 7, v232
	v_lshl_or_b32 v141, v141, 7, v232
	v_lshl_or_b32 v142, v142, 7, v232
	v_lshl_or_b32 v143, v143, 7, v232
	buffer_load_dwordx2 v[64:65], v128, s[20:23], s1 offen
	buffer_load_dwordx2 v[66:67], v129, s[20:23], s1 offen
	buffer_load_dwordx2 v[68:69], v130, s[20:23], s1 offen
	buffer_load_dwordx2 v[70:71], v131, s[20:23], s1 offen
	buffer_load_dwordx2 v[72:73], v132, s[20:23], s1 offen
	buffer_load_dwordx2 v[74:75], v133, s[20:23], s1 offen
	buffer_load_dwordx2 v[76:77], v134, s[20:23], s1 offen
	buffer_load_dwordx2 v[78:79], v135, s[20:23], s1 offen
	buffer_load_dwordx2 v[80:81], v136, s[20:23], s1 offen
	buffer_load_dwordx2 v[82:83], v137, s[20:23], s1 offen
	buffer_load_dwordx2 v[84:85], v138, s[20:23], s1 offen
	buffer_load_dwordx2 v[86:87], v139, s[20:23], s1 offen
	buffer_load_dwordx2 v[88:89], v140, s[20:23], s1 offen
	buffer_load_dwordx2 v[90:91], v141, s[20:23], s1 offen
	buffer_load_dwordx2 v[92:93], v142, s[20:23], s1 offen
	buffer_load_dwordx2 v[94:95], v143, s[20:23], s1 offen
	ds_read_b64 v[128:129], v233 offset:1792
	ds_read_b64 v[130:131], v233 offset:1824
	ds_read_b64 v[132:133], v233 offset:1856
	ds_read_b64 v[134:135], v233 offset:1888
	ds_read_b64 v[136:137], v233 offset:1920
	ds_read_b64 v[138:139], v233 offset:1952
	ds_read_b64 v[140:141], v233 offset:1984
	ds_read_b64 v[142:143], v233 offset:2016
	ds_read_b64 v[160:161], v234 offset:1024
	ds_read_b64 v[162:163], v234 offset:1056
	ds_read_b64 v[164:165], v234 offset:1088
	ds_read_b64 v[166:167], v234 offset:1120
	ds_read_b64 v[168:169], v234 offset:1152
	ds_read_b64 v[170:171], v234 offset:1184
	ds_read_b64 v[172:173], v234 offset:1216
	ds_read_b64 v[174:175], v234 offset:1248
	s_waitcnt vmcnt(50)
	v_and_b32_e32 v144, v176, v235
	v_and_b32_e32 v145, v176, v236
	v_and_b32_e32 v146, v176, v237
	v_and_b32_e32 v147, v176, v238
	v_and_b32_e32 v148, v177, v235
	v_and_b32_e32 v149, v177, v236
	v_and_b32_e32 v150, v177, v237
	v_and_b32_e32 v151, v177, v238
	v_and_b32_e32 v204, v178, v235
	v_and_b32_e32 v205, v178, v236
	v_and_b32_e32 v206, v178, v237
	v_and_b32_e32 v207, v178, v238
	v_and_b32_e32 v208, v179, v235
	v_and_b32_e32 v209, v179, v236
	v_and_b32_e32 v210, v179, v237
	v_and_b32_e32 v211, v179, v238
	v_mfma_scale_f32_16x16x128_f8f6f4 v[216:219], v[96:99], v[144:151], v[216:219], v240, v241 op_sel_hi:[0,0,0] cbsz:4
	v_lshlrev_b32_e32 v252, 16, v228
	v_and_b32_e32 v253, 0xffff0000, v228
	v_lshlrev_b32_e32 v254, 16, v229
	v_and_b32_e32 v144, v180, v235
	v_and_b32_e32 v145, v180, v236
	v_and_b32_e32 v146, v180, v237
	v_and_b32_e32 v147, v180, v238
	v_and_b32_e32 v148, v181, v235
	v_and_b32_e32 v149, v181, v236
	v_and_b32_e32 v150, v181, v237
	v_and_b32_e32 v151, v181, v238
	v_mfma_scale_f32_16x16x128_f8f6f4 v[216:219], v[100:103], v[204:211], v[216:219], v240, v241 op_sel_hi:[0,0,0] cbsz:4
	v_and_b32_e32 v255, 0xffff0000, v229
	v_add_f32_e32 v252, v212, v252
	v_add_f32_e32 v253, v213, v253
	v_and_b32_e32 v204, v182, v235
	v_and_b32_e32 v205, v182, v236
	v_and_b32_e32 v206, v182, v237
	v_and_b32_e32 v207, v182, v238
	v_and_b32_e32 v208, v183, v235
	v_and_b32_e32 v209, v183, v236
	v_and_b32_e32 v210, v183, v237
	v_and_b32_e32 v211, v183, v238
	v_mfma_scale_f32_16x16x128_f8f6f4 v[216:219], v[104:107], v[144:151], v[216:219], v240, v241 op_sel_hi:[0,0,0] cbsz:4
	v_add_f32_e32 v254, v214, v254
	v_add_f32_e32 v255, v215, v255
	v_mul_f32_e32 v192, v252, v252
	v_and_b32_e32 v144, v184, v235
	v_and_b32_e32 v145, v184, v236
	v_and_b32_e32 v146, v184, v237
	v_and_b32_e32 v147, v184, v238
	v_and_b32_e32 v148, v185, v235
	v_and_b32_e32 v149, v185, v236
	v_and_b32_e32 v150, v185, v237
	v_and_b32_e32 v151, v185, v238
	v_mfma_scale_f32_16x16x128_f8f6f4 v[216:219], v[108:111], v[204:211], v[216:219], v240, v241 op_sel_hi:[0,0,0] cbsz:4
	v_mul_f32_e32 v193, v254, v254
	v_fmac_f32_e32 v192, v253, v253
	v_fmac_f32_e32 v193, v255, v255
	v_and_b32_e32 v204, v186, v235
	v_and_b32_e32 v205, v186, v236
	v_and_b32_e32 v206, v186, v237
	v_and_b32_e32 v207, v186, v238
	v_and_b32_e32 v208, v187, v235
	v_and_b32_e32 v209, v187, v236
	v_and_b32_e32 v210, v187, v237
	v_and_b32_e32 v211, v187, v238
	v_mfma_scale_f32_16x16x128_f8f6f4 v[216:219], v[112:115], v[144:151], v[216:219], v240, v241 op_sel_hi:[0,0,0] cbsz:4
	v_cvt_pk_bf16_f32 v250, v252, v253
	v_cvt_pk_bf16_f32 v251, v254, v255
	v_add_f32_e32 v192, v192, v193
	v_and_b32_e32 v144, v188, v235
	v_and_b32_e32 v145, v188, v236
	v_and_b32_e32 v146, v188, v237
	v_and_b32_e32 v147, v188, v238
	v_and_b32_e32 v148, v189, v235
	v_and_b32_e32 v149, v189, v236
	v_and_b32_e32 v150, v189, v237
	v_and_b32_e32 v151, v189, v238
	v_mfma_scale_f32_16x16x128_f8f6f4 v[216:219], v[116:119], v[204:211], v[216:219], v240, v241 op_sel_hi:[0,0,0] cbsz:4
	v_add_f32_e32 v220, v220, v192
	v_and_b32_e32 v204, v190, v235
	v_and_b32_e32 v205, v190, v236
	v_and_b32_e32 v206, v190, v237
	v_and_b32_e32 v207, v190, v238
	v_and_b32_e32 v208, v191, v235
	v_and_b32_e32 v209, v191, v236
	v_and_b32_e32 v210, v191, v237
	v_and_b32_e32 v211, v191, v238
	v_mfma_scale_f32_16x16x128_f8f6f4 v[216:219], v[120:123], v[144:151], v[216:219], v240, v241 op_sel_hi:[0,0,0] cbsz:4
	s_nop 0
	v_mfma_scale_f32_16x16x128_f8f6f4 v[216:219], v[124:127], v[204:211], v[216:219], v240, v241 op_sel_hi:[0,0,0] cbsz:4
	s_lshl_b32 s64, s0, 9
	s_add_u32 s64, s64, 0x0
	s_add_u32 s76, s28, s64
	s_addc_u32 s77, s29, 0
	global_store_dwordx2 v239, v[250:251], s[76:77]
	s_lshl_b32 s64, s0, 9
	s_add_u32 s64, s64, 0x2000
	s_add_u32 s70, s28, s64
	s_addc_u32 s71, s29, 0
	global_load_dwordx2 v[228:229], v239, s[70:71]
	s_waitcnt lgkmcnt(0)
	v_lshl_or_b32 v128, v128, 7, v232
	v_lshl_or_b32 v129, v129, 7, v232
	v_lshl_or_b32 v130, v130, 7, v232
	v_lshl_or_b32 v131, v131, 7, v232
	v_lshl_or_b32 v132, v132, 7, v232
	v_lshl_or_b32 v133, v133, 7, v232
	v_lshl_or_b32 v134, v134, 7, v232
	v_lshl_or_b32 v135, v135, 7, v232
	v_lshl_or_b32 v136, v136, 7, v232
	v_lshl_or_b32 v137, v137, 7, v232
	v_lshl_or_b32 v138, v138, 7, v232
	v_lshl_or_b32 v139, v139, 7, v232
	v_lshl_or_b32 v140, v140, 7, v232
	v_lshl_or_b32 v141, v141, 7, v232
	v_lshl_or_b32 v142, v142, 7, v232
	v_lshl_or_b32 v143, v143, 7, v232
	buffer_load_dwordx2 v[96:97], v128, s[20:23], s1 offen
	buffer_load_dwordx2 v[98:99], v129, s[20:23], s1 offen
	buffer_load_dwordx2 v[100:101], v130, s[20:23], s1 offen
	buffer_load_dwordx2 v[102:103], v131, s[20:23], s1 offen
	buffer_load_dwordx2 v[104:105], v132, s[20:23], s1 offen
	buffer_load_dwordx2 v[106:107], v133, s[20:23], s1 offen
	buffer_load_dwordx2 v[108:109], v134, s[20:23], s1 offen
	buffer_load_dwordx2 v[110:111], v135, s[20:23], s1 offen
	buffer_load_dwordx2 v[112:113], v136, s[20:23], s1 offen
	buffer_load_dwordx2 v[114:115], v137, s[20:23], s1 offen
	buffer_load_dwordx2 v[116:117], v138, s[20:23], s1 offen
	buffer_load_dwordx2 v[118:119], v139, s[20:23], s1 offen
	buffer_load_dwordx2 v[120:121], v140, s[20:23], s1 offen
	buffer_load_dwordx2 v[122:123], v141, s[20:23], s1 offen
	buffer_load_dwordx2 v[124:125], v142, s[20:23], s1 offen
	buffer_load_dwordx2 v[126:127], v143, s[20:23], s1 offen
	ds_read_b64 v[128:129], v233 offset:2048
	ds_read_b64 v[130:131], v233 offset:2080
	ds_read_b64 v[132:133], v233 offset:2112
	ds_read_b64 v[134:135], v233 offset:2144
	ds_read_b64 v[136:137], v233 offset:2176
	ds_read_b64 v[138:139], v233 offset:2208
	ds_read_b64 v[140:141], v233 offset:2240
	ds_read_b64 v[142:143], v233 offset:2272
	ds_read_b64 v[176:177], v234 offset:1280
	ds_read_b64 v[178:179], v234 offset:1312
	ds_read_b64 v[180:181], v234 offset:1344
	ds_read_b64 v[182:183], v234 offset:1376
	ds_read_b64 v[184:185], v234 offset:1408
	ds_read_b64 v[186:187], v234 offset:1440
	ds_read_b64 v[188:189], v234 offset:1472
	ds_read_b64 v[190:191], v234 offset:1504
	s_waitcnt vmcnt(52)
	v_and_b32_e32 v144, v160, v235
	v_and_b32_e32 v145, v160, v236
	v_and_b32_e32 v146, v160, v237
	v_and_b32_e32 v147, v160, v238
	v_and_b32_e32 v148, v161, v235
	v_and_b32_e32 v149, v161, v236
	v_and_b32_e32 v150, v161, v237
	v_and_b32_e32 v151, v161, v238
	v_and_b32_e32 v204, v162, v235
	v_and_b32_e32 v205, v162, v236
	v_and_b32_e32 v206, v162, v237
	v_and_b32_e32 v207, v162, v238
	v_and_b32_e32 v208, v163, v235
	v_and_b32_e32 v209, v163, v236
	v_and_b32_e32 v210, v163, v237
	v_and_b32_e32 v211, v163, v238
	v_mfma_scale_f32_16x16x128_f8f6f4 v[212:215], v[0:3], v[144:151], 0, v240, v241 op_sel_hi:[0,0,0] cbsz:4
	v_and_b32_e32 v144, v164, v235
	v_and_b32_e32 v145, v164, v236
	v_and_b32_e32 v146, v164, v237
	v_and_b32_e32 v147, v164, v238
	v_and_b32_e32 v148, v165, v235
	v_and_b32_e32 v149, v165, v236
	v_and_b32_e32 v150, v165, v237
	v_and_b32_e32 v151, v165, v238
	v_mfma_scale_f32_16x16x128_f8f6f4 v[212:215], v[4:7], v[204:211], v[212:215], v240, v241 op_sel_hi:[0,0,0] cbsz:4
	v_and_b32_e32 v204, v166, v235
	v_and_b32_e32 v205, v166, v236
	v_and_b32_e32 v206, v166, v237
	v_and_b32_e32 v207, v166, v238
	v_and_b32_e32 v208, v167, v235
	v_and_b32_e32 v209, v167, v236
	v_and_b32_e32 v210, v167, v237
	v_and_b32_e32 v211, v167, v238
	v_mfma_scale_f32_16x16x128_f8f6f4 v[212:215], v[8:11], v[144:151], v[212:215], v240, v241 op_sel_hi:[0,0,0] cbsz:4
	v_and_b32_e32 v144, v168, v235
	v_and_b32_e32 v145, v168, v236
	v_and_b32_e32 v146, v168, v237
	v_and_b32_e32 v147, v168, v238
	v_and_b32_e32 v148, v169, v235
	v_and_b32_e32 v149, v169, v236
	v_and_b32_e32 v150, v169, v237
	v_and_b32_e32 v151, v169, v238
	v_mfma_scale_f32_16x16x128_f8f6f4 v[212:215], v[12:15], v[204:211], v[212:215], v240, v241 op_sel_hi:[0,0,0] cbsz:4
	v_and_b32_e32 v204, v170, v235
	v_and_b32_e32 v205, v170, v236
	v_and_b32_e32 v206, v170, v237
	v_and_b32_e32 v207, v170, v238
	v_and_b32_e32 v208, v171, v235
	v_and_b32_e32 v209, v171, v236
	v_and_b32_e32 v210, v171, v237
	v_and_b32_e32 v211, v171, v238
	v_mfma_scale_f32_16x16x128_f8f6f4 v[212:215], v[16:19], v[144:151], v[212:215], v240, v241 op_sel_hi:[0,0,0] cbsz:4
	v_and_b32_e32 v144, v172, v235
	v_and_b32_e32 v145, v172, v236
	v_and_b32_e32 v146, v172, v237
	v_and_b32_e32 v147, v172, v238
	v_and_b32_e32 v148, v173, v235
	v_and_b32_e32 v149, v173, v236
	v_and_b32_e32 v150, v173, v237
	v_and_b32_e32 v151, v173, v238
	v_mfma_scale_f32_16x16x128_f8f6f4 v[212:215], v[20:23], v[204:211], v[212:215], v240, v241 op_sel_hi:[0,0,0] cbsz:4
	v_and_b32_e32 v204, v174, v235
	v_and_b32_e32 v205, v174, v236
	v_and_b32_e32 v206, v174, v237
	v_and_b32_e32 v207, v174, v238
	v_and_b32_e32 v208, v175, v235
	v_and_b32_e32 v209, v175, v236
	v_and_b32_e32 v210, v175, v237
	v_and_b32_e32 v211, v175, v238
	v_mfma_scale_f32_16x16x128_f8f6f4 v[212:215], v[24:27], v[144:151], v[212:215], v240, v241 op_sel_hi:[0,0,0] cbsz:4
	s_nop 0
	v_mfma_scale_f32_16x16x128_f8f6f4 v[212:215], v[28:31], v[204:211], v[212:215], v240, v241 op_sel_hi:[0,0,0] cbsz:4
	s_waitcnt lgkmcnt(0)
	v_lshl_or_b32 v128, v128, 7, v232
	v_lshl_or_b32 v129, v129, 7, v232
	v_lshl_or_b32 v130, v130, 7, v232
	v_lshl_or_b32 v131, v131, 7, v232
	v_lshl_or_b32 v132, v132, 7, v232
	v_lshl_or_b32 v133, v133, 7, v232
	v_lshl_or_b32 v134, v134, 7, v232
	v_lshl_or_b32 v135, v135, 7, v232
	v_lshl_or_b32 v136, v136, 7, v232
	v_lshl_or_b32 v137, v137, 7, v232
	v_lshl_or_b32 v138, v138, 7, v232
	v_lshl_or_b32 v139, v139, 7, v232
	v_lshl_or_b32 v140, v140, 7, v232
	v_lshl_or_b32 v141, v141, 7, v232
	v_lshl_or_b32 v142, v142, 7, v232
	v_lshl_or_b32 v143, v143, 7, v232
	buffer_load_dwordx2 v[0:1], v128, s[20:23], s1 offen
	buffer_load_dwordx2 v[2:3], v129, s[20:23], s1 offen
	buffer_load_dwordx2 v[4:5], v130, s[20:23], s1 offen
	buffer_load_dwordx2 v[6:7], v131, s[20:23], s1 offen
	buffer_load_dwordx2 v[8:9], v132, s[20:23], s1 offen
	buffer_load_dwordx2 v[10:11], v133, s[20:23], s1 offen
	buffer_load_dwordx2 v[12:13], v134, s[20:23], s1 offen
	buffer_load_dwordx2 v[14:15], v135, s[20:23], s1 offen
	buffer_load_dwordx2 v[16:17], v136, s[20:23], s1 offen
	buffer_load_dwordx2 v[18:19], v137, s[20:23], s1 offen
	buffer_load_dwordx2 v[20:21], v138, s[20:23], s1 offen
	buffer_load_dwordx2 v[22:23], v139, s[20:23], s1 offen
	buffer_load_dwordx2 v[24:25], v140, s[20:23], s1 offen
	buffer_load_dwordx2 v[26:27], v141, s[20:23], s1 offen
	buffer_load_dwordx2 v[28:29], v142, s[20:23], s1 offen
	buffer_load_dwordx2 v[30:31], v143, s[20:23], s1 offen
	ds_read_b64 v[128:129], v233 offset:2304
	ds_read_b64 v[130:131], v233 offset:2336
	ds_read_b64 v[132:133], v233 offset:2368
	ds_read_b64 v[134:135], v233 offset:2400
	ds_read_b64 v[136:137], v233 offset:2432
	ds_read_b64 v[138:139], v233 offset:2464
	ds_read_b64 v[140:141], v233 offset:2496
	ds_read_b64 v[142:143], v233 offset:2528
	ds_read_b64 v[160:161], v234 offset:1536
	ds_read_b64 v[162:163], v234 offset:1568
	ds_read_b64 v[164:165], v234 offset:1600
	ds_read_b64 v[166:167], v234 offset:1632
	ds_read_b64 v[168:169], v234 offset:1664
	ds_read_b64 v[170:171], v234 offset:1696
	ds_read_b64 v[172:173], v234 offset:1728
	ds_read_b64 v[174:175], v234 offset:1760
	s_waitcnt vmcnt(50)
	v_and_b32_e32 v144, v176, v235
	v_and_b32_e32 v145, v176, v236
	v_and_b32_e32 v146, v176, v237
	v_and_b32_e32 v147, v176, v238
	v_and_b32_e32 v148, v177, v235
	v_and_b32_e32 v149, v177, v236
	v_and_b32_e32 v150, v177, v237
	v_and_b32_e32 v151, v177, v238
	v_and_b32_e32 v204, v178, v235
	v_and_b32_e32 v205, v178, v236
	v_and_b32_e32 v206, v178, v237
	v_and_b32_e32 v207, v178, v238
	v_and_b32_e32 v208, v179, v235
	v_and_b32_e32 v209, v179, v236
	v_and_b32_e32 v210, v179, v237
	v_and_b32_e32 v211, v179, v238
	v_mfma_scale_f32_16x16x128_f8f6f4 v[212:215], v[32:35], v[144:151], v[212:215], v240, v241 op_sel_hi:[0,0,0] cbsz:4
	v_lshlrev_b32_e32 v252, 16, v230
	v_and_b32_e32 v253, 0xffff0000, v230
	v_lshlrev_b32_e32 v254, 16, v231
	v_and_b32_e32 v144, v180, v235
	v_and_b32_e32 v145, v180, v236
	v_and_b32_e32 v146, v180, v237
	v_and_b32_e32 v147, v180, v238
	v_and_b32_e32 v148, v181, v235
	v_and_b32_e32 v149, v181, v236
	v_and_b32_e32 v150, v181, v237
	v_and_b32_e32 v151, v181, v238
	v_mfma_scale_f32_16x16x128_f8f6f4 v[212:215], v[36:39], v[204:211], v[212:215], v240, v241 op_sel_hi:[0,0,0] cbsz:4
	v_and_b32_e32 v255, 0xffff0000, v231
	v_add_f32_e32 v252, v216, v252
	v_add_f32_e32 v253, v217, v253
	v_and_b32_e32 v204, v182, v235
	v_and_b32_e32 v205, v182, v236
	v_and_b32_e32 v206, v182, v237
	v_and_b32_e32 v207, v182, v238
	v_and_b32_e32 v208, v183, v235
	v_and_b32_e32 v209, v183, v236
	v_and_b32_e32 v210, v183, v237
	v_and_b32_e32 v211, v183, v238
	v_mfma_scale_f32_16x16x128_f8f6f4 v[212:215], v[40:43], v[144:151], v[212:215], v240, v241 op_sel_hi:[0,0,0] cbsz:4
	v_add_f32_e32 v254, v218, v254
	v_add_f32_e32 v255, v219, v255
	v_mul_f32_e32 v192, v252, v252
	v_and_b32_e32 v144, v184, v235
	v_and_b32_e32 v145, v184, v236
	v_and_b32_e32 v146, v184, v237
	v_and_b32_e32 v147, v184, v238
	v_and_b32_e32 v148, v185, v235
	v_and_b32_e32 v149, v185, v236
	v_and_b32_e32 v150, v185, v237
	v_and_b32_e32 v151, v185, v238
	v_mfma_scale_f32_16x16x128_f8f6f4 v[212:215], v[44:47], v[204:211], v[212:215], v240, v241 op_sel_hi:[0,0,0] cbsz:4
	v_mul_f32_e32 v193, v254, v254
	v_fmac_f32_e32 v192, v253, v253
	v_fmac_f32_e32 v193, v255, v255
	v_and_b32_e32 v204, v186, v235
	v_and_b32_e32 v205, v186, v236
	v_and_b32_e32 v206, v186, v237
	v_and_b32_e32 v207, v186, v238
	v_and_b32_e32 v208, v187, v235
	v_and_b32_e32 v209, v187, v236
	v_and_b32_e32 v210, v187, v237
	v_and_b32_e32 v211, v187, v238
	v_mfma_scale_f32_16x16x128_f8f6f4 v[212:215], v[48:51], v[144:151], v[212:215], v240, v241 op_sel_hi:[0,0,0] cbsz:4
	v_cvt_pk_bf16_f32 v250, v252, v253
	v_cvt_pk_bf16_f32 v251, v254, v255
	v_add_f32_e32 v192, v192, v193
	v_and_b32_e32 v144, v188, v235
	v_and_b32_e32 v145, v188, v236
	v_and_b32_e32 v146, v188, v237
	v_and_b32_e32 v147, v188, v238
	v_and_b32_e32 v148, v189, v235
	v_and_b32_e32 v149, v189, v236
	v_and_b32_e32 v150, v189, v237
	v_and_b32_e32 v151, v189, v238
	v_mfma_scale_f32_16x16x128_f8f6f4 v[212:215], v[52:55], v[204:211], v[212:215], v240, v241 op_sel_hi:[0,0,0] cbsz:4
	v_add_f32_e32 v221, v221, v192
	v_and_b32_e32 v204, v190, v235
	v_and_b32_e32 v205, v190, v236
	v_and_b32_e32 v206, v190, v237
	v_and_b32_e32 v207, v190, v238
	v_and_b32_e32 v208, v191, v235
	v_and_b32_e32 v209, v191, v236
	v_and_b32_e32 v210, v191, v237
	v_and_b32_e32 v211, v191, v238
	v_mfma_scale_f32_16x16x128_f8f6f4 v[212:215], v[56:59], v[144:151], v[212:215], v240, v241 op_sel_hi:[0,0,0] cbsz:4
	s_nop 0
	v_mfma_scale_f32_16x16x128_f8f6f4 v[212:215], v[60:63], v[204:211], v[212:215], v240, v241 op_sel_hi:[0,0,0] cbsz:4
	s_lshl_b32 s64, s0, 9
	s_add_u32 s64, s64, 0x1000
	s_add_u32 s76, s28, s64
	s_addc_u32 s77, s29, 0
	global_store_dwordx2 v239, v[250:251], s[76:77]
	s_lshl_b32 s64, s0, 9
	s_add_u32 s64, s64, 0x3000
	s_add_u32 s70, s28, s64
	s_addc_u32 s71, s29, 0
	global_load_dwordx2 v[230:231], v239, s[70:71]
	s_waitcnt lgkmcnt(0)
	v_lshl_or_b32 v128, v128, 7, v232
	v_lshl_or_b32 v129, v129, 7, v232
	v_lshl_or_b32 v130, v130, 7, v232
	v_lshl_or_b32 v131, v131, 7, v232
	v_lshl_or_b32 v132, v132, 7, v232
	v_lshl_or_b32 v133, v133, 7, v232
	v_lshl_or_b32 v134, v134, 7, v232
	v_lshl_or_b32 v135, v135, 7, v232
	v_lshl_or_b32 v136, v136, 7, v232
	v_lshl_or_b32 v137, v137, 7, v232
	v_lshl_or_b32 v138, v138, 7, v232
	v_lshl_or_b32 v139, v139, 7, v232
	v_lshl_or_b32 v140, v140, 7, v232
	v_lshl_or_b32 v141, v141, 7, v232
	v_lshl_or_b32 v142, v142, 7, v232
	v_lshl_or_b32 v143, v143, 7, v232
	buffer_load_dwordx2 v[32:33], v128, s[20:23], s1 offen
	buffer_load_dwordx2 v[34:35], v129, s[20:23], s1 offen
	buffer_load_dwordx2 v[36:37], v130, s[20:23], s1 offen
	buffer_load_dwordx2 v[38:39], v131, s[20:23], s1 offen
	buffer_load_dwordx2 v[40:41], v132, s[20:23], s1 offen
	buffer_load_dwordx2 v[42:43], v133, s[20:23], s1 offen
	buffer_load_dwordx2 v[44:45], v134, s[20:23], s1 offen
	buffer_load_dwordx2 v[46:47], v135, s[20:23], s1 offen
	buffer_load_dwordx2 v[48:49], v136, s[20:23], s1 offen
	buffer_load_dwordx2 v[50:51], v137, s[20:23], s1 offen
	buffer_load_dwordx2 v[52:53], v138, s[20:23], s1 offen
	buffer_load_dwordx2 v[54:55], v139, s[20:23], s1 offen
	buffer_load_dwordx2 v[56:57], v140, s[20:23], s1 offen
	buffer_load_dwordx2 v[58:59], v141, s[20:23], s1 offen
	buffer_load_dwordx2 v[60:61], v142, s[20:23], s1 offen
	buffer_load_dwordx2 v[62:63], v143, s[20:23], s1 offen
	ds_read_b64 v[128:129], v233 offset:2560
	ds_read_b64 v[130:131], v233 offset:2592
	ds_read_b64 v[132:133], v233 offset:2624
	ds_read_b64 v[134:135], v233 offset:2656
	ds_read_b64 v[136:137], v233 offset:2688
	ds_read_b64 v[138:139], v233 offset:2720
	ds_read_b64 v[140:141], v233 offset:2752
	ds_read_b64 v[142:143], v233 offset:2784
	ds_read_b64 v[176:177], v234 offset:1792
	ds_read_b64 v[178:179], v234 offset:1824
	ds_read_b64 v[180:181], v234 offset:1856
	ds_read_b64 v[182:183], v234 offset:1888
	ds_read_b64 v[184:185], v234 offset:1920
	ds_read_b64 v[186:187], v234 offset:1952
	ds_read_b64 v[188:189], v234 offset:1984
	ds_read_b64 v[190:191], v234 offset:2016
	s_waitcnt vmcnt(52)
	v_and_b32_e32 v144, v160, v235
	v_and_b32_e32 v145, v160, v236
	v_and_b32_e32 v146, v160, v237
	v_and_b32_e32 v147, v160, v238
	v_and_b32_e32 v148, v161, v235
	v_and_b32_e32 v149, v161, v236
	v_and_b32_e32 v150, v161, v237
	v_and_b32_e32 v151, v161, v238
	v_and_b32_e32 v204, v162, v235
	v_and_b32_e32 v205, v162, v236
	v_and_b32_e32 v206, v162, v237
	v_and_b32_e32 v207, v162, v238
	v_and_b32_e32 v208, v163, v235
	v_and_b32_e32 v209, v163, v236
	v_and_b32_e32 v210, v163, v237
	v_and_b32_e32 v211, v163, v238
	v_mfma_scale_f32_16x16x128_f8f6f4 v[216:219], v[64:67], v[144:151], 0, v240, v241 op_sel_hi:[0,0,0] cbsz:4
	v_and_b32_e32 v144, v164, v235
	v_and_b32_e32 v145, v164, v236
	v_and_b32_e32 v146, v164, v237
	v_and_b32_e32 v147, v164, v238
	v_and_b32_e32 v148, v165, v235
	v_and_b32_e32 v149, v165, v236
	v_and_b32_e32 v150, v165, v237
	v_and_b32_e32 v151, v165, v238
	v_mfma_scale_f32_16x16x128_f8f6f4 v[216:219], v[68:71], v[204:211], v[216:219], v240, v241 op_sel_hi:[0,0,0] cbsz:4
	v_and_b32_e32 v204, v166, v235
	v_and_b32_e32 v205, v166, v236
	v_and_b32_e32 v206, v166, v237
	v_and_b32_e32 v207, v166, v238
	v_and_b32_e32 v208, v167, v235
	v_and_b32_e32 v209, v167, v236
	v_and_b32_e32 v210, v167, v237
	v_and_b32_e32 v211, v167, v238
	v_mfma_scale_f32_16x16x128_f8f6f4 v[216:219], v[72:75], v[144:151], v[216:219], v240, v241 op_sel_hi:[0,0,0] cbsz:4
	v_and_b32_e32 v144, v168, v235
	v_and_b32_e32 v145, v168, v236
	v_and_b32_e32 v146, v168, v237
	v_and_b32_e32 v147, v168, v238
	v_and_b32_e32 v148, v169, v235
	v_and_b32_e32 v149, v169, v236
	v_and_b32_e32 v150, v169, v237
	v_and_b32_e32 v151, v169, v238
	v_mfma_scale_f32_16x16x128_f8f6f4 v[216:219], v[76:79], v[204:211], v[216:219], v240, v241 op_sel_hi:[0,0,0] cbsz:4
	v_and_b32_e32 v204, v170, v235
	v_and_b32_e32 v205, v170, v236
	v_and_b32_e32 v206, v170, v237
	v_and_b32_e32 v207, v170, v238
	v_and_b32_e32 v208, v171, v235
	v_and_b32_e32 v209, v171, v236
	v_and_b32_e32 v210, v171, v237
	v_and_b32_e32 v211, v171, v238
	v_mfma_scale_f32_16x16x128_f8f6f4 v[216:219], v[80:83], v[144:151], v[216:219], v240, v241 op_sel_hi:[0,0,0] cbsz:4
	v_and_b32_e32 v144, v172, v235
	v_and_b32_e32 v145, v172, v236
	v_and_b32_e32 v146, v172, v237
	v_and_b32_e32 v147, v172, v238
	v_and_b32_e32 v148, v173, v235
	v_and_b32_e32 v149, v173, v236
	v_and_b32_e32 v150, v173, v237
	v_and_b32_e32 v151, v173, v238
	v_mfma_scale_f32_16x16x128_f8f6f4 v[216:219], v[84:87], v[204:211], v[216:219], v240, v241 op_sel_hi:[0,0,0] cbsz:4
	v_and_b32_e32 v204, v174, v235
	v_and_b32_e32 v205, v174, v236
	v_and_b32_e32 v206, v174, v237
	v_and_b32_e32 v207, v174, v238
	v_and_b32_e32 v208, v175, v235
	v_and_b32_e32 v209, v175, v236
	v_and_b32_e32 v210, v175, v237
	v_and_b32_e32 v211, v175, v238
	v_mfma_scale_f32_16x16x128_f8f6f4 v[216:219], v[88:91], v[144:151], v[216:219], v240, v241 op_sel_hi:[0,0,0] cbsz:4
	s_nop 0
	v_mfma_scale_f32_16x16x128_f8f6f4 v[216:219], v[92:95], v[204:211], v[216:219], v240, v241 op_sel_hi:[0,0,0] cbsz:4
	s_waitcnt lgkmcnt(0)
	v_lshl_or_b32 v128, v128, 7, v232
	v_lshl_or_b32 v129, v129, 7, v232
	v_lshl_or_b32 v130, v130, 7, v232
	v_lshl_or_b32 v131, v131, 7, v232
	v_lshl_or_b32 v132, v132, 7, v232
	v_lshl_or_b32 v133, v133, 7, v232
	v_lshl_or_b32 v134, v134, 7, v232
	v_lshl_or_b32 v135, v135, 7, v232
	v_lshl_or_b32 v136, v136, 7, v232
	v_lshl_or_b32 v137, v137, 7, v232
	v_lshl_or_b32 v138, v138, 7, v232
	v_lshl_or_b32 v139, v139, 7, v232
	v_lshl_or_b32 v140, v140, 7, v232
	v_lshl_or_b32 v141, v141, 7, v232
	v_lshl_or_b32 v142, v142, 7, v232
	v_lshl_or_b32 v143, v143, 7, v232
	buffer_load_dwordx2 v[64:65], v128, s[20:23], s1 offen
	buffer_load_dwordx2 v[66:67], v129, s[20:23], s1 offen
	buffer_load_dwordx2 v[68:69], v130, s[20:23], s1 offen
	buffer_load_dwordx2 v[70:71], v131, s[20:23], s1 offen
	buffer_load_dwordx2 v[72:73], v132, s[20:23], s1 offen
	buffer_load_dwordx2 v[74:75], v133, s[20:23], s1 offen
	buffer_load_dwordx2 v[76:77], v134, s[20:23], s1 offen
	buffer_load_dwordx2 v[78:79], v135, s[20:23], s1 offen
	buffer_load_dwordx2 v[80:81], v136, s[20:23], s1 offen
	buffer_load_dwordx2 v[82:83], v137, s[20:23], s1 offen
	buffer_load_dwordx2 v[84:85], v138, s[20:23], s1 offen
	buffer_load_dwordx2 v[86:87], v139, s[20:23], s1 offen
	buffer_load_dwordx2 v[88:89], v140, s[20:23], s1 offen
	buffer_load_dwordx2 v[90:91], v141, s[20:23], s1 offen
	buffer_load_dwordx2 v[92:93], v142, s[20:23], s1 offen
	buffer_load_dwordx2 v[94:95], v143, s[20:23], s1 offen
	ds_read_b64 v[128:129], v233 offset:2816
	ds_read_b64 v[130:131], v233 offset:2848
	ds_read_b64 v[132:133], v233 offset:2880
	ds_read_b64 v[134:135], v233 offset:2912
	ds_read_b64 v[136:137], v233 offset:2944
	ds_read_b64 v[138:139], v233 offset:2976
	ds_read_b64 v[140:141], v233 offset:3008
	ds_read_b64 v[142:143], v233 offset:3040
	ds_read_b64 v[160:161], v234 offset:2048
	ds_read_b64 v[162:163], v234 offset:2080
	ds_read_b64 v[164:165], v234 offset:2112
	ds_read_b64 v[166:167], v234 offset:2144
	ds_read_b64 v[168:169], v234 offset:2176
	ds_read_b64 v[170:171], v234 offset:2208
	ds_read_b64 v[172:173], v234 offset:2240
	ds_read_b64 v[174:175], v234 offset:2272
	s_waitcnt vmcnt(50)
	v_and_b32_e32 v144, v176, v235
	v_and_b32_e32 v145, v176, v236
	v_and_b32_e32 v146, v176, v237
	v_and_b32_e32 v147, v176, v238
	v_and_b32_e32 v148, v177, v235
	v_and_b32_e32 v149, v177, v236
	v_and_b32_e32 v150, v177, v237
	v_and_b32_e32 v151, v177, v238
	v_and_b32_e32 v204, v178, v235
	v_and_b32_e32 v205, v178, v236
	v_and_b32_e32 v206, v178, v237
	v_and_b32_e32 v207, v178, v238
	v_and_b32_e32 v208, v179, v235
	v_and_b32_e32 v209, v179, v236
	v_and_b32_e32 v210, v179, v237
	v_and_b32_e32 v211, v179, v238
	v_mfma_scale_f32_16x16x128_f8f6f4 v[216:219], v[96:99], v[144:151], v[216:219], v240, v241 op_sel_hi:[0,0,0] cbsz:4
	v_lshlrev_b32_e32 v252, 16, v228
	v_and_b32_e32 v253, 0xffff0000, v228
	v_lshlrev_b32_e32 v254, 16, v229
	v_and_b32_e32 v144, v180, v235
	v_and_b32_e32 v145, v180, v236
	v_and_b32_e32 v146, v180, v237
	v_and_b32_e32 v147, v180, v238
	v_and_b32_e32 v148, v181, v235
	v_and_b32_e32 v149, v181, v236
	v_and_b32_e32 v150, v181, v237
	v_and_b32_e32 v151, v181, v238
	v_mfma_scale_f32_16x16x128_f8f6f4 v[216:219], v[100:103], v[204:211], v[216:219], v240, v241 op_sel_hi:[0,0,0] cbsz:4
	v_and_b32_e32 v255, 0xffff0000, v229
	v_add_f32_e32 v252, v212, v252
	v_add_f32_e32 v253, v213, v253
	v_and_b32_e32 v204, v182, v235
	v_and_b32_e32 v205, v182, v236
	v_and_b32_e32 v206, v182, v237
	v_and_b32_e32 v207, v182, v238
	v_and_b32_e32 v208, v183, v235
	v_and_b32_e32 v209, v183, v236
	v_and_b32_e32 v210, v183, v237
	v_and_b32_e32 v211, v183, v238
	v_mfma_scale_f32_16x16x128_f8f6f4 v[216:219], v[104:107], v[144:151], v[216:219], v240, v241 op_sel_hi:[0,0,0] cbsz:4
	v_add_f32_e32 v254, v214, v254
	v_add_f32_e32 v255, v215, v255
	v_mul_f32_e32 v192, v252, v252
	v_and_b32_e32 v144, v184, v235
	v_and_b32_e32 v145, v184, v236
	v_and_b32_e32 v146, v184, v237
	v_and_b32_e32 v147, v184, v238
	v_and_b32_e32 v148, v185, v235
	v_and_b32_e32 v149, v185, v236
	v_and_b32_e32 v150, v185, v237
	v_and_b32_e32 v151, v185, v238
	v_mfma_scale_f32_16x16x128_f8f6f4 v[216:219], v[108:111], v[204:211], v[216:219], v240, v241 op_sel_hi:[0,0,0] cbsz:4
	v_mul_f32_e32 v193, v254, v254
	v_fmac_f32_e32 v192, v253, v253
	v_fmac_f32_e32 v193, v255, v255
	v_and_b32_e32 v204, v186, v235
	v_and_b32_e32 v205, v186, v236
	v_and_b32_e32 v206, v186, v237
	v_and_b32_e32 v207, v186, v238
	v_and_b32_e32 v208, v187, v235
	v_and_b32_e32 v209, v187, v236
	v_and_b32_e32 v210, v187, v237
	v_and_b32_e32 v211, v187, v238
	v_mfma_scale_f32_16x16x128_f8f6f4 v[216:219], v[112:115], v[144:151], v[216:219], v240, v241 op_sel_hi:[0,0,0] cbsz:4
	v_cvt_pk_bf16_f32 v250, v252, v253
	v_cvt_pk_bf16_f32 v251, v254, v255
	v_add_f32_e32 v192, v192, v193
	v_and_b32_e32 v144, v188, v235
	v_and_b32_e32 v145, v188, v236
	v_and_b32_e32 v146, v188, v237
	v_and_b32_e32 v147, v188, v238
	v_and_b32_e32 v148, v189, v235
	v_and_b32_e32 v149, v189, v236
	v_and_b32_e32 v150, v189, v237
	v_and_b32_e32 v151, v189, v238
	v_mfma_scale_f32_16x16x128_f8f6f4 v[216:219], v[116:119], v[204:211], v[216:219], v240, v241 op_sel_hi:[0,0,0] cbsz:4
	v_add_f32_e32 v222, v222, v192
	v_and_b32_e32 v204, v190, v235
	v_and_b32_e32 v205, v190, v236
	v_and_b32_e32 v206, v190, v237
	v_and_b32_e32 v207, v190, v238
	v_and_b32_e32 v208, v191, v235
	v_and_b32_e32 v209, v191, v236
	v_and_b32_e32 v210, v191, v237
	v_and_b32_e32 v211, v191, v238
	v_mfma_scale_f32_16x16x128_f8f6f4 v[216:219], v[120:123], v[144:151], v[216:219], v240, v241 op_sel_hi:[0,0,0] cbsz:4
	s_nop 0
	v_mfma_scale_f32_16x16x128_f8f6f4 v[216:219], v[124:127], v[204:211], v[216:219], v240, v241 op_sel_hi:[0,0,0] cbsz:4
	s_lshl_b32 s64, s0, 9
	s_add_u32 s64, s64, 0x2000
	s_add_u32 s76, s28, s64
	s_addc_u32 s77, s29, 0
	global_store_dwordx2 v239, v[250:251], s[76:77]
	s_lshl_b32 s64, s0, 9
	s_add_u32 s64, s64, 0x4000
	s_add_u32 s70, s28, s64
	s_addc_u32 s71, s29, 0
	global_load_dwordx2 v[228:229], v239, s[70:71]
	s_waitcnt lgkmcnt(0)
	v_lshl_or_b32 v128, v128, 7, v232
	v_lshl_or_b32 v129, v129, 7, v232
	v_lshl_or_b32 v130, v130, 7, v232
	v_lshl_or_b32 v131, v131, 7, v232
	v_lshl_or_b32 v132, v132, 7, v232
	v_lshl_or_b32 v133, v133, 7, v232
	v_lshl_or_b32 v134, v134, 7, v232
	v_lshl_or_b32 v135, v135, 7, v232
	v_lshl_or_b32 v136, v136, 7, v232
	v_lshl_or_b32 v137, v137, 7, v232
	v_lshl_or_b32 v138, v138, 7, v232
	v_lshl_or_b32 v139, v139, 7, v232
	v_lshl_or_b32 v140, v140, 7, v232
	v_lshl_or_b32 v141, v141, 7, v232
	v_lshl_or_b32 v142, v142, 7, v232
	v_lshl_or_b32 v143, v143, 7, v232
	buffer_load_dwordx2 v[96:97], v128, s[20:23], s1 offen
	buffer_load_dwordx2 v[98:99], v129, s[20:23], s1 offen
	buffer_load_dwordx2 v[100:101], v130, s[20:23], s1 offen
	buffer_load_dwordx2 v[102:103], v131, s[20:23], s1 offen
	buffer_load_dwordx2 v[104:105], v132, s[20:23], s1 offen
	buffer_load_dwordx2 v[106:107], v133, s[20:23], s1 offen
	buffer_load_dwordx2 v[108:109], v134, s[20:23], s1 offen
	buffer_load_dwordx2 v[110:111], v135, s[20:23], s1 offen
	buffer_load_dwordx2 v[112:113], v136, s[20:23], s1 offen
	buffer_load_dwordx2 v[114:115], v137, s[20:23], s1 offen
	buffer_load_dwordx2 v[116:117], v138, s[20:23], s1 offen
	buffer_load_dwordx2 v[118:119], v139, s[20:23], s1 offen
	buffer_load_dwordx2 v[120:121], v140, s[20:23], s1 offen
	buffer_load_dwordx2 v[122:123], v141, s[20:23], s1 offen
	buffer_load_dwordx2 v[124:125], v142, s[20:23], s1 offen
	buffer_load_dwordx2 v[126:127], v143, s[20:23], s1 offen
	ds_read_b64 v[128:129], v233 offset:3072
	ds_read_b64 v[130:131], v233 offset:3104
	ds_read_b64 v[132:133], v233 offset:3136
	ds_read_b64 v[134:135], v233 offset:3168
	ds_read_b64 v[136:137], v233 offset:3200
	ds_read_b64 v[138:139], v233 offset:3232
	ds_read_b64 v[140:141], v233 offset:3264
	ds_read_b64 v[142:143], v233 offset:3296
	ds_read_b64 v[176:177], v234 offset:2304
	ds_read_b64 v[178:179], v234 offset:2336
	ds_read_b64 v[180:181], v234 offset:2368
	ds_read_b64 v[182:183], v234 offset:2400
	ds_read_b64 v[184:185], v234 offset:2432
	ds_read_b64 v[186:187], v234 offset:2464
	ds_read_b64 v[188:189], v234 offset:2496
	ds_read_b64 v[190:191], v234 offset:2528
	s_waitcnt vmcnt(52)
	v_and_b32_e32 v144, v160, v235
	v_and_b32_e32 v145, v160, v236
	v_and_b32_e32 v146, v160, v237
	v_and_b32_e32 v147, v160, v238
	v_and_b32_e32 v148, v161, v235
	v_and_b32_e32 v149, v161, v236
	v_and_b32_e32 v150, v161, v237
	v_and_b32_e32 v151, v161, v238
	v_and_b32_e32 v204, v162, v235
	v_and_b32_e32 v205, v162, v236
	v_and_b32_e32 v206, v162, v237
	v_and_b32_e32 v207, v162, v238
	v_and_b32_e32 v208, v163, v235
	v_and_b32_e32 v209, v163, v236
	v_and_b32_e32 v210, v163, v237
	v_and_b32_e32 v211, v163, v238
	v_mfma_scale_f32_16x16x128_f8f6f4 v[212:215], v[0:3], v[144:151], 0, v240, v241 op_sel_hi:[0,0,0] cbsz:4
	v_and_b32_e32 v144, v164, v235
	v_and_b32_e32 v145, v164, v236
	v_and_b32_e32 v146, v164, v237
	v_and_b32_e32 v147, v164, v238
	v_and_b32_e32 v148, v165, v235
	v_and_b32_e32 v149, v165, v236
	v_and_b32_e32 v150, v165, v237
	v_and_b32_e32 v151, v165, v238
	v_mfma_scale_f32_16x16x128_f8f6f4 v[212:215], v[4:7], v[204:211], v[212:215], v240, v241 op_sel_hi:[0,0,0] cbsz:4
	v_and_b32_e32 v204, v166, v235
	v_and_b32_e32 v205, v166, v236
	v_and_b32_e32 v206, v166, v237
	v_and_b32_e32 v207, v166, v238
	v_and_b32_e32 v208, v167, v235
	v_and_b32_e32 v209, v167, v236
	v_and_b32_e32 v210, v167, v237
	v_and_b32_e32 v211, v167, v238
	v_mfma_scale_f32_16x16x128_f8f6f4 v[212:215], v[8:11], v[144:151], v[212:215], v240, v241 op_sel_hi:[0,0,0] cbsz:4
	v_and_b32_e32 v144, v168, v235
	v_and_b32_e32 v145, v168, v236
	v_and_b32_e32 v146, v168, v237
	v_and_b32_e32 v147, v168, v238
	v_and_b32_e32 v148, v169, v235
	v_and_b32_e32 v149, v169, v236
	v_and_b32_e32 v150, v169, v237
	v_and_b32_e32 v151, v169, v238
	v_mfma_scale_f32_16x16x128_f8f6f4 v[212:215], v[12:15], v[204:211], v[212:215], v240, v241 op_sel_hi:[0,0,0] cbsz:4
	v_and_b32_e32 v204, v170, v235
	v_and_b32_e32 v205, v170, v236
	v_and_b32_e32 v206, v170, v237
	v_and_b32_e32 v207, v170, v238
	v_and_b32_e32 v208, v171, v235
	v_and_b32_e32 v209, v171, v236
	v_and_b32_e32 v210, v171, v237
	v_and_b32_e32 v211, v171, v238
	v_mfma_scale_f32_16x16x128_f8f6f4 v[212:215], v[16:19], v[144:151], v[212:215], v240, v241 op_sel_hi:[0,0,0] cbsz:4
	v_and_b32_e32 v144, v172, v235
	v_and_b32_e32 v145, v172, v236
	v_and_b32_e32 v146, v172, v237
	v_and_b32_e32 v147, v172, v238
	v_and_b32_e32 v148, v173, v235
	v_and_b32_e32 v149, v173, v236
	v_and_b32_e32 v150, v173, v237
	v_and_b32_e32 v151, v173, v238
	v_mfma_scale_f32_16x16x128_f8f6f4 v[212:215], v[20:23], v[204:211], v[212:215], v240, v241 op_sel_hi:[0,0,0] cbsz:4
	v_and_b32_e32 v204, v174, v235
	v_and_b32_e32 v205, v174, v236
	v_and_b32_e32 v206, v174, v237
	v_and_b32_e32 v207, v174, v238
	v_and_b32_e32 v208, v175, v235
	v_and_b32_e32 v209, v175, v236
	v_and_b32_e32 v210, v175, v237
	v_and_b32_e32 v211, v175, v238
	v_mfma_scale_f32_16x16x128_f8f6f4 v[212:215], v[24:27], v[144:151], v[212:215], v240, v241 op_sel_hi:[0,0,0] cbsz:4
	s_nop 0
	v_mfma_scale_f32_16x16x128_f8f6f4 v[212:215], v[28:31], v[204:211], v[212:215], v240, v241 op_sel_hi:[0,0,0] cbsz:4
	s_waitcnt lgkmcnt(0)
	v_lshl_or_b32 v128, v128, 7, v232
	v_lshl_or_b32 v129, v129, 7, v232
	v_lshl_or_b32 v130, v130, 7, v232
	v_lshl_or_b32 v131, v131, 7, v232
	v_lshl_or_b32 v132, v132, 7, v232
	v_lshl_or_b32 v133, v133, 7, v232
	v_lshl_or_b32 v134, v134, 7, v232
	v_lshl_or_b32 v135, v135, 7, v232
	v_lshl_or_b32 v136, v136, 7, v232
	v_lshl_or_b32 v137, v137, 7, v232
	v_lshl_or_b32 v138, v138, 7, v232
	v_lshl_or_b32 v139, v139, 7, v232
	v_lshl_or_b32 v140, v140, 7, v232
	v_lshl_or_b32 v141, v141, 7, v232
	v_lshl_or_b32 v142, v142, 7, v232
	v_lshl_or_b32 v143, v143, 7, v232
	buffer_load_dwordx2 v[0:1], v128, s[20:23], s1 offen
	buffer_load_dwordx2 v[2:3], v129, s[20:23], s1 offen
	buffer_load_dwordx2 v[4:5], v130, s[20:23], s1 offen
	buffer_load_dwordx2 v[6:7], v131, s[20:23], s1 offen
	buffer_load_dwordx2 v[8:9], v132, s[20:23], s1 offen
	buffer_load_dwordx2 v[10:11], v133, s[20:23], s1 offen
	buffer_load_dwordx2 v[12:13], v134, s[20:23], s1 offen
	buffer_load_dwordx2 v[14:15], v135, s[20:23], s1 offen
	buffer_load_dwordx2 v[16:17], v136, s[20:23], s1 offen
	buffer_load_dwordx2 v[18:19], v137, s[20:23], s1 offen
	buffer_load_dwordx2 v[20:21], v138, s[20:23], s1 offen
	buffer_load_dwordx2 v[22:23], v139, s[20:23], s1 offen
	buffer_load_dwordx2 v[24:25], v140, s[20:23], s1 offen
	buffer_load_dwordx2 v[26:27], v141, s[20:23], s1 offen
	buffer_load_dwordx2 v[28:29], v142, s[20:23], s1 offen
	buffer_load_dwordx2 v[30:31], v143, s[20:23], s1 offen
	ds_read_b64 v[128:129], v233 offset:3328
	ds_read_b64 v[130:131], v233 offset:3360
	ds_read_b64 v[132:133], v233 offset:3392
	ds_read_b64 v[134:135], v233 offset:3424
	ds_read_b64 v[136:137], v233 offset:3456
	ds_read_b64 v[138:139], v233 offset:3488
	ds_read_b64 v[140:141], v233 offset:3520
	ds_read_b64 v[142:143], v233 offset:3552
	ds_read_b64 v[160:161], v234 offset:2560
	ds_read_b64 v[162:163], v234 offset:2592
	ds_read_b64 v[164:165], v234 offset:2624
	ds_read_b64 v[166:167], v234 offset:2656
	ds_read_b64 v[168:169], v234 offset:2688
	ds_read_b64 v[170:171], v234 offset:2720
	ds_read_b64 v[172:173], v234 offset:2752
	ds_read_b64 v[174:175], v234 offset:2784
	s_waitcnt vmcnt(50)
	v_and_b32_e32 v144, v176, v235
	v_and_b32_e32 v145, v176, v236
	v_and_b32_e32 v146, v176, v237
	v_and_b32_e32 v147, v176, v238
	v_and_b32_e32 v148, v177, v235
	v_and_b32_e32 v149, v177, v236
	v_and_b32_e32 v150, v177, v237
	v_and_b32_e32 v151, v177, v238
	v_and_b32_e32 v204, v178, v235
	v_and_b32_e32 v205, v178, v236
	v_and_b32_e32 v206, v178, v237
	v_and_b32_e32 v207, v178, v238
	v_and_b32_e32 v208, v179, v235
	v_and_b32_e32 v209, v179, v236
	v_and_b32_e32 v210, v179, v237
	v_and_b32_e32 v211, v179, v238
	v_mfma_scale_f32_16x16x128_f8f6f4 v[212:215], v[32:35], v[144:151], v[212:215], v240, v241 op_sel_hi:[0,0,0] cbsz:4
	v_lshlrev_b32_e32 v252, 16, v230
	v_and_b32_e32 v253, 0xffff0000, v230
	v_lshlrev_b32_e32 v254, 16, v231
	v_and_b32_e32 v144, v180, v235
	v_and_b32_e32 v145, v180, v236
	v_and_b32_e32 v146, v180, v237
	v_and_b32_e32 v147, v180, v238
	v_and_b32_e32 v148, v181, v235
	v_and_b32_e32 v149, v181, v236
	v_and_b32_e32 v150, v181, v237
	v_and_b32_e32 v151, v181, v238
	v_mfma_scale_f32_16x16x128_f8f6f4 v[212:215], v[36:39], v[204:211], v[212:215], v240, v241 op_sel_hi:[0,0,0] cbsz:4
	v_and_b32_e32 v255, 0xffff0000, v231
	v_add_f32_e32 v252, v216, v252
	v_add_f32_e32 v253, v217, v253
	v_and_b32_e32 v204, v182, v235
	v_and_b32_e32 v205, v182, v236
	v_and_b32_e32 v206, v182, v237
	v_and_b32_e32 v207, v182, v238
	v_and_b32_e32 v208, v183, v235
	v_and_b32_e32 v209, v183, v236
	v_and_b32_e32 v210, v183, v237
	v_and_b32_e32 v211, v183, v238
	v_mfma_scale_f32_16x16x128_f8f6f4 v[212:215], v[40:43], v[144:151], v[212:215], v240, v241 op_sel_hi:[0,0,0] cbsz:4
	v_add_f32_e32 v254, v218, v254
	v_add_f32_e32 v255, v219, v255
	v_mul_f32_e32 v192, v252, v252
	v_and_b32_e32 v144, v184, v235
	v_and_b32_e32 v145, v184, v236
	v_and_b32_e32 v146, v184, v237
	v_and_b32_e32 v147, v184, v238
	v_and_b32_e32 v148, v185, v235
	v_and_b32_e32 v149, v185, v236
	v_and_b32_e32 v150, v185, v237
	v_and_b32_e32 v151, v185, v238
	v_mfma_scale_f32_16x16x128_f8f6f4 v[212:215], v[44:47], v[204:211], v[212:215], v240, v241 op_sel_hi:[0,0,0] cbsz:4
	v_mul_f32_e32 v193, v254, v254
	v_fmac_f32_e32 v192, v253, v253
	v_fmac_f32_e32 v193, v255, v255
	v_and_b32_e32 v204, v186, v235
	v_and_b32_e32 v205, v186, v236
	v_and_b32_e32 v206, v186, v237
	v_and_b32_e32 v207, v186, v238
	v_and_b32_e32 v208, v187, v235
	v_and_b32_e32 v209, v187, v236
	v_and_b32_e32 v210, v187, v237
	v_and_b32_e32 v211, v187, v238
	v_mfma_scale_f32_16x16x128_f8f6f4 v[212:215], v[48:51], v[144:151], v[212:215], v240, v241 op_sel_hi:[0,0,0] cbsz:4
	v_cvt_pk_bf16_f32 v250, v252, v253
	v_cvt_pk_bf16_f32 v251, v254, v255
	v_add_f32_e32 v192, v192, v193
	v_and_b32_e32 v144, v188, v235
	v_and_b32_e32 v145, v188, v236
	v_and_b32_e32 v146, v188, v237
	v_and_b32_e32 v147, v188, v238
	v_and_b32_e32 v148, v189, v235
	v_and_b32_e32 v149, v189, v236
	v_and_b32_e32 v150, v189, v237
	v_and_b32_e32 v151, v189, v238
	v_mfma_scale_f32_16x16x128_f8f6f4 v[212:215], v[52:55], v[204:211], v[212:215], v240, v241 op_sel_hi:[0,0,0] cbsz:4
	v_add_f32_e32 v223, v223, v192
	v_and_b32_e32 v204, v190, v235
	v_and_b32_e32 v205, v190, v236
	v_and_b32_e32 v206, v190, v237
	v_and_b32_e32 v207, v190, v238
	v_and_b32_e32 v208, v191, v235
	v_and_b32_e32 v209, v191, v236
	v_and_b32_e32 v210, v191, v237
	v_and_b32_e32 v211, v191, v238
	v_mfma_scale_f32_16x16x128_f8f6f4 v[212:215], v[56:59], v[144:151], v[212:215], v240, v241 op_sel_hi:[0,0,0] cbsz:4
	s_nop 0
	v_mfma_scale_f32_16x16x128_f8f6f4 v[212:215], v[60:63], v[204:211], v[212:215], v240, v241 op_sel_hi:[0,0,0] cbsz:4
	s_lshl_b32 s64, s0, 9
	s_add_u32 s64, s64, 0x3000
	s_add_u32 s76, s28, s64
	s_addc_u32 s77, s29, 0
	global_store_dwordx2 v239, v[250:251], s[76:77]
	s_lshl_b32 s64, s0, 9
	s_add_u32 s64, s64, 0x5000
	s_add_u32 s70, s28, s64
	s_addc_u32 s71, s29, 0
	global_load_dwordx2 v[230:231], v239, s[70:71]
	s_waitcnt lgkmcnt(0)
	v_lshl_or_b32 v128, v128, 7, v232
	v_lshl_or_b32 v129, v129, 7, v232
	v_lshl_or_b32 v130, v130, 7, v232
	v_lshl_or_b32 v131, v131, 7, v232
	v_lshl_or_b32 v132, v132, 7, v232
	v_lshl_or_b32 v133, v133, 7, v232
	v_lshl_or_b32 v134, v134, 7, v232
	v_lshl_or_b32 v135, v135, 7, v232
	v_lshl_or_b32 v136, v136, 7, v232
	v_lshl_or_b32 v137, v137, 7, v232
	v_lshl_or_b32 v138, v138, 7, v232
	v_lshl_or_b32 v139, v139, 7, v232
	v_lshl_or_b32 v140, v140, 7, v232
	v_lshl_or_b32 v141, v141, 7, v232
	v_lshl_or_b32 v142, v142, 7, v232
	v_lshl_or_b32 v143, v143, 7, v232
	buffer_load_dwordx2 v[32:33], v128, s[20:23], s1 offen
	buffer_load_dwordx2 v[34:35], v129, s[20:23], s1 offen
	buffer_load_dwordx2 v[36:37], v130, s[20:23], s1 offen
	buffer_load_dwordx2 v[38:39], v131, s[20:23], s1 offen
	buffer_load_dwordx2 v[40:41], v132, s[20:23], s1 offen
	buffer_load_dwordx2 v[42:43], v133, s[20:23], s1 offen
	buffer_load_dwordx2 v[44:45], v134, s[20:23], s1 offen
	buffer_load_dwordx2 v[46:47], v135, s[20:23], s1 offen
	buffer_load_dwordx2 v[48:49], v136, s[20:23], s1 offen
	buffer_load_dwordx2 v[50:51], v137, s[20:23], s1 offen
	buffer_load_dwordx2 v[52:53], v138, s[20:23], s1 offen
	buffer_load_dwordx2 v[54:55], v139, s[20:23], s1 offen
	buffer_load_dwordx2 v[56:57], v140, s[20:23], s1 offen
	buffer_load_dwordx2 v[58:59], v141, s[20:23], s1 offen
	buffer_load_dwordx2 v[60:61], v142, s[20:23], s1 offen
	buffer_load_dwordx2 v[62:63], v143, s[20:23], s1 offen
	ds_read_b64 v[128:129], v233 offset:3584
	ds_read_b64 v[130:131], v233 offset:3616
	ds_read_b64 v[132:133], v233 offset:3648
	ds_read_b64 v[134:135], v233 offset:3680
	ds_read_b64 v[136:137], v233 offset:3712
	ds_read_b64 v[138:139], v233 offset:3744
	ds_read_b64 v[140:141], v233 offset:3776
	ds_read_b64 v[142:143], v233 offset:3808
	ds_read_b64 v[176:177], v234 offset:2816
	ds_read_b64 v[178:179], v234 offset:2848
	ds_read_b64 v[180:181], v234 offset:2880
	ds_read_b64 v[182:183], v234 offset:2912
	ds_read_b64 v[184:185], v234 offset:2944
	ds_read_b64 v[186:187], v234 offset:2976
	ds_read_b64 v[188:189], v234 offset:3008
	ds_read_b64 v[190:191], v234 offset:3040
	s_waitcnt vmcnt(52)
	v_and_b32_e32 v144, v160, v235
	v_and_b32_e32 v145, v160, v236
	v_and_b32_e32 v146, v160, v237
	v_and_b32_e32 v147, v160, v238
	v_and_b32_e32 v148, v161, v235
	v_and_b32_e32 v149, v161, v236
	v_and_b32_e32 v150, v161, v237
	v_and_b32_e32 v151, v161, v238
	v_and_b32_e32 v204, v162, v235
	v_and_b32_e32 v205, v162, v236
	v_and_b32_e32 v206, v162, v237
	v_and_b32_e32 v207, v162, v238
	v_and_b32_e32 v208, v163, v235
	v_and_b32_e32 v209, v163, v236
	v_and_b32_e32 v210, v163, v237
	v_and_b32_e32 v211, v163, v238
	v_mfma_scale_f32_16x16x128_f8f6f4 v[216:219], v[64:67], v[144:151], 0, v240, v241 op_sel_hi:[0,0,0] cbsz:4
	v_and_b32_e32 v144, v164, v235
	v_and_b32_e32 v145, v164, v236
	v_and_b32_e32 v146, v164, v237
	v_and_b32_e32 v147, v164, v238
	v_and_b32_e32 v148, v165, v235
	v_and_b32_e32 v149, v165, v236
	v_and_b32_e32 v150, v165, v237
	v_and_b32_e32 v151, v165, v238
	v_mfma_scale_f32_16x16x128_f8f6f4 v[216:219], v[68:71], v[204:211], v[216:219], v240, v241 op_sel_hi:[0,0,0] cbsz:4
	v_and_b32_e32 v204, v166, v235
	v_and_b32_e32 v205, v166, v236
	v_and_b32_e32 v206, v166, v237
	v_and_b32_e32 v207, v166, v238
	v_and_b32_e32 v208, v167, v235
	v_and_b32_e32 v209, v167, v236
	v_and_b32_e32 v210, v167, v237
	v_and_b32_e32 v211, v167, v238
	v_mfma_scale_f32_16x16x128_f8f6f4 v[216:219], v[72:75], v[144:151], v[216:219], v240, v241 op_sel_hi:[0,0,0] cbsz:4
	v_and_b32_e32 v144, v168, v235
	v_and_b32_e32 v145, v168, v236
	v_and_b32_e32 v146, v168, v237
	v_and_b32_e32 v147, v168, v238
	v_and_b32_e32 v148, v169, v235
	v_and_b32_e32 v149, v169, v236
	v_and_b32_e32 v150, v169, v237
	v_and_b32_e32 v151, v169, v238
	v_mfma_scale_f32_16x16x128_f8f6f4 v[216:219], v[76:79], v[204:211], v[216:219], v240, v241 op_sel_hi:[0,0,0] cbsz:4
	v_and_b32_e32 v204, v170, v235
	v_and_b32_e32 v205, v170, v236
	v_and_b32_e32 v206, v170, v237
	v_and_b32_e32 v207, v170, v238
	v_and_b32_e32 v208, v171, v235
	v_and_b32_e32 v209, v171, v236
	v_and_b32_e32 v210, v171, v237
	v_and_b32_e32 v211, v171, v238
	v_mfma_scale_f32_16x16x128_f8f6f4 v[216:219], v[80:83], v[144:151], v[216:219], v240, v241 op_sel_hi:[0,0,0] cbsz:4
	v_and_b32_e32 v144, v172, v235
	v_and_b32_e32 v145, v172, v236
	v_and_b32_e32 v146, v172, v237
	v_and_b32_e32 v147, v172, v238
	v_and_b32_e32 v148, v173, v235
	v_and_b32_e32 v149, v173, v236
	v_and_b32_e32 v150, v173, v237
	v_and_b32_e32 v151, v173, v238
	v_mfma_scale_f32_16x16x128_f8f6f4 v[216:219], v[84:87], v[204:211], v[216:219], v240, v241 op_sel_hi:[0,0,0] cbsz:4
	v_and_b32_e32 v204, v174, v235
	v_and_b32_e32 v205, v174, v236
	v_and_b32_e32 v206, v174, v237
	v_and_b32_e32 v207, v174, v238
	v_and_b32_e32 v208, v175, v235
	v_and_b32_e32 v209, v175, v236
	v_and_b32_e32 v210, v175, v237
	v_and_b32_e32 v211, v175, v238
	v_mfma_scale_f32_16x16x128_f8f6f4 v[216:219], v[88:91], v[144:151], v[216:219], v240, v241 op_sel_hi:[0,0,0] cbsz:4
	s_nop 0
	v_mfma_scale_f32_16x16x128_f8f6f4 v[216:219], v[92:95], v[204:211], v[216:219], v240, v241 op_sel_hi:[0,0,0] cbsz:4
	s_waitcnt lgkmcnt(0)
	v_lshl_or_b32 v128, v128, 7, v232
	v_lshl_or_b32 v129, v129, 7, v232
	v_lshl_or_b32 v130, v130, 7, v232
	v_lshl_or_b32 v131, v131, 7, v232
	v_lshl_or_b32 v132, v132, 7, v232
	v_lshl_or_b32 v133, v133, 7, v232
	v_lshl_or_b32 v134, v134, 7, v232
	v_lshl_or_b32 v135, v135, 7, v232
	v_lshl_or_b32 v136, v136, 7, v232
	v_lshl_or_b32 v137, v137, 7, v232
	v_lshl_or_b32 v138, v138, 7, v232
	v_lshl_or_b32 v139, v139, 7, v232
	v_lshl_or_b32 v140, v140, 7, v232
	v_lshl_or_b32 v141, v141, 7, v232
	v_lshl_or_b32 v142, v142, 7, v232
	v_lshl_or_b32 v143, v143, 7, v232
	buffer_load_dwordx2 v[64:65], v128, s[20:23], s1 offen
	buffer_load_dwordx2 v[66:67], v129, s[20:23], s1 offen
	buffer_load_dwordx2 v[68:69], v130, s[20:23], s1 offen
	buffer_load_dwordx2 v[70:71], v131, s[20:23], s1 offen
	buffer_load_dwordx2 v[72:73], v132, s[20:23], s1 offen
	buffer_load_dwordx2 v[74:75], v133, s[20:23], s1 offen
	buffer_load_dwordx2 v[76:77], v134, s[20:23], s1 offen
	buffer_load_dwordx2 v[78:79], v135, s[20:23], s1 offen
	buffer_load_dwordx2 v[80:81], v136, s[20:23], s1 offen
	buffer_load_dwordx2 v[82:83], v137, s[20:23], s1 offen
	buffer_load_dwordx2 v[84:85], v138, s[20:23], s1 offen
	buffer_load_dwordx2 v[86:87], v139, s[20:23], s1 offen
	buffer_load_dwordx2 v[88:89], v140, s[20:23], s1 offen
	buffer_load_dwordx2 v[90:91], v141, s[20:23], s1 offen
	buffer_load_dwordx2 v[92:93], v142, s[20:23], s1 offen
	buffer_load_dwordx2 v[94:95], v143, s[20:23], s1 offen
	ds_read_b64 v[128:129], v233 offset:3840
	ds_read_b64 v[130:131], v233 offset:3872
	ds_read_b64 v[132:133], v233 offset:3904
	ds_read_b64 v[134:135], v233 offset:3936
	ds_read_b64 v[136:137], v233 offset:3968
	ds_read_b64 v[138:139], v233 offset:4000
	ds_read_b64 v[140:141], v233 offset:4032
	ds_read_b64 v[142:143], v233 offset:4064
	ds_read_b64 v[160:161], v234 offset:3072
	ds_read_b64 v[162:163], v234 offset:3104
	ds_read_b64 v[164:165], v234 offset:3136
	ds_read_b64 v[166:167], v234 offset:3168
	ds_read_b64 v[168:169], v234 offset:3200
	ds_read_b64 v[170:171], v234 offset:3232
	ds_read_b64 v[172:173], v234 offset:3264
	ds_read_b64 v[174:175], v234 offset:3296
	s_waitcnt vmcnt(50)
	v_and_b32_e32 v144, v176, v235
	v_and_b32_e32 v145, v176, v236
	v_and_b32_e32 v146, v176, v237
	v_and_b32_e32 v147, v176, v238
	v_and_b32_e32 v148, v177, v235
	v_and_b32_e32 v149, v177, v236
	v_and_b32_e32 v150, v177, v237
	v_and_b32_e32 v151, v177, v238
	v_and_b32_e32 v204, v178, v235
	v_and_b32_e32 v205, v178, v236
	v_and_b32_e32 v206, v178, v237
	v_and_b32_e32 v207, v178, v238
	v_and_b32_e32 v208, v179, v235
	v_and_b32_e32 v209, v179, v236
	v_and_b32_e32 v210, v179, v237
	v_and_b32_e32 v211, v179, v238
	v_mfma_scale_f32_16x16x128_f8f6f4 v[216:219], v[96:99], v[144:151], v[216:219], v240, v241 op_sel_hi:[0,0,0] cbsz:4
	v_lshlrev_b32_e32 v252, 16, v228
	v_and_b32_e32 v253, 0xffff0000, v228
	v_lshlrev_b32_e32 v254, 16, v229
	v_and_b32_e32 v144, v180, v235
	v_and_b32_e32 v145, v180, v236
	v_and_b32_e32 v146, v180, v237
	v_and_b32_e32 v147, v180, v238
	v_and_b32_e32 v148, v181, v235
	v_and_b32_e32 v149, v181, v236
	v_and_b32_e32 v150, v181, v237
	v_and_b32_e32 v151, v181, v238
	v_mfma_scale_f32_16x16x128_f8f6f4 v[216:219], v[100:103], v[204:211], v[216:219], v240, v241 op_sel_hi:[0,0,0] cbsz:4
	v_and_b32_e32 v255, 0xffff0000, v229
	v_add_f32_e32 v252, v212, v252
	v_add_f32_e32 v253, v213, v253
	v_and_b32_e32 v204, v182, v235
	v_and_b32_e32 v205, v182, v236
	v_and_b32_e32 v206, v182, v237
	v_and_b32_e32 v207, v182, v238
	v_and_b32_e32 v208, v183, v235
	v_and_b32_e32 v209, v183, v236
	v_and_b32_e32 v210, v183, v237
	v_and_b32_e32 v211, v183, v238
	v_mfma_scale_f32_16x16x128_f8f6f4 v[216:219], v[104:107], v[144:151], v[216:219], v240, v241 op_sel_hi:[0,0,0] cbsz:4
	v_add_f32_e32 v254, v214, v254
	v_add_f32_e32 v255, v215, v255
	v_mul_f32_e32 v192, v252, v252
	v_and_b32_e32 v144, v184, v235
	v_and_b32_e32 v145, v184, v236
	v_and_b32_e32 v146, v184, v237
	v_and_b32_e32 v147, v184, v238
	v_and_b32_e32 v148, v185, v235
	v_and_b32_e32 v149, v185, v236
	v_and_b32_e32 v150, v185, v237
	v_and_b32_e32 v151, v185, v238
	v_mfma_scale_f32_16x16x128_f8f6f4 v[216:219], v[108:111], v[204:211], v[216:219], v240, v241 op_sel_hi:[0,0,0] cbsz:4
	v_mul_f32_e32 v193, v254, v254
	v_fmac_f32_e32 v192, v253, v253
	v_fmac_f32_e32 v193, v255, v255
	v_and_b32_e32 v204, v186, v235
	v_and_b32_e32 v205, v186, v236
	v_and_b32_e32 v206, v186, v237
	v_and_b32_e32 v207, v186, v238
	v_and_b32_e32 v208, v187, v235
	v_and_b32_e32 v209, v187, v236
	v_and_b32_e32 v210, v187, v237
	v_and_b32_e32 v211, v187, v238
	v_mfma_scale_f32_16x16x128_f8f6f4 v[216:219], v[112:115], v[144:151], v[216:219], v240, v241 op_sel_hi:[0,0,0] cbsz:4
	v_cvt_pk_bf16_f32 v250, v252, v253
	v_cvt_pk_bf16_f32 v251, v254, v255
	v_add_f32_e32 v192, v192, v193
	v_and_b32_e32 v144, v188, v235
	v_and_b32_e32 v145, v188, v236
	v_and_b32_e32 v146, v188, v237
	v_and_b32_e32 v147, v188, v238
	v_and_b32_e32 v148, v189, v235
	v_and_b32_e32 v149, v189, v236
	v_and_b32_e32 v150, v189, v237
	v_and_b32_e32 v151, v189, v238
	v_mfma_scale_f32_16x16x128_f8f6f4 v[216:219], v[116:119], v[204:211], v[216:219], v240, v241 op_sel_hi:[0,0,0] cbsz:4
	v_add_f32_e32 v224, v224, v192
	v_and_b32_e32 v204, v190, v235
	v_and_b32_e32 v205, v190, v236
	v_and_b32_e32 v206, v190, v237
	v_and_b32_e32 v207, v190, v238
	v_and_b32_e32 v208, v191, v235
	v_and_b32_e32 v209, v191, v236
	v_and_b32_e32 v210, v191, v237
	v_and_b32_e32 v211, v191, v238
	v_mfma_scale_f32_16x16x128_f8f6f4 v[216:219], v[120:123], v[144:151], v[216:219], v240, v241 op_sel_hi:[0,0,0] cbsz:4
	s_nop 0
	v_mfma_scale_f32_16x16x128_f8f6f4 v[216:219], v[124:127], v[204:211], v[216:219], v240, v241 op_sel_hi:[0,0,0] cbsz:4
	s_lshl_b32 s64, s0, 9
	s_add_u32 s64, s64, 0x4000
	s_add_u32 s76, s28, s64
	s_addc_u32 s77, s29, 0
	global_store_dwordx2 v239, v[250:251], s[76:77]
	s_lshl_b32 s64, s0, 9
	s_add_u32 s64, s64, 0x6000
	s_add_u32 s70, s28, s64
	s_addc_u32 s71, s29, 0
	global_load_dwordx2 v[228:229], v239, s[70:71]
	s_waitcnt lgkmcnt(0)
	v_lshl_or_b32 v128, v128, 7, v232
	v_lshl_or_b32 v129, v129, 7, v232
	v_lshl_or_b32 v130, v130, 7, v232
	v_lshl_or_b32 v131, v131, 7, v232
	v_lshl_or_b32 v132, v132, 7, v232
	v_lshl_or_b32 v133, v133, 7, v232
	v_lshl_or_b32 v134, v134, 7, v232
	v_lshl_or_b32 v135, v135, 7, v232
	v_lshl_or_b32 v136, v136, 7, v232
	v_lshl_or_b32 v137, v137, 7, v232
	v_lshl_or_b32 v138, v138, 7, v232
	v_lshl_or_b32 v139, v139, 7, v232
	v_lshl_or_b32 v140, v140, 7, v232
	v_lshl_or_b32 v141, v141, 7, v232
	v_lshl_or_b32 v142, v142, 7, v232
	v_lshl_or_b32 v143, v143, 7, v232
	buffer_load_dwordx2 v[96:97], v128, s[20:23], s1 offen
	buffer_load_dwordx2 v[98:99], v129, s[20:23], s1 offen
	buffer_load_dwordx2 v[100:101], v130, s[20:23], s1 offen
	buffer_load_dwordx2 v[102:103], v131, s[20:23], s1 offen
	buffer_load_dwordx2 v[104:105], v132, s[20:23], s1 offen
	buffer_load_dwordx2 v[106:107], v133, s[20:23], s1 offen
	buffer_load_dwordx2 v[108:109], v134, s[20:23], s1 offen
	buffer_load_dwordx2 v[110:111], v135, s[20:23], s1 offen
	buffer_load_dwordx2 v[112:113], v136, s[20:23], s1 offen
	buffer_load_dwordx2 v[114:115], v137, s[20:23], s1 offen
	buffer_load_dwordx2 v[116:117], v138, s[20:23], s1 offen
	buffer_load_dwordx2 v[118:119], v139, s[20:23], s1 offen
	buffer_load_dwordx2 v[120:121], v140, s[20:23], s1 offen
	buffer_load_dwordx2 v[122:123], v141, s[20:23], s1 offen
	buffer_load_dwordx2 v[124:125], v142, s[20:23], s1 offen
	buffer_load_dwordx2 v[126:127], v143, s[20:23], s1 offen
	ds_read_b64 v[128:129], v233 offset:0
	ds_read_b64 v[130:131], v233 offset:32
	ds_read_b64 v[132:133], v233 offset:64
	ds_read_b64 v[134:135], v233 offset:96
	ds_read_b64 v[136:137], v233 offset:128
	ds_read_b64 v[138:139], v233 offset:160
	ds_read_b64 v[140:141], v233 offset:192
	ds_read_b64 v[142:143], v233 offset:224
	ds_read_b64 v[176:177], v234 offset:3328
	ds_read_b64 v[178:179], v234 offset:3360
	ds_read_b64 v[180:181], v234 offset:3392
	ds_read_b64 v[182:183], v234 offset:3424
	ds_read_b64 v[184:185], v234 offset:3456
	ds_read_b64 v[186:187], v234 offset:3488
	ds_read_b64 v[188:189], v234 offset:3520
	ds_read_b64 v[190:191], v234 offset:3552
	s_waitcnt vmcnt(52)
	v_and_b32_e32 v144, v160, v235
	v_and_b32_e32 v145, v160, v236
	v_and_b32_e32 v146, v160, v237
	v_and_b32_e32 v147, v160, v238
	v_and_b32_e32 v148, v161, v235
	v_and_b32_e32 v149, v161, v236
	v_and_b32_e32 v150, v161, v237
	v_and_b32_e32 v151, v161, v238
	v_and_b32_e32 v204, v162, v235
	v_and_b32_e32 v205, v162, v236
	v_and_b32_e32 v206, v162, v237
	v_and_b32_e32 v207, v162, v238
	v_and_b32_e32 v208, v163, v235
	v_and_b32_e32 v209, v163, v236
	v_and_b32_e32 v210, v163, v237
	v_and_b32_e32 v211, v163, v238
	v_mfma_scale_f32_16x16x128_f8f6f4 v[212:215], v[0:3], v[144:151], 0, v240, v241 op_sel_hi:[0,0,0] cbsz:4
	v_and_b32_e32 v144, v164, v235
	v_and_b32_e32 v145, v164, v236
	v_and_b32_e32 v146, v164, v237
	v_and_b32_e32 v147, v164, v238
	v_and_b32_e32 v148, v165, v235
	v_and_b32_e32 v149, v165, v236
	v_and_b32_e32 v150, v165, v237
	v_and_b32_e32 v151, v165, v238
	v_mfma_scale_f32_16x16x128_f8f6f4 v[212:215], v[4:7], v[204:211], v[212:215], v240, v241 op_sel_hi:[0,0,0] cbsz:4
	v_and_b32_e32 v204, v166, v235
	v_and_b32_e32 v205, v166, v236
	v_and_b32_e32 v206, v166, v237
	v_and_b32_e32 v207, v166, v238
	v_and_b32_e32 v208, v167, v235
	v_and_b32_e32 v209, v167, v236
	v_and_b32_e32 v210, v167, v237
	v_and_b32_e32 v211, v167, v238
	v_mfma_scale_f32_16x16x128_f8f6f4 v[212:215], v[8:11], v[144:151], v[212:215], v240, v241 op_sel_hi:[0,0,0] cbsz:4
	v_and_b32_e32 v144, v168, v235
	v_and_b32_e32 v145, v168, v236
	v_and_b32_e32 v146, v168, v237
	v_and_b32_e32 v147, v168, v238
	v_and_b32_e32 v148, v169, v235
	v_and_b32_e32 v149, v169, v236
	v_and_b32_e32 v150, v169, v237
	v_and_b32_e32 v151, v169, v238
	v_mfma_scale_f32_16x16x128_f8f6f4 v[212:215], v[12:15], v[204:211], v[212:215], v240, v241 op_sel_hi:[0,0,0] cbsz:4
	v_and_b32_e32 v204, v170, v235
	v_and_b32_e32 v205, v170, v236
	v_and_b32_e32 v206, v170, v237
	v_and_b32_e32 v207, v170, v238
	v_and_b32_e32 v208, v171, v235
	v_and_b32_e32 v209, v171, v236
	v_and_b32_e32 v210, v171, v237
	v_and_b32_e32 v211, v171, v238
	v_mfma_scale_f32_16x16x128_f8f6f4 v[212:215], v[16:19], v[144:151], v[212:215], v240, v241 op_sel_hi:[0,0,0] cbsz:4
	v_and_b32_e32 v144, v172, v235
	v_and_b32_e32 v145, v172, v236
	v_and_b32_e32 v146, v172, v237
	v_and_b32_e32 v147, v172, v238
	v_and_b32_e32 v148, v173, v235
	v_and_b32_e32 v149, v173, v236
	v_and_b32_e32 v150, v173, v237
	v_and_b32_e32 v151, v173, v238
	v_mfma_scale_f32_16x16x128_f8f6f4 v[212:215], v[20:23], v[204:211], v[212:215], v240, v241 op_sel_hi:[0,0,0] cbsz:4
	v_and_b32_e32 v204, v174, v235
	v_and_b32_e32 v205, v174, v236
	v_and_b32_e32 v206, v174, v237
	v_and_b32_e32 v207, v174, v238
	v_and_b32_e32 v208, v175, v235
	v_and_b32_e32 v209, v175, v236
	v_and_b32_e32 v210, v175, v237
	v_and_b32_e32 v211, v175, v238
	v_mfma_scale_f32_16x16x128_f8f6f4 v[212:215], v[24:27], v[144:151], v[212:215], v240, v241 op_sel_hi:[0,0,0] cbsz:4
	s_nop 0
	v_mfma_scale_f32_16x16x128_f8f6f4 v[212:215], v[28:31], v[204:211], v[212:215], v240, v241 op_sel_hi:[0,0,0] cbsz:4
	s_waitcnt lgkmcnt(0)
	v_lshl_or_b32 v128, v128, 7, v232
	v_lshl_or_b32 v129, v129, 7, v232
	v_lshl_or_b32 v130, v130, 7, v232
	v_lshl_or_b32 v131, v131, 7, v232
	v_lshl_or_b32 v132, v132, 7, v232
	v_lshl_or_b32 v133, v133, 7, v232
	v_lshl_or_b32 v134, v134, 7, v232
	v_lshl_or_b32 v135, v135, 7, v232
	v_lshl_or_b32 v136, v136, 7, v232
	v_lshl_or_b32 v137, v137, 7, v232
	v_lshl_or_b32 v138, v138, 7, v232
	v_lshl_or_b32 v139, v139, 7, v232
	v_lshl_or_b32 v140, v140, 7, v232
	v_lshl_or_b32 v141, v141, 7, v232
	v_lshl_or_b32 v142, v142, 7, v232
	v_lshl_or_b32 v143, v143, 7, v232
	buffer_load_dwordx2 v[0:1], v128, s[20:23], s60 offen
	buffer_load_dwordx2 v[2:3], v129, s[20:23], s60 offen
	buffer_load_dwordx2 v[4:5], v130, s[20:23], s60 offen
	buffer_load_dwordx2 v[6:7], v131, s[20:23], s60 offen
	buffer_load_dwordx2 v[8:9], v132, s[20:23], s60 offen
	buffer_load_dwordx2 v[10:11], v133, s[20:23], s60 offen
	buffer_load_dwordx2 v[12:13], v134, s[20:23], s60 offen
	buffer_load_dwordx2 v[14:15], v135, s[20:23], s60 offen
	buffer_load_dwordx2 v[16:17], v136, s[20:23], s60 offen
	buffer_load_dwordx2 v[18:19], v137, s[20:23], s60 offen
	buffer_load_dwordx2 v[20:21], v138, s[20:23], s60 offen
	buffer_load_dwordx2 v[22:23], v139, s[20:23], s60 offen
	buffer_load_dwordx2 v[24:25], v140, s[20:23], s60 offen
	buffer_load_dwordx2 v[26:27], v141, s[20:23], s60 offen
	buffer_load_dwordx2 v[28:29], v142, s[20:23], s60 offen
	buffer_load_dwordx2 v[30:31], v143, s[20:23], s60 offen
	ds_read_b64 v[128:129], v233 offset:256
	ds_read_b64 v[130:131], v233 offset:288
	ds_read_b64 v[132:133], v233 offset:320
	ds_read_b64 v[134:135], v233 offset:352
	ds_read_b64 v[136:137], v233 offset:384
	ds_read_b64 v[138:139], v233 offset:416
	ds_read_b64 v[140:141], v233 offset:448
	ds_read_b64 v[142:143], v233 offset:480
	ds_read_b64 v[160:161], v234 offset:3584
	ds_read_b64 v[162:163], v234 offset:3616
	ds_read_b64 v[164:165], v234 offset:3648
	ds_read_b64 v[166:167], v234 offset:3680
	ds_read_b64 v[168:169], v234 offset:3712
	ds_read_b64 v[170:171], v234 offset:3744
	ds_read_b64 v[172:173], v234 offset:3776
	ds_read_b64 v[174:175], v234 offset:3808
	s_waitcnt vmcnt(50)
	v_and_b32_e32 v144, v176, v235
	v_and_b32_e32 v145, v176, v236
	v_and_b32_e32 v146, v176, v237
	v_and_b32_e32 v147, v176, v238
	v_and_b32_e32 v148, v177, v235
	v_and_b32_e32 v149, v177, v236
	v_and_b32_e32 v150, v177, v237
	v_and_b32_e32 v151, v177, v238
	v_and_b32_e32 v204, v178, v235
	v_and_b32_e32 v205, v178, v236
	v_and_b32_e32 v206, v178, v237
	v_and_b32_e32 v207, v178, v238
	v_and_b32_e32 v208, v179, v235
	v_and_b32_e32 v209, v179, v236
	v_and_b32_e32 v210, v179, v237
	v_and_b32_e32 v211, v179, v238
	v_mfma_scale_f32_16x16x128_f8f6f4 v[212:215], v[32:35], v[144:151], v[212:215], v240, v241 op_sel_hi:[0,0,0] cbsz:4
	v_lshlrev_b32_e32 v252, 16, v230
	v_and_b32_e32 v253, 0xffff0000, v230
	v_lshlrev_b32_e32 v254, 16, v231
	v_and_b32_e32 v144, v180, v235
	v_and_b32_e32 v145, v180, v236
	v_and_b32_e32 v146, v180, v237
	v_and_b32_e32 v147, v180, v238
	v_and_b32_e32 v148, v181, v235
	v_and_b32_e32 v149, v181, v236
	v_and_b32_e32 v150, v181, v237
	v_and_b32_e32 v151, v181, v238
	v_mfma_scale_f32_16x16x128_f8f6f4 v[212:215], v[36:39], v[204:211], v[212:215], v240, v241 op_sel_hi:[0,0,0] cbsz:4
	v_and_b32_e32 v255, 0xffff0000, v231
	v_add_f32_e32 v252, v216, v252
	v_add_f32_e32 v253, v217, v253
	v_and_b32_e32 v204, v182, v235
	v_and_b32_e32 v205, v182, v236
	v_and_b32_e32 v206, v182, v237
	v_and_b32_e32 v207, v182, v238
	v_and_b32_e32 v208, v183, v235
	v_and_b32_e32 v209, v183, v236
	v_and_b32_e32 v210, v183, v237
	v_and_b32_e32 v211, v183, v238
	v_mfma_scale_f32_16x16x128_f8f6f4 v[212:215], v[40:43], v[144:151], v[212:215], v240, v241 op_sel_hi:[0,0,0] cbsz:4
	v_add_f32_e32 v254, v218, v254
	v_add_f32_e32 v255, v219, v255
	v_mul_f32_e32 v192, v252, v252
	v_and_b32_e32 v144, v184, v235
	v_and_b32_e32 v145, v184, v236
	v_and_b32_e32 v146, v184, v237
	v_and_b32_e32 v147, v184, v238
	v_and_b32_e32 v148, v185, v235
	v_and_b32_e32 v149, v185, v236
	v_and_b32_e32 v150, v185, v237
	v_and_b32_e32 v151, v185, v238
	v_mfma_scale_f32_16x16x128_f8f6f4 v[212:215], v[44:47], v[204:211], v[212:215], v240, v241 op_sel_hi:[0,0,0] cbsz:4
	v_mul_f32_e32 v193, v254, v254
	v_fmac_f32_e32 v192, v253, v253
	v_fmac_f32_e32 v193, v255, v255
	v_and_b32_e32 v204, v186, v235
	v_and_b32_e32 v205, v186, v236
	v_and_b32_e32 v206, v186, v237
	v_and_b32_e32 v207, v186, v238
	v_and_b32_e32 v208, v187, v235
	v_and_b32_e32 v209, v187, v236
	v_and_b32_e32 v210, v187, v237
	v_and_b32_e32 v211, v187, v238
	v_mfma_scale_f32_16x16x128_f8f6f4 v[212:215], v[48:51], v[144:151], v[212:215], v240, v241 op_sel_hi:[0,0,0] cbsz:4
	v_cvt_pk_bf16_f32 v250, v252, v253
	v_cvt_pk_bf16_f32 v251, v254, v255
	v_add_f32_e32 v192, v192, v193
	v_and_b32_e32 v144, v188, v235
	v_and_b32_e32 v145, v188, v236
	v_and_b32_e32 v146, v188, v237
	v_and_b32_e32 v147, v188, v238
	v_and_b32_e32 v148, v189, v235
	v_and_b32_e32 v149, v189, v236
	v_and_b32_e32 v150, v189, v237
	v_and_b32_e32 v151, v189, v238
	v_mfma_scale_f32_16x16x128_f8f6f4 v[212:215], v[52:55], v[204:211], v[212:215], v240, v241 op_sel_hi:[0,0,0] cbsz:4
	v_add_f32_e32 v225, v225, v192
	v_and_b32_e32 v204, v190, v235
	v_and_b32_e32 v205, v190, v236
	v_and_b32_e32 v206, v190, v237
	v_and_b32_e32 v207, v190, v238
	v_and_b32_e32 v208, v191, v235
	v_and_b32_e32 v209, v191, v236
	v_and_b32_e32 v210, v191, v237
	v_and_b32_e32 v211, v191, v238
	v_mfma_scale_f32_16x16x128_f8f6f4 v[212:215], v[56:59], v[144:151], v[212:215], v240, v241 op_sel_hi:[0,0,0] cbsz:4
	s_nop 0
	v_mfma_scale_f32_16x16x128_f8f6f4 v[212:215], v[60:63], v[204:211], v[212:215], v240, v241 op_sel_hi:[0,0,0] cbsz:4
	s_lshl_b32 s64, s0, 9
	s_add_u32 s64, s64, 0x5000
	s_add_u32 s76, s28, s64
	s_addc_u32 s77, s29, 0
	global_store_dwordx2 v239, v[250:251], s[76:77]
	s_lshl_b32 s64, s0, 9
	s_add_u32 s64, s64, 0x7000
	s_add_u32 s70, s28, s64
	s_addc_u32 s71, s29, 0
	global_load_dwordx2 v[230:231], v239, s[70:71]
	s_waitcnt lgkmcnt(0)
	v_lshl_or_b32 v128, v128, 7, v232
	v_lshl_or_b32 v129, v129, 7, v232
	v_lshl_or_b32 v130, v130, 7, v232
	v_lshl_or_b32 v131, v131, 7, v232
	v_lshl_or_b32 v132, v132, 7, v232
	v_lshl_or_b32 v133, v133, 7, v232
	v_lshl_or_b32 v134, v134, 7, v232
	v_lshl_or_b32 v135, v135, 7, v232
	v_lshl_or_b32 v136, v136, 7, v232
	v_lshl_or_b32 v137, v137, 7, v232
	v_lshl_or_b32 v138, v138, 7, v232
	v_lshl_or_b32 v139, v139, 7, v232
	v_lshl_or_b32 v140, v140, 7, v232
	v_lshl_or_b32 v141, v141, 7, v232
	v_lshl_or_b32 v142, v142, 7, v232
	v_lshl_or_b32 v143, v143, 7, v232
	buffer_load_dwordx2 v[32:33], v128, s[20:23], s60 offen
	buffer_load_dwordx2 v[34:35], v129, s[20:23], s60 offen
	buffer_load_dwordx2 v[36:37], v130, s[20:23], s60 offen
	buffer_load_dwordx2 v[38:39], v131, s[20:23], s60 offen
	buffer_load_dwordx2 v[40:41], v132, s[20:23], s60 offen
	buffer_load_dwordx2 v[42:43], v133, s[20:23], s60 offen
	buffer_load_dwordx2 v[44:45], v134, s[20:23], s60 offen
	buffer_load_dwordx2 v[46:47], v135, s[20:23], s60 offen
	buffer_load_dwordx2 v[48:49], v136, s[20:23], s60 offen
	buffer_load_dwordx2 v[50:51], v137, s[20:23], s60 offen
	buffer_load_dwordx2 v[52:53], v138, s[20:23], s60 offen
	buffer_load_dwordx2 v[54:55], v139, s[20:23], s60 offen
	buffer_load_dwordx2 v[56:57], v140, s[20:23], s60 offen
	buffer_load_dwordx2 v[58:59], v141, s[20:23], s60 offen
	buffer_load_dwordx2 v[60:61], v142, s[20:23], s60 offen
	buffer_load_dwordx2 v[62:63], v143, s[20:23], s60 offen
	ds_read_b64 v[128:129], v233 offset:512
	ds_read_b64 v[130:131], v233 offset:544
	ds_read_b64 v[132:133], v233 offset:576
	ds_read_b64 v[134:135], v233 offset:608
	ds_read_b64 v[136:137], v233 offset:640
	ds_read_b64 v[138:139], v233 offset:672
	ds_read_b64 v[140:141], v233 offset:704
	ds_read_b64 v[142:143], v233 offset:736
	ds_read_b64 v[176:177], v234 offset:3840
	ds_read_b64 v[178:179], v234 offset:3872
	ds_read_b64 v[180:181], v234 offset:3904
	ds_read_b64 v[182:183], v234 offset:3936
	ds_read_b64 v[184:185], v234 offset:3968
	ds_read_b64 v[186:187], v234 offset:4000
	ds_read_b64 v[188:189], v234 offset:4032
	ds_read_b64 v[190:191], v234 offset:4064
	s_waitcnt vmcnt(52)
	v_and_b32_e32 v144, v160, v235
	v_and_b32_e32 v145, v160, v236
	v_and_b32_e32 v146, v160, v237
	v_and_b32_e32 v147, v160, v238
	v_and_b32_e32 v148, v161, v235
	v_and_b32_e32 v149, v161, v236
	v_and_b32_e32 v150, v161, v237
	v_and_b32_e32 v151, v161, v238
	v_and_b32_e32 v204, v162, v235
	v_and_b32_e32 v205, v162, v236
	v_and_b32_e32 v206, v162, v237
	v_and_b32_e32 v207, v162, v238
	v_and_b32_e32 v208, v163, v235
	v_and_b32_e32 v209, v163, v236
	v_and_b32_e32 v210, v163, v237
	v_and_b32_e32 v211, v163, v238
	v_mfma_scale_f32_16x16x128_f8f6f4 v[216:219], v[64:67], v[144:151], 0, v240, v241 op_sel_hi:[0,0,0] cbsz:4
	v_and_b32_e32 v144, v164, v235
	v_and_b32_e32 v145, v164, v236
	v_and_b32_e32 v146, v164, v237
	v_and_b32_e32 v147, v164, v238
	v_and_b32_e32 v148, v165, v235
	v_and_b32_e32 v149, v165, v236
	v_and_b32_e32 v150, v165, v237
	v_and_b32_e32 v151, v165, v238
	v_mfma_scale_f32_16x16x128_f8f6f4 v[216:219], v[68:71], v[204:211], v[216:219], v240, v241 op_sel_hi:[0,0,0] cbsz:4
	v_and_b32_e32 v204, v166, v235
	v_and_b32_e32 v205, v166, v236
	v_and_b32_e32 v206, v166, v237
	v_and_b32_e32 v207, v166, v238
	v_and_b32_e32 v208, v167, v235
	v_and_b32_e32 v209, v167, v236
	v_and_b32_e32 v210, v167, v237
	v_and_b32_e32 v211, v167, v238
	v_mfma_scale_f32_16x16x128_f8f6f4 v[216:219], v[72:75], v[144:151], v[216:219], v240, v241 op_sel_hi:[0,0,0] cbsz:4
	v_and_b32_e32 v144, v168, v235
	v_and_b32_e32 v145, v168, v236
	v_and_b32_e32 v146, v168, v237
	v_and_b32_e32 v147, v168, v238
	v_and_b32_e32 v148, v169, v235
	v_and_b32_e32 v149, v169, v236
	v_and_b32_e32 v150, v169, v237
	v_and_b32_e32 v151, v169, v238
	v_mfma_scale_f32_16x16x128_f8f6f4 v[216:219], v[76:79], v[204:211], v[216:219], v240, v241 op_sel_hi:[0,0,0] cbsz:4
	v_and_b32_e32 v204, v170, v235
	v_and_b32_e32 v205, v170, v236
	v_and_b32_e32 v206, v170, v237
	v_and_b32_e32 v207, v170, v238
	v_and_b32_e32 v208, v171, v235
	v_and_b32_e32 v209, v171, v236
	v_and_b32_e32 v210, v171, v237
	v_and_b32_e32 v211, v171, v238
	v_mfma_scale_f32_16x16x128_f8f6f4 v[216:219], v[80:83], v[144:151], v[216:219], v240, v241 op_sel_hi:[0,0,0] cbsz:4
	v_and_b32_e32 v144, v172, v235
	v_and_b32_e32 v145, v172, v236
	v_and_b32_e32 v146, v172, v237
	v_and_b32_e32 v147, v172, v238
	v_and_b32_e32 v148, v173, v235
	v_and_b32_e32 v149, v173, v236
	v_and_b32_e32 v150, v173, v237
	v_and_b32_e32 v151, v173, v238
	v_mfma_scale_f32_16x16x128_f8f6f4 v[216:219], v[84:87], v[204:211], v[216:219], v240, v241 op_sel_hi:[0,0,0] cbsz:4
	v_and_b32_e32 v204, v174, v235
	v_and_b32_e32 v205, v174, v236
	v_and_b32_e32 v206, v174, v237
	v_and_b32_e32 v207, v174, v238
	v_and_b32_e32 v208, v175, v235
	v_and_b32_e32 v209, v175, v236
	v_and_b32_e32 v210, v175, v237
	v_and_b32_e32 v211, v175, v238
	v_mfma_scale_f32_16x16x128_f8f6f4 v[216:219], v[88:91], v[144:151], v[216:219], v240, v241 op_sel_hi:[0,0,0] cbsz:4
	s_nop 0
	v_mfma_scale_f32_16x16x128_f8f6f4 v[216:219], v[92:95], v[204:211], v[216:219], v240, v241 op_sel_hi:[0,0,0] cbsz:4
	s_waitcnt lgkmcnt(0)
	v_lshl_or_b32 v128, v128, 7, v232
	v_lshl_or_b32 v129, v129, 7, v232
	v_lshl_or_b32 v130, v130, 7, v232
	v_lshl_or_b32 v131, v131, 7, v232
	v_lshl_or_b32 v132, v132, 7, v232
	v_lshl_or_b32 v133, v133, 7, v232
	v_lshl_or_b32 v134, v134, 7, v232
	v_lshl_or_b32 v135, v135, 7, v232
	v_lshl_or_b32 v136, v136, 7, v232
	v_lshl_or_b32 v137, v137, 7, v232
	v_lshl_or_b32 v138, v138, 7, v232
	v_lshl_or_b32 v139, v139, 7, v232
	v_lshl_or_b32 v140, v140, 7, v232
	v_lshl_or_b32 v141, v141, 7, v232
	v_lshl_or_b32 v142, v142, 7, v232
	v_lshl_or_b32 v143, v143, 7, v232
	buffer_load_dwordx2 v[64:65], v128, s[20:23], s60 offen
	buffer_load_dwordx2 v[66:67], v129, s[20:23], s60 offen
	buffer_load_dwordx2 v[68:69], v130, s[20:23], s60 offen
	buffer_load_dwordx2 v[70:71], v131, s[20:23], s60 offen
	buffer_load_dwordx2 v[72:73], v132, s[20:23], s60 offen
	buffer_load_dwordx2 v[74:75], v133, s[20:23], s60 offen
	buffer_load_dwordx2 v[76:77], v134, s[20:23], s60 offen
	buffer_load_dwordx2 v[78:79], v135, s[20:23], s60 offen
	buffer_load_dwordx2 v[80:81], v136, s[20:23], s60 offen
	buffer_load_dwordx2 v[82:83], v137, s[20:23], s60 offen
	buffer_load_dwordx2 v[84:85], v138, s[20:23], s60 offen
	buffer_load_dwordx2 v[86:87], v139, s[20:23], s60 offen
	buffer_load_dwordx2 v[88:89], v140, s[20:23], s60 offen
	buffer_load_dwordx2 v[90:91], v141, s[20:23], s60 offen
	buffer_load_dwordx2 v[92:93], v142, s[20:23], s60 offen
	buffer_load_dwordx2 v[94:95], v143, s[20:23], s60 offen
	ds_read_b64 v[128:129], v233 offset:768
	ds_read_b64 v[130:131], v233 offset:800
	ds_read_b64 v[132:133], v233 offset:832
	ds_read_b64 v[134:135], v233 offset:864
	ds_read_b64 v[136:137], v233 offset:896
	ds_read_b64 v[138:139], v233 offset:928
	ds_read_b64 v[140:141], v233 offset:960
	ds_read_b64 v[142:143], v233 offset:992
	ds_read_b64 v[160:161], v247 offset:0
	ds_read_b64 v[162:163], v247 offset:32
	ds_read_b64 v[164:165], v247 offset:64
	ds_read_b64 v[166:167], v247 offset:96
	ds_read_b64 v[168:169], v247 offset:128
	ds_read_b64 v[170:171], v247 offset:160
	ds_read_b64 v[172:173], v247 offset:192
	ds_read_b64 v[174:175], v247 offset:224
	s_waitcnt vmcnt(50)
	v_and_b32_e32 v144, v176, v235
	v_and_b32_e32 v145, v176, v236
	v_and_b32_e32 v146, v176, v237
	v_and_b32_e32 v147, v176, v238
	v_and_b32_e32 v148, v177, v235
	v_and_b32_e32 v149, v177, v236
	v_and_b32_e32 v150, v177, v237
	v_and_b32_e32 v151, v177, v238
	v_and_b32_e32 v204, v178, v235
	v_and_b32_e32 v205, v178, v236
	v_and_b32_e32 v206, v178, v237
	v_and_b32_e32 v207, v178, v238
	v_and_b32_e32 v208, v179, v235
	v_and_b32_e32 v209, v179, v236
	v_and_b32_e32 v210, v179, v237
	v_and_b32_e32 v211, v179, v238
	v_mfma_scale_f32_16x16x128_f8f6f4 v[216:219], v[96:99], v[144:151], v[216:219], v240, v241 op_sel_hi:[0,0,0] cbsz:4
	v_lshlrev_b32_e32 v252, 16, v228
	v_and_b32_e32 v253, 0xffff0000, v228
	v_lshlrev_b32_e32 v254, 16, v229
	v_and_b32_e32 v144, v180, v235
	v_and_b32_e32 v145, v180, v236
	v_and_b32_e32 v146, v180, v237
	v_and_b32_e32 v147, v180, v238
	v_and_b32_e32 v148, v181, v235
	v_and_b32_e32 v149, v181, v236
	v_and_b32_e32 v150, v181, v237
	v_and_b32_e32 v151, v181, v238
	v_mfma_scale_f32_16x16x128_f8f6f4 v[216:219], v[100:103], v[204:211], v[216:219], v240, v241 op_sel_hi:[0,0,0] cbsz:4
	v_and_b32_e32 v255, 0xffff0000, v229
	v_add_f32_e32 v252, v212, v252
	v_add_f32_e32 v253, v213, v253
	v_and_b32_e32 v204, v182, v235
	v_and_b32_e32 v205, v182, v236
	v_and_b32_e32 v206, v182, v237
	v_and_b32_e32 v207, v182, v238
	v_and_b32_e32 v208, v183, v235
	v_and_b32_e32 v209, v183, v236
	v_and_b32_e32 v210, v183, v237
	v_and_b32_e32 v211, v183, v238
	v_mfma_scale_f32_16x16x128_f8f6f4 v[216:219], v[104:107], v[144:151], v[216:219], v240, v241 op_sel_hi:[0,0,0] cbsz:4
	v_add_f32_e32 v254, v214, v254
	v_add_f32_e32 v255, v215, v255
	v_mul_f32_e32 v192, v252, v252
	v_and_b32_e32 v144, v184, v235
	v_and_b32_e32 v145, v184, v236
	v_and_b32_e32 v146, v184, v237
	v_and_b32_e32 v147, v184, v238
	v_and_b32_e32 v148, v185, v235
	v_and_b32_e32 v149, v185, v236
	v_and_b32_e32 v150, v185, v237
	v_and_b32_e32 v151, v185, v238
	v_mfma_scale_f32_16x16x128_f8f6f4 v[216:219], v[108:111], v[204:211], v[216:219], v240, v241 op_sel_hi:[0,0,0] cbsz:4
	v_mul_f32_e32 v193, v254, v254
	v_fmac_f32_e32 v192, v253, v253
	v_fmac_f32_e32 v193, v255, v255
	v_and_b32_e32 v204, v186, v235
	v_and_b32_e32 v205, v186, v236
	v_and_b32_e32 v206, v186, v237
	v_and_b32_e32 v207, v186, v238
	v_and_b32_e32 v208, v187, v235
	v_and_b32_e32 v209, v187, v236
	v_and_b32_e32 v210, v187, v237
	v_and_b32_e32 v211, v187, v238
	v_mfma_scale_f32_16x16x128_f8f6f4 v[216:219], v[112:115], v[144:151], v[216:219], v240, v241 op_sel_hi:[0,0,0] cbsz:4
	v_cvt_pk_bf16_f32 v250, v252, v253
	v_cvt_pk_bf16_f32 v251, v254, v255
	v_add_f32_e32 v192, v192, v193
	v_and_b32_e32 v144, v188, v235
	v_and_b32_e32 v145, v188, v236
	v_and_b32_e32 v146, v188, v237
	v_and_b32_e32 v147, v188, v238
	v_and_b32_e32 v148, v189, v235
	v_and_b32_e32 v149, v189, v236
	v_and_b32_e32 v150, v189, v237
	v_and_b32_e32 v151, v189, v238
	v_mfma_scale_f32_16x16x128_f8f6f4 v[216:219], v[116:119], v[204:211], v[216:219], v240, v241 op_sel_hi:[0,0,0] cbsz:4
	v_add_f32_e32 v226, v226, v192
	v_and_b32_e32 v204, v190, v235
	v_and_b32_e32 v205, v190, v236
	v_and_b32_e32 v206, v190, v237
	v_and_b32_e32 v207, v190, v238
	v_and_b32_e32 v208, v191, v235
	v_and_b32_e32 v209, v191, v236
	v_and_b32_e32 v210, v191, v237
	v_and_b32_e32 v211, v191, v238
	v_mfma_scale_f32_16x16x128_f8f6f4 v[216:219], v[120:123], v[144:151], v[216:219], v240, v241 op_sel_hi:[0,0,0] cbsz:4
	s_nop 0
	v_mfma_scale_f32_16x16x128_f8f6f4 v[216:219], v[124:127], v[204:211], v[216:219], v240, v241 op_sel_hi:[0,0,0] cbsz:4
	s_lshl_b32 s64, s0, 9
	s_add_u32 s64, s64, 0x6000
	s_add_u32 s76, s28, s64
	s_addc_u32 s77, s29, 0
	global_store_dwordx2 v239, v[250:251], s[76:77]
	s_add_u32 s0, s0, 1
	s_lshl_b32 s1, s0, 21
	s_add_u32 s60, s1, 0x200000
	s_cmp_ge_u32 s0, 3
	s_movk_i32 s65, 0x2000
	s_cselect_b32 s64, s65, 0x1000
	v_mov_b32_e32 v234, v247
	v_add_u32_e32 v247, s64, v233
	s_cmp_lt_u32 s0, 8
	s_cbranch_scc1 .LpgL1_vloop
	s_waitcnt vmcnt(0)
	s_nop 15
	v_lshlrev_b32_e32 v252, 16, v230
	v_and_b32_e32 v253, 0xffff0000, v230
	v_lshlrev_b32_e32 v254, 16, v231
	v_and_b32_e32 v255, 0xffff0000, v231
	v_add_f32_e32 v252, v216, v252
	v_add_f32_e32 v253, v217, v253
	v_add_f32_e32 v254, v218, v254
	v_add_f32_e32 v255, v219, v255
	v_mul_f32_e32 v192, v252, v252
	v_mul_f32_e32 v193, v254, v254
	v_fmac_f32_e32 v192, v253, v253
	v_fmac_f32_e32 v193, v255, v255
	v_cvt_pk_bf16_f32 v250, v252, v253
	v_cvt_pk_bf16_f32 v251, v254, v255
	v_add_f32_e32 v192, v192, v193
	v_add_f32_e32 v227, v227, v192
	s_lshl_b32 s64, s0, 9
	s_add_u32 s64, s64, 0x6e00
	s_add_u32 s76, s28, s64
	s_addc_u32 s77, s29, 0
	global_store_dwordx2 v239, v[250:251], s[76:77]
	s_nop 1
	v_add_f32_dpp v220, v220, v220 quad_perm:[1,0,3,2] row_mask:0xf bank_mask:0xf bound_ctrl:1
	s_nop 1
	v_add_f32_dpp v220, v220, v220 quad_perm:[2,3,0,1] row_mask:0xf bank_mask:0xf bound_ctrl:1
	s_nop 1
	v_add_f32_dpp v220, v220, v220 row_half_mirror row_mask:0xf bank_mask:0xf bound_ctrl:1
	s_nop 1
	v_add_f32_dpp v220, v220, v220 row_mirror row_mask:0xf bank_mask:0xf bound_ctrl:1
	v_mov_b32_e32 v249, v220
	s_nop 1
	v_permlane16_swap_b32_e32 v220, v249
	v_add_f32_e32 v220, v220, v249
	v_mov_b32_e32 v249, v220
	s_nop 1
	v_permlane32_swap_b32_e32 v220, v249
	v_add_f32_e32 v220, v220, v249
	s_nop 1
	v_add_f32_dpp v221, v221, v221 quad_perm:[1,0,3,2] row_mask:0xf bank_mask:0xf bound_ctrl:1
	s_nop 1
	v_add_f32_dpp v221, v221, v221 quad_perm:[2,3,0,1] row_mask:0xf bank_mask:0xf bound_ctrl:1
	s_nop 1
	v_add_f32_dpp v221, v221, v221 row_half_mirror row_mask:0xf bank_mask:0xf bound_ctrl:1
	s_nop 1
	v_add_f32_dpp v221, v221, v221 row_mirror row_mask:0xf bank_mask:0xf bound_ctrl:1
	v_mov_b32_e32 v249, v221
	s_nop 1
	v_permlane16_swap_b32_e32 v221, v249
	v_add_f32_e32 v221, v221, v249
	v_mov_b32_e32 v249, v221
	s_nop 1
	v_permlane32_swap_b32_e32 v221, v249
	v_add_f32_e32 v221, v221, v249
	s_nop 1
	v_add_f32_dpp v222, v222, v222 quad_perm:[1,0,3,2] row_mask:0xf bank_mask:0xf bound_ctrl:1
	s_nop 1
	v_add_f32_dpp v222, v222, v222 quad_perm:[2,3,0,1] row_mask:0xf bank_mask:0xf bound_ctrl:1
	s_nop 1
	v_add_f32_dpp v222, v222, v222 row_half_mirror row_mask:0xf bank_mask:0xf bound_ctrl:1
	s_nop 1
	v_add_f32_dpp v222, v222, v222 row_mirror row_mask:0xf bank_mask:0xf bound_ctrl:1
	v_mov_b32_e32 v249, v222
	s_nop 1
	v_permlane16_swap_b32_e32 v222, v249
	v_add_f32_e32 v222, v222, v249
	v_mov_b32_e32 v249, v222
	s_nop 1
	v_permlane32_swap_b32_e32 v222, v249
	v_add_f32_e32 v222, v222, v249
	s_nop 1
	v_add_f32_dpp v223, v223, v223 quad_perm:[1,0,3,2] row_mask:0xf bank_mask:0xf bound_ctrl:1
	s_nop 1
	v_add_f32_dpp v223, v223, v223 quad_perm:[2,3,0,1] row_mask:0xf bank_mask:0xf bound_ctrl:1
	s_nop 1
	v_add_f32_dpp v223, v223, v223 row_half_mirror row_mask:0xf bank_mask:0xf bound_ctrl:1
	s_nop 1
	v_add_f32_dpp v223, v223, v223 row_mirror row_mask:0xf bank_mask:0xf bound_ctrl:1
	v_mov_b32_e32 v249, v223
	s_nop 1
	v_permlane16_swap_b32_e32 v223, v249
	v_add_f32_e32 v223, v223, v249
	v_mov_b32_e32 v249, v223
	s_nop 1
	v_permlane32_swap_b32_e32 v223, v249
	v_add_f32_e32 v223, v223, v249
	s_nop 1
	v_add_f32_dpp v224, v224, v224 quad_perm:[1,0,3,2] row_mask:0xf bank_mask:0xf bound_ctrl:1
	s_nop 1
	v_add_f32_dpp v224, v224, v224 quad_perm:[2,3,0,1] row_mask:0xf bank_mask:0xf bound_ctrl:1
	s_nop 1
	v_add_f32_dpp v224, v224, v224 row_half_mirror row_mask:0xf bank_mask:0xf bound_ctrl:1
	s_nop 1
	v_add_f32_dpp v224, v224, v224 row_mirror row_mask:0xf bank_mask:0xf bound_ctrl:1
	v_mov_b32_e32 v249, v224
	s_nop 1
	v_permlane16_swap_b32_e32 v224, v249
	v_add_f32_e32 v224, v224, v249
	v_mov_b32_e32 v249, v224
	s_nop 1
	v_permlane32_swap_b32_e32 v224, v249
	v_add_f32_e32 v224, v224, v249
	s_nop 1
	v_add_f32_dpp v225, v225, v225 quad_perm:[1,0,3,2] row_mask:0xf bank_mask:0xf bound_ctrl:1
	s_nop 1
	v_add_f32_dpp v225, v225, v225 quad_perm:[2,3,0,1] row_mask:0xf bank_mask:0xf bound_ctrl:1
	s_nop 1
	v_add_f32_dpp v225, v225, v225 row_half_mirror row_mask:0xf bank_mask:0xf bound_ctrl:1
	s_nop 1
	v_add_f32_dpp v225, v225, v225 row_mirror row_mask:0xf bank_mask:0xf bound_ctrl:1
	v_mov_b32_e32 v249, v225
	s_nop 1
	v_permlane16_swap_b32_e32 v225, v249
	v_add_f32_e32 v225, v225, v249
	v_mov_b32_e32 v249, v225
	s_nop 1
	v_permlane32_swap_b32_e32 v225, v249
	v_add_f32_e32 v225, v225, v249
	s_nop 1
	v_add_f32_dpp v226, v226, v226 quad_perm:[1,0,3,2] row_mask:0xf bank_mask:0xf bound_ctrl:1
	s_nop 1
	v_add_f32_dpp v226, v226, v226 quad_perm:[2,3,0,1] row_mask:0xf bank_mask:0xf bound_ctrl:1
	s_nop 1
	v_add_f32_dpp v226, v226, v226 row_half_mirror row_mask:0xf bank_mask:0xf bound_ctrl:1
	s_nop 1
	v_add_f32_dpp v226, v226, v226 row_mirror row_mask:0xf bank_mask:0xf bound_ctrl:1
	v_mov_b32_e32 v249, v226
	s_nop 1
	v_permlane16_swap_b32_e32 v226, v249
	v_add_f32_e32 v226, v226, v249
	v_mov_b32_e32 v249, v226
	s_nop 1
	v_permlane32_swap_b32_e32 v226, v249
	v_add_f32_e32 v226, v226, v249
	s_nop 1
	v_add_f32_dpp v227, v227, v227 quad_perm:[1,0,3,2] row_mask:0xf bank_mask:0xf bound_ctrl:1
	s_nop 1
	v_add_f32_dpp v227, v227, v227 quad_perm:[2,3,0,1] row_mask:0xf bank_mask:0xf bound_ctrl:1
	s_nop 1
	v_add_f32_dpp v227, v227, v227 row_half_mirror row_mask:0xf bank_mask:0xf bound_ctrl:1
	s_nop 1
	v_add_f32_dpp v227, v227, v227 row_mirror row_mask:0xf bank_mask:0xf bound_ctrl:1
	v_mov_b32_e32 v249, v227
	s_nop 1
	v_permlane16_swap_b32_e32 v227, v249
	v_add_f32_e32 v227, v227, v249
	v_mov_b32_e32 v249, v227
	s_nop 1
	v_permlane32_swap_b32_e32 v227, v249
	v_add_f32_e32 v227, v227, v249
	s_waitcnt vmcnt(0)
	v_lshlrev_b32_e32 v250, 1, v239
	v_add_u32_e32 v251, 0x1000, v250
	global_load_dwordx4 v[0:3], v250, s[66:67] offset:0
	global_load_dwordx4 v[4:7], v250, s[66:67] offset:1024
	global_load_dwordx4 v[8:11], v250, s[66:67] offset:2048
	global_load_dwordx4 v[12:15], v250, s[66:67] offset:3072
	global_load_dwordx4 v[16:19], v251, s[66:67] offset:0
	global_load_dwordx4 v[20:23], v251, s[66:67] offset:1024
	global_load_dwordx4 v[24:27], v251, s[66:67] offset:2048
	global_load_dwordx4 v[28:31], v251, s[66:67] offset:3072
	v_mov_b32_e32 v120, 0x358637bd
	v_fmamk_f32 v220, v220, 0x3a000000, v120
	v_cmp_gt_f32_e32 vcc, s96, v220
	v_mul_f32_e32 v121, 0x4b800000, v220
	s_nop 0
	v_cndmask_b32_e32 v220, v220, v121, vcc
	v_rsq_f32_e32 v220, v220
	s_nop 0
	v_mul_f32_e32 v121, 0x45800000, v220
	v_cndmask_b32_e32 v220, v220, v121, vcc
	v_fmamk_f32 v221, v221, 0x3a000000, v120
	v_cmp_gt_f32_e32 vcc, s96, v221
	v_mul_f32_e32 v121, 0x4b800000, v221
	s_nop 0
	v_cndmask_b32_e32 v221, v221, v121, vcc
	v_rsq_f32_e32 v221, v221
	s_nop 0
	v_mul_f32_e32 v121, 0x45800000, v221
	v_cndmask_b32_e32 v221, v221, v121, vcc
	v_fmamk_f32 v222, v222, 0x3a000000, v120
	v_cmp_gt_f32_e32 vcc, s96, v222
	v_mul_f32_e32 v121, 0x4b800000, v222
	s_nop 0
	v_cndmask_b32_e32 v222, v222, v121, vcc
	v_rsq_f32_e32 v222, v222
	s_nop 0
	v_mul_f32_e32 v121, 0x45800000, v222
	v_cndmask_b32_e32 v222, v222, v121, vcc
	v_fmamk_f32 v223, v223, 0x3a000000, v120
	v_cmp_gt_f32_e32 vcc, s96, v223
	v_mul_f32_e32 v121, 0x4b800000, v223
	s_nop 0
	v_cndmask_b32_e32 v223, v223, v121, vcc
	v_rsq_f32_e32 v223, v223
	s_nop 0
	v_mul_f32_e32 v121, 0x45800000, v223
	v_cndmask_b32_e32 v223, v223, v121, vcc
	v_fmamk_f32 v224, v224, 0x3a000000, v120
	v_cmp_gt_f32_e32 vcc, s96, v224
	v_mul_f32_e32 v121, 0x4b800000, v224
	s_nop 0
	v_cndmask_b32_e32 v224, v224, v121, vcc
	v_rsq_f32_e32 v224, v224
	s_nop 0
	v_mul_f32_e32 v121, 0x45800000, v224
	v_cndmask_b32_e32 v224, v224, v121, vcc
	v_fmamk_f32 v225, v225, 0x3a000000, v120
	v_cmp_gt_f32_e32 vcc, s96, v225
	v_mul_f32_e32 v121, 0x4b800000, v225
	s_nop 0
	v_cndmask_b32_e32 v225, v225, v121, vcc
	v_rsq_f32_e32 v225, v225
	s_nop 0
	v_mul_f32_e32 v121, 0x45800000, v225
	v_cndmask_b32_e32 v225, v225, v121, vcc
	v_fmamk_f32 v226, v226, 0x3a000000, v120
	v_cmp_gt_f32_e32 vcc, s96, v226
	v_mul_f32_e32 v121, 0x4b800000, v226
	s_nop 0
	v_cndmask_b32_e32 v226, v226, v121, vcc
	v_rsq_f32_e32 v226, v226
	s_nop 0
	v_mul_f32_e32 v121, 0x45800000, v226
	v_cndmask_b32_e32 v226, v226, v121, vcc
	v_fmamk_f32 v227, v227, 0x3a000000, v120
	v_cmp_gt_f32_e32 vcc, s96, v227
	v_mul_f32_e32 v121, 0x4b800000, v227
	s_nop 0
	v_cndmask_b32_e32 v227, v227, v121, vcc
	v_rsq_f32_e32 v227, v227
	s_nop 0
	v_mul_f32_e32 v121, 0x45800000, v227
	v_cndmask_b32_e32 v227, v227, v121, vcc
	s_add_u32 s70, s28, 0x0
	s_addc_u32 s71, s29, 0
	global_load_dwordx2 v[32:33], v239, s[70:71] offset:0
	global_load_dwordx2 v[34:35], v239, s[70:71] offset:512
	global_load_dwordx2 v[36:37], v239, s[70:71] offset:1024
	global_load_dwordx2 v[38:39], v239, s[70:71] offset:1536
	global_load_dwordx2 v[40:41], v239, s[70:71] offset:2048
	global_load_dwordx2 v[42:43], v239, s[70:71] offset:2560
	global_load_dwordx2 v[44:45], v239, s[70:71] offset:3072
	global_load_dwordx2 v[46:47], v239, s[70:71] offset:3584
	s_add_u32 s70, s28, 0x1000
	s_addc_u32 s71, s29, 0
	global_load_dwordx2 v[48:49], v239, s[70:71] offset:0
	global_load_dwordx2 v[50:51], v239, s[70:71] offset:512
	global_load_dwordx2 v[52:53], v239, s[70:71] offset:1024
	global_load_dwordx2 v[54:55], v239, s[70:71] offset:1536
	global_load_dwordx2 v[56:57], v239, s[70:71] offset:2048
	global_load_dwordx2 v[58:59], v239, s[70:71] offset:2560
	global_load_dwordx2 v[60:61], v239, s[70:71] offset:3072
	global_load_dwordx2 v[62:63], v239, s[70:71] offset:3584
	s_waitcnt vmcnt(8)
	s_add_u32 s76, s46, 0x0
	s_addc_u32 s77, s47, 0
	v_lshlrev_b32_e32 v64, 16, v32
	v_and_b32_e32 v65, 0xffff0000, v32
	v_lshlrev_b32_e32 v66, 16, v33
	v_and_b32_e32 v67, 0xffff0000, v33
	v_mul_f32_e32 v64, v64, v220
	v_mul_f32_e32 v65, v65, v220
	v_mul_f32_e32 v66, v66, v220
	v_mul_f32_e32 v67, v67, v220
	v_mul_f32_e32 v64, v64, v0
	v_mul_f32_e32 v65, v65, v1
	v_mul_f32_e32 v66, v66, v2
	v_mul_f32_e32 v67, v67, v3
	global_store_dwordx4 v250, v[64:67], s[76:77] offset:0 nt
	v_lshlrev_b32_e32 v68, 16, v34
	v_and_b32_e32 v69, 0xffff0000, v34
	v_lshlrev_b32_e32 v70, 16, v35
	v_and_b32_e32 v71, 0xffff0000, v35
	v_mul_f32_e32 v68, v68, v220
	v_mul_f32_e32 v69, v69, v220
	v_mul_f32_e32 v70, v70, v220
	v_mul_f32_e32 v71, v71, v220
	v_mul_f32_e32 v68, v68, v4
	v_mul_f32_e32 v69, v69, v5
	v_mul_f32_e32 v70, v70, v6
	v_mul_f32_e32 v71, v71, v7
	global_store_dwordx4 v250, v[68:71], s[76:77] offset:1024 nt
	v_lshlrev_b32_e32 v72, 16, v36
	v_and_b32_e32 v73, 0xffff0000, v36
	v_lshlrev_b32_e32 v74, 16, v37
	v_and_b32_e32 v75, 0xffff0000, v37
	v_mul_f32_e32 v72, v72, v220
	v_mul_f32_e32 v73, v73, v220
	v_mul_f32_e32 v74, v74, v220
	v_mul_f32_e32 v75, v75, v220
	v_mul_f32_e32 v72, v72, v8
	v_mul_f32_e32 v73, v73, v9
	v_mul_f32_e32 v74, v74, v10
	v_mul_f32_e32 v75, v75, v11
	global_store_dwordx4 v250, v[72:75], s[76:77] offset:2048 nt
	v_lshlrev_b32_e32 v76, 16, v38
	v_and_b32_e32 v77, 0xffff0000, v38
	v_lshlrev_b32_e32 v78, 16, v39
	v_and_b32_e32 v79, 0xffff0000, v39
	v_mul_f32_e32 v76, v76, v220
	v_mul_f32_e32 v77, v77, v220
	v_mul_f32_e32 v78, v78, v220
	v_mul_f32_e32 v79, v79, v220
	v_mul_f32_e32 v76, v76, v12
	v_mul_f32_e32 v77, v77, v13
	v_mul_f32_e32 v78, v78, v14
	v_mul_f32_e32 v79, v79, v15
	global_store_dwordx4 v250, v[76:79], s[76:77] offset:3072 nt
	v_lshlrev_b32_e32 v64, 16, v40
	v_and_b32_e32 v65, 0xffff0000, v40
	v_lshlrev_b32_e32 v66, 16, v41
	v_and_b32_e32 v67, 0xffff0000, v41
	v_mul_f32_e32 v64, v64, v220
	v_mul_f32_e32 v65, v65, v220
	v_mul_f32_e32 v66, v66, v220
	v_mul_f32_e32 v67, v67, v220
	v_mul_f32_e32 v64, v64, v16
	v_mul_f32_e32 v65, v65, v17
	v_mul_f32_e32 v66, v66, v18
	v_mul_f32_e32 v67, v67, v19
	global_store_dwordx4 v251, v[64:67], s[76:77] offset:0 nt
	v_lshlrev_b32_e32 v68, 16, v42
	v_and_b32_e32 v69, 0xffff0000, v42
	v_lshlrev_b32_e32 v70, 16, v43
	v_and_b32_e32 v71, 0xffff0000, v43
	v_mul_f32_e32 v68, v68, v220
	v_mul_f32_e32 v69, v69, v220
	v_mul_f32_e32 v70, v70, v220
	v_mul_f32_e32 v71, v71, v220
	v_mul_f32_e32 v68, v68, v20
	v_mul_f32_e32 v69, v69, v21
	v_mul_f32_e32 v70, v70, v22
	v_mul_f32_e32 v71, v71, v23
	global_store_dwordx4 v251, v[68:71], s[76:77] offset:1024 nt
	v_lshlrev_b32_e32 v72, 16, v44
	v_and_b32_e32 v73, 0xffff0000, v44
	v_lshlrev_b32_e32 v74, 16, v45
	v_and_b32_e32 v75, 0xffff0000, v45
	v_mul_f32_e32 v72, v72, v220
	v_mul_f32_e32 v73, v73, v220
	v_mul_f32_e32 v74, v74, v220
	v_mul_f32_e32 v75, v75, v220
	v_mul_f32_e32 v72, v72, v24
	v_mul_f32_e32 v73, v73, v25
	v_mul_f32_e32 v74, v74, v26
	v_mul_f32_e32 v75, v75, v27
	global_store_dwordx4 v251, v[72:75], s[76:77] offset:2048 nt
	v_lshlrev_b32_e32 v76, 16, v46
	v_and_b32_e32 v77, 0xffff0000, v46
	v_lshlrev_b32_e32 v78, 16, v47
	v_and_b32_e32 v79, 0xffff0000, v47
	v_mul_f32_e32 v76, v76, v220
	v_mul_f32_e32 v77, v77, v220
	v_mul_f32_e32 v78, v78, v220
	v_mul_f32_e32 v79, v79, v220
	v_mul_f32_e32 v76, v76, v28
	v_mul_f32_e32 v77, v77, v29
	v_mul_f32_e32 v78, v78, v30
	v_mul_f32_e32 v79, v79, v31
	global_store_dwordx4 v251, v[76:79], s[76:77] offset:3072 nt
	s_add_u32 s70, s28, 0x2000
	s_addc_u32 s71, s29, 0
	global_load_dwordx2 v[32:33], v239, s[70:71] offset:0
	global_load_dwordx2 v[34:35], v239, s[70:71] offset:512
	global_load_dwordx2 v[36:37], v239, s[70:71] offset:1024
	global_load_dwordx2 v[38:39], v239, s[70:71] offset:1536
	global_load_dwordx2 v[40:41], v239, s[70:71] offset:2048
	global_load_dwordx2 v[42:43], v239, s[70:71] offset:2560
	global_load_dwordx2 v[44:45], v239, s[70:71] offset:3072
	global_load_dwordx2 v[46:47], v239, s[70:71] offset:3584
	s_waitcnt vmcnt(16)
	s_add_u32 s76, s46, 0x2000
	s_addc_u32 s77, s47, 0
	v_lshlrev_b32_e32 v64, 16, v48
	v_and_b32_e32 v65, 0xffff0000, v48
	v_lshlrev_b32_e32 v66, 16, v49
	v_and_b32_e32 v67, 0xffff0000, v49
	v_mul_f32_e32 v64, v64, v221
	v_mul_f32_e32 v65, v65, v221
	v_mul_f32_e32 v66, v66, v221
	v_mul_f32_e32 v67, v67, v221
	v_mul_f32_e32 v64, v64, v0
	v_mul_f32_e32 v65, v65, v1
	v_mul_f32_e32 v66, v66, v2
	v_mul_f32_e32 v67, v67, v3
	global_store_dwordx4 v250, v[64:67], s[76:77] offset:0 nt
	v_lshlrev_b32_e32 v68, 16, v50
	v_and_b32_e32 v69, 0xffff0000, v50
	v_lshlrev_b32_e32 v70, 16, v51
	v_and_b32_e32 v71, 0xffff0000, v51
	v_mul_f32_e32 v68, v68, v221
	v_mul_f32_e32 v69, v69, v221
	v_mul_f32_e32 v70, v70, v221
	v_mul_f32_e32 v71, v71, v221
	v_mul_f32_e32 v68, v68, v4
	v_mul_f32_e32 v69, v69, v5
	v_mul_f32_e32 v70, v70, v6
	v_mul_f32_e32 v71, v71, v7
	global_store_dwordx4 v250, v[68:71], s[76:77] offset:1024 nt
	v_lshlrev_b32_e32 v72, 16, v52
	v_and_b32_e32 v73, 0xffff0000, v52
	v_lshlrev_b32_e32 v74, 16, v53
	v_and_b32_e32 v75, 0xffff0000, v53
	v_mul_f32_e32 v72, v72, v221
	v_mul_f32_e32 v73, v73, v221
	v_mul_f32_e32 v74, v74, v221
	v_mul_f32_e32 v75, v75, v221
	v_mul_f32_e32 v72, v72, v8
	v_mul_f32_e32 v73, v73, v9
	v_mul_f32_e32 v74, v74, v10
	v_mul_f32_e32 v75, v75, v11
	global_store_dwordx4 v250, v[72:75], s[76:77] offset:2048 nt
	v_lshlrev_b32_e32 v76, 16, v54
	v_and_b32_e32 v77, 0xffff0000, v54
	v_lshlrev_b32_e32 v78, 16, v55
	v_and_b32_e32 v79, 0xffff0000, v55
	v_mul_f32_e32 v76, v76, v221
	v_mul_f32_e32 v77, v77, v221
	v_mul_f32_e32 v78, v78, v221
	v_mul_f32_e32 v79, v79, v221
	v_mul_f32_e32 v76, v76, v12
	v_mul_f32_e32 v77, v77, v13
	v_mul_f32_e32 v78, v78, v14
	v_mul_f32_e32 v79, v79, v15
	global_store_dwordx4 v250, v[76:79], s[76:77] offset:3072 nt
	v_lshlrev_b32_e32 v64, 16, v56
	v_and_b32_e32 v65, 0xffff0000, v56
	v_lshlrev_b32_e32 v66, 16, v57
	v_and_b32_e32 v67, 0xffff0000, v57
	v_mul_f32_e32 v64, v64, v221
	v_mul_f32_e32 v65, v65, v221
	v_mul_f32_e32 v66, v66, v221
	v_mul_f32_e32 v67, v67, v221
	v_mul_f32_e32 v64, v64, v16
	v_mul_f32_e32 v65, v65, v17
	v_mul_f32_e32 v66, v66, v18
	v_mul_f32_e32 v67, v67, v19
	global_store_dwordx4 v251, v[64:67], s[76:77] offset:0 nt
	v_lshlrev_b32_e32 v68, 16, v58
	v_and_b32_e32 v69, 0xffff0000, v58
	v_lshlrev_b32_e32 v70, 16, v59
	v_and_b32_e32 v71, 0xffff0000, v59
	v_mul_f32_e32 v68, v68, v221
	v_mul_f32_e32 v69, v69, v221
	v_mul_f32_e32 v70, v70, v221
	v_mul_f32_e32 v71, v71, v221
	v_mul_f32_e32 v68, v68, v20
	v_mul_f32_e32 v69, v69, v21
	v_mul_f32_e32 v70, v70, v22
	v_mul_f32_e32 v71, v71, v23
	global_store_dwordx4 v251, v[68:71], s[76:77] offset:1024 nt
	v_lshlrev_b32_e32 v72, 16, v60
	v_and_b32_e32 v73, 0xffff0000, v60
	v_lshlrev_b32_e32 v74, 16, v61
	v_and_b32_e32 v75, 0xffff0000, v61
	v_mul_f32_e32 v72, v72, v221
	v_mul_f32_e32 v73, v73, v221
	v_mul_f32_e32 v74, v74, v221
	v_mul_f32_e32 v75, v75, v221
	v_mul_f32_e32 v72, v72, v24
	v_mul_f32_e32 v73, v73, v25
	v_mul_f32_e32 v74, v74, v26
	v_mul_f32_e32 v75, v75, v27
	global_store_dwordx4 v251, v[72:75], s[76:77] offset:2048 nt
	v_lshlrev_b32_e32 v76, 16, v62
	v_and_b32_e32 v77, 0xffff0000, v62
	v_lshlrev_b32_e32 v78, 16, v63
	v_and_b32_e32 v79, 0xffff0000, v63
	v_mul_f32_e32 v76, v76, v221
	v_mul_f32_e32 v77, v77, v221
	v_mul_f32_e32 v78, v78, v221
	v_mul_f32_e32 v79, v79, v221
	v_mul_f32_e32 v76, v76, v28
	v_mul_f32_e32 v77, v77, v29
	v_mul_f32_e32 v78, v78, v30
	v_mul_f32_e32 v79, v79, v31
	global_store_dwordx4 v251, v[76:79], s[76:77] offset:3072 nt
	s_add_u32 s70, s28, 0x3000
	s_addc_u32 s71, s29, 0
	global_load_dwordx2 v[48:49], v239, s[70:71] offset:0
	global_load_dwordx2 v[50:51], v239, s[70:71] offset:512
	global_load_dwordx2 v[52:53], v239, s[70:71] offset:1024
	global_load_dwordx2 v[54:55], v239, s[70:71] offset:1536
	global_load_dwordx2 v[56:57], v239, s[70:71] offset:2048
	global_load_dwordx2 v[58:59], v239, s[70:71] offset:2560
	global_load_dwordx2 v[60:61], v239, s[70:71] offset:3072
	global_load_dwordx2 v[62:63], v239, s[70:71] offset:3584
	s_waitcnt vmcnt(16)
	s_add_u32 s76, s46, 0x4000
	s_addc_u32 s77, s47, 0
	v_lshlrev_b32_e32 v64, 16, v32
	v_and_b32_e32 v65, 0xffff0000, v32
	v_lshlrev_b32_e32 v66, 16, v33
	v_and_b32_e32 v67, 0xffff0000, v33
	v_mul_f32_e32 v64, v64, v222
	v_mul_f32_e32 v65, v65, v222
	v_mul_f32_e32 v66, v66, v222
	v_mul_f32_e32 v67, v67, v222
	v_mul_f32_e32 v64, v64, v0
	v_mul_f32_e32 v65, v65, v1
	v_mul_f32_e32 v66, v66, v2
	v_mul_f32_e32 v67, v67, v3
	global_store_dwordx4 v250, v[64:67], s[76:77] offset:0 nt
	v_lshlrev_b32_e32 v68, 16, v34
	v_and_b32_e32 v69, 0xffff0000, v34
	v_lshlrev_b32_e32 v70, 16, v35
	v_and_b32_e32 v71, 0xffff0000, v35
	v_mul_f32_e32 v68, v68, v222
	v_mul_f32_e32 v69, v69, v222
	v_mul_f32_e32 v70, v70, v222
	v_mul_f32_e32 v71, v71, v222
	v_mul_f32_e32 v68, v68, v4
	v_mul_f32_e32 v69, v69, v5
	v_mul_f32_e32 v70, v70, v6
	v_mul_f32_e32 v71, v71, v7
	global_store_dwordx4 v250, v[68:71], s[76:77] offset:1024 nt
	v_lshlrev_b32_e32 v72, 16, v36
	v_and_b32_e32 v73, 0xffff0000, v36
	v_lshlrev_b32_e32 v74, 16, v37
	v_and_b32_e32 v75, 0xffff0000, v37
	v_mul_f32_e32 v72, v72, v222
	v_mul_f32_e32 v73, v73, v222
	v_mul_f32_e32 v74, v74, v222
	v_mul_f32_e32 v75, v75, v222
	v_mul_f32_e32 v72, v72, v8
	v_mul_f32_e32 v73, v73, v9
	v_mul_f32_e32 v74, v74, v10
	v_mul_f32_e32 v75, v75, v11
	global_store_dwordx4 v250, v[72:75], s[76:77] offset:2048 nt
	v_lshlrev_b32_e32 v76, 16, v38
	v_and_b32_e32 v77, 0xffff0000, v38
	v_lshlrev_b32_e32 v78, 16, v39
	v_and_b32_e32 v79, 0xffff0000, v39
	v_mul_f32_e32 v76, v76, v222
	v_mul_f32_e32 v77, v77, v222
	v_mul_f32_e32 v78, v78, v222
	v_mul_f32_e32 v79, v79, v222
	v_mul_f32_e32 v76, v76, v12
	v_mul_f32_e32 v77, v77, v13
	v_mul_f32_e32 v78, v78, v14
	v_mul_f32_e32 v79, v79, v15
	global_store_dwordx4 v250, v[76:79], s[76:77] offset:3072 nt
	v_lshlrev_b32_e32 v64, 16, v40
	v_and_b32_e32 v65, 0xffff0000, v40
	v_lshlrev_b32_e32 v66, 16, v41
	v_and_b32_e32 v67, 0xffff0000, v41
	v_mul_f32_e32 v64, v64, v222
	v_mul_f32_e32 v65, v65, v222
	v_mul_f32_e32 v66, v66, v222
	v_mul_f32_e32 v67, v67, v222
	v_mul_f32_e32 v64, v64, v16
	v_mul_f32_e32 v65, v65, v17
	v_mul_f32_e32 v66, v66, v18
	v_mul_f32_e32 v67, v67, v19
	global_store_dwordx4 v251, v[64:67], s[76:77] offset:0 nt
	v_lshlrev_b32_e32 v68, 16, v42
	v_and_b32_e32 v69, 0xffff0000, v42
	v_lshlrev_b32_e32 v70, 16, v43
	v_and_b32_e32 v71, 0xffff0000, v43
	v_mul_f32_e32 v68, v68, v222
	v_mul_f32_e32 v69, v69, v222
	v_mul_f32_e32 v70, v70, v222
	v_mul_f32_e32 v71, v71, v222
	v_mul_f32_e32 v68, v68, v20
	v_mul_f32_e32 v69, v69, v21
	v_mul_f32_e32 v70, v70, v22
	v_mul_f32_e32 v71, v71, v23
	global_store_dwordx4 v251, v[68:71], s[76:77] offset:1024 nt
	v_lshlrev_b32_e32 v72, 16, v44
	v_and_b32_e32 v73, 0xffff0000, v44
	v_lshlrev_b32_e32 v74, 16, v45
	v_and_b32_e32 v75, 0xffff0000, v45
	v_mul_f32_e32 v72, v72, v222
	v_mul_f32_e32 v73, v73, v222
	v_mul_f32_e32 v74, v74, v222
	v_mul_f32_e32 v75, v75, v222
	v_mul_f32_e32 v72, v72, v24
	v_mul_f32_e32 v73, v73, v25
	v_mul_f32_e32 v74, v74, v26
	v_mul_f32_e32 v75, v75, v27
	global_store_dwordx4 v251, v[72:75], s[76:77] offset:2048 nt
	v_lshlrev_b32_e32 v76, 16, v46
	v_and_b32_e32 v77, 0xffff0000, v46
	v_lshlrev_b32_e32 v78, 16, v47
	v_and_b32_e32 v79, 0xffff0000, v47
	v_mul_f32_e32 v76, v76, v222
	v_mul_f32_e32 v77, v77, v222
	v_mul_f32_e32 v78, v78, v222
	v_mul_f32_e32 v79, v79, v222
	v_mul_f32_e32 v76, v76, v28
	v_mul_f32_e32 v77, v77, v29
	v_mul_f32_e32 v78, v78, v30
	v_mul_f32_e32 v79, v79, v31
	global_store_dwordx4 v251, v[76:79], s[76:77] offset:3072 nt
	s_add_u32 s70, s28, 0x4000
	s_addc_u32 s71, s29, 0
	global_load_dwordx2 v[32:33], v239, s[70:71] offset:0
	global_load_dwordx2 v[34:35], v239, s[70:71] offset:512
	global_load_dwordx2 v[36:37], v239, s[70:71] offset:1024
	global_load_dwordx2 v[38:39], v239, s[70:71] offset:1536
	global_load_dwordx2 v[40:41], v239, s[70:71] offset:2048
	global_load_dwordx2 v[42:43], v239, s[70:71] offset:2560
	global_load_dwordx2 v[44:45], v239, s[70:71] offset:3072
	global_load_dwordx2 v[46:47], v239, s[70:71] offset:3584
	s_waitcnt vmcnt(16)
	s_add_u32 s76, s46, 0x6000
	s_addc_u32 s77, s47, 0
	v_lshlrev_b32_e32 v64, 16, v48
	v_and_b32_e32 v65, 0xffff0000, v48
	v_lshlrev_b32_e32 v66, 16, v49
	v_and_b32_e32 v67, 0xffff0000, v49
	v_mul_f32_e32 v64, v64, v223
	v_mul_f32_e32 v65, v65, v223
	v_mul_f32_e32 v66, v66, v223
	v_mul_f32_e32 v67, v67, v223
	v_mul_f32_e32 v64, v64, v0
	v_mul_f32_e32 v65, v65, v1
	v_mul_f32_e32 v66, v66, v2
	v_mul_f32_e32 v67, v67, v3
	global_store_dwordx4 v250, v[64:67], s[76:77] offset:0 nt
	v_lshlrev_b32_e32 v68, 16, v50
	v_and_b32_e32 v69, 0xffff0000, v50
	v_lshlrev_b32_e32 v70, 16, v51
	v_and_b32_e32 v71, 0xffff0000, v51
	v_mul_f32_e32 v68, v68, v223
	v_mul_f32_e32 v69, v69, v223
	v_mul_f32_e32 v70, v70, v223
	v_mul_f32_e32 v71, v71, v223
	v_mul_f32_e32 v68, v68, v4
	v_mul_f32_e32 v69, v69, v5
	v_mul_f32_e32 v70, v70, v6
	v_mul_f32_e32 v71, v71, v7
	global_store_dwordx4 v250, v[68:71], s[76:77] offset:1024 nt
	v_lshlrev_b32_e32 v72, 16, v52
	v_and_b32_e32 v73, 0xffff0000, v52
	v_lshlrev_b32_e32 v74, 16, v53
	v_and_b32_e32 v75, 0xffff0000, v53
	v_mul_f32_e32 v72, v72, v223
	v_mul_f32_e32 v73, v73, v223
	v_mul_f32_e32 v74, v74, v223
	v_mul_f32_e32 v75, v75, v223
	v_mul_f32_e32 v72, v72, v8
	v_mul_f32_e32 v73, v73, v9
	v_mul_f32_e32 v74, v74, v10
	v_mul_f32_e32 v75, v75, v11
	global_store_dwordx4 v250, v[72:75], s[76:77] offset:2048 nt
	v_lshlrev_b32_e32 v76, 16, v54
	v_and_b32_e32 v77, 0xffff0000, v54
	v_lshlrev_b32_e32 v78, 16, v55
	v_and_b32_e32 v79, 0xffff0000, v55
	v_mul_f32_e32 v76, v76, v223
	v_mul_f32_e32 v77, v77, v223
	v_mul_f32_e32 v78, v78, v223
	v_mul_f32_e32 v79, v79, v223
	v_mul_f32_e32 v76, v76, v12
	v_mul_f32_e32 v77, v77, v13
	v_mul_f32_e32 v78, v78, v14
	v_mul_f32_e32 v79, v79, v15
	global_store_dwordx4 v250, v[76:79], s[76:77] offset:3072 nt
	v_lshlrev_b32_e32 v64, 16, v56
	v_and_b32_e32 v65, 0xffff0000, v56
	v_lshlrev_b32_e32 v66, 16, v57
	v_and_b32_e32 v67, 0xffff0000, v57
	v_mul_f32_e32 v64, v64, v223
	v_mul_f32_e32 v65, v65, v223
	v_mul_f32_e32 v66, v66, v223
	v_mul_f32_e32 v67, v67, v223
	v_mul_f32_e32 v64, v64, v16
	v_mul_f32_e32 v65, v65, v17
	v_mul_f32_e32 v66, v66, v18
	v_mul_f32_e32 v67, v67, v19
	global_store_dwordx4 v251, v[64:67], s[76:77] offset:0 nt
	v_lshlrev_b32_e32 v68, 16, v58
	v_and_b32_e32 v69, 0xffff0000, v58
	v_lshlrev_b32_e32 v70, 16, v59
	v_and_b32_e32 v71, 0xffff0000, v59
	v_mul_f32_e32 v68, v68, v223
	v_mul_f32_e32 v69, v69, v223
	v_mul_f32_e32 v70, v70, v223
	v_mul_f32_e32 v71, v71, v223
	v_mul_f32_e32 v68, v68, v20
	v_mul_f32_e32 v69, v69, v21
	v_mul_f32_e32 v70, v70, v22
	v_mul_f32_e32 v71, v71, v23
	global_store_dwordx4 v251, v[68:71], s[76:77] offset:1024 nt
	v_lshlrev_b32_e32 v72, 16, v60
	v_and_b32_e32 v73, 0xffff0000, v60
	v_lshlrev_b32_e32 v74, 16, v61
	v_and_b32_e32 v75, 0xffff0000, v61
	v_mul_f32_e32 v72, v72, v223
	v_mul_f32_e32 v73, v73, v223
	v_mul_f32_e32 v74, v74, v223
	v_mul_f32_e32 v75, v75, v223
	v_mul_f32_e32 v72, v72, v24
	v_mul_f32_e32 v73, v73, v25
	v_mul_f32_e32 v74, v74, v26
	v_mul_f32_e32 v75, v75, v27
	global_store_dwordx4 v251, v[72:75], s[76:77] offset:2048 nt
	v_lshlrev_b32_e32 v76, 16, v62
	v_and_b32_e32 v77, 0xffff0000, v62
	v_lshlrev_b32_e32 v78, 16, v63
	v_and_b32_e32 v79, 0xffff0000, v63
	v_mul_f32_e32 v76, v76, v223
	v_mul_f32_e32 v77, v77, v223
	v_mul_f32_e32 v78, v78, v223
	v_mul_f32_e32 v79, v79, v223
	v_mul_f32_e32 v76, v76, v28
	v_mul_f32_e32 v77, v77, v29
	v_mul_f32_e32 v78, v78, v30
	v_mul_f32_e32 v79, v79, v31
	global_store_dwordx4 v251, v[76:79], s[76:77] offset:3072 nt
	s_add_u32 s70, s28, 0x5000
	s_addc_u32 s71, s29, 0
	global_load_dwordx2 v[48:49], v239, s[70:71] offset:0
	global_load_dwordx2 v[50:51], v239, s[70:71] offset:512
	global_load_dwordx2 v[52:53], v239, s[70:71] offset:1024
	global_load_dwordx2 v[54:55], v239, s[70:71] offset:1536
	global_load_dwordx2 v[56:57], v239, s[70:71] offset:2048
	global_load_dwordx2 v[58:59], v239, s[70:71] offset:2560
	global_load_dwordx2 v[60:61], v239, s[70:71] offset:3072
	global_load_dwordx2 v[62:63], v239, s[70:71] offset:3584
	s_waitcnt vmcnt(16)
	s_add_u32 s76, s46, 0x8000
	s_addc_u32 s77, s47, 0
	v_lshlrev_b32_e32 v64, 16, v32
	v_and_b32_e32 v65, 0xffff0000, v32
	v_lshlrev_b32_e32 v66, 16, v33
	v_and_b32_e32 v67, 0xffff0000, v33
	v_mul_f32_e32 v64, v64, v224
	v_mul_f32_e32 v65, v65, v224
	v_mul_f32_e32 v66, v66, v224
	v_mul_f32_e32 v67, v67, v224
	v_mul_f32_e32 v64, v64, v0
	v_mul_f32_e32 v65, v65, v1
	v_mul_f32_e32 v66, v66, v2
	v_mul_f32_e32 v67, v67, v3
	global_store_dwordx4 v250, v[64:67], s[76:77] offset:0 nt
	v_lshlrev_b32_e32 v68, 16, v34
	v_and_b32_e32 v69, 0xffff0000, v34
	v_lshlrev_b32_e32 v70, 16, v35
	v_and_b32_e32 v71, 0xffff0000, v35
	v_mul_f32_e32 v68, v68, v224
	v_mul_f32_e32 v69, v69, v224
	v_mul_f32_e32 v70, v70, v224
	v_mul_f32_e32 v71, v71, v224
	v_mul_f32_e32 v68, v68, v4
	v_mul_f32_e32 v69, v69, v5
	v_mul_f32_e32 v70, v70, v6
	v_mul_f32_e32 v71, v71, v7
	global_store_dwordx4 v250, v[68:71], s[76:77] offset:1024 nt
	v_lshlrev_b32_e32 v72, 16, v36
	v_and_b32_e32 v73, 0xffff0000, v36
	v_lshlrev_b32_e32 v74, 16, v37
	v_and_b32_e32 v75, 0xffff0000, v37
	v_mul_f32_e32 v72, v72, v224
	v_mul_f32_e32 v73, v73, v224
	v_mul_f32_e32 v74, v74, v224
	v_mul_f32_e32 v75, v75, v224
	v_mul_f32_e32 v72, v72, v8
	v_mul_f32_e32 v73, v73, v9
	v_mul_f32_e32 v74, v74, v10
	v_mul_f32_e32 v75, v75, v11
	global_store_dwordx4 v250, v[72:75], s[76:77] offset:2048 nt
	v_lshlrev_b32_e32 v76, 16, v38
	v_and_b32_e32 v77, 0xffff0000, v38
	v_lshlrev_b32_e32 v78, 16, v39
	v_and_b32_e32 v79, 0xffff0000, v39
	v_mul_f32_e32 v76, v76, v224
	v_mul_f32_e32 v77, v77, v224
	v_mul_f32_e32 v78, v78, v224
	v_mul_f32_e32 v79, v79, v224
	v_mul_f32_e32 v76, v76, v12
	v_mul_f32_e32 v77, v77, v13
	v_mul_f32_e32 v78, v78, v14
	v_mul_f32_e32 v79, v79, v15
	global_store_dwordx4 v250, v[76:79], s[76:77] offset:3072 nt
	v_lshlrev_b32_e32 v64, 16, v40
	v_and_b32_e32 v65, 0xffff0000, v40
	v_lshlrev_b32_e32 v66, 16, v41
	v_and_b32_e32 v67, 0xffff0000, v41
	v_mul_f32_e32 v64, v64, v224
	v_mul_f32_e32 v65, v65, v224
	v_mul_f32_e32 v66, v66, v224
	v_mul_f32_e32 v67, v67, v224
	v_mul_f32_e32 v64, v64, v16
	v_mul_f32_e32 v65, v65, v17
	v_mul_f32_e32 v66, v66, v18
	v_mul_f32_e32 v67, v67, v19
	global_store_dwordx4 v251, v[64:67], s[76:77] offset:0 nt
	v_lshlrev_b32_e32 v68, 16, v42
	v_and_b32_e32 v69, 0xffff0000, v42
	v_lshlrev_b32_e32 v70, 16, v43
	v_and_b32_e32 v71, 0xffff0000, v43
	v_mul_f32_e32 v68, v68, v224
	v_mul_f32_e32 v69, v69, v224
	v_mul_f32_e32 v70, v70, v224
	v_mul_f32_e32 v71, v71, v224
	v_mul_f32_e32 v68, v68, v20
	v_mul_f32_e32 v69, v69, v21
	v_mul_f32_e32 v70, v70, v22
	v_mul_f32_e32 v71, v71, v23
	global_store_dwordx4 v251, v[68:71], s[76:77] offset:1024 nt
	v_lshlrev_b32_e32 v72, 16, v44
	v_and_b32_e32 v73, 0xffff0000, v44
	v_lshlrev_b32_e32 v74, 16, v45
	v_and_b32_e32 v75, 0xffff0000, v45
	v_mul_f32_e32 v72, v72, v224
	v_mul_f32_e32 v73, v73, v224
	v_mul_f32_e32 v74, v74, v224
	v_mul_f32_e32 v75, v75, v224
	v_mul_f32_e32 v72, v72, v24
	v_mul_f32_e32 v73, v73, v25
	v_mul_f32_e32 v74, v74, v26
	v_mul_f32_e32 v75, v75, v27
	global_store_dwordx4 v251, v[72:75], s[76:77] offset:2048 nt
	v_lshlrev_b32_e32 v76, 16, v46
	v_and_b32_e32 v77, 0xffff0000, v46
	v_lshlrev_b32_e32 v78, 16, v47
	v_and_b32_e32 v79, 0xffff0000, v47
	v_mul_f32_e32 v76, v76, v224
	v_mul_f32_e32 v77, v77, v224
	v_mul_f32_e32 v78, v78, v224
	v_mul_f32_e32 v79, v79, v224
	v_mul_f32_e32 v76, v76, v28
	v_mul_f32_e32 v77, v77, v29
	v_mul_f32_e32 v78, v78, v30
	v_mul_f32_e32 v79, v79, v31
	global_store_dwordx4 v251, v[76:79], s[76:77] offset:3072 nt
	s_add_u32 s70, s28, 0x6000
	s_addc_u32 s71, s29, 0
	global_load_dwordx2 v[32:33], v239, s[70:71] offset:0
	global_load_dwordx2 v[34:35], v239, s[70:71] offset:512
	global_load_dwordx2 v[36:37], v239, s[70:71] offset:1024
	global_load_dwordx2 v[38:39], v239, s[70:71] offset:1536
	global_load_dwordx2 v[40:41], v239, s[70:71] offset:2048
	global_load_dwordx2 v[42:43], v239, s[70:71] offset:2560
	global_load_dwordx2 v[44:45], v239, s[70:71] offset:3072
	global_load_dwordx2 v[46:47], v239, s[70:71] offset:3584
	s_waitcnt vmcnt(16)
	s_add_u32 s76, s46, 0xa000
	s_addc_u32 s77, s47, 0
	v_lshlrev_b32_e32 v64, 16, v48
	v_and_b32_e32 v65, 0xffff0000, v48
	v_lshlrev_b32_e32 v66, 16, v49
	v_and_b32_e32 v67, 0xffff0000, v49
	v_mul_f32_e32 v64, v64, v225
	v_mul_f32_e32 v65, v65, v225
	v_mul_f32_e32 v66, v66, v225
	v_mul_f32_e32 v67, v67, v225
	v_mul_f32_e32 v64, v64, v0
	v_mul_f32_e32 v65, v65, v1
	v_mul_f32_e32 v66, v66, v2
	v_mul_f32_e32 v67, v67, v3
	global_store_dwordx4 v250, v[64:67], s[76:77] offset:0 nt
	v_lshlrev_b32_e32 v68, 16, v50
	v_and_b32_e32 v69, 0xffff0000, v50
	v_lshlrev_b32_e32 v70, 16, v51
	v_and_b32_e32 v71, 0xffff0000, v51
	v_mul_f32_e32 v68, v68, v225
	v_mul_f32_e32 v69, v69, v225
	v_mul_f32_e32 v70, v70, v225
	v_mul_f32_e32 v71, v71, v225
	v_mul_f32_e32 v68, v68, v4
	v_mul_f32_e32 v69, v69, v5
	v_mul_f32_e32 v70, v70, v6
	v_mul_f32_e32 v71, v71, v7
	global_store_dwordx4 v250, v[68:71], s[76:77] offset:1024 nt
	v_lshlrev_b32_e32 v72, 16, v52
	v_and_b32_e32 v73, 0xffff0000, v52
	v_lshlrev_b32_e32 v74, 16, v53
	v_and_b32_e32 v75, 0xffff0000, v53
	v_mul_f32_e32 v72, v72, v225
	v_mul_f32_e32 v73, v73, v225
	v_mul_f32_e32 v74, v74, v225
	v_mul_f32_e32 v75, v75, v225
	v_mul_f32_e32 v72, v72, v8
	v_mul_f32_e32 v73, v73, v9
	v_mul_f32_e32 v74, v74, v10
	v_mul_f32_e32 v75, v75, v11
	global_store_dwordx4 v250, v[72:75], s[76:77] offset:2048 nt
	v_lshlrev_b32_e32 v76, 16, v54
	v_and_b32_e32 v77, 0xffff0000, v54
	v_lshlrev_b32_e32 v78, 16, v55
	v_and_b32_e32 v79, 0xffff0000, v55
	v_mul_f32_e32 v76, v76, v225
	v_mul_f32_e32 v77, v77, v225
	v_mul_f32_e32 v78, v78, v225
	v_mul_f32_e32 v79, v79, v225
	v_mul_f32_e32 v76, v76, v12
	v_mul_f32_e32 v77, v77, v13
	v_mul_f32_e32 v78, v78, v14
	v_mul_f32_e32 v79, v79, v15
	global_store_dwordx4 v250, v[76:79], s[76:77] offset:3072 nt
	v_lshlrev_b32_e32 v64, 16, v56
	v_and_b32_e32 v65, 0xffff0000, v56
	v_lshlrev_b32_e32 v66, 16, v57
	v_and_b32_e32 v67, 0xffff0000, v57
	v_mul_f32_e32 v64, v64, v225
	v_mul_f32_e32 v65, v65, v225
	v_mul_f32_e32 v66, v66, v225
	v_mul_f32_e32 v67, v67, v225
	v_mul_f32_e32 v64, v64, v16
	v_mul_f32_e32 v65, v65, v17
	v_mul_f32_e32 v66, v66, v18
	v_mul_f32_e32 v67, v67, v19
	global_store_dwordx4 v251, v[64:67], s[76:77] offset:0 nt
	v_lshlrev_b32_e32 v68, 16, v58
	v_and_b32_e32 v69, 0xffff0000, v58
	v_lshlrev_b32_e32 v70, 16, v59
	v_and_b32_e32 v71, 0xffff0000, v59
	v_mul_f32_e32 v68, v68, v225
	v_mul_f32_e32 v69, v69, v225
	v_mul_f32_e32 v70, v70, v225
	v_mul_f32_e32 v71, v71, v225
	v_mul_f32_e32 v68, v68, v20
	v_mul_f32_e32 v69, v69, v21
	v_mul_f32_e32 v70, v70, v22
	v_mul_f32_e32 v71, v71, v23
	global_store_dwordx4 v251, v[68:71], s[76:77] offset:1024 nt
	v_lshlrev_b32_e32 v72, 16, v60
	v_and_b32_e32 v73, 0xffff0000, v60
	v_lshlrev_b32_e32 v74, 16, v61
	v_and_b32_e32 v75, 0xffff0000, v61
	v_mul_f32_e32 v72, v72, v225
	v_mul_f32_e32 v73, v73, v225
	v_mul_f32_e32 v74, v74, v225
	v_mul_f32_e32 v75, v75, v225
	v_mul_f32_e32 v72, v72, v24
	v_mul_f32_e32 v73, v73, v25
	v_mul_f32_e32 v74, v74, v26
	v_mul_f32_e32 v75, v75, v27
	global_store_dwordx4 v251, v[72:75], s[76:77] offset:2048 nt
	v_lshlrev_b32_e32 v76, 16, v62
	v_and_b32_e32 v77, 0xffff0000, v62
	v_lshlrev_b32_e32 v78, 16, v63
	v_and_b32_e32 v79, 0xffff0000, v63
	v_mul_f32_e32 v76, v76, v225
	v_mul_f32_e32 v77, v77, v225
	v_mul_f32_e32 v78, v78, v225
	v_mul_f32_e32 v79, v79, v225
	v_mul_f32_e32 v76, v76, v28
	v_mul_f32_e32 v77, v77, v29
	v_mul_f32_e32 v78, v78, v30
	v_mul_f32_e32 v79, v79, v31
	global_store_dwordx4 v251, v[76:79], s[76:77] offset:3072 nt
	s_add_u32 s70, s28, 0x7000
	s_addc_u32 s71, s29, 0
	global_load_dwordx2 v[48:49], v239, s[70:71] offset:0
	global_load_dwordx2 v[50:51], v239, s[70:71] offset:512
	global_load_dwordx2 v[52:53], v239, s[70:71] offset:1024
	global_load_dwordx2 v[54:55], v239, s[70:71] offset:1536
	global_load_dwordx2 v[56:57], v239, s[70:71] offset:2048
	global_load_dwordx2 v[58:59], v239, s[70:71] offset:2560
	global_load_dwordx2 v[60:61], v239, s[70:71] offset:3072
	global_load_dwordx2 v[62:63], v239, s[70:71] offset:3584
	s_waitcnt vmcnt(16)
	s_add_u32 s76, s46, 0xc000
	s_addc_u32 s77, s47, 0
	v_lshlrev_b32_e32 v64, 16, v32
	v_and_b32_e32 v65, 0xffff0000, v32
	v_lshlrev_b32_e32 v66, 16, v33
	v_and_b32_e32 v67, 0xffff0000, v33
	v_mul_f32_e32 v64, v64, v226
	v_mul_f32_e32 v65, v65, v226
	v_mul_f32_e32 v66, v66, v226
	v_mul_f32_e32 v67, v67, v226
	v_mul_f32_e32 v64, v64, v0
	v_mul_f32_e32 v65, v65, v1
	v_mul_f32_e32 v66, v66, v2
	v_mul_f32_e32 v67, v67, v3
	global_store_dwordx4 v250, v[64:67], s[76:77] offset:0 nt
	v_lshlrev_b32_e32 v68, 16, v34
	v_and_b32_e32 v69, 0xffff0000, v34
	v_lshlrev_b32_e32 v70, 16, v35
	v_and_b32_e32 v71, 0xffff0000, v35
	v_mul_f32_e32 v68, v68, v226
	v_mul_f32_e32 v69, v69, v226
	v_mul_f32_e32 v70, v70, v226
	v_mul_f32_e32 v71, v71, v226
	v_mul_f32_e32 v68, v68, v4
	v_mul_f32_e32 v69, v69, v5
	v_mul_f32_e32 v70, v70, v6
	v_mul_f32_e32 v71, v71, v7
	global_store_dwordx4 v250, v[68:71], s[76:77] offset:1024 nt
	v_lshlrev_b32_e32 v72, 16, v36
	v_and_b32_e32 v73, 0xffff0000, v36
	v_lshlrev_b32_e32 v74, 16, v37
	v_and_b32_e32 v75, 0xffff0000, v37
	v_mul_f32_e32 v72, v72, v226
	v_mul_f32_e32 v73, v73, v226
	v_mul_f32_e32 v74, v74, v226
	v_mul_f32_e32 v75, v75, v226
	v_mul_f32_e32 v72, v72, v8
	v_mul_f32_e32 v73, v73, v9
	v_mul_f32_e32 v74, v74, v10
	v_mul_f32_e32 v75, v75, v11
	global_store_dwordx4 v250, v[72:75], s[76:77] offset:2048 nt
	v_lshlrev_b32_e32 v76, 16, v38
	v_and_b32_e32 v77, 0xffff0000, v38
	v_lshlrev_b32_e32 v78, 16, v39
	v_and_b32_e32 v79, 0xffff0000, v39
	v_mul_f32_e32 v76, v76, v226
	v_mul_f32_e32 v77, v77, v226
	v_mul_f32_e32 v78, v78, v226
	v_mul_f32_e32 v79, v79, v226
	v_mul_f32_e32 v76, v76, v12
	v_mul_f32_e32 v77, v77, v13
	v_mul_f32_e32 v78, v78, v14
	v_mul_f32_e32 v79, v79, v15
	global_store_dwordx4 v250, v[76:79], s[76:77] offset:3072 nt
	v_lshlrev_b32_e32 v64, 16, v40
	v_and_b32_e32 v65, 0xffff0000, v40
	v_lshlrev_b32_e32 v66, 16, v41
	v_and_b32_e32 v67, 0xffff0000, v41
	v_mul_f32_e32 v64, v64, v226
	v_mul_f32_e32 v65, v65, v226
	v_mul_f32_e32 v66, v66, v226
	v_mul_f32_e32 v67, v67, v226
	v_mul_f32_e32 v64, v64, v16
	v_mul_f32_e32 v65, v65, v17
	v_mul_f32_e32 v66, v66, v18
	v_mul_f32_e32 v67, v67, v19
	global_store_dwordx4 v251, v[64:67], s[76:77] offset:0 nt
	v_lshlrev_b32_e32 v68, 16, v42
	v_and_b32_e32 v69, 0xffff0000, v42
	v_lshlrev_b32_e32 v70, 16, v43
	v_and_b32_e32 v71, 0xffff0000, v43
	v_mul_f32_e32 v68, v68, v226
	v_mul_f32_e32 v69, v69, v226
	v_mul_f32_e32 v70, v70, v226
	v_mul_f32_e32 v71, v71, v226
	v_mul_f32_e32 v68, v68, v20
	v_mul_f32_e32 v69, v69, v21
	v_mul_f32_e32 v70, v70, v22
	v_mul_f32_e32 v71, v71, v23
	global_store_dwordx4 v251, v[68:71], s[76:77] offset:1024 nt
	v_lshlrev_b32_e32 v72, 16, v44
	v_and_b32_e32 v73, 0xffff0000, v44
	v_lshlrev_b32_e32 v74, 16, v45
	v_and_b32_e32 v75, 0xffff0000, v45
	v_mul_f32_e32 v72, v72, v226
	v_mul_f32_e32 v73, v73, v226
	v_mul_f32_e32 v74, v74, v226
	v_mul_f32_e32 v75, v75, v226
	v_mul_f32_e32 v72, v72, v24
	v_mul_f32_e32 v73, v73, v25
	v_mul_f32_e32 v74, v74, v26
	v_mul_f32_e32 v75, v75, v27
	global_store_dwordx4 v251, v[72:75], s[76:77] offset:2048 nt
	v_lshlrev_b32_e32 v76, 16, v46
	v_and_b32_e32 v77, 0xffff0000, v46
	v_lshlrev_b32_e32 v78, 16, v47
	v_and_b32_e32 v79, 0xffff0000, v47
	v_mul_f32_e32 v76, v76, v226
	v_mul_f32_e32 v77, v77, v226
	v_mul_f32_e32 v78, v78, v226
	v_mul_f32_e32 v79, v79, v226
	v_mul_f32_e32 v76, v76, v28
	v_mul_f32_e32 v77, v77, v29
	v_mul_f32_e32 v78, v78, v30
	v_mul_f32_e32 v79, v79, v31
	global_store_dwordx4 v251, v[76:79], s[76:77] offset:3072 nt
	s_waitcnt vmcnt(8)
	s_add_u32 s76, s46, 0xe000
	s_addc_u32 s77, s47, 0
	v_lshlrev_b32_e32 v64, 16, v48
	v_and_b32_e32 v65, 0xffff0000, v48
	v_lshlrev_b32_e32 v66, 16, v49
	v_and_b32_e32 v67, 0xffff0000, v49
	v_mul_f32_e32 v64, v64, v227
	v_mul_f32_e32 v65, v65, v227
	v_mul_f32_e32 v66, v66, v227
	v_mul_f32_e32 v67, v67, v227
	v_mul_f32_e32 v64, v64, v0
	v_mul_f32_e32 v65, v65, v1
	v_mul_f32_e32 v66, v66, v2
	v_mul_f32_e32 v67, v67, v3
	global_store_dwordx4 v250, v[64:67], s[76:77] offset:0 nt
	v_lshlrev_b32_e32 v68, 16, v50
	v_and_b32_e32 v69, 0xffff0000, v50
	v_lshlrev_b32_e32 v70, 16, v51
	v_and_b32_e32 v71, 0xffff0000, v51
	v_mul_f32_e32 v68, v68, v227
	v_mul_f32_e32 v69, v69, v227
	v_mul_f32_e32 v70, v70, v227
	v_mul_f32_e32 v71, v71, v227
	v_mul_f32_e32 v68, v68, v4
	v_mul_f32_e32 v69, v69, v5
	v_mul_f32_e32 v70, v70, v6
	v_mul_f32_e32 v71, v71, v7
	global_store_dwordx4 v250, v[68:71], s[76:77] offset:1024 nt
	v_lshlrev_b32_e32 v72, 16, v52
	v_and_b32_e32 v73, 0xffff0000, v52
	v_lshlrev_b32_e32 v74, 16, v53
	v_and_b32_e32 v75, 0xffff0000, v53
	v_mul_f32_e32 v72, v72, v227
	v_mul_f32_e32 v73, v73, v227
	v_mul_f32_e32 v74, v74, v227
	v_mul_f32_e32 v75, v75, v227
	v_mul_f32_e32 v72, v72, v8
	v_mul_f32_e32 v73, v73, v9
	v_mul_f32_e32 v74, v74, v10
	v_mul_f32_e32 v75, v75, v11
	global_store_dwordx4 v250, v[72:75], s[76:77] offset:2048 nt
	v_lshlrev_b32_e32 v76, 16, v54
	v_and_b32_e32 v77, 0xffff0000, v54
	v_lshlrev_b32_e32 v78, 16, v55
	v_and_b32_e32 v79, 0xffff0000, v55
	v_mul_f32_e32 v76, v76, v227
	v_mul_f32_e32 v77, v77, v227
	v_mul_f32_e32 v78, v78, v227
	v_mul_f32_e32 v79, v79, v227
	v_mul_f32_e32 v76, v76, v12
	v_mul_f32_e32 v77, v77, v13
	v_mul_f32_e32 v78, v78, v14
	v_mul_f32_e32 v79, v79, v15
	global_store_dwordx4 v250, v[76:79], s[76:77] offset:3072 nt
	v_lshlrev_b32_e32 v64, 16, v56
	v_and_b32_e32 v65, 0xffff0000, v56
	v_lshlrev_b32_e32 v66, 16, v57
	v_and_b32_e32 v67, 0xffff0000, v57
	v_mul_f32_e32 v64, v64, v227
	v_mul_f32_e32 v65, v65, v227
	v_mul_f32_e32 v66, v66, v227
	v_mul_f32_e32 v67, v67, v227
	v_mul_f32_e32 v64, v64, v16
	v_mul_f32_e32 v65, v65, v17
	v_mul_f32_e32 v66, v66, v18
	v_mul_f32_e32 v67, v67, v19
	global_store_dwordx4 v251, v[64:67], s[76:77] offset:0 nt
	v_lshlrev_b32_e32 v68, 16, v58
	v_and_b32_e32 v69, 0xffff0000, v58
	v_lshlrev_b32_e32 v70, 16, v59
	v_and_b32_e32 v71, 0xffff0000, v59
	v_mul_f32_e32 v68, v68, v227
	v_mul_f32_e32 v69, v69, v227
	v_mul_f32_e32 v70, v70, v227
	v_mul_f32_e32 v71, v71, v227
	v_mul_f32_e32 v68, v68, v20
	v_mul_f32_e32 v69, v69, v21
	v_mul_f32_e32 v70, v70, v22
	v_mul_f32_e32 v71, v71, v23
	global_store_dwordx4 v251, v[68:71], s[76:77] offset:1024 nt
	v_lshlrev_b32_e32 v72, 16, v60
	v_and_b32_e32 v73, 0xffff0000, v60
	v_lshlrev_b32_e32 v74, 16, v61
	v_and_b32_e32 v75, 0xffff0000, v61
	v_mul_f32_e32 v72, v72, v227
	v_mul_f32_e32 v73, v73, v227
	v_mul_f32_e32 v74, v74, v227
	v_mul_f32_e32 v75, v75, v227
	v_mul_f32_e32 v72, v72, v24
	v_mul_f32_e32 v73, v73, v25
	v_mul_f32_e32 v74, v74, v26
	v_mul_f32_e32 v75, v75, v27
	global_store_dwordx4 v251, v[72:75], s[76:77] offset:2048 nt
	v_lshlrev_b32_e32 v76, 16, v62
	v_and_b32_e32 v77, 0xffff0000, v62
	v_lshlrev_b32_e32 v78, 16, v63
	v_and_b32_e32 v79, 0xffff0000, v63
	v_mul_f32_e32 v76, v76, v227
	v_mul_f32_e32 v77, v77, v227
	v_mul_f32_e32 v78, v78, v227
	v_mul_f32_e32 v79, v79, v227
	v_mul_f32_e32 v76, v76, v28
	v_mul_f32_e32 v77, v77, v29
	v_mul_f32_e32 v78, v78, v30
	v_mul_f32_e32 v79, v79, v31
	global_store_dwordx4 v251, v[76:79], s[76:77] offset:3072 nt
	s_add_u32 s63, s63, s90
	s_cmpk_lt_i32 s63, 0x800
	s_cbranch_scc1 .LpgL1_group

	.amdhsa_kernel _Z4mega4Args
		.amdhsa_group_segment_fixed_size 0
		.amdhsa_private_segment_fixed_size 0
		.amdhsa_kernarg_size 376
		.amdhsa_user_sgpr_count 2
		.amdhsa_user_sgpr_dispatch_ptr 0
		.amdhsa_user_sgpr_queue_ptr 0
		.amdhsa_user_sgpr_kernarg_segment_ptr 1
		.amdhsa_user_sgpr_dispatch_id 0
		.amdhsa_user_sgpr_kernarg_preload_length 0
		.amdhsa_user_sgpr_kernarg_preload_offset 0
		.amdhsa_user_sgpr_private_segment_size 0
		.amdhsa_uses_dynamic_stack 0
		.amdhsa_enable_private_segment 0
		.amdhsa_system_sgpr_workgroup_id_x 1
		.amdhsa_system_sgpr_workgroup_id_y 0
		.amdhsa_system_sgpr_workgroup_id_z 0
		.amdhsa_system_sgpr_workgroup_info 0
		.amdhsa_system_vgpr_workitem_id 2
		.amdhsa_next_free_vgpr 256
		.amdhsa_next_free_sgpr 98
		.amdhsa_accum_offset 256
		.amdhsa_reserve_vcc 1
		.amdhsa_float_round_mode_32 0
		.amdhsa_float_round_mode_16_64 0
		.amdhsa_float_denorm_mode_32 3
		.amdhsa_float_denorm_mode_16_64 3
		.amdhsa_dx10_clamp 1
		.amdhsa_ieee_mode 1
		.amdhsa_fp16_overflow 0
		.amdhsa_tg_split 0
		.amdhsa_exception_fp_ieee_invalid_op 0
		.amdhsa_exception_fp_denorm_src 0
		.amdhsa_exception_fp_ieee_div_zero 0
		.amdhsa_exception_fp_ieee_overflow 0
		.amdhsa_exception_fp_ieee_underflow 0
		.amdhsa_exception_fp_ieee_inexact 0
		.amdhsa_exception_int_div_zero 0
	.end_amdhsa_kernel

amdhsa.kernels:
  - .agpr_count:     0
    .args:
      - .offset:         0
        .size:           120
        .value_kind:     by_value
      - .offset:         120
        .size:           4
        .value_kind:     hidden_block_count_x
      - .offset:         124
        .size:           4
        .value_kind:     hidden_block_count_y
      - .offset:         128
        .size:           4
        .value_kind:     hidden_block_count_z
      - .offset:         132
        .size:           2
        .value_kind:     hidden_group_size_x
      - .offset:         134
        .size:           2
        .value_kind:     hidden_group_size_y
      - .offset:         136
        .size:           2
        .value_kind:     hidden_group_size_z
      - .offset:         138
        .size:           2
        .value_kind:     hidden_remainder_x
      - .offset:         140
        .size:           2
        .value_kind:     hidden_remainder_y
      - .offset:         142
        .size:           2
        .value_kind:     hidden_remainder_z
      - .offset:         160
        .size:           8
        .value_kind:     hidden_global_offset_x
      - .offset:         168
        .size:           8
        .value_kind:     hidden_global_offset_y
      - .offset:         176
        .size:           8
        .value_kind:     hidden_global_offset_z
      - .offset:         184
        .size:           2
        .value_kind:     hidden_grid_dims
      - .offset:         208
        .size:           8
        .value_kind:     hidden_multigrid_sync_arg
      - .offset:         240
        .size:           4
        .value_kind:     hidden_dynamic_lds_size
    .group_segment_fixed_size: 0
    .kernarg_segment_align: 8
    .kernarg_segment_size: 376
    .language:       OpenCL C
    .language_version:
      - 2
      - 0
    .max_flat_workgroup_size: 512
    .name:           _Z4mega4Args
    .private_segment_fixed_size: 0
    .sgpr_count:     104
    .sgpr_spill_count: 13
    .symbol:         _Z4mega4Args.kd
    .uniform_work_group_size: 1
    .uses_dynamic_stack: false
    .vgpr_count:     256
    .vgpr_spill_count: 0
    .wavefront_size: 64
